# speedup vs baseline: 1.0045x; 1.0045x over previous
; #define PG8_STAGE(bufoff, gbase, voff) do { _Pragma("unroll") for (int _i = 0; _i < 2; ++_i) \
;         __builtin_amdgcn_global_load_lds((const unsigned*)((const char*)(gbase) + (voff)[_i]), (PG8_LAS unsigned*)(lds + (bufoff) + ldsw + _i * 8192), 16, 0, 0); } while (0)
; #define PG8_LDA(dst, b, h) do { _Pragma("unroll") for (int m = 0; m < 4; ++m) _Pragma("unroll") for (int k = 0; k < 2; ++k) dst[m][k] = *(const PG8_LAS bf16x8*)(lds + PG8_SA(b, h) + aoff + m * 2048 + k * 1024); } while (0)
; #define PG8_LDB(dst, b, h) do { _Pragma("unroll") for (int n = 0; n < 2; ++n) _Pragma("unroll") for (int k = 0; k < 2; ++k) dst[n][k] = *(const PG8_LAS bf16x8*)(lds + PG8_SB(b, h) + boff + n * 2048 + k * 1024); } while (0)
; #define PG8_MMA(ai, bj, At, Bt) do { __builtin_amdgcn_s_setprio(1); _Pragma("unroll") for (int m = 0; m < 4; ++m) _Pragma("unroll") for (int n = 0; n < 2; ++n) _Pragma("unroll") for (int k = 0; k < 2; ++k) \
;         acc[ai][bj][m][n] = __builtin_amdgcn_mfma_f32_16x16x32_bf16(Bt[n][k], At[m][k], acc[ai][bj][m][n], 0, 0, 0); __builtin_amdgcn_s_setprio(0); } while (0)
; #define PG8_WAIT_V(n) asm volatile("s_waitcnt vmcnt(" #n ")" ::: "memory")
; #define PG8_WAIT_L(n) asm volatile("s_waitcnt lgkmcnt(" #n ")" ::: "memory")
; template <class Epi, class Sched, bool ALIGN_EPI = false, bool SP2 = false>
; __device__ __forceinline__ void gemm_phase(PG8_LAS unsigned char* lds, const Gemm g, const Sched& S, const Epi& E) {
;     ...
;             const bool last = (t == nt - 2);
;             const char* a1 = cA + (size_t)(t + 1) * kstep;
;             const char* a2 = last ? nA : cA + (size_t)(t + 2) * kstep; const char* b2 = last ? nB : cB + (size_t)(t + 2) * kstep;
;             const char* a3 = a2 + kstep; const char* b3 = b2 + kstep;
;             if (last && has_next) S.a_ready(nxt);
;             if constexpr (SP2) {
;             PG8_LDB(B0, 0, 0); PG8_LDB(B1, 0, 1); PG8_SCHED; PG8_LDA(At, 0, 0); PG8_STAGE(PG8_SA(1, 1), a1 + hstep, voffA);
;             PG8_WAIT_V(8); PG8_WAIT_L(0); PG8_BAR; PG8_MMA(0, 0, At, B0); PG8_MMA(0, 1, At, B1); PG8_BAR; PG8_SCHED;
;             PG8_LDA(At, 0, 1); PG8_STAGE(PG8_SB(0, 0), b2, voffB); PG8_STAGE(PG8_SB(0, 1), b2 + hstep, voffB); PG8_STAGE(PG8_SA(0, 0), a2, voffA);
;             PG8_WAIT_V(8); PG8_WAIT_L(0); PG8_BAR; PG8_MMA(1, 0, At, B0); PG8_MMA(1, 1, At, B1); PG8_BAR; PG8_SCHED;
.LBB0_121:
	ds_read_b128 v[148:151], v159
	ds_read_b128 v[168:171], v159 offset:1024
	ds_read_b128 v[172:175], v159 offset:2048
	ds_read_b128 v[176:179], v159 offset:3072
	ds_read_b128 v[180:183], v160
	ds_read_b128 v[184:187], v160 offset:1024
	ds_read_b128 v[188:191], v160 offset:2048
	ds_read_b128 v[192:195], v160 offset:3072
	s_add_i32 s46, s42, 2
	s_add_u32 s47, s6, 0x80
	s_addc_u32 s43, s7, 0
	s_cmp_eq_u32 s93, s42
	s_cselect_b32 s42, s38, s47
	s_cselect_b32 s43, s39, s43
	s_cselect_b32 s69, s41, vcc_lo
	s_cselect_b32 s68, s40, s0
	v_lshl_add_u64 v[152:153], s[6:7], 0, v[142:143]
	s_add_i32 m0, s64, 0xc000
	ds_read_b128 v[196:199], v161
	ds_read_b128 v[200:203], v161 offset:1024
	ds_read_b128 v[204:207], v161 offset:2048
	ds_read_b128 v[208:211], v161 offset:3072
	ds_read_b128 v[212:215], v161 offset:4096
	ds_read_b128 v[216:219], v161 offset:5120
	ds_read_b128 v[220:223], v161 offset:6144
	ds_read_b128 v[224:227], v161 offset:7168
	global_load_lds_dwordx4 v[152:153], off
	v_lshl_add_u64 v[152:153], s[6:7], 0, v[140:141]
	s_add_i32 m0, s64, 0xe000
	s_nop 0
	global_load_lds_dwordx4 v[152:153], off
	s_waitcnt vmcnt(8)
	s_waitcnt lgkmcnt(0)
	s_barrier
	s_setprio 1
	v_mfma_f32_16x16x32_bf16 v[126:129], v[148:151], v[196:199], v[126:129]
	v_mfma_f32_16x16x32_bf16 v[122:125], v[172:175], v[196:199], v[122:125]
	v_mfma_f32_16x16x32_bf16 v[110:113], v[148:151], v[204:207], v[110:113]
	v_mfma_f32_16x16x32_bf16 v[106:109], v[172:175], v[204:207], v[106:109]
	v_mfma_f32_16x16x32_bf16 v[94:97], v[148:151], v[212:215], v[94:97]
	v_mfma_f32_16x16x32_bf16 v[90:93], v[172:175], v[212:215], v[90:93]
	v_mfma_f32_16x16x32_bf16 v[78:81], v[148:151], v[220:223], v[78:81]
	v_mfma_f32_16x16x32_bf16 v[74:77], v[172:175], v[220:223], v[74:77]
	v_mfma_f32_16x16x32_bf16 v[126:129], v[168:171], v[200:203], v[126:129]
	v_mfma_f32_16x16x32_bf16 v[122:125], v[176:179], v[200:203], v[122:125]
	v_mfma_f32_16x16x32_bf16 v[110:113], v[168:171], v[208:211], v[110:113]
	v_mfma_f32_16x16x32_bf16 v[106:109], v[176:179], v[208:211], v[106:109]
	v_mfma_f32_16x16x32_bf16 v[94:97], v[168:171], v[216:219], v[94:97]
	v_mfma_f32_16x16x32_bf16 v[90:93], v[176:179], v[216:219], v[90:93]
	v_mfma_f32_16x16x32_bf16 v[78:81], v[168:171], v[224:227], v[78:81]
	v_mfma_f32_16x16x32_bf16 v[74:77], v[176:179], v[224:227], v[74:77]
	v_mfma_f32_16x16x32_bf16 v[118:121], v[180:183], v[196:199], v[118:121]
	v_mfma_f32_16x16x32_bf16 v[114:117], v[188:191], v[196:199], v[114:117]
	v_mfma_f32_16x16x32_bf16 v[102:105], v[180:183], v[204:207], v[102:105]
	v_mfma_f32_16x16x32_bf16 v[98:101], v[188:191], v[204:207], v[98:101]
	v_mfma_f32_16x16x32_bf16 v[86:89], v[180:183], v[212:215], v[86:89]
	v_mfma_f32_16x16x32_bf16 v[82:85], v[188:191], v[212:215], v[82:85]
	v_mfma_f32_16x16x32_bf16 v[70:73], v[180:183], v[220:223], v[70:73]
	v_mfma_f32_16x16x32_bf16 v[66:69], v[188:191], v[220:223], v[66:69]
	v_mfma_f32_16x16x32_bf16 v[118:121], v[184:187], v[200:203], v[118:121]
	v_mfma_f32_16x16x32_bf16 v[114:117], v[192:195], v[200:203], v[114:117]
	v_mfma_f32_16x16x32_bf16 v[102:105], v[184:187], v[208:211], v[102:105]
	v_mfma_f32_16x16x32_bf16 v[98:101], v[192:195], v[208:211], v[98:101]
	v_mfma_f32_16x16x32_bf16 v[86:89], v[184:187], v[216:219], v[86:89]
	v_mfma_f32_16x16x32_bf16 v[82:85], v[192:195], v[216:219], v[82:85]
	v_mfma_f32_16x16x32_bf16 v[70:73], v[184:187], v[224:227], v[70:73]
	v_mfma_f32_16x16x32_bf16 v[66:69], v[192:195], v[224:227], v[66:69]
	s_setprio 0
	s_barrier
	s_add_i32 s47, s97, s55
	v_lshl_add_u64 v[152:153], s[68:69], 0, v[132:133]
	s_mov_b32 m0, s47
	ds_read_b128 v[196:199], v161 offset:16384
	ds_read_b128 v[200:203], v161 offset:17408
	ds_read_b128 v[204:207], v161 offset:18432
	ds_read_b128 v[208:211], v161 offset:19456
	ds_read_b128 v[212:215], v161 offset:20480
	ds_read_b128 v[216:219], v161 offset:21504
	ds_read_b128 v[220:223], v161 offset:22528
	ds_read_b128 v[224:227], v161 offset:23552
	global_load_lds_dwordx4 v[152:153], off
	s_add_i32 m0, s47, 0x2000
	v_lshl_add_u64 v[228:229], s[68:69], 0, v[136:137]
	s_add_u32 s68, s68, s10
	s_addc_u32 s69, s69, s11
	s_add_i32 s47, s80, s55
	global_load_lds_dwordx4 v[228:229], off
	v_lshl_add_u64 v[230:231], s[68:69], 0, v[132:133]
	s_mov_b32 m0, s47
	v_lshl_add_u64 v[232:233], s[68:69], 0, v[136:137]
	global_load_lds_dwordx4 v[230:231], off
	s_add_i32 m0, s47, 0x2000
	v_lshl_add_u64 v[234:235], s[42:43], 0, v[130:131]
	global_load_lds_dwordx4 v[232:233], off
	s_mov_b32 m0, s64
	v_lshl_add_u64 v[236:237], s[42:43], 0, v[134:135]
	global_load_lds_dwordx4 v[234:235], off
	s_mov_b32 m0, s65
	s_nop 0
	global_load_lds_dwordx4 v[236:237], off
	s_waitcnt vmcnt(8)
	s_waitcnt lgkmcnt(0)
	s_barrier
; #define PG8_STAGE(bufoff, gbase, voff) do { _Pragma("unroll") for (int _i = 0; _i < 2; ++_i) \
;         __builtin_amdgcn_global_load_lds((const unsigned*)((const char*)(gbase) + (voff)[_i]), (PG8_LAS unsigned*)(lds + (bufoff) + ldsw + _i * 8192), 16, 0, 0); } while (0)
; #define PG8_LDA(dst, b, h) do { _Pragma("unroll") for (int m = 0; m < 4; ++m) _Pragma("unroll") for (int k = 0; k < 2; ++k) dst[m][k] = *(const PG8_LAS bf16x8*)(lds + PG8_SA(b, h) + aoff + m * 2048 + k * 1024); } while (0)
; #define PG8_LDB(dst, b, h) do { _Pragma("unroll") for (int n = 0; n < 2; ++n) _Pragma("unroll") for (int k = 0; k < 2; ++k) dst[n][k] = *(const PG8_LAS bf16x8*)(lds + PG8_SB(b, h) + boff + n * 2048 + k * 1024); } while (0)
; #define PG8_MMA(ai, bj, At, Bt) do { __builtin_amdgcn_s_setprio(1); _Pragma("unroll") for (int m = 0; m < 4; ++m) _Pragma("unroll") for (int n = 0; n < 2; ++n) _Pragma("unroll") for (int k = 0; k < 2; ++k) \
;         acc[ai][bj][m][n] = __builtin_amdgcn_mfma_f32_16x16x32_bf16(Bt[n][k], At[m][k], acc[ai][bj][m][n], 0, 0, 0); __builtin_amdgcn_s_setprio(0); } while (0)
; #define PG8_WAIT_V(n) asm volatile("s_waitcnt vmcnt(" #n ")" ::: "memory")
; #define PG8_WAIT_L(n) asm volatile("s_waitcnt lgkmcnt(" #n ")" ::: "memory")
; #define PG8_BAR __builtin_amdgcn_s_barrier()
; #define PG8_SCHED __builtin_amdgcn_sched_barrier(0)
; template <class Epi, class Sched, bool ALIGN_EPI = false, bool SP2 = false>
; __device__ __forceinline__ void gemm_phase(PG8_LAS unsigned char* lds, const Gemm g, const Sched& S, const Epi& E) {
;     ...
;             PG8_WAIT_V(8); PG8_WAIT_L(0); PG8_BAR; PG8_MMA(1, 0, At, B0); PG8_MMA(1, 1, At, B1); PG8_BAR; PG8_SCHED;
;             PG8_LDB(B0, 1, 0); PG8_LDB(B1, 1, 1); PG8_SCHED; PG8_LDA(At, 1, 0); PG8_STAGE(PG8_SA(0, 1), a2 + hstep, voffA);
;             PG8_WAIT_V(8); PG8_WAIT_L(0); PG8_BAR; PG8_MMA(0, 0, At, B0); PG8_MMA(0, 1, At, B1); PG8_BAR; PG8_SCHED;
	s_setprio 1
	v_mfma_f32_16x16x32_bf16 v[62:65], v[148:151], v[196:199], v[62:65]
	v_mfma_f32_16x16x32_bf16 v[58:61], v[172:175], v[196:199], v[58:61]
	v_mfma_f32_16x16x32_bf16 v[46:49], v[148:151], v[204:207], v[46:49]
	v_mfma_f32_16x16x32_bf16 v[42:45], v[172:175], v[204:207], v[42:45]
	v_mfma_f32_16x16x32_bf16 v[30:33], v[148:151], v[212:215], v[30:33]
	v_mfma_f32_16x16x32_bf16 v[26:29], v[172:175], v[212:215], v[26:29]
	v_mfma_f32_16x16x32_bf16 v[14:17], v[148:151], v[220:223], v[14:17]
	v_mfma_f32_16x16x32_bf16 v[10:13], v[172:175], v[220:223], v[10:13]
	v_mfma_f32_16x16x32_bf16 v[62:65], v[168:171], v[200:203], v[62:65]
	v_mfma_f32_16x16x32_bf16 v[58:61], v[176:179], v[200:203], v[58:61]
	v_mfma_f32_16x16x32_bf16 v[46:49], v[168:171], v[208:211], v[46:49]
	v_mfma_f32_16x16x32_bf16 v[42:45], v[176:179], v[208:211], v[42:45]
	v_mfma_f32_16x16x32_bf16 v[30:33], v[168:171], v[216:219], v[30:33]
	v_mfma_f32_16x16x32_bf16 v[26:29], v[176:179], v[216:219], v[26:29]
	v_mfma_f32_16x16x32_bf16 v[14:17], v[168:171], v[224:227], v[14:17]
	v_mfma_f32_16x16x32_bf16 v[10:13], v[176:179], v[224:227], v[10:13]
	v_mfma_f32_16x16x32_bf16 v[54:57], v[180:183], v[196:199], v[54:57]
	v_mfma_f32_16x16x32_bf16 v[50:53], v[188:191], v[196:199], v[50:53]
	v_mfma_f32_16x16x32_bf16 v[38:41], v[180:183], v[204:207], v[38:41]
	v_mfma_f32_16x16x32_bf16 v[34:37], v[188:191], v[204:207], v[34:37]
	v_mfma_f32_16x16x32_bf16 v[22:25], v[180:183], v[212:215], v[22:25]
	v_mfma_f32_16x16x32_bf16 v[18:21], v[188:191], v[212:215], v[18:21]
	v_mfma_f32_16x16x32_bf16 v[6:9], v[180:183], v[220:223], v[6:9]
	v_mfma_f32_16x16x32_bf16 v[2:5], v[188:191], v[220:223], v[2:5]
	v_mfma_f32_16x16x32_bf16 v[54:57], v[184:187], v[200:203], v[54:57]
	v_mfma_f32_16x16x32_bf16 v[50:53], v[192:195], v[200:203], v[50:53]
	v_mfma_f32_16x16x32_bf16 v[38:41], v[184:187], v[208:211], v[38:41]
	v_mfma_f32_16x16x32_bf16 v[34:37], v[192:195], v[208:211], v[34:37]
	v_mfma_f32_16x16x32_bf16 v[22:25], v[184:187], v[216:219], v[22:25]
	v_mfma_f32_16x16x32_bf16 v[18:21], v[192:195], v[216:219], v[18:21]
	v_mfma_f32_16x16x32_bf16 v[6:9], v[184:187], v[224:227], v[6:9]
	v_mfma_f32_16x16x32_bf16 v[2:5], v[192:195], v[224:227], v[2:5]
	s_setprio 0
	s_barrier
	s_add_i32 s47, 0, 0x18000
	v_add_u32_e32 v138, s47, v154
	s_add_i32 s68, 0, 0x1c000
	ds_read_b128 v[148:151], v138
	ds_read_b128 v[168:171], v138 offset:1024
	ds_read_b128 v[172:175], v138 offset:2048
	ds_read_b128 v[176:179], v138 offset:3072
	v_add_u32_e32 v138, s68, v154
	ds_read_b128 v[180:183], v138
	ds_read_b128 v[184:187], v138 offset:1024
	ds_read_b128 v[188:191], v138 offset:2048
	ds_read_b128 v[192:195], v138 offset:3072
	s_add_u32 s42, s42, s10
	s_addc_u32 s43, s43, s11
	s_mov_b32 m0, s66
	v_lshl_add_u64 v[238:239], s[42:43], 0, v[130:131]
	ds_read_b128 v[196:199], v161 offset:32768
	ds_read_b128 v[200:203], v161 offset:33792
	ds_read_b128 v[204:207], v161 offset:34816
	ds_read_b128 v[208:211], v161 offset:35840
	ds_read_b128 v[212:215], v161 offset:36864
	ds_read_b128 v[216:219], v161 offset:37888
	ds_read_b128 v[220:223], v161 offset:38912
	ds_read_b128 v[224:227], v161 offset:39936
	global_load_lds_dwordx4 v[238:239], off
	v_lshl_add_u64 v[238:239], s[42:43], 0, v[134:135]
	s_mov_b32 m0, s67
	s_nop 0
	global_load_lds_dwordx4 v[238:239], off
	s_waitcnt vmcnt(8)
	s_waitcnt lgkmcnt(0)
	s_barrier
	s_setprio 1
	v_mfma_f32_16x16x32_bf16 v[126:129], v[148:151], v[196:199], v[126:129]
	v_mfma_f32_16x16x32_bf16 v[122:125], v[172:175], v[196:199], v[122:125]
	v_mfma_f32_16x16x32_bf16 v[110:113], v[148:151], v[204:207], v[110:113]
	v_mfma_f32_16x16x32_bf16 v[106:109], v[172:175], v[204:207], v[106:109]
	v_mfma_f32_16x16x32_bf16 v[94:97], v[148:151], v[212:215], v[94:97]
	v_mfma_f32_16x16x32_bf16 v[90:93], v[172:175], v[212:215], v[90:93]
	v_mfma_f32_16x16x32_bf16 v[78:81], v[148:151], v[220:223], v[78:81]
	v_mfma_f32_16x16x32_bf16 v[74:77], v[172:175], v[220:223], v[74:77]
	v_mfma_f32_16x16x32_bf16 v[126:129], v[168:171], v[200:203], v[126:129]
	v_mfma_f32_16x16x32_bf16 v[122:125], v[176:179], v[200:203], v[122:125]
	v_mfma_f32_16x16x32_bf16 v[110:113], v[168:171], v[208:211], v[110:113]
	v_mfma_f32_16x16x32_bf16 v[106:109], v[176:179], v[208:211], v[106:109]
	v_mfma_f32_16x16x32_bf16 v[94:97], v[168:171], v[216:219], v[94:97]
	v_mfma_f32_16x16x32_bf16 v[90:93], v[176:179], v[216:219], v[90:93]
	v_mfma_f32_16x16x32_bf16 v[78:81], v[168:171], v[224:227], v[78:81]
	v_mfma_f32_16x16x32_bf16 v[74:77], v[176:179], v[224:227], v[74:77]
	v_mfma_f32_16x16x32_bf16 v[118:121], v[180:183], v[196:199], v[118:121]
	v_mfma_f32_16x16x32_bf16 v[114:117], v[188:191], v[196:199], v[114:117]
	v_mfma_f32_16x16x32_bf16 v[102:105], v[180:183], v[204:207], v[102:105]
	v_mfma_f32_16x16x32_bf16 v[98:101], v[188:191], v[204:207], v[98:101]
	v_mfma_f32_16x16x32_bf16 v[86:89], v[180:183], v[212:215], v[86:89]
	v_mfma_f32_16x16x32_bf16 v[82:85], v[188:191], v[212:215], v[82:85]
	v_mfma_f32_16x16x32_bf16 v[70:73], v[180:183], v[220:223], v[70:73]
	v_mfma_f32_16x16x32_bf16 v[66:69], v[188:191], v[220:223], v[66:69]
	v_mfma_f32_16x16x32_bf16 v[118:121], v[184:187], v[200:203], v[118:121]
	v_mfma_f32_16x16x32_bf16 v[114:117], v[192:195], v[200:203], v[114:117]
	v_mfma_f32_16x16x32_bf16 v[102:105], v[184:187], v[208:211], v[102:105]
	v_mfma_f32_16x16x32_bf16 v[98:101], v[192:195], v[208:211], v[98:101]
	v_mfma_f32_16x16x32_bf16 v[86:89], v[184:187], v[216:219], v[86:89]
	v_mfma_f32_16x16x32_bf16 v[82:85], v[192:195], v[216:219], v[82:85]
	v_mfma_f32_16x16x32_bf16 v[70:73], v[184:187], v[224:227], v[70:73]
	v_mfma_f32_16x16x32_bf16 v[66:69], v[192:195], v[224:227], v[66:69]
	s_setprio 0
	s_barrier
; #define PG8_STAGE(bufoff, gbase, voff) do { _Pragma("unroll") for (int _i = 0; _i < 2; ++_i) \
;         __builtin_amdgcn_global_load_lds((const unsigned*)((const char*)(gbase) + (voff)[_i]), (PG8_LAS unsigned*)(lds + (bufoff) + ldsw + _i * 8192), 16, 0, 0); } while (0)
; #define PG8_LDA(dst, b, h) do { _Pragma("unroll") for (int m = 0; m < 4; ++m) _Pragma("unroll") for (int k = 0; k < 2; ++k) dst[m][k] = *(const PG8_LAS bf16x8*)(lds + PG8_SA(b, h) + aoff + m * 2048 + k * 1024); } while (0)
; #define PG8_MMA(ai, bj, At, Bt) do { __builtin_amdgcn_s_setprio(1); _Pragma("unroll") for (int m = 0; m < 4; ++m) _Pragma("unroll") for (int n = 0; n < 2; ++n) _Pragma("unroll") for (int k = 0; k < 2; ++k) \
;         acc[ai][bj][m][n] = __builtin_amdgcn_mfma_f32_16x16x32_bf16(Bt[n][k], At[m][k], acc[ai][bj][m][n], 0, 0, 0); __builtin_amdgcn_s_setprio(0); } while (0)
; #define PG8_WAIT_V(n) asm volatile("s_waitcnt vmcnt(" #n ")" ::: "memory")
; #define PG8_WAIT_L(n) asm volatile("s_waitcnt lgkmcnt(" #n ")" ::: "memory")
; #define PG8_BAR __builtin_amdgcn_s_barrier()
; #define PG8_SCHED __builtin_amdgcn_sched_barrier(0)
; template <class Epi, class Sched, bool ALIGN_EPI = false, bool SP2 = false>
; __device__ __forceinline__ void gemm_phase(PG8_LAS unsigned char* lds, const Gemm g, const Sched& S, const Epi& E) {
;     ...
;             PG8_LDA(At, 1, 1); PG8_STAGE(PG8_SB(1, 0), b3, voffB); PG8_STAGE(PG8_SB(1, 1), b3 + hstep, voffB); PG8_STAGE(PG8_SA(1, 0), a3, voffA);
;             PG8_WAIT_V(8); PG8_WAIT_L(0); PG8_BAR; PG8_MMA(1, 0, At, B0); PG8_MMA(1, 1, At, B1); PG8_BAR; PG8_SCHED;
	s_add_i32 s42, s47, s55
	v_lshl_add_u64 v[152:153], v[152:153], 0, s[30:31]
	s_mov_b32 m0, s42
	ds_read_b128 v[196:199], v161 offset:49152
	ds_read_b128 v[200:203], v161 offset:50176
	ds_read_b128 v[204:207], v161 offset:51200
	ds_read_b128 v[208:211], v161 offset:52224
	ds_read_b128 v[212:215], v161 offset:53248
	ds_read_b128 v[216:219], v161 offset:54272
	ds_read_b128 v[220:223], v161 offset:55296
	ds_read_b128 v[224:227], v161 offset:56320
	global_load_lds_dwordx4 v[152:153], off
	v_lshl_add_u64 v[152:153], v[228:229], 0, s[30:31]
	s_add_i32 m0, s42, 0x2000
	s_add_i32 s42, s68, s55
	global_load_lds_dwordx4 v[152:153], off
	v_lshl_add_u64 v[152:153], v[230:231], 0, s[30:31]
	s_mov_b32 m0, s42
	s_nop 0
	global_load_lds_dwordx4 v[152:153], off
	v_lshl_add_u64 v[152:153], v[232:233], 0, s[30:31]
	s_add_i32 m0, s42, 0x2000
	s_nop 0
	global_load_lds_dwordx4 v[152:153], off
	v_lshl_add_u64 v[152:153], v[234:235], 0, s[30:31]
	s_mov_b32 m0, s89
	s_nop 0
	global_load_lds_dwordx4 v[152:153], off
	v_lshl_add_u64 v[152:153], v[236:237], 0, s[30:31]
	s_mov_b32 m0, s90
	s_nop 0
	global_load_lds_dwordx4 v[152:153], off
	s_waitcnt vmcnt(8)
	s_waitcnt lgkmcnt(0)
	s_barrier
	s_setprio 1
	v_mfma_f32_16x16x32_bf16 v[62:65], v[148:151], v[196:199], v[62:65]
	v_mfma_f32_16x16x32_bf16 v[58:61], v[172:175], v[196:199], v[58:61]
	v_mfma_f32_16x16x32_bf16 v[46:49], v[148:151], v[204:207], v[46:49]
	v_mfma_f32_16x16x32_bf16 v[42:45], v[172:175], v[204:207], v[42:45]
	v_mfma_f32_16x16x32_bf16 v[30:33], v[148:151], v[212:215], v[30:33]
	v_mfma_f32_16x16x32_bf16 v[26:29], v[172:175], v[212:215], v[26:29]
	v_mfma_f32_16x16x32_bf16 v[14:17], v[148:151], v[220:223], v[14:17]
	v_mfma_f32_16x16x32_bf16 v[10:13], v[172:175], v[220:223], v[10:13]
	v_mfma_f32_16x16x32_bf16 v[62:65], v[168:171], v[200:203], v[62:65]
	v_mfma_f32_16x16x32_bf16 v[58:61], v[176:179], v[200:203], v[58:61]
	v_mfma_f32_16x16x32_bf16 v[46:49], v[168:171], v[208:211], v[46:49]
	v_mfma_f32_16x16x32_bf16 v[42:45], v[176:179], v[208:211], v[42:45]
	v_mfma_f32_16x16x32_bf16 v[30:33], v[168:171], v[216:219], v[30:33]
	v_mfma_f32_16x16x32_bf16 v[26:29], v[176:179], v[216:219], v[26:29]
	v_mfma_f32_16x16x32_bf16 v[14:17], v[168:171], v[224:227], v[14:17]
	v_mfma_f32_16x16x32_bf16 v[10:13], v[176:179], v[224:227], v[10:13]
	v_mfma_f32_16x16x32_bf16 v[54:57], v[180:183], v[196:199], v[54:57]
	v_mfma_f32_16x16x32_bf16 v[50:53], v[188:191], v[196:199], v[50:53]
	v_mfma_f32_16x16x32_bf16 v[38:41], v[180:183], v[204:207], v[38:41]
	v_mfma_f32_16x16x32_bf16 v[34:37], v[188:191], v[204:207], v[34:37]
	v_mfma_f32_16x16x32_bf16 v[22:25], v[180:183], v[212:215], v[22:25]
	v_mfma_f32_16x16x32_bf16 v[18:21], v[188:191], v[212:215], v[18:21]
	v_mfma_f32_16x16x32_bf16 v[6:9], v[180:183], v[220:223], v[6:9]
	v_mfma_f32_16x16x32_bf16 v[2:5], v[188:191], v[220:223], v[2:5]
	v_mfma_f32_16x16x32_bf16 v[54:57], v[184:187], v[200:203], v[54:57]
	v_mfma_f32_16x16x32_bf16 v[50:53], v[192:195], v[200:203], v[50:53]
	v_mfma_f32_16x16x32_bf16 v[38:41], v[184:187], v[208:211], v[38:41]
	v_mfma_f32_16x16x32_bf16 v[34:37], v[192:195], v[208:211], v[34:37]
	v_mfma_f32_16x16x32_bf16 v[22:25], v[184:187], v[216:219], v[22:25]
	v_mfma_f32_16x16x32_bf16 v[18:21], v[192:195], v[216:219], v[18:21]
	v_mfma_f32_16x16x32_bf16 v[6:9], v[184:187], v[224:227], v[6:9]
	v_mfma_f32_16x16x32_bf16 v[2:5], v[192:195], v[224:227], v[2:5]
	s_setprio 0
	s_barrier
	s_add_u32 s0, s0, 0x100
	s_addc_u32 vcc_lo, vcc_lo, 0
	s_add_u32 s6, s6, 0x100
	s_addc_u32 s7, s7, 0
	s_cmp_ge_i32 s46, s91
	s_mov_b32 s42, s46
	s_cbranch_scc0 .LBB0_121

; #define PG8_STAGE(bufoff, gbase, voff) do { _Pragma("unroll") for (int _i = 0; _i < 2; ++_i) \
;         __builtin_amdgcn_global_load_lds((const unsigned*)((const char*)(gbase) + (voff)[_i]), (PG8_LAS unsigned*)(lds + (bufoff) + ldsw + _i * 8192), 16, 0, 0); } while (0)
; #define PG8_LDA(dst, b, h) do { _Pragma("unroll") for (int m = 0; m < 4; ++m) _Pragma("unroll") for (int k = 0; k < 2; ++k) dst[m][k] = *(const PG8_LAS bf16x8*)(lds + PG8_SA(b, h) + aoff + m * 2048 + k * 1024); } while (0)
; #define PG8_LDB(dst, b, h) do { _Pragma("unroll") for (int n = 0; n < 2; ++n) _Pragma("unroll") for (int k = 0; k < 2; ++k) dst[n][k] = *(const PG8_LAS bf16x8*)(lds + PG8_SB(b, h) + boff + n * 2048 + k * 1024); } while (0)
; #define PG8_MMA(ai, bj, At, Bt) do { __builtin_amdgcn_s_setprio(1); _Pragma("unroll") for (int m = 0; m < 4; ++m) _Pragma("unroll") for (int n = 0; n < 2; ++n) _Pragma("unroll") for (int k = 0; k < 2; ++k) \
;         acc[ai][bj][m][n] = __builtin_amdgcn_mfma_f32_16x16x32_bf16(Bt[n][k], At[m][k], acc[ai][bj][m][n], 0, 0, 0); __builtin_amdgcn_s_setprio(0); } while (0)
; #define PG8_WAIT_V(n) asm volatile("s_waitcnt vmcnt(" #n ")" ::: "memory")
; #define PG8_WAIT_L(n) asm volatile("s_waitcnt lgkmcnt(" #n ")" ::: "memory")
; template <class Epi, class Sched, bool ALIGN_EPI = false, bool SP2 = false>
; __device__ __forceinline__ void gemm_phase(PG8_LAS unsigned char* lds, const Gemm g, const Sched& S, const Epi& E) {
;     ...
;             const bool last = (t == nt - 2);
;             const char* a1 = cA + (size_t)(t + 1) * kstep;
;             const char* a2 = last ? nA : cA + (size_t)(t + 2) * kstep; const char* b2 = last ? nB : cB + (size_t)(t + 2) * kstep;
;             const char* a3 = a2 + kstep; const char* b3 = b2 + kstep;
;             if (last && has_next) S.a_ready(nxt);
;             if constexpr (SP2) {
;             PG8_LDB(B0, 0, 0); PG8_LDB(B1, 0, 1); PG8_SCHED; PG8_LDA(At, 0, 0); PG8_STAGE(PG8_SA(1, 1), a1 + hstep, voffA);
;             PG8_WAIT_V(8); PG8_WAIT_L(0); PG8_BAR; PG8_MMA(0, 0, At, B0); PG8_MMA(0, 1, At, B1); PG8_BAR; PG8_SCHED;
;             PG8_LDA(At, 0, 1); PG8_STAGE(PG8_SB(0, 0), b2, voffB); PG8_STAGE(PG8_SB(0, 1), b2 + hstep, voffB); PG8_STAGE(PG8_SA(0, 0), a2, voffA);
;             PG8_WAIT_V(8); PG8_WAIT_L(0); PG8_BAR; PG8_MMA(1, 0, At, B0); PG8_MMA(1, 1, At, B1); PG8_BAR; PG8_SCHED;
.LBB0_497:
	ds_read_b128 v[146:149], v152
	ds_read_b128 v[156:159], v152 offset:1024
	ds_read_b128 v[160:163], v152 offset:2048
	ds_read_b128 v[164:167], v152 offset:3072
	ds_read_b128 v[168:171], v153
	ds_read_b128 v[172:175], v153 offset:1024
	ds_read_b128 v[176:179], v153 offset:2048
	ds_read_b128 v[180:183], v153 offset:3072
	s_add_i32 s60, s34, 2
	s_add_u32 s61, s30, 0x80
	s_addc_u32 s35, s31, 0
	s_cmp_eq_u32 s44, s34
	s_cselect_b32 s34, s6, s61
	s_cselect_b32 s35, s7, s35
	s_cselect_b32 s63, s29, s59
	s_cselect_b32 s62, s28, s58
	v_lshl_add_u64 v[216:217], s[30:31], 0, v[140:141]
	s_add_i32 m0, s39, 0xc000
	ds_read_b128 v[184:187], v154
	ds_read_b128 v[188:191], v154 offset:1024
	ds_read_b128 v[192:195], v154 offset:2048
	ds_read_b128 v[196:199], v154 offset:3072
	ds_read_b128 v[200:203], v154 offset:4096
	ds_read_b128 v[204:207], v154 offset:5120
	ds_read_b128 v[208:211], v154 offset:6144
	ds_read_b128 v[212:215], v154 offset:7168
	global_load_lds_dwordx4 v[216:217], off
	v_lshl_add_u64 v[216:217], s[30:31], 0, v[138:139]
	s_add_i32 m0, s39, 0xe000
	s_nop 0
	global_load_lds_dwordx4 v[216:217], off
	s_waitcnt vmcnt(8)
	s_waitcnt lgkmcnt(0)
	s_barrier
	s_setprio 1
	v_mfma_f32_16x16x32_bf16 v[126:129], v[146:149], v[184:187], v[126:129]
	v_mfma_f32_16x16x32_bf16 v[122:125], v[160:163], v[184:187], v[122:125]
	v_mfma_f32_16x16x32_bf16 v[110:113], v[146:149], v[192:195], v[110:113]
	v_mfma_f32_16x16x32_bf16 v[106:109], v[160:163], v[192:195], v[106:109]
	v_mfma_f32_16x16x32_bf16 v[94:97], v[146:149], v[200:203], v[94:97]
	v_mfma_f32_16x16x32_bf16 v[90:93], v[160:163], v[200:203], v[90:93]
	v_mfma_f32_16x16x32_bf16 v[78:81], v[146:149], v[208:211], v[78:81]
	v_mfma_f32_16x16x32_bf16 v[74:77], v[160:163], v[208:211], v[74:77]
	v_mfma_f32_16x16x32_bf16 v[126:129], v[156:159], v[188:191], v[126:129]
	v_mfma_f32_16x16x32_bf16 v[122:125], v[164:167], v[188:191], v[122:125]
	v_mfma_f32_16x16x32_bf16 v[110:113], v[156:159], v[196:199], v[110:113]
	v_mfma_f32_16x16x32_bf16 v[106:109], v[164:167], v[196:199], v[106:109]
	v_mfma_f32_16x16x32_bf16 v[94:97], v[156:159], v[204:207], v[94:97]
	v_mfma_f32_16x16x32_bf16 v[90:93], v[164:167], v[204:207], v[90:93]
	v_mfma_f32_16x16x32_bf16 v[78:81], v[156:159], v[212:215], v[78:81]
	v_mfma_f32_16x16x32_bf16 v[74:77], v[164:167], v[212:215], v[74:77]
	v_mfma_f32_16x16x32_bf16 v[118:121], v[168:171], v[184:187], v[118:121]
	v_mfma_f32_16x16x32_bf16 v[114:117], v[176:179], v[184:187], v[114:117]
	v_mfma_f32_16x16x32_bf16 v[102:105], v[168:171], v[192:195], v[102:105]
	v_mfma_f32_16x16x32_bf16 v[98:101], v[176:179], v[192:195], v[98:101]
	v_mfma_f32_16x16x32_bf16 v[86:89], v[168:171], v[200:203], v[86:89]
	v_mfma_f32_16x16x32_bf16 v[82:85], v[176:179], v[200:203], v[82:85]
	v_mfma_f32_16x16x32_bf16 v[70:73], v[168:171], v[208:211], v[70:73]
	v_mfma_f32_16x16x32_bf16 v[66:69], v[176:179], v[208:211], v[66:69]
	v_mfma_f32_16x16x32_bf16 v[118:121], v[172:175], v[188:191], v[118:121]
	v_mfma_f32_16x16x32_bf16 v[114:117], v[180:183], v[188:191], v[114:117]
	v_mfma_f32_16x16x32_bf16 v[102:105], v[172:175], v[196:199], v[102:105]
	v_mfma_f32_16x16x32_bf16 v[98:101], v[180:183], v[196:199], v[98:101]
	v_mfma_f32_16x16x32_bf16 v[86:89], v[172:175], v[204:207], v[86:89]
	v_mfma_f32_16x16x32_bf16 v[82:85], v[180:183], v[204:207], v[82:85]
	v_mfma_f32_16x16x32_bf16 v[70:73], v[172:175], v[212:215], v[70:73]
	v_mfma_f32_16x16x32_bf16 v[66:69], v[180:183], v[212:215], v[66:69]
	s_setprio 0
	s_barrier
	s_add_i32 s61, s54, s38
	v_lshl_add_u64 v[216:217], s[62:63], 0, v[132:133]
	s_mov_b32 m0, s61
	ds_read_b128 v[184:187], v154 offset:16384
	ds_read_b128 v[188:191], v154 offset:17408
	ds_read_b128 v[192:195], v154 offset:18432
	ds_read_b128 v[196:199], v154 offset:19456
	ds_read_b128 v[200:203], v154 offset:20480
	ds_read_b128 v[204:207], v154 offset:21504
	ds_read_b128 v[208:211], v154 offset:22528
	ds_read_b128 v[212:215], v154 offset:23552
	global_load_lds_dwordx4 v[216:217], off
	s_add_i32 m0, s61, 0x2000
	v_lshl_add_u64 v[218:219], s[62:63], 0, v[136:137]
	s_add_u32 s62, s62, s12
	s_addc_u32 s63, s63, s13
	s_add_i32 s61, s55, s38
	global_load_lds_dwordx4 v[218:219], off
	v_lshl_add_u64 v[220:221], s[62:63], 0, v[132:133]
	s_mov_b32 m0, s61
	v_lshl_add_u64 v[222:223], s[62:63], 0, v[136:137]
	global_load_lds_dwordx4 v[220:221], off
	s_add_i32 m0, s61, 0x2000
	v_lshl_add_u64 v[224:225], s[34:35], 0, v[130:131]
	global_load_lds_dwordx4 v[222:223], off
	s_mov_b32 m0, s39
	v_lshl_add_u64 v[226:227], s[34:35], 0, v[134:135]
	global_load_lds_dwordx4 v[224:225], off
	s_mov_b32 m0, s40
	s_nop 0
	global_load_lds_dwordx4 v[226:227], off
	s_waitcnt vmcnt(8)
	s_waitcnt lgkmcnt(0)
	s_barrier
; #define PG8_STAGE(bufoff, gbase, voff) do { _Pragma("unroll") for (int _i = 0; _i < 2; ++_i) \
;         __builtin_amdgcn_global_load_lds((const unsigned*)((const char*)(gbase) + (voff)[_i]), (PG8_LAS unsigned*)(lds + (bufoff) + ldsw + _i * 8192), 16, 0, 0); } while (0)
; #define PG8_LDA(dst, b, h) do { _Pragma("unroll") for (int m = 0; m < 4; ++m) _Pragma("unroll") for (int k = 0; k < 2; ++k) dst[m][k] = *(const PG8_LAS bf16x8*)(lds + PG8_SA(b, h) + aoff + m * 2048 + k * 1024); } while (0)
; #define PG8_LDB(dst, b, h) do { _Pragma("unroll") for (int n = 0; n < 2; ++n) _Pragma("unroll") for (int k = 0; k < 2; ++k) dst[n][k] = *(const PG8_LAS bf16x8*)(lds + PG8_SB(b, h) + boff + n * 2048 + k * 1024); } while (0)
; #define PG8_MMA(ai, bj, At, Bt) do { __builtin_amdgcn_s_setprio(1); _Pragma("unroll") for (int m = 0; m < 4; ++m) _Pragma("unroll") for (int n = 0; n < 2; ++n) _Pragma("unroll") for (int k = 0; k < 2; ++k) \
;         acc[ai][bj][m][n] = __builtin_amdgcn_mfma_f32_16x16x32_bf16(Bt[n][k], At[m][k], acc[ai][bj][m][n], 0, 0, 0); __builtin_amdgcn_s_setprio(0); } while (0)
; #define PG8_WAIT_V(n) asm volatile("s_waitcnt vmcnt(" #n ")" ::: "memory")
; #define PG8_WAIT_L(n) asm volatile("s_waitcnt lgkmcnt(" #n ")" ::: "memory")
; #define PG8_BAR __builtin_amdgcn_s_barrier()
; #define PG8_SCHED __builtin_amdgcn_sched_barrier(0)
; template <class Epi, class Sched, bool ALIGN_EPI = false, bool SP2 = false>
; __device__ __forceinline__ void gemm_phase(PG8_LAS unsigned char* lds, const Gemm g, const Sched& S, const Epi& E) {
;     ...
;             PG8_WAIT_V(8); PG8_WAIT_L(0); PG8_BAR; PG8_MMA(1, 0, At, B0); PG8_MMA(1, 1, At, B1); PG8_BAR; PG8_SCHED;
;             PG8_LDB(B0, 1, 0); PG8_LDB(B1, 1, 1); PG8_SCHED; PG8_LDA(At, 1, 0); PG8_STAGE(PG8_SA(0, 1), a2 + hstep, voffA);
;             PG8_WAIT_V(8); PG8_WAIT_L(0); PG8_BAR; PG8_MMA(0, 0, At, B0); PG8_MMA(0, 1, At, B1); PG8_BAR; PG8_SCHED;
	s_setprio 1
	v_mfma_f32_16x16x32_bf16 v[62:65], v[146:149], v[184:187], v[62:65]
	v_mfma_f32_16x16x32_bf16 v[58:61], v[160:163], v[184:187], v[58:61]
	v_mfma_f32_16x16x32_bf16 v[46:49], v[146:149], v[192:195], v[46:49]
	v_mfma_f32_16x16x32_bf16 v[42:45], v[160:163], v[192:195], v[42:45]
	v_mfma_f32_16x16x32_bf16 v[30:33], v[146:149], v[200:203], v[30:33]
	v_mfma_f32_16x16x32_bf16 v[26:29], v[160:163], v[200:203], v[26:29]
	v_mfma_f32_16x16x32_bf16 v[14:17], v[146:149], v[208:211], v[14:17]
	v_mfma_f32_16x16x32_bf16 v[10:13], v[160:163], v[208:211], v[10:13]
	v_mfma_f32_16x16x32_bf16 v[62:65], v[156:159], v[188:191], v[62:65]
	v_mfma_f32_16x16x32_bf16 v[58:61], v[164:167], v[188:191], v[58:61]
	v_mfma_f32_16x16x32_bf16 v[46:49], v[156:159], v[196:199], v[46:49]
	v_mfma_f32_16x16x32_bf16 v[42:45], v[164:167], v[196:199], v[42:45]
	v_mfma_f32_16x16x32_bf16 v[30:33], v[156:159], v[204:207], v[30:33]
	v_mfma_f32_16x16x32_bf16 v[26:29], v[164:167], v[204:207], v[26:29]
	v_mfma_f32_16x16x32_bf16 v[14:17], v[156:159], v[212:215], v[14:17]
	v_mfma_f32_16x16x32_bf16 v[10:13], v[164:167], v[212:215], v[10:13]
	v_mfma_f32_16x16x32_bf16 v[54:57], v[168:171], v[184:187], v[54:57]
	v_mfma_f32_16x16x32_bf16 v[50:53], v[176:179], v[184:187], v[50:53]
	v_mfma_f32_16x16x32_bf16 v[38:41], v[168:171], v[192:195], v[38:41]
	v_mfma_f32_16x16x32_bf16 v[34:37], v[176:179], v[192:195], v[34:37]
	v_mfma_f32_16x16x32_bf16 v[22:25], v[168:171], v[200:203], v[22:25]
	v_mfma_f32_16x16x32_bf16 v[18:21], v[176:179], v[200:203], v[18:21]
	v_mfma_f32_16x16x32_bf16 v[6:9], v[168:171], v[208:211], v[6:9]
	v_mfma_f32_16x16x32_bf16 v[2:5], v[176:179], v[208:211], v[2:5]
	v_mfma_f32_16x16x32_bf16 v[54:57], v[172:175], v[188:191], v[54:57]
	v_mfma_f32_16x16x32_bf16 v[50:53], v[180:183], v[188:191], v[50:53]
	v_mfma_f32_16x16x32_bf16 v[38:41], v[172:175], v[196:199], v[38:41]
	v_mfma_f32_16x16x32_bf16 v[34:37], v[180:183], v[196:199], v[34:37]
	v_mfma_f32_16x16x32_bf16 v[22:25], v[172:175], v[204:207], v[22:25]
	v_mfma_f32_16x16x32_bf16 v[18:21], v[180:183], v[204:207], v[18:21]
	v_mfma_f32_16x16x32_bf16 v[6:9], v[172:175], v[212:215], v[6:9]
	v_mfma_f32_16x16x32_bf16 v[2:5], v[180:183], v[212:215], v[2:5]
	s_setprio 0
	s_barrier
	s_add_i32 s61, 0, 0x18000
	v_add_u32_e32 v155, s61, v150
	s_add_i32 s62, 0, 0x1c000
	ds_read_b128 v[146:149], v155
	ds_read_b128 v[156:159], v155 offset:1024
	ds_read_b128 v[160:163], v155 offset:2048
	ds_read_b128 v[164:167], v155 offset:3072
	v_add_u32_e32 v155, s62, v150
	ds_read_b128 v[168:171], v155
	ds_read_b128 v[172:175], v155 offset:1024
	ds_read_b128 v[176:179], v155 offset:2048
	ds_read_b128 v[180:183], v155 offset:3072
	s_add_u32 s34, s34, s12
	s_addc_u32 s35, s35, s13
	s_mov_b32 m0, s41
	v_lshl_add_u64 v[228:229], s[34:35], 0, v[130:131]
	ds_read_b128 v[184:187], v154 offset:32768
	ds_read_b128 v[188:191], v154 offset:33792
	ds_read_b128 v[192:195], v154 offset:34816
	ds_read_b128 v[196:199], v154 offset:35840
	ds_read_b128 v[200:203], v154 offset:36864
	ds_read_b128 v[204:207], v154 offset:37888
	ds_read_b128 v[208:211], v154 offset:38912
	ds_read_b128 v[212:215], v154 offset:39936
	global_load_lds_dwordx4 v[228:229], off
	v_lshl_add_u64 v[228:229], s[34:35], 0, v[134:135]
	s_mov_b32 m0, s42
	s_nop 0
	global_load_lds_dwordx4 v[228:229], off
	s_waitcnt vmcnt(8)
	s_waitcnt lgkmcnt(0)
	s_barrier
	s_setprio 1
	v_mfma_f32_16x16x32_bf16 v[126:129], v[146:149], v[184:187], v[126:129]
	v_mfma_f32_16x16x32_bf16 v[122:125], v[160:163], v[184:187], v[122:125]
	v_mfma_f32_16x16x32_bf16 v[110:113], v[146:149], v[192:195], v[110:113]
	v_mfma_f32_16x16x32_bf16 v[106:109], v[160:163], v[192:195], v[106:109]
	v_mfma_f32_16x16x32_bf16 v[94:97], v[146:149], v[200:203], v[94:97]
	v_mfma_f32_16x16x32_bf16 v[90:93], v[160:163], v[200:203], v[90:93]
	v_mfma_f32_16x16x32_bf16 v[78:81], v[146:149], v[208:211], v[78:81]
	v_mfma_f32_16x16x32_bf16 v[74:77], v[160:163], v[208:211], v[74:77]
	v_mfma_f32_16x16x32_bf16 v[126:129], v[156:159], v[188:191], v[126:129]
	v_mfma_f32_16x16x32_bf16 v[122:125], v[164:167], v[188:191], v[122:125]
	v_mfma_f32_16x16x32_bf16 v[110:113], v[156:159], v[196:199], v[110:113]
	v_mfma_f32_16x16x32_bf16 v[106:109], v[164:167], v[196:199], v[106:109]
	v_mfma_f32_16x16x32_bf16 v[94:97], v[156:159], v[204:207], v[94:97]
	v_mfma_f32_16x16x32_bf16 v[90:93], v[164:167], v[204:207], v[90:93]
	v_mfma_f32_16x16x32_bf16 v[78:81], v[156:159], v[212:215], v[78:81]
	v_mfma_f32_16x16x32_bf16 v[74:77], v[164:167], v[212:215], v[74:77]
	v_mfma_f32_16x16x32_bf16 v[118:121], v[168:171], v[184:187], v[118:121]
	v_mfma_f32_16x16x32_bf16 v[114:117], v[176:179], v[184:187], v[114:117]
	v_mfma_f32_16x16x32_bf16 v[102:105], v[168:171], v[192:195], v[102:105]
	v_mfma_f32_16x16x32_bf16 v[98:101], v[176:179], v[192:195], v[98:101]
	v_mfma_f32_16x16x32_bf16 v[86:89], v[168:171], v[200:203], v[86:89]
	v_mfma_f32_16x16x32_bf16 v[82:85], v[176:179], v[200:203], v[82:85]
	v_mfma_f32_16x16x32_bf16 v[70:73], v[168:171], v[208:211], v[70:73]
	v_mfma_f32_16x16x32_bf16 v[66:69], v[176:179], v[208:211], v[66:69]
	v_mfma_f32_16x16x32_bf16 v[118:121], v[172:175], v[188:191], v[118:121]
	v_mfma_f32_16x16x32_bf16 v[114:117], v[180:183], v[188:191], v[114:117]
	v_mfma_f32_16x16x32_bf16 v[102:105], v[172:175], v[196:199], v[102:105]
	v_mfma_f32_16x16x32_bf16 v[98:101], v[180:183], v[196:199], v[98:101]
	v_mfma_f32_16x16x32_bf16 v[86:89], v[172:175], v[204:207], v[86:89]
	v_mfma_f32_16x16x32_bf16 v[82:85], v[180:183], v[204:207], v[82:85]
	v_mfma_f32_16x16x32_bf16 v[70:73], v[172:175], v[212:215], v[70:73]
	v_mfma_f32_16x16x32_bf16 v[66:69], v[180:183], v[212:215], v[66:69]
	s_setprio 0
	s_barrier
; #define PG8_STAGE(bufoff, gbase, voff) do { _Pragma("unroll") for (int _i = 0; _i < 2; ++_i) \
;         __builtin_amdgcn_global_load_lds((const unsigned*)((const char*)(gbase) + (voff)[_i]), (PG8_LAS unsigned*)(lds + (bufoff) + ldsw + _i * 8192), 16, 0, 0); } while (0)
; #define PG8_LDA(dst, b, h) do { _Pragma("unroll") for (int m = 0; m < 4; ++m) _Pragma("unroll") for (int k = 0; k < 2; ++k) dst[m][k] = *(const PG8_LAS bf16x8*)(lds + PG8_SA(b, h) + aoff + m * 2048 + k * 1024); } while (0)
; #define PG8_MMA(ai, bj, At, Bt) do { __builtin_amdgcn_s_setprio(1); _Pragma("unroll") for (int m = 0; m < 4; ++m) _Pragma("unroll") for (int n = 0; n < 2; ++n) _Pragma("unroll") for (int k = 0; k < 2; ++k) \
;         acc[ai][bj][m][n] = __builtin_amdgcn_mfma_f32_16x16x32_bf16(Bt[n][k], At[m][k], acc[ai][bj][m][n], 0, 0, 0); __builtin_amdgcn_s_setprio(0); } while (0)
; #define PG8_WAIT_V(n) asm volatile("s_waitcnt vmcnt(" #n ")" ::: "memory")
; #define PG8_WAIT_L(n) asm volatile("s_waitcnt lgkmcnt(" #n ")" ::: "memory")
; #define PG8_BAR __builtin_amdgcn_s_barrier()
; #define PG8_SCHED __builtin_amdgcn_sched_barrier(0)
; template <class Epi, class Sched, bool ALIGN_EPI = false, bool SP2 = false>
; __device__ __forceinline__ void gemm_phase(PG8_LAS unsigned char* lds, const Gemm g, const Sched& S, const Epi& E) {
;     ...
;             PG8_LDA(At, 1, 1); PG8_STAGE(PG8_SB(1, 0), b3, voffB); PG8_STAGE(PG8_SB(1, 1), b3 + hstep, voffB); PG8_STAGE(PG8_SA(1, 0), a3, voffA);
;             PG8_WAIT_V(8); PG8_WAIT_L(0); PG8_BAR; PG8_MMA(1, 0, At, B0); PG8_MMA(1, 1, At, B1); PG8_BAR; PG8_SCHED;
	s_add_i32 s34, s61, s38
	v_lshl_add_u64 v[216:217], v[216:217], 0, s[20:21]
	s_mov_b32 m0, s34
	ds_read_b128 v[184:187], v154 offset:49152
	ds_read_b128 v[188:191], v154 offset:50176
	ds_read_b128 v[192:195], v154 offset:51200
	ds_read_b128 v[196:199], v154 offset:52224
	ds_read_b128 v[200:203], v154 offset:53248
	ds_read_b128 v[204:207], v154 offset:54272
	ds_read_b128 v[208:211], v154 offset:55296
	ds_read_b128 v[212:215], v154 offset:56320
	global_load_lds_dwordx4 v[216:217], off
	v_lshl_add_u64 v[216:217], v[218:219], 0, s[20:21]
	s_add_i32 m0, s34, 0x2000
	s_add_i32 s34, s62, s38
	global_load_lds_dwordx4 v[216:217], off
	v_lshl_add_u64 v[216:217], v[220:221], 0, s[20:21]
	s_mov_b32 m0, s34
	s_nop 0
	global_load_lds_dwordx4 v[216:217], off
	v_lshl_add_u64 v[216:217], v[222:223], 0, s[20:21]
	s_add_i32 m0, s34, 0x2000
	s_nop 0
	global_load_lds_dwordx4 v[216:217], off
	v_lshl_add_u64 v[216:217], v[224:225], 0, s[20:21]
	s_mov_b32 m0, s46
	s_nop 0
	global_load_lds_dwordx4 v[216:217], off
	v_lshl_add_u64 v[216:217], v[226:227], 0, s[20:21]
	s_mov_b32 m0, s47
	s_nop 0
	global_load_lds_dwordx4 v[216:217], off
	s_waitcnt vmcnt(8)
	s_waitcnt lgkmcnt(0)
	s_barrier
	s_setprio 1
	v_mfma_f32_16x16x32_bf16 v[62:65], v[146:149], v[184:187], v[62:65]
	v_mfma_f32_16x16x32_bf16 v[58:61], v[160:163], v[184:187], v[58:61]
	v_mfma_f32_16x16x32_bf16 v[46:49], v[146:149], v[192:195], v[46:49]
	v_mfma_f32_16x16x32_bf16 v[42:45], v[160:163], v[192:195], v[42:45]
	v_mfma_f32_16x16x32_bf16 v[30:33], v[146:149], v[200:203], v[30:33]
	v_mfma_f32_16x16x32_bf16 v[26:29], v[160:163], v[200:203], v[26:29]
	v_mfma_f32_16x16x32_bf16 v[14:17], v[146:149], v[208:211], v[14:17]
	v_mfma_f32_16x16x32_bf16 v[10:13], v[160:163], v[208:211], v[10:13]
	v_mfma_f32_16x16x32_bf16 v[62:65], v[156:159], v[188:191], v[62:65]
	v_mfma_f32_16x16x32_bf16 v[58:61], v[164:167], v[188:191], v[58:61]
	v_mfma_f32_16x16x32_bf16 v[46:49], v[156:159], v[196:199], v[46:49]
	v_mfma_f32_16x16x32_bf16 v[42:45], v[164:167], v[196:199], v[42:45]
	v_mfma_f32_16x16x32_bf16 v[30:33], v[156:159], v[204:207], v[30:33]
	v_mfma_f32_16x16x32_bf16 v[26:29], v[164:167], v[204:207], v[26:29]
	v_mfma_f32_16x16x32_bf16 v[14:17], v[156:159], v[212:215], v[14:17]
	v_mfma_f32_16x16x32_bf16 v[10:13], v[164:167], v[212:215], v[10:13]
	v_mfma_f32_16x16x32_bf16 v[54:57], v[168:171], v[184:187], v[54:57]
	v_mfma_f32_16x16x32_bf16 v[50:53], v[176:179], v[184:187], v[50:53]
	v_mfma_f32_16x16x32_bf16 v[38:41], v[168:171], v[192:195], v[38:41]
	v_mfma_f32_16x16x32_bf16 v[34:37], v[176:179], v[192:195], v[34:37]
	v_mfma_f32_16x16x32_bf16 v[22:25], v[168:171], v[200:203], v[22:25]
	v_mfma_f32_16x16x32_bf16 v[18:21], v[176:179], v[200:203], v[18:21]
	v_mfma_f32_16x16x32_bf16 v[6:9], v[168:171], v[208:211], v[6:9]
	v_mfma_f32_16x16x32_bf16 v[2:5], v[176:179], v[208:211], v[2:5]
	v_mfma_f32_16x16x32_bf16 v[54:57], v[172:175], v[188:191], v[54:57]
	v_mfma_f32_16x16x32_bf16 v[50:53], v[180:183], v[188:191], v[50:53]
	v_mfma_f32_16x16x32_bf16 v[38:41], v[172:175], v[196:199], v[38:41]
	v_mfma_f32_16x16x32_bf16 v[34:37], v[180:183], v[196:199], v[34:37]
	v_mfma_f32_16x16x32_bf16 v[22:25], v[172:175], v[204:207], v[22:25]
	v_mfma_f32_16x16x32_bf16 v[18:21], v[180:183], v[204:207], v[18:21]
	v_mfma_f32_16x16x32_bf16 v[6:9], v[172:175], v[212:215], v[6:9]
	v_mfma_f32_16x16x32_bf16 v[2:5], v[180:183], v[212:215], v[2:5]
	s_setprio 0
	s_barrier
	s_add_u32 s58, s58, 0x100
	s_addc_u32 s59, s59, 0
	s_add_u32 s30, s30, 0x100
	s_addc_u32 s31, s31, 0
	s_cmp_ge_i32 s60, s52
	s_mov_b32 s34, s60
	s_cbranch_scc0 .LBB0_497

; #define PG8_STAGE(bufoff, gbase, voff) do { _Pragma("unroll") for (int _i = 0; _i < 2; ++_i) \
;         __builtin_amdgcn_global_load_lds((const unsigned*)((const char*)(gbase) + (voff)[_i]), (PG8_LAS unsigned*)(lds + (bufoff) + ldsw + _i * 8192), 16, 0, 0); } while (0)
; #define PG8_LDA(dst, b, h) do { _Pragma("unroll") for (int m = 0; m < 4; ++m) _Pragma("unroll") for (int k = 0; k < 2; ++k) dst[m][k] = *(const PG8_LAS bf16x8*)(lds + PG8_SA(b, h) + aoff + m * 2048 + k * 1024); } while (0)
; #define PG8_LDB(dst, b, h) do { _Pragma("unroll") for (int n = 0; n < 2; ++n) _Pragma("unroll") for (int k = 0; k < 2; ++k) dst[n][k] = *(const PG8_LAS bf16x8*)(lds + PG8_SB(b, h) + boff + n * 2048 + k * 1024); } while (0)
; #define PG8_MMA(ai, bj, At, Bt) do { __builtin_amdgcn_s_setprio(1); _Pragma("unroll") for (int m = 0; m < 4; ++m) _Pragma("unroll") for (int n = 0; n < 2; ++n) _Pragma("unroll") for (int k = 0; k < 2; ++k) \
;         acc[ai][bj][m][n] = __builtin_amdgcn_mfma_f32_16x16x32_bf16(Bt[n][k], At[m][k], acc[ai][bj][m][n], 0, 0, 0); __builtin_amdgcn_s_setprio(0); } while (0)
; #define PG8_WAIT_V(n) asm volatile("s_waitcnt vmcnt(" #n ")" ::: "memory")
; #define PG8_WAIT_L(n) asm volatile("s_waitcnt lgkmcnt(" #n ")" ::: "memory")
; template <class Epi, class Sched, bool ALIGN_EPI = false, bool SP2 = false>
; __device__ __forceinline__ void gemm_phase(PG8_LAS unsigned char* lds, const Gemm g, const Sched& S, const Epi& E) {
;     ...
;             const bool last = (t == nt - 2);
;             const char* a1 = cA + (size_t)(t + 1) * kstep;
;             const char* a2 = last ? nA : cA + (size_t)(t + 2) * kstep; const char* b2 = last ? nB : cB + (size_t)(t + 2) * kstep;
;             const char* a3 = a2 + kstep; const char* b3 = b2 + kstep;
;             if (last && has_next) S.a_ready(nxt);
;             if constexpr (SP2) {
;             PG8_LDB(B0, 0, 0); PG8_LDB(B1, 0, 1); PG8_SCHED; PG8_LDA(At, 0, 0); PG8_STAGE(PG8_SA(1, 1), a1 + hstep, voffA);
;             PG8_WAIT_V(8); PG8_WAIT_L(0); PG8_BAR; PG8_MMA(0, 0, At, B0); PG8_MMA(0, 1, At, B1); PG8_BAR; PG8_SCHED;
;             PG8_LDA(At, 0, 1); PG8_STAGE(PG8_SB(0, 0), b2, voffB); PG8_STAGE(PG8_SB(0, 1), b2 + hstep, voffB); PG8_STAGE(PG8_SA(0, 0), a2, voffA);
;             PG8_WAIT_V(8); PG8_WAIT_L(0); PG8_BAR; PG8_MMA(1, 0, At, B0); PG8_MMA(1, 1, At, B1); PG8_BAR; PG8_SCHED;
.LBB0_582:
	ds_read_b128 v[152:155], v148
	ds_read_b128 v[156:159], v148 offset:1024
	ds_read_b128 v[160:163], v148 offset:2048
	ds_read_b128 v[164:167], v148 offset:3072
	ds_read_b128 v[168:171], v149
	ds_read_b128 v[172:175], v149 offset:1024
	ds_read_b128 v[176:179], v149 offset:2048
	ds_read_b128 v[180:183], v149 offset:3072
	s_add_i32 s60, s30, 2
	s_add_u32 s61, s28, 0x80
	s_addc_u32 s31, s29, 0
	s_cmp_eq_u32 s45, s30
	s_cselect_b32 s30, s6, s61
	s_cselect_b32 s31, s7, s31
	s_cselect_b32 s63, s25, s59
	s_cselect_b32 s62, s24, s58
	v_lshl_add_u64 v[216:217], s[28:29], 0, v[140:141]
	s_add_i32 m0, s0, 0xc000
	ds_read_b128 v[184:187], v150
	ds_read_b128 v[188:191], v150 offset:1024
	ds_read_b128 v[192:195], v150 offset:2048
	ds_read_b128 v[196:199], v150 offset:3072
	ds_read_b128 v[200:203], v150 offset:4096
	ds_read_b128 v[204:207], v150 offset:5120
	ds_read_b128 v[208:211], v150 offset:6144
	ds_read_b128 v[212:215], v150 offset:7168
	global_load_lds_dwordx4 v[216:217], off
	v_lshl_add_u64 v[216:217], s[28:29], 0, v[138:139]
	s_add_i32 m0, s0, 0xe000
	s_nop 0
	global_load_lds_dwordx4 v[216:217], off
	s_waitcnt vmcnt(8)
	s_waitcnt lgkmcnt(0)
	s_barrier
	s_setprio 1
	v_mfma_f32_16x16x32_bf16 v[122:125], v[152:155], v[184:187], v[122:125]
	v_mfma_f32_16x16x32_bf16 v[126:129], v[160:163], v[184:187], v[126:129]
	v_mfma_f32_16x16x32_bf16 v[110:113], v[152:155], v[192:195], v[110:113]
	v_mfma_f32_16x16x32_bf16 v[106:109], v[160:163], v[192:195], v[106:109]
	v_mfma_f32_16x16x32_bf16 v[94:97], v[152:155], v[200:203], v[94:97]
	v_mfma_f32_16x16x32_bf16 v[90:93], v[160:163], v[200:203], v[90:93]
	v_mfma_f32_16x16x32_bf16 v[78:81], v[152:155], v[208:211], v[78:81]
	v_mfma_f32_16x16x32_bf16 v[74:77], v[160:163], v[208:211], v[74:77]
	v_mfma_f32_16x16x32_bf16 v[122:125], v[156:159], v[188:191], v[122:125]
	v_mfma_f32_16x16x32_bf16 v[126:129], v[164:167], v[188:191], v[126:129]
	v_mfma_f32_16x16x32_bf16 v[110:113], v[156:159], v[196:199], v[110:113]
	v_mfma_f32_16x16x32_bf16 v[106:109], v[164:167], v[196:199], v[106:109]
	v_mfma_f32_16x16x32_bf16 v[94:97], v[156:159], v[204:207], v[94:97]
	v_mfma_f32_16x16x32_bf16 v[90:93], v[164:167], v[204:207], v[90:93]
	v_mfma_f32_16x16x32_bf16 v[78:81], v[156:159], v[212:215], v[78:81]
	v_mfma_f32_16x16x32_bf16 v[74:77], v[164:167], v[212:215], v[74:77]
	v_mfma_f32_16x16x32_bf16 v[118:121], v[168:171], v[184:187], v[118:121]
	v_mfma_f32_16x16x32_bf16 v[114:117], v[176:179], v[184:187], v[114:117]
	v_mfma_f32_16x16x32_bf16 v[102:105], v[168:171], v[192:195], v[102:105]
	v_mfma_f32_16x16x32_bf16 v[98:101], v[176:179], v[192:195], v[98:101]
	v_mfma_f32_16x16x32_bf16 v[86:89], v[168:171], v[200:203], v[86:89]
	v_mfma_f32_16x16x32_bf16 v[82:85], v[176:179], v[200:203], v[82:85]
	v_mfma_f32_16x16x32_bf16 v[70:73], v[168:171], v[208:211], v[70:73]
	v_mfma_f32_16x16x32_bf16 v[66:69], v[176:179], v[208:211], v[66:69]
	v_mfma_f32_16x16x32_bf16 v[118:121], v[172:175], v[188:191], v[118:121]
	v_mfma_f32_16x16x32_bf16 v[114:117], v[180:183], v[188:191], v[114:117]
	v_mfma_f32_16x16x32_bf16 v[102:105], v[172:175], v[196:199], v[102:105]
	v_mfma_f32_16x16x32_bf16 v[98:101], v[180:183], v[196:199], v[98:101]
	v_mfma_f32_16x16x32_bf16 v[86:89], v[172:175], v[204:207], v[86:89]
	v_mfma_f32_16x16x32_bf16 v[82:85], v[180:183], v[204:207], v[82:85]
	v_mfma_f32_16x16x32_bf16 v[70:73], v[172:175], v[212:215], v[70:73]
	v_mfma_f32_16x16x32_bf16 v[66:69], v[180:183], v[212:215], v[66:69]
	s_setprio 0
	s_barrier
	s_add_i32 s61, s52, s38
	v_lshl_add_u64 v[216:217], s[62:63], 0, v[132:133]
	s_mov_b32 m0, s61
	ds_read_b128 v[184:187], v150 offset:16384
	ds_read_b128 v[188:191], v150 offset:17408
	ds_read_b128 v[192:195], v150 offset:18432
	ds_read_b128 v[196:199], v150 offset:19456
	ds_read_b128 v[200:203], v150 offset:20480
	ds_read_b128 v[204:207], v150 offset:21504
	ds_read_b128 v[208:211], v150 offset:22528
	ds_read_b128 v[212:215], v150 offset:23552
	global_load_lds_dwordx4 v[216:217], off
	s_add_i32 m0, s61, 0x2000
	v_lshl_add_u64 v[218:219], s[62:63], 0, v[136:137]
	s_add_u32 s62, s62, s10
	s_addc_u32 s63, s63, s11
	s_add_i32 s61, s53, s38
	global_load_lds_dwordx4 v[218:219], off
	v_lshl_add_u64 v[220:221], s[62:63], 0, v[132:133]
	s_mov_b32 m0, s61
	v_lshl_add_u64 v[222:223], s[62:63], 0, v[136:137]
	global_load_lds_dwordx4 v[220:221], off
	s_add_i32 m0, s61, 0x2000
	v_lshl_add_u64 v[224:225], s[30:31], 0, v[130:131]
	global_load_lds_dwordx4 v[222:223], off
	s_mov_b32 m0, s0
	v_lshl_add_u64 v[226:227], s[30:31], 0, v[134:135]
	global_load_lds_dwordx4 v[224:225], off
	s_mov_b32 m0, s1
	s_nop 0
	global_load_lds_dwordx4 v[226:227], off
	s_waitcnt vmcnt(8)
	s_waitcnt lgkmcnt(0)
	s_barrier
; #define PG8_STAGE(bufoff, gbase, voff) do { _Pragma("unroll") for (int _i = 0; _i < 2; ++_i) \
;         __builtin_amdgcn_global_load_lds((const unsigned*)((const char*)(gbase) + (voff)[_i]), (PG8_LAS unsigned*)(lds + (bufoff) + ldsw + _i * 8192), 16, 0, 0); } while (0)
; #define PG8_LDA(dst, b, h) do { _Pragma("unroll") for (int m = 0; m < 4; ++m) _Pragma("unroll") for (int k = 0; k < 2; ++k) dst[m][k] = *(const PG8_LAS bf16x8*)(lds + PG8_SA(b, h) + aoff + m * 2048 + k * 1024); } while (0)
; #define PG8_LDB(dst, b, h) do { _Pragma("unroll") for (int n = 0; n < 2; ++n) _Pragma("unroll") for (int k = 0; k < 2; ++k) dst[n][k] = *(const PG8_LAS bf16x8*)(lds + PG8_SB(b, h) + boff + n * 2048 + k * 1024); } while (0)
; #define PG8_MMA(ai, bj, At, Bt) do { __builtin_amdgcn_s_setprio(1); _Pragma("unroll") for (int m = 0; m < 4; ++m) _Pragma("unroll") for (int n = 0; n < 2; ++n) _Pragma("unroll") for (int k = 0; k < 2; ++k) \
;         acc[ai][bj][m][n] = __builtin_amdgcn_mfma_f32_16x16x32_bf16(Bt[n][k], At[m][k], acc[ai][bj][m][n], 0, 0, 0); __builtin_amdgcn_s_setprio(0); } while (0)
; #define PG8_WAIT_V(n) asm volatile("s_waitcnt vmcnt(" #n ")" ::: "memory")
; #define PG8_WAIT_L(n) asm volatile("s_waitcnt lgkmcnt(" #n ")" ::: "memory")
; #define PG8_BAR __builtin_amdgcn_s_barrier()
; #define PG8_SCHED __builtin_amdgcn_sched_barrier(0)
; template <class Epi, class Sched, bool ALIGN_EPI = false, bool SP2 = false>
; __device__ __forceinline__ void gemm_phase(PG8_LAS unsigned char* lds, const Gemm g, const Sched& S, const Epi& E) {
;     ...
;             PG8_WAIT_V(8); PG8_WAIT_L(0); PG8_BAR; PG8_MMA(1, 0, At, B0); PG8_MMA(1, 1, At, B1); PG8_BAR; PG8_SCHED;
;             PG8_LDB(B0, 1, 0); PG8_LDB(B1, 1, 1); PG8_SCHED; PG8_LDA(At, 1, 0); PG8_STAGE(PG8_SA(0, 1), a2 + hstep, voffA);
;             PG8_WAIT_V(8); PG8_WAIT_L(0); PG8_BAR; PG8_MMA(0, 0, At, B0); PG8_MMA(0, 1, At, B1); PG8_BAR; PG8_SCHED;
	s_setprio 1
	v_mfma_f32_16x16x32_bf16 v[62:65], v[152:155], v[184:187], v[62:65]
	v_mfma_f32_16x16x32_bf16 v[58:61], v[160:163], v[184:187], v[58:61]
	v_mfma_f32_16x16x32_bf16 v[46:49], v[152:155], v[192:195], v[46:49]
	v_mfma_f32_16x16x32_bf16 v[42:45], v[160:163], v[192:195], v[42:45]
	v_mfma_f32_16x16x32_bf16 v[30:33], v[152:155], v[200:203], v[30:33]
	v_mfma_f32_16x16x32_bf16 v[26:29], v[160:163], v[200:203], v[26:29]
	v_mfma_f32_16x16x32_bf16 v[14:17], v[152:155], v[208:211], v[14:17]
	v_mfma_f32_16x16x32_bf16 v[10:13], v[160:163], v[208:211], v[10:13]
	v_mfma_f32_16x16x32_bf16 v[62:65], v[156:159], v[188:191], v[62:65]
	v_mfma_f32_16x16x32_bf16 v[58:61], v[164:167], v[188:191], v[58:61]
	v_mfma_f32_16x16x32_bf16 v[46:49], v[156:159], v[196:199], v[46:49]
	v_mfma_f32_16x16x32_bf16 v[42:45], v[164:167], v[196:199], v[42:45]
	v_mfma_f32_16x16x32_bf16 v[30:33], v[156:159], v[204:207], v[30:33]
	v_mfma_f32_16x16x32_bf16 v[26:29], v[164:167], v[204:207], v[26:29]
	v_mfma_f32_16x16x32_bf16 v[14:17], v[156:159], v[212:215], v[14:17]
	v_mfma_f32_16x16x32_bf16 v[10:13], v[164:167], v[212:215], v[10:13]
	v_mfma_f32_16x16x32_bf16 v[54:57], v[168:171], v[184:187], v[54:57]
	v_mfma_f32_16x16x32_bf16 v[50:53], v[176:179], v[184:187], v[50:53]
	v_mfma_f32_16x16x32_bf16 v[38:41], v[168:171], v[192:195], v[38:41]
	v_mfma_f32_16x16x32_bf16 v[34:37], v[176:179], v[192:195], v[34:37]
	v_mfma_f32_16x16x32_bf16 v[22:25], v[168:171], v[200:203], v[22:25]
	v_mfma_f32_16x16x32_bf16 v[18:21], v[176:179], v[200:203], v[18:21]
	v_mfma_f32_16x16x32_bf16 v[6:9], v[168:171], v[208:211], v[6:9]
	v_mfma_f32_16x16x32_bf16 v[2:5], v[176:179], v[208:211], v[2:5]
	v_mfma_f32_16x16x32_bf16 v[54:57], v[172:175], v[188:191], v[54:57]
	v_mfma_f32_16x16x32_bf16 v[50:53], v[180:183], v[188:191], v[50:53]
	v_mfma_f32_16x16x32_bf16 v[38:41], v[172:175], v[196:199], v[38:41]
	v_mfma_f32_16x16x32_bf16 v[34:37], v[180:183], v[196:199], v[34:37]
	v_mfma_f32_16x16x32_bf16 v[22:25], v[172:175], v[204:207], v[22:25]
	v_mfma_f32_16x16x32_bf16 v[18:21], v[180:183], v[204:207], v[18:21]
	v_mfma_f32_16x16x32_bf16 v[6:9], v[172:175], v[212:215], v[6:9]
	v_mfma_f32_16x16x32_bf16 v[2:5], v[180:183], v[212:215], v[2:5]
	s_setprio 0
	s_barrier
	s_add_i32 s61, 0, 0x18000
	v_add_u32_e32 v151, s61, v146
	s_add_i32 s62, 0, 0x1c000
	ds_read_b128 v[152:155], v151
	ds_read_b128 v[156:159], v151 offset:1024
	ds_read_b128 v[160:163], v151 offset:2048
	ds_read_b128 v[164:167], v151 offset:3072
	v_add_u32_e32 v151, s62, v146
	ds_read_b128 v[168:171], v151
	ds_read_b128 v[172:175], v151 offset:1024
	ds_read_b128 v[176:179], v151 offset:2048
	ds_read_b128 v[180:183], v151 offset:3072
	s_add_u32 s30, s30, s10
	s_addc_u32 s31, s31, s11
	s_mov_b32 m0, s39
	v_lshl_add_u64 v[228:229], s[30:31], 0, v[130:131]
	ds_read_b128 v[184:187], v150 offset:32768
	ds_read_b128 v[188:191], v150 offset:33792
	ds_read_b128 v[192:195], v150 offset:34816
	ds_read_b128 v[196:199], v150 offset:35840
	ds_read_b128 v[200:203], v150 offset:36864
	ds_read_b128 v[204:207], v150 offset:37888
	ds_read_b128 v[208:211], v150 offset:38912
	ds_read_b128 v[212:215], v150 offset:39936
	global_load_lds_dwordx4 v[228:229], off
	v_lshl_add_u64 v[228:229], s[30:31], 0, v[134:135]
	s_mov_b32 m0, s40
	s_nop 0
	global_load_lds_dwordx4 v[228:229], off
	s_waitcnt vmcnt(8)
	s_waitcnt lgkmcnt(0)
	s_barrier
	s_setprio 1
	v_mfma_f32_16x16x32_bf16 v[122:125], v[152:155], v[184:187], v[122:125]
	v_mfma_f32_16x16x32_bf16 v[126:129], v[160:163], v[184:187], v[126:129]
	v_mfma_f32_16x16x32_bf16 v[110:113], v[152:155], v[192:195], v[110:113]
	v_mfma_f32_16x16x32_bf16 v[106:109], v[160:163], v[192:195], v[106:109]
	v_mfma_f32_16x16x32_bf16 v[94:97], v[152:155], v[200:203], v[94:97]
	v_mfma_f32_16x16x32_bf16 v[90:93], v[160:163], v[200:203], v[90:93]
	v_mfma_f32_16x16x32_bf16 v[78:81], v[152:155], v[208:211], v[78:81]
	v_mfma_f32_16x16x32_bf16 v[74:77], v[160:163], v[208:211], v[74:77]
	v_mfma_f32_16x16x32_bf16 v[122:125], v[156:159], v[188:191], v[122:125]
	v_mfma_f32_16x16x32_bf16 v[126:129], v[164:167], v[188:191], v[126:129]
	v_mfma_f32_16x16x32_bf16 v[110:113], v[156:159], v[196:199], v[110:113]
	v_mfma_f32_16x16x32_bf16 v[106:109], v[164:167], v[196:199], v[106:109]
	v_mfma_f32_16x16x32_bf16 v[94:97], v[156:159], v[204:207], v[94:97]
	v_mfma_f32_16x16x32_bf16 v[90:93], v[164:167], v[204:207], v[90:93]
	v_mfma_f32_16x16x32_bf16 v[78:81], v[156:159], v[212:215], v[78:81]
	v_mfma_f32_16x16x32_bf16 v[74:77], v[164:167], v[212:215], v[74:77]
	v_mfma_f32_16x16x32_bf16 v[118:121], v[168:171], v[184:187], v[118:121]
	v_mfma_f32_16x16x32_bf16 v[114:117], v[176:179], v[184:187], v[114:117]
	v_mfma_f32_16x16x32_bf16 v[102:105], v[168:171], v[192:195], v[102:105]
	v_mfma_f32_16x16x32_bf16 v[98:101], v[176:179], v[192:195], v[98:101]
	v_mfma_f32_16x16x32_bf16 v[86:89], v[168:171], v[200:203], v[86:89]
	v_mfma_f32_16x16x32_bf16 v[82:85], v[176:179], v[200:203], v[82:85]
	v_mfma_f32_16x16x32_bf16 v[70:73], v[168:171], v[208:211], v[70:73]
	v_mfma_f32_16x16x32_bf16 v[66:69], v[176:179], v[208:211], v[66:69]
	v_mfma_f32_16x16x32_bf16 v[118:121], v[172:175], v[188:191], v[118:121]
	v_mfma_f32_16x16x32_bf16 v[114:117], v[180:183], v[188:191], v[114:117]
	v_mfma_f32_16x16x32_bf16 v[102:105], v[172:175], v[196:199], v[102:105]
	v_mfma_f32_16x16x32_bf16 v[98:101], v[180:183], v[196:199], v[98:101]
	v_mfma_f32_16x16x32_bf16 v[86:89], v[172:175], v[204:207], v[86:89]
	v_mfma_f32_16x16x32_bf16 v[82:85], v[180:183], v[204:207], v[82:85]
	v_mfma_f32_16x16x32_bf16 v[70:73], v[172:175], v[212:215], v[70:73]
	v_mfma_f32_16x16x32_bf16 v[66:69], v[180:183], v[212:215], v[66:69]
	s_setprio 0
	s_barrier
; #define PG8_STAGE(bufoff, gbase, voff) do { _Pragma("unroll") for (int _i = 0; _i < 2; ++_i) \
;         __builtin_amdgcn_global_load_lds((const unsigned*)((const char*)(gbase) + (voff)[_i]), (PG8_LAS unsigned*)(lds + (bufoff) + ldsw + _i * 8192), 16, 0, 0); } while (0)
; #define PG8_LDA(dst, b, h) do { _Pragma("unroll") for (int m = 0; m < 4; ++m) _Pragma("unroll") for (int k = 0; k < 2; ++k) dst[m][k] = *(const PG8_LAS bf16x8*)(lds + PG8_SA(b, h) + aoff + m * 2048 + k * 1024); } while (0)
; #define PG8_MMA(ai, bj, At, Bt) do { __builtin_amdgcn_s_setprio(1); _Pragma("unroll") for (int m = 0; m < 4; ++m) _Pragma("unroll") for (int n = 0; n < 2; ++n) _Pragma("unroll") for (int k = 0; k < 2; ++k) \
;         acc[ai][bj][m][n] = __builtin_amdgcn_mfma_f32_16x16x32_bf16(Bt[n][k], At[m][k], acc[ai][bj][m][n], 0, 0, 0); __builtin_amdgcn_s_setprio(0); } while (0)
; #define PG8_WAIT_V(n) asm volatile("s_waitcnt vmcnt(" #n ")" ::: "memory")
; #define PG8_WAIT_L(n) asm volatile("s_waitcnt lgkmcnt(" #n ")" ::: "memory")
; #define PG8_BAR __builtin_amdgcn_s_barrier()
; #define PG8_SCHED __builtin_amdgcn_sched_barrier(0)
; template <class Epi, class Sched, bool ALIGN_EPI = false, bool SP2 = false>
; __device__ __forceinline__ void gemm_phase(PG8_LAS unsigned char* lds, const Gemm g, const Sched& S, const Epi& E) {
;     ...
;             PG8_LDA(At, 1, 1); PG8_STAGE(PG8_SB(1, 0), b3, voffB); PG8_STAGE(PG8_SB(1, 1), b3 + hstep, voffB); PG8_STAGE(PG8_SA(1, 0), a3, voffA);
;             PG8_WAIT_V(8); PG8_WAIT_L(0); PG8_BAR; PG8_MMA(1, 0, At, B0); PG8_MMA(1, 1, At, B1); PG8_BAR; PG8_SCHED;
	s_add_i32 s30, s61, s38
	v_lshl_add_u64 v[216:217], v[216:217], 0, s[18:19]
	s_mov_b32 m0, s30
	ds_read_b128 v[184:187], v150 offset:49152
	ds_read_b128 v[188:191], v150 offset:50176
	ds_read_b128 v[192:195], v150 offset:51200
	ds_read_b128 v[196:199], v150 offset:52224
	ds_read_b128 v[200:203], v150 offset:53248
	ds_read_b128 v[204:207], v150 offset:54272
	ds_read_b128 v[208:211], v150 offset:55296
	ds_read_b128 v[212:215], v150 offset:56320
	global_load_lds_dwordx4 v[216:217], off
	v_lshl_add_u64 v[216:217], v[218:219], 0, s[18:19]
	s_add_i32 m0, s30, 0x2000
	s_add_i32 s30, s62, s38
	global_load_lds_dwordx4 v[216:217], off
	v_lshl_add_u64 v[216:217], v[220:221], 0, s[18:19]
	s_mov_b32 m0, s30
	s_nop 0
	global_load_lds_dwordx4 v[216:217], off
	v_lshl_add_u64 v[216:217], v[222:223], 0, s[18:19]
	s_add_i32 m0, s30, 0x2000
	s_nop 0
	global_load_lds_dwordx4 v[216:217], off
	v_lshl_add_u64 v[216:217], v[224:225], 0, s[18:19]
	s_mov_b32 m0, s42
	s_nop 0
	global_load_lds_dwordx4 v[216:217], off
	v_lshl_add_u64 v[216:217], v[226:227], 0, s[18:19]
	s_mov_b32 m0, s43
	s_nop 0
	global_load_lds_dwordx4 v[216:217], off
	s_waitcnt vmcnt(8)
	s_waitcnt lgkmcnt(0)
	s_barrier
	s_setprio 1
	v_mfma_f32_16x16x32_bf16 v[62:65], v[152:155], v[184:187], v[62:65]
	v_mfma_f32_16x16x32_bf16 v[58:61], v[160:163], v[184:187], v[58:61]
	v_mfma_f32_16x16x32_bf16 v[46:49], v[152:155], v[192:195], v[46:49]
	v_mfma_f32_16x16x32_bf16 v[42:45], v[160:163], v[192:195], v[42:45]
	v_mfma_f32_16x16x32_bf16 v[30:33], v[152:155], v[200:203], v[30:33]
	v_mfma_f32_16x16x32_bf16 v[26:29], v[160:163], v[200:203], v[26:29]
	v_mfma_f32_16x16x32_bf16 v[14:17], v[152:155], v[208:211], v[14:17]
	v_mfma_f32_16x16x32_bf16 v[10:13], v[160:163], v[208:211], v[10:13]
	v_mfma_f32_16x16x32_bf16 v[62:65], v[156:159], v[188:191], v[62:65]
	v_mfma_f32_16x16x32_bf16 v[58:61], v[164:167], v[188:191], v[58:61]
	v_mfma_f32_16x16x32_bf16 v[46:49], v[156:159], v[196:199], v[46:49]
	v_mfma_f32_16x16x32_bf16 v[42:45], v[164:167], v[196:199], v[42:45]
	v_mfma_f32_16x16x32_bf16 v[30:33], v[156:159], v[204:207], v[30:33]
	v_mfma_f32_16x16x32_bf16 v[26:29], v[164:167], v[204:207], v[26:29]
	v_mfma_f32_16x16x32_bf16 v[14:17], v[156:159], v[212:215], v[14:17]
	v_mfma_f32_16x16x32_bf16 v[10:13], v[164:167], v[212:215], v[10:13]
	v_mfma_f32_16x16x32_bf16 v[54:57], v[168:171], v[184:187], v[54:57]
	v_mfma_f32_16x16x32_bf16 v[50:53], v[176:179], v[184:187], v[50:53]
	v_mfma_f32_16x16x32_bf16 v[38:41], v[168:171], v[192:195], v[38:41]
	v_mfma_f32_16x16x32_bf16 v[34:37], v[176:179], v[192:195], v[34:37]
	v_mfma_f32_16x16x32_bf16 v[22:25], v[168:171], v[200:203], v[22:25]
	v_mfma_f32_16x16x32_bf16 v[18:21], v[176:179], v[200:203], v[18:21]
	v_mfma_f32_16x16x32_bf16 v[6:9], v[168:171], v[208:211], v[6:9]
	v_mfma_f32_16x16x32_bf16 v[2:5], v[176:179], v[208:211], v[2:5]
	v_mfma_f32_16x16x32_bf16 v[54:57], v[172:175], v[188:191], v[54:57]
	v_mfma_f32_16x16x32_bf16 v[50:53], v[180:183], v[188:191], v[50:53]
	v_mfma_f32_16x16x32_bf16 v[38:41], v[172:175], v[196:199], v[38:41]
	v_mfma_f32_16x16x32_bf16 v[34:37], v[180:183], v[196:199], v[34:37]
	v_mfma_f32_16x16x32_bf16 v[22:25], v[172:175], v[204:207], v[22:25]
	v_mfma_f32_16x16x32_bf16 v[18:21], v[180:183], v[204:207], v[18:21]
	v_mfma_f32_16x16x32_bf16 v[6:9], v[172:175], v[212:215], v[6:9]
	v_mfma_f32_16x16x32_bf16 v[2:5], v[180:183], v[212:215], v[2:5]
	s_setprio 0
	s_barrier
	s_add_u32 s58, s58, 0x100
	s_addc_u32 s59, s59, 0
	s_add_u32 s28, s28, 0x100
	s_addc_u32 s29, s29, 0
	s_cmp_ge_i32 s60, s44
	s_mov_b32 s30, s60
	s_cbranch_scc0 .LBB0_582

; #define PG8_STAGE(bufoff, gbase, voff) do { _Pragma("unroll") for (int _i = 0; _i < 2; ++_i) \
;         __builtin_amdgcn_global_load_lds((const unsigned*)((const char*)(gbase) + (voff)[_i]), (PG8_LAS unsigned*)(lds + (bufoff) + ldsw + _i * 8192), 16, 0, 0); } while (0)
; #define PG8_LDA(dst, b, h) do { _Pragma("unroll") for (int m = 0; m < 4; ++m) _Pragma("unroll") for (int k = 0; k < 2; ++k) dst[m][k] = *(const PG8_LAS bf16x8*)(lds + PG8_SA(b, h) + aoff + m * 2048 + k * 1024); } while (0)
; #define PG8_LDB(dst, b, h) do { _Pragma("unroll") for (int n = 0; n < 2; ++n) _Pragma("unroll") for (int k = 0; k < 2; ++k) dst[n][k] = *(const PG8_LAS bf16x8*)(lds + PG8_SB(b, h) + boff + n * 2048 + k * 1024); } while (0)
; #define PG8_MMA(ai, bj, At, Bt) do { __builtin_amdgcn_s_setprio(1); _Pragma("unroll") for (int m = 0; m < 4; ++m) _Pragma("unroll") for (int n = 0; n < 2; ++n) _Pragma("unroll") for (int k = 0; k < 2; ++k) \
;         acc[ai][bj][m][n] = __builtin_amdgcn_mfma_f32_16x16x32_bf16(Bt[n][k], At[m][k], acc[ai][bj][m][n], 0, 0, 0); __builtin_amdgcn_s_setprio(0); } while (0)
; #define PG8_WAIT_V(n) asm volatile("s_waitcnt vmcnt(" #n ")" ::: "memory")
; #define PG8_WAIT_L(n) asm volatile("s_waitcnt lgkmcnt(" #n ")" ::: "memory")
; template <class Epi, class Sched, bool ALIGN_EPI = false, bool SP2 = false>
; __device__ __forceinline__ void gemm_phase(PG8_LAS unsigned char* lds, const Gemm g, const Sched& S, const Epi& E) {
;     ...
;             const bool last = (t == nt - 2);
;             const char* a1 = cA + (size_t)(t + 1) * kstep;
;             const char* a2 = last ? nA : cA + (size_t)(t + 2) * kstep; const char* b2 = last ? nB : cB + (size_t)(t + 2) * kstep;
;             const char* a3 = a2 + kstep; const char* b3 = b2 + kstep;
;             if (last && has_next) S.a_ready(nxt);
;             if constexpr (SP2) {
;             PG8_LDB(B0, 0, 0); PG8_LDB(B1, 0, 1); PG8_SCHED; PG8_LDA(At, 0, 0); PG8_STAGE(PG8_SA(1, 1), a1 + hstep, voffA);
;             PG8_WAIT_V(8); PG8_WAIT_L(0); PG8_BAR; PG8_MMA(0, 0, At, B0); PG8_MMA(0, 1, At, B1); PG8_BAR; PG8_SCHED;
;             PG8_LDA(At, 0, 1); PG8_STAGE(PG8_SB(0, 0), b2, voffB); PG8_STAGE(PG8_SB(0, 1), b2 + hstep, voffB); PG8_STAGE(PG8_SA(0, 0), a2, voffA);
;             PG8_WAIT_V(8); PG8_WAIT_L(0); PG8_BAR; PG8_MMA(1, 0, At, B0); PG8_MMA(1, 1, At, B1); PG8_BAR; PG8_SCHED;
.LBB0_749:
	ds_read_b128 v[152:155], v148
	ds_read_b128 v[156:159], v148 offset:1024
	ds_read_b128 v[160:163], v148 offset:2048
	ds_read_b128 v[164:167], v148 offset:3072
	ds_read_b128 v[168:171], v149
	ds_read_b128 v[172:175], v149 offset:1024
	ds_read_b128 v[176:179], v149 offset:2048
	ds_read_b128 v[180:183], v149 offset:3072
	s_add_i32 s60, s30, 2
	s_add_u32 s61, s28, 0x80
	s_addc_u32 s31, s29, 0
	s_cmp_eq_u32 s48, s30
	s_cselect_b32 s30, s6, s61
	s_cselect_b32 s31, s7, s31
	s_cselect_b32 s63, s25, s59
	s_cselect_b32 s62, s24, s58
	v_lshl_add_u64 v[216:217], s[28:29], 0, v[140:141]
	s_add_i32 m0, s40, 0xc000
	ds_read_b128 v[184:187], v150
	ds_read_b128 v[188:191], v150 offset:1024
	ds_read_b128 v[192:195], v150 offset:2048
	ds_read_b128 v[196:199], v150 offset:3072
	ds_read_b128 v[200:203], v150 offset:4096
	ds_read_b128 v[204:207], v150 offset:5120
	ds_read_b128 v[208:211], v150 offset:6144
	ds_read_b128 v[212:215], v150 offset:7168
	global_load_lds_dwordx4 v[216:217], off
	v_lshl_add_u64 v[216:217], s[28:29], 0, v[138:139]
	s_add_i32 m0, s40, 0xe000
	s_nop 0
	global_load_lds_dwordx4 v[216:217], off
	s_waitcnt vmcnt(8)
	s_waitcnt lgkmcnt(0)
	s_barrier
	s_setprio 1
	v_mfma_f32_16x16x32_bf16 v[122:125], v[152:155], v[184:187], v[122:125]
	v_mfma_f32_16x16x32_bf16 v[118:121], v[160:163], v[184:187], v[118:121]
	v_mfma_f32_16x16x32_bf16 v[110:113], v[152:155], v[192:195], v[110:113]
	v_mfma_f32_16x16x32_bf16 v[102:105], v[160:163], v[192:195], v[102:105]
	v_mfma_f32_16x16x32_bf16 v[94:97], v[152:155], v[200:203], v[94:97]
	v_mfma_f32_16x16x32_bf16 v[86:89], v[160:163], v[200:203], v[86:89]
	v_mfma_f32_16x16x32_bf16 v[78:81], v[152:155], v[208:211], v[78:81]
	v_mfma_f32_16x16x32_bf16 v[70:73], v[160:163], v[208:211], v[70:73]
	v_mfma_f32_16x16x32_bf16 v[122:125], v[156:159], v[188:191], v[122:125]
	v_mfma_f32_16x16x32_bf16 v[118:121], v[164:167], v[188:191], v[118:121]
	v_mfma_f32_16x16x32_bf16 v[110:113], v[156:159], v[196:199], v[110:113]
	v_mfma_f32_16x16x32_bf16 v[102:105], v[164:167], v[196:199], v[102:105]
	v_mfma_f32_16x16x32_bf16 v[94:97], v[156:159], v[204:207], v[94:97]
	v_mfma_f32_16x16x32_bf16 v[86:89], v[164:167], v[204:207], v[86:89]
	v_mfma_f32_16x16x32_bf16 v[78:81], v[156:159], v[212:215], v[78:81]
	v_mfma_f32_16x16x32_bf16 v[70:73], v[164:167], v[212:215], v[70:73]
	v_mfma_f32_16x16x32_bf16 v[126:129], v[168:171], v[184:187], v[126:129]
	v_mfma_f32_16x16x32_bf16 v[114:117], v[176:179], v[184:187], v[114:117]
	v_mfma_f32_16x16x32_bf16 v[106:109], v[168:171], v[192:195], v[106:109]
	v_mfma_f32_16x16x32_bf16 v[98:101], v[176:179], v[192:195], v[98:101]
	v_mfma_f32_16x16x32_bf16 v[90:93], v[168:171], v[200:203], v[90:93]
	v_mfma_f32_16x16x32_bf16 v[82:85], v[176:179], v[200:203], v[82:85]
	v_mfma_f32_16x16x32_bf16 v[74:77], v[168:171], v[208:211], v[74:77]
	v_mfma_f32_16x16x32_bf16 v[66:69], v[176:179], v[208:211], v[66:69]
	v_mfma_f32_16x16x32_bf16 v[126:129], v[172:175], v[188:191], v[126:129]
	v_mfma_f32_16x16x32_bf16 v[114:117], v[180:183], v[188:191], v[114:117]
	v_mfma_f32_16x16x32_bf16 v[106:109], v[172:175], v[196:199], v[106:109]
	v_mfma_f32_16x16x32_bf16 v[98:101], v[180:183], v[196:199], v[98:101]
	v_mfma_f32_16x16x32_bf16 v[90:93], v[172:175], v[204:207], v[90:93]
	v_mfma_f32_16x16x32_bf16 v[82:85], v[180:183], v[204:207], v[82:85]
	v_mfma_f32_16x16x32_bf16 v[74:77], v[172:175], v[212:215], v[74:77]
	v_mfma_f32_16x16x32_bf16 v[66:69], v[180:183], v[212:215], v[66:69]
	s_setprio 0
	s_barrier
	s_add_i32 s61, s53, s37
	v_lshl_add_u64 v[216:217], s[62:63], 0, v[134:135]
	s_mov_b32 m0, s61
	ds_read_b128 v[184:187], v150 offset:16384
	ds_read_b128 v[188:191], v150 offset:17408
	ds_read_b128 v[192:195], v150 offset:18432
	ds_read_b128 v[196:199], v150 offset:19456
	ds_read_b128 v[200:203], v150 offset:20480
	ds_read_b128 v[204:207], v150 offset:21504
	ds_read_b128 v[208:211], v150 offset:22528
	ds_read_b128 v[212:215], v150 offset:23552
	global_load_lds_dwordx4 v[216:217], off
	s_add_i32 m0, s61, 0x2000
	v_lshl_add_u64 v[218:219], s[62:63], 0, v[130:131]
	s_add_u32 s62, s62, s10
	s_addc_u32 s63, s63, s11
	s_add_i32 s61, s54, s37
	global_load_lds_dwordx4 v[218:219], off
	v_lshl_add_u64 v[220:221], s[62:63], 0, v[134:135]
	s_mov_b32 m0, s61
	v_lshl_add_u64 v[222:223], s[62:63], 0, v[130:131]
	global_load_lds_dwordx4 v[220:221], off
	s_add_i32 m0, s61, 0x2000
	v_lshl_add_u64 v[224:225], s[30:31], 0, v[136:137]
	global_load_lds_dwordx4 v[222:223], off
	s_mov_b32 m0, s40
	v_lshl_add_u64 v[226:227], s[30:31], 0, v[132:133]
	global_load_lds_dwordx4 v[224:225], off
	s_mov_b32 m0, s41
	s_nop 0
	global_load_lds_dwordx4 v[226:227], off
	s_waitcnt vmcnt(8)
	s_waitcnt lgkmcnt(0)
	s_barrier
; #define PG8_STAGE(bufoff, gbase, voff) do { _Pragma("unroll") for (int _i = 0; _i < 2; ++_i) \
;         __builtin_amdgcn_global_load_lds((const unsigned*)((const char*)(gbase) + (voff)[_i]), (PG8_LAS unsigned*)(lds + (bufoff) + ldsw + _i * 8192), 16, 0, 0); } while (0)
; #define PG8_LDA(dst, b, h) do { _Pragma("unroll") for (int m = 0; m < 4; ++m) _Pragma("unroll") for (int k = 0; k < 2; ++k) dst[m][k] = *(const PG8_LAS bf16x8*)(lds + PG8_SA(b, h) + aoff + m * 2048 + k * 1024); } while (0)
; #define PG8_LDB(dst, b, h) do { _Pragma("unroll") for (int n = 0; n < 2; ++n) _Pragma("unroll") for (int k = 0; k < 2; ++k) dst[n][k] = *(const PG8_LAS bf16x8*)(lds + PG8_SB(b, h) + boff + n * 2048 + k * 1024); } while (0)
; #define PG8_MMA(ai, bj, At, Bt) do { __builtin_amdgcn_s_setprio(1); _Pragma("unroll") for (int m = 0; m < 4; ++m) _Pragma("unroll") for (int n = 0; n < 2; ++n) _Pragma("unroll") for (int k = 0; k < 2; ++k) \
;         acc[ai][bj][m][n] = __builtin_amdgcn_mfma_f32_16x16x32_bf16(Bt[n][k], At[m][k], acc[ai][bj][m][n], 0, 0, 0); __builtin_amdgcn_s_setprio(0); } while (0)
; #define PG8_WAIT_V(n) asm volatile("s_waitcnt vmcnt(" #n ")" ::: "memory")
; #define PG8_WAIT_L(n) asm volatile("s_waitcnt lgkmcnt(" #n ")" ::: "memory")
; #define PG8_BAR __builtin_amdgcn_s_barrier()
; #define PG8_SCHED __builtin_amdgcn_sched_barrier(0)
; template <class Epi, class Sched, bool ALIGN_EPI = false, bool SP2 = false>
; __device__ __forceinline__ void gemm_phase(PG8_LAS unsigned char* lds, const Gemm g, const Sched& S, const Epi& E) {
;     ...
;             PG8_WAIT_V(8); PG8_WAIT_L(0); PG8_BAR; PG8_MMA(1, 0, At, B0); PG8_MMA(1, 1, At, B1); PG8_BAR; PG8_SCHED;
;             PG8_LDB(B0, 1, 0); PG8_LDB(B1, 1, 1); PG8_SCHED; PG8_LDA(At, 1, 0); PG8_STAGE(PG8_SA(0, 1), a2 + hstep, voffA);
;             PG8_WAIT_V(8); PG8_WAIT_L(0); PG8_BAR; PG8_MMA(0, 0, At, B0); PG8_MMA(0, 1, At, B1); PG8_BAR; PG8_SCHED;
	s_setprio 1
	v_mfma_f32_16x16x32_bf16 v[62:65], v[152:155], v[184:187], v[62:65]
	v_mfma_f32_16x16x32_bf16 v[54:57], v[160:163], v[184:187], v[54:57]
	v_mfma_f32_16x16x32_bf16 v[46:49], v[152:155], v[192:195], v[46:49]
	v_mfma_f32_16x16x32_bf16 v[38:41], v[160:163], v[192:195], v[38:41]
	v_mfma_f32_16x16x32_bf16 v[30:33], v[152:155], v[200:203], v[30:33]
	v_mfma_f32_16x16x32_bf16 v[22:25], v[160:163], v[200:203], v[22:25]
	v_mfma_f32_16x16x32_bf16 v[14:17], v[152:155], v[208:211], v[14:17]
	v_mfma_f32_16x16x32_bf16 v[6:9], v[160:163], v[208:211], v[6:9]
	v_mfma_f32_16x16x32_bf16 v[62:65], v[156:159], v[188:191], v[62:65]
	v_mfma_f32_16x16x32_bf16 v[54:57], v[164:167], v[188:191], v[54:57]
	v_mfma_f32_16x16x32_bf16 v[46:49], v[156:159], v[196:199], v[46:49]
	v_mfma_f32_16x16x32_bf16 v[38:41], v[164:167], v[196:199], v[38:41]
	v_mfma_f32_16x16x32_bf16 v[30:33], v[156:159], v[204:207], v[30:33]
	v_mfma_f32_16x16x32_bf16 v[22:25], v[164:167], v[204:207], v[22:25]
	v_mfma_f32_16x16x32_bf16 v[14:17], v[156:159], v[212:215], v[14:17]
	v_mfma_f32_16x16x32_bf16 v[6:9], v[164:167], v[212:215], v[6:9]
	v_mfma_f32_16x16x32_bf16 v[58:61], v[168:171], v[184:187], v[58:61]
	v_mfma_f32_16x16x32_bf16 v[50:53], v[176:179], v[184:187], v[50:53]
	v_mfma_f32_16x16x32_bf16 v[42:45], v[168:171], v[192:195], v[42:45]
	v_mfma_f32_16x16x32_bf16 v[34:37], v[176:179], v[192:195], v[34:37]
	v_mfma_f32_16x16x32_bf16 v[26:29], v[168:171], v[200:203], v[26:29]
	v_mfma_f32_16x16x32_bf16 v[18:21], v[176:179], v[200:203], v[18:21]
	v_mfma_f32_16x16x32_bf16 v[10:13], v[168:171], v[208:211], v[10:13]
	v_mfma_f32_16x16x32_bf16 v[2:5], v[176:179], v[208:211], v[2:5]
	v_mfma_f32_16x16x32_bf16 v[58:61], v[172:175], v[188:191], v[58:61]
	v_mfma_f32_16x16x32_bf16 v[50:53], v[180:183], v[188:191], v[50:53]
	v_mfma_f32_16x16x32_bf16 v[42:45], v[172:175], v[196:199], v[42:45]
	v_mfma_f32_16x16x32_bf16 v[34:37], v[180:183], v[196:199], v[34:37]
	v_mfma_f32_16x16x32_bf16 v[26:29], v[172:175], v[204:207], v[26:29]
	v_mfma_f32_16x16x32_bf16 v[18:21], v[180:183], v[204:207], v[18:21]
	v_mfma_f32_16x16x32_bf16 v[10:13], v[172:175], v[212:215], v[10:13]
	v_mfma_f32_16x16x32_bf16 v[2:5], v[180:183], v[212:215], v[2:5]
	s_setprio 0
	s_barrier
	s_add_i32 s61, 0, 0x18000
	v_add_u32_e32 v151, s61, v146
	s_add_i32 s62, 0, 0x1c000
	ds_read_b128 v[152:155], v151
	ds_read_b128 v[156:159], v151 offset:1024
	ds_read_b128 v[160:163], v151 offset:2048
	ds_read_b128 v[164:167], v151 offset:3072
	v_add_u32_e32 v151, s62, v146
	ds_read_b128 v[168:171], v151
	ds_read_b128 v[172:175], v151 offset:1024
	ds_read_b128 v[176:179], v151 offset:2048
	ds_read_b128 v[180:183], v151 offset:3072
	s_add_u32 s30, s30, s10
	s_addc_u32 s31, s31, s11
	s_mov_b32 m0, s42
	v_lshl_add_u64 v[228:229], s[30:31], 0, v[136:137]
	ds_read_b128 v[184:187], v150 offset:32768
	ds_read_b128 v[188:191], v150 offset:33792
	ds_read_b128 v[192:195], v150 offset:34816
	ds_read_b128 v[196:199], v150 offset:35840
	ds_read_b128 v[200:203], v150 offset:36864
	ds_read_b128 v[204:207], v150 offset:37888
	ds_read_b128 v[208:211], v150 offset:38912
	ds_read_b128 v[212:215], v150 offset:39936
	global_load_lds_dwordx4 v[228:229], off
	v_lshl_add_u64 v[228:229], s[30:31], 0, v[132:133]
	s_mov_b32 m0, s43
	s_nop 0
	global_load_lds_dwordx4 v[228:229], off
	s_waitcnt vmcnt(8)
	s_waitcnt lgkmcnt(0)
	s_barrier
	s_setprio 1
	v_mfma_f32_16x16x32_bf16 v[122:125], v[152:155], v[184:187], v[122:125]
	v_mfma_f32_16x16x32_bf16 v[118:121], v[160:163], v[184:187], v[118:121]
	v_mfma_f32_16x16x32_bf16 v[110:113], v[152:155], v[192:195], v[110:113]
	v_mfma_f32_16x16x32_bf16 v[102:105], v[160:163], v[192:195], v[102:105]
	v_mfma_f32_16x16x32_bf16 v[94:97], v[152:155], v[200:203], v[94:97]
	v_mfma_f32_16x16x32_bf16 v[86:89], v[160:163], v[200:203], v[86:89]
	v_mfma_f32_16x16x32_bf16 v[78:81], v[152:155], v[208:211], v[78:81]
	v_mfma_f32_16x16x32_bf16 v[70:73], v[160:163], v[208:211], v[70:73]
	v_mfma_f32_16x16x32_bf16 v[122:125], v[156:159], v[188:191], v[122:125]
	v_mfma_f32_16x16x32_bf16 v[118:121], v[164:167], v[188:191], v[118:121]
	v_mfma_f32_16x16x32_bf16 v[110:113], v[156:159], v[196:199], v[110:113]
	v_mfma_f32_16x16x32_bf16 v[102:105], v[164:167], v[196:199], v[102:105]
	v_mfma_f32_16x16x32_bf16 v[94:97], v[156:159], v[204:207], v[94:97]
	v_mfma_f32_16x16x32_bf16 v[86:89], v[164:167], v[204:207], v[86:89]
	v_mfma_f32_16x16x32_bf16 v[78:81], v[156:159], v[212:215], v[78:81]
	v_mfma_f32_16x16x32_bf16 v[70:73], v[164:167], v[212:215], v[70:73]
	v_mfma_f32_16x16x32_bf16 v[126:129], v[168:171], v[184:187], v[126:129]
	v_mfma_f32_16x16x32_bf16 v[114:117], v[176:179], v[184:187], v[114:117]
	v_mfma_f32_16x16x32_bf16 v[106:109], v[168:171], v[192:195], v[106:109]
	v_mfma_f32_16x16x32_bf16 v[98:101], v[176:179], v[192:195], v[98:101]
	v_mfma_f32_16x16x32_bf16 v[90:93], v[168:171], v[200:203], v[90:93]
	v_mfma_f32_16x16x32_bf16 v[82:85], v[176:179], v[200:203], v[82:85]
	v_mfma_f32_16x16x32_bf16 v[74:77], v[168:171], v[208:211], v[74:77]
	v_mfma_f32_16x16x32_bf16 v[66:69], v[176:179], v[208:211], v[66:69]
	v_mfma_f32_16x16x32_bf16 v[126:129], v[172:175], v[188:191], v[126:129]
	v_mfma_f32_16x16x32_bf16 v[114:117], v[180:183], v[188:191], v[114:117]
	v_mfma_f32_16x16x32_bf16 v[106:109], v[172:175], v[196:199], v[106:109]
	v_mfma_f32_16x16x32_bf16 v[98:101], v[180:183], v[196:199], v[98:101]
	v_mfma_f32_16x16x32_bf16 v[90:93], v[172:175], v[204:207], v[90:93]
	v_mfma_f32_16x16x32_bf16 v[82:85], v[180:183], v[204:207], v[82:85]
	v_mfma_f32_16x16x32_bf16 v[74:77], v[172:175], v[212:215], v[74:77]
	v_mfma_f32_16x16x32_bf16 v[66:69], v[180:183], v[212:215], v[66:69]
	s_setprio 0
	s_barrier
; #define PG8_STAGE(bufoff, gbase, voff) do { _Pragma("unroll") for (int _i = 0; _i < 2; ++_i) \
;         __builtin_amdgcn_global_load_lds((const unsigned*)((const char*)(gbase) + (voff)[_i]), (PG8_LAS unsigned*)(lds + (bufoff) + ldsw + _i * 8192), 16, 0, 0); } while (0)
; #define PG8_LDA(dst, b, h) do { _Pragma("unroll") for (int m = 0; m < 4; ++m) _Pragma("unroll") for (int k = 0; k < 2; ++k) dst[m][k] = *(const PG8_LAS bf16x8*)(lds + PG8_SA(b, h) + aoff + m * 2048 + k * 1024); } while (0)
; #define PG8_MMA(ai, bj, At, Bt) do { __builtin_amdgcn_s_setprio(1); _Pragma("unroll") for (int m = 0; m < 4; ++m) _Pragma("unroll") for (int n = 0; n < 2; ++n) _Pragma("unroll") for (int k = 0; k < 2; ++k) \
;         acc[ai][bj][m][n] = __builtin_amdgcn_mfma_f32_16x16x32_bf16(Bt[n][k], At[m][k], acc[ai][bj][m][n], 0, 0, 0); __builtin_amdgcn_s_setprio(0); } while (0)
; #define PG8_WAIT_V(n) asm volatile("s_waitcnt vmcnt(" #n ")" ::: "memory")
; #define PG8_WAIT_L(n) asm volatile("s_waitcnt lgkmcnt(" #n ")" ::: "memory")
; #define PG8_BAR __builtin_amdgcn_s_barrier()
; #define PG8_SCHED __builtin_amdgcn_sched_barrier(0)
; template <class Epi, class Sched, bool ALIGN_EPI = false, bool SP2 = false>
; __device__ __forceinline__ void gemm_phase(PG8_LAS unsigned char* lds, const Gemm g, const Sched& S, const Epi& E) {
;     ...
;             PG8_LDA(At, 1, 1); PG8_STAGE(PG8_SB(1, 0), b3, voffB); PG8_STAGE(PG8_SB(1, 1), b3 + hstep, voffB); PG8_STAGE(PG8_SA(1, 0), a3, voffA);
;             PG8_WAIT_V(8); PG8_WAIT_L(0); PG8_BAR; PG8_MMA(1, 0, At, B0); PG8_MMA(1, 1, At, B1); PG8_BAR; PG8_SCHED;
	s_add_i32 s30, s61, s37
	v_lshl_add_u64 v[216:217], v[216:217], 0, s[18:19]
	s_mov_b32 m0, s30
	ds_read_b128 v[184:187], v150 offset:49152
	ds_read_b128 v[188:191], v150 offset:50176
	ds_read_b128 v[192:195], v150 offset:51200
	ds_read_b128 v[196:199], v150 offset:52224
	ds_read_b128 v[200:203], v150 offset:53248
	ds_read_b128 v[204:207], v150 offset:54272
	ds_read_b128 v[208:211], v150 offset:55296
	ds_read_b128 v[212:215], v150 offset:56320
	global_load_lds_dwordx4 v[216:217], off
	v_lshl_add_u64 v[216:217], v[218:219], 0, s[18:19]
	s_add_i32 m0, s30, 0x2000
	s_add_i32 s30, s62, s37
	global_load_lds_dwordx4 v[216:217], off
	v_lshl_add_u64 v[216:217], v[220:221], 0, s[18:19]
	s_mov_b32 m0, s30
	s_nop 0
	global_load_lds_dwordx4 v[216:217], off
	v_lshl_add_u64 v[216:217], v[222:223], 0, s[18:19]
	s_add_i32 m0, s30, 0x2000
	s_nop 0
	global_load_lds_dwordx4 v[216:217], off
	v_lshl_add_u64 v[216:217], v[224:225], 0, s[18:19]
	s_mov_b32 m0, s45
	s_nop 0
	global_load_lds_dwordx4 v[216:217], off
	v_lshl_add_u64 v[216:217], v[226:227], 0, s[18:19]
	s_mov_b32 m0, s46
	s_nop 0
	global_load_lds_dwordx4 v[216:217], off
	s_waitcnt vmcnt(8)
	s_waitcnt lgkmcnt(0)
	s_barrier
	s_setprio 1
	v_mfma_f32_16x16x32_bf16 v[62:65], v[152:155], v[184:187], v[62:65]
	v_mfma_f32_16x16x32_bf16 v[54:57], v[160:163], v[184:187], v[54:57]
	v_mfma_f32_16x16x32_bf16 v[46:49], v[152:155], v[192:195], v[46:49]
	v_mfma_f32_16x16x32_bf16 v[38:41], v[160:163], v[192:195], v[38:41]
	v_mfma_f32_16x16x32_bf16 v[30:33], v[152:155], v[200:203], v[30:33]
	v_mfma_f32_16x16x32_bf16 v[22:25], v[160:163], v[200:203], v[22:25]
	v_mfma_f32_16x16x32_bf16 v[14:17], v[152:155], v[208:211], v[14:17]
	v_mfma_f32_16x16x32_bf16 v[6:9], v[160:163], v[208:211], v[6:9]
	v_mfma_f32_16x16x32_bf16 v[62:65], v[156:159], v[188:191], v[62:65]
	v_mfma_f32_16x16x32_bf16 v[54:57], v[164:167], v[188:191], v[54:57]
	v_mfma_f32_16x16x32_bf16 v[46:49], v[156:159], v[196:199], v[46:49]
	v_mfma_f32_16x16x32_bf16 v[38:41], v[164:167], v[196:199], v[38:41]
	v_mfma_f32_16x16x32_bf16 v[30:33], v[156:159], v[204:207], v[30:33]
	v_mfma_f32_16x16x32_bf16 v[22:25], v[164:167], v[204:207], v[22:25]
	v_mfma_f32_16x16x32_bf16 v[14:17], v[156:159], v[212:215], v[14:17]
	v_mfma_f32_16x16x32_bf16 v[6:9], v[164:167], v[212:215], v[6:9]
	v_mfma_f32_16x16x32_bf16 v[58:61], v[168:171], v[184:187], v[58:61]
	v_mfma_f32_16x16x32_bf16 v[50:53], v[176:179], v[184:187], v[50:53]
	v_mfma_f32_16x16x32_bf16 v[42:45], v[168:171], v[192:195], v[42:45]
	v_mfma_f32_16x16x32_bf16 v[34:37], v[176:179], v[192:195], v[34:37]
	v_mfma_f32_16x16x32_bf16 v[26:29], v[168:171], v[200:203], v[26:29]
	v_mfma_f32_16x16x32_bf16 v[18:21], v[176:179], v[200:203], v[18:21]
	v_mfma_f32_16x16x32_bf16 v[10:13], v[168:171], v[208:211], v[10:13]
	v_mfma_f32_16x16x32_bf16 v[2:5], v[176:179], v[208:211], v[2:5]
	v_mfma_f32_16x16x32_bf16 v[58:61], v[172:175], v[188:191], v[58:61]
	v_mfma_f32_16x16x32_bf16 v[50:53], v[180:183], v[188:191], v[50:53]
	v_mfma_f32_16x16x32_bf16 v[42:45], v[172:175], v[196:199], v[42:45]
	v_mfma_f32_16x16x32_bf16 v[34:37], v[180:183], v[196:199], v[34:37]
	v_mfma_f32_16x16x32_bf16 v[26:29], v[172:175], v[204:207], v[26:29]
	v_mfma_f32_16x16x32_bf16 v[18:21], v[180:183], v[204:207], v[18:21]
	v_mfma_f32_16x16x32_bf16 v[10:13], v[172:175], v[212:215], v[10:13]
	v_mfma_f32_16x16x32_bf16 v[2:5], v[180:183], v[212:215], v[2:5]
	s_setprio 0
	s_barrier
	s_add_u32 s58, s58, 0x100
	s_addc_u32 s59, s59, 0
	s_add_u32 s28, s28, 0x100
	s_addc_u32 s29, s29, 0
	s_cmp_ge_i32 s60, s47
	s_mov_b32 s30, s60
	s_cbranch_scc0 .LBB0_749

; #define PG8_STAGE(bufoff, gbase, voff) do { _Pragma("unroll") for (int _i = 0; _i < 2; ++_i) \
;         __builtin_amdgcn_global_load_lds((const unsigned*)((const char*)(gbase) + (voff)[_i]), (PG8_LAS unsigned*)(lds + (bufoff) + ldsw + _i * 8192), 16, 0, 0); } while (0)
; #define PG8_LDA(dst, b, h) do { _Pragma("unroll") for (int m = 0; m < 4; ++m) _Pragma("unroll") for (int k = 0; k < 2; ++k) dst[m][k] = *(const PG8_LAS bf16x8*)(lds + PG8_SA(b, h) + aoff + m * 2048 + k * 1024); } while (0)
; #define PG8_LDB(dst, b, h) do { _Pragma("unroll") for (int n = 0; n < 2; ++n) _Pragma("unroll") for (int k = 0; k < 2; ++k) dst[n][k] = *(const PG8_LAS bf16x8*)(lds + PG8_SB(b, h) + boff + n * 2048 + k * 1024); } while (0)
; #define PG8_MMA(ai, bj, At, Bt) do { __builtin_amdgcn_s_setprio(1); _Pragma("unroll") for (int m = 0; m < 4; ++m) _Pragma("unroll") for (int n = 0; n < 2; ++n) _Pragma("unroll") for (int k = 0; k < 2; ++k) \
;         acc[ai][bj][m][n] = __builtin_amdgcn_mfma_f32_16x16x32_bf16(Bt[n][k], At[m][k], acc[ai][bj][m][n], 0, 0, 0); __builtin_amdgcn_s_setprio(0); } while (0)
; #define PG8_WAIT_V(n) asm volatile("s_waitcnt vmcnt(" #n ")" ::: "memory")
; #define PG8_WAIT_L(n) asm volatile("s_waitcnt lgkmcnt(" #n ")" ::: "memory")
; template <class Epi, class Sched, bool ALIGN_EPI = false, bool SP2 = false>
; __device__ __forceinline__ void gemm_phase(PG8_LAS unsigned char* lds, const Gemm g, const Sched& S, const Epi& E) {
;     ...
;             const bool last = (t == nt - 2);
;             const char* a1 = cA + (size_t)(t + 1) * kstep;
;             const char* a2 = last ? nA : cA + (size_t)(t + 2) * kstep; const char* b2 = last ? nB : cB + (size_t)(t + 2) * kstep;
;             const char* a3 = a2 + kstep; const char* b3 = b2 + kstep;
;             if (last && has_next) S.a_ready(nxt);
;             if constexpr (SP2) {
;             PG8_LDB(B0, 0, 0); PG8_LDB(B1, 0, 1); PG8_SCHED; PG8_LDA(At, 0, 0); PG8_STAGE(PG8_SA(1, 1), a1 + hstep, voffA);
;             PG8_WAIT_V(8); PG8_WAIT_L(0); PG8_BAR; PG8_MMA(0, 0, At, B0); PG8_MMA(0, 1, At, B1); PG8_BAR; PG8_SCHED;
;             PG8_LDA(At, 0, 1); PG8_STAGE(PG8_SB(0, 0), b2, voffB); PG8_STAGE(PG8_SB(0, 1), b2 + hstep, voffB); PG8_STAGE(PG8_SA(0, 0), a2, voffA);
;             PG8_WAIT_V(8); PG8_WAIT_L(0); PG8_BAR; PG8_MMA(1, 0, At, B0); PG8_MMA(1, 1, At, B1); PG8_BAR; PG8_SCHED;
.LBB0_834:
	ds_read_b128 v[152:155], v148
	ds_read_b128 v[156:159], v148 offset:1024
	ds_read_b128 v[160:163], v148 offset:2048
	ds_read_b128 v[164:167], v148 offset:3072
	ds_read_b128 v[168:171], v149
	ds_read_b128 v[172:175], v149 offset:1024
	ds_read_b128 v[176:179], v149 offset:2048
	ds_read_b128 v[180:183], v149 offset:3072
	s_add_i32 s58, s30, 2
	s_add_u32 s59, s28, 0x80
	s_addc_u32 s31, s29, 0
	s_cmp_eq_u32 s45, s30
	s_cselect_b32 s30, s6, s59
	s_cselect_b32 s31, s7, s31
	s_cselect_b32 s61, s25, s57
	s_cselect_b32 s60, s24, s56
	v_lshl_add_u64 v[216:217], s[28:29], 0, v[140:141]
	s_add_i32 m0, s0, 0xc000
	ds_read_b128 v[184:187], v150
	ds_read_b128 v[188:191], v150 offset:1024
	ds_read_b128 v[192:195], v150 offset:2048
	ds_read_b128 v[196:199], v150 offset:3072
	ds_read_b128 v[200:203], v150 offset:4096
	ds_read_b128 v[204:207], v150 offset:5120
	ds_read_b128 v[208:211], v150 offset:6144
	ds_read_b128 v[212:215], v150 offset:7168
	global_load_lds_dwordx4 v[216:217], off
	v_lshl_add_u64 v[216:217], s[28:29], 0, v[138:139]
	s_add_i32 m0, s0, 0xe000
	s_nop 0
	global_load_lds_dwordx4 v[216:217], off
	s_waitcnt vmcnt(8)
	s_waitcnt lgkmcnt(0)
	s_barrier
	s_setprio 1
	v_mfma_f32_16x16x32_bf16 v[122:125], v[152:155], v[184:187], v[122:125]
	v_mfma_f32_16x16x32_bf16 v[126:129], v[160:163], v[184:187], v[126:129]
	v_mfma_f32_16x16x32_bf16 v[110:113], v[152:155], v[192:195], v[110:113]
	v_mfma_f32_16x16x32_bf16 v[106:109], v[160:163], v[192:195], v[106:109]
	v_mfma_f32_16x16x32_bf16 v[94:97], v[152:155], v[200:203], v[94:97]
	v_mfma_f32_16x16x32_bf16 v[90:93], v[160:163], v[200:203], v[90:93]
	v_mfma_f32_16x16x32_bf16 v[78:81], v[152:155], v[208:211], v[78:81]
	v_mfma_f32_16x16x32_bf16 v[74:77], v[160:163], v[208:211], v[74:77]
	v_mfma_f32_16x16x32_bf16 v[122:125], v[156:159], v[188:191], v[122:125]
	v_mfma_f32_16x16x32_bf16 v[126:129], v[164:167], v[188:191], v[126:129]
	v_mfma_f32_16x16x32_bf16 v[110:113], v[156:159], v[196:199], v[110:113]
	v_mfma_f32_16x16x32_bf16 v[106:109], v[164:167], v[196:199], v[106:109]
	v_mfma_f32_16x16x32_bf16 v[94:97], v[156:159], v[204:207], v[94:97]
	v_mfma_f32_16x16x32_bf16 v[90:93], v[164:167], v[204:207], v[90:93]
	v_mfma_f32_16x16x32_bf16 v[78:81], v[156:159], v[212:215], v[78:81]
	v_mfma_f32_16x16x32_bf16 v[74:77], v[164:167], v[212:215], v[74:77]
	v_mfma_f32_16x16x32_bf16 v[118:121], v[168:171], v[184:187], v[118:121]
	v_mfma_f32_16x16x32_bf16 v[114:117], v[176:179], v[184:187], v[114:117]
	v_mfma_f32_16x16x32_bf16 v[102:105], v[168:171], v[192:195], v[102:105]
	v_mfma_f32_16x16x32_bf16 v[98:101], v[176:179], v[192:195], v[98:101]
	v_mfma_f32_16x16x32_bf16 v[86:89], v[168:171], v[200:203], v[86:89]
	v_mfma_f32_16x16x32_bf16 v[82:85], v[176:179], v[200:203], v[82:85]
	v_mfma_f32_16x16x32_bf16 v[70:73], v[168:171], v[208:211], v[70:73]
	v_mfma_f32_16x16x32_bf16 v[66:69], v[176:179], v[208:211], v[66:69]
	v_mfma_f32_16x16x32_bf16 v[118:121], v[172:175], v[188:191], v[118:121]
	v_mfma_f32_16x16x32_bf16 v[114:117], v[180:183], v[188:191], v[114:117]
	v_mfma_f32_16x16x32_bf16 v[102:105], v[172:175], v[196:199], v[102:105]
	v_mfma_f32_16x16x32_bf16 v[98:101], v[180:183], v[196:199], v[98:101]
	v_mfma_f32_16x16x32_bf16 v[86:89], v[172:175], v[204:207], v[86:89]
	v_mfma_f32_16x16x32_bf16 v[82:85], v[180:183], v[204:207], v[82:85]
	v_mfma_f32_16x16x32_bf16 v[70:73], v[172:175], v[212:215], v[70:73]
	v_mfma_f32_16x16x32_bf16 v[66:69], v[180:183], v[212:215], v[66:69]
	s_setprio 0
	s_barrier
	s_add_i32 s59, s48, s38
	v_lshl_add_u64 v[216:217], s[60:61], 0, v[132:133]
	s_mov_b32 m0, s59
	ds_read_b128 v[184:187], v150 offset:16384
	ds_read_b128 v[188:191], v150 offset:17408
	ds_read_b128 v[192:195], v150 offset:18432
	ds_read_b128 v[196:199], v150 offset:19456
	ds_read_b128 v[200:203], v150 offset:20480
	ds_read_b128 v[204:207], v150 offset:21504
	ds_read_b128 v[208:211], v150 offset:22528
	ds_read_b128 v[212:215], v150 offset:23552
	global_load_lds_dwordx4 v[216:217], off
	s_add_i32 m0, s59, 0x2000
	v_lshl_add_u64 v[218:219], s[60:61], 0, v[136:137]
	s_add_u32 s60, s60, s10
	s_addc_u32 s61, s61, s11
	s_add_i32 s59, s49, s38
	global_load_lds_dwordx4 v[218:219], off
	v_lshl_add_u64 v[220:221], s[60:61], 0, v[132:133]
	s_mov_b32 m0, s59
	v_lshl_add_u64 v[222:223], s[60:61], 0, v[136:137]
	global_load_lds_dwordx4 v[220:221], off
	s_add_i32 m0, s59, 0x2000
	v_lshl_add_u64 v[224:225], s[30:31], 0, v[130:131]
	global_load_lds_dwordx4 v[222:223], off
	s_mov_b32 m0, s0
	v_lshl_add_u64 v[226:227], s[30:31], 0, v[134:135]
	global_load_lds_dwordx4 v[224:225], off
	s_mov_b32 m0, s1
	s_nop 0
	global_load_lds_dwordx4 v[226:227], off
	s_waitcnt vmcnt(8)
	s_waitcnt lgkmcnt(0)
	s_barrier
; #define PG8_STAGE(bufoff, gbase, voff) do { _Pragma("unroll") for (int _i = 0; _i < 2; ++_i) \
;         __builtin_amdgcn_global_load_lds((const unsigned*)((const char*)(gbase) + (voff)[_i]), (PG8_LAS unsigned*)(lds + (bufoff) + ldsw + _i * 8192), 16, 0, 0); } while (0)
; #define PG8_LDA(dst, b, h) do { _Pragma("unroll") for (int m = 0; m < 4; ++m) _Pragma("unroll") for (int k = 0; k < 2; ++k) dst[m][k] = *(const PG8_LAS bf16x8*)(lds + PG8_SA(b, h) + aoff + m * 2048 + k * 1024); } while (0)
; #define PG8_LDB(dst, b, h) do { _Pragma("unroll") for (int n = 0; n < 2; ++n) _Pragma("unroll") for (int k = 0; k < 2; ++k) dst[n][k] = *(const PG8_LAS bf16x8*)(lds + PG8_SB(b, h) + boff + n * 2048 + k * 1024); } while (0)
; #define PG8_MMA(ai, bj, At, Bt) do { __builtin_amdgcn_s_setprio(1); _Pragma("unroll") for (int m = 0; m < 4; ++m) _Pragma("unroll") for (int n = 0; n < 2; ++n) _Pragma("unroll") for (int k = 0; k < 2; ++k) \
;         acc[ai][bj][m][n] = __builtin_amdgcn_mfma_f32_16x16x32_bf16(Bt[n][k], At[m][k], acc[ai][bj][m][n], 0, 0, 0); __builtin_amdgcn_s_setprio(0); } while (0)
; #define PG8_WAIT_V(n) asm volatile("s_waitcnt vmcnt(" #n ")" ::: "memory")
; #define PG8_WAIT_L(n) asm volatile("s_waitcnt lgkmcnt(" #n ")" ::: "memory")
; #define PG8_BAR __builtin_amdgcn_s_barrier()
; #define PG8_SCHED __builtin_amdgcn_sched_barrier(0)
; template <class Epi, class Sched, bool ALIGN_EPI = false, bool SP2 = false>
; __device__ __forceinline__ void gemm_phase(PG8_LAS unsigned char* lds, const Gemm g, const Sched& S, const Epi& E) {
;     ...
;             PG8_WAIT_V(8); PG8_WAIT_L(0); PG8_BAR; PG8_MMA(1, 0, At, B0); PG8_MMA(1, 1, At, B1); PG8_BAR; PG8_SCHED;
;             PG8_LDB(B0, 1, 0); PG8_LDB(B1, 1, 1); PG8_SCHED; PG8_LDA(At, 1, 0); PG8_STAGE(PG8_SA(0, 1), a2 + hstep, voffA);
;             PG8_WAIT_V(8); PG8_WAIT_L(0); PG8_BAR; PG8_MMA(0, 0, At, B0); PG8_MMA(0, 1, At, B1); PG8_BAR; PG8_SCHED;
	s_setprio 1
	v_mfma_f32_16x16x32_bf16 v[62:65], v[152:155], v[184:187], v[62:65]
	v_mfma_f32_16x16x32_bf16 v[58:61], v[160:163], v[184:187], v[58:61]
	v_mfma_f32_16x16x32_bf16 v[46:49], v[152:155], v[192:195], v[46:49]
	v_mfma_f32_16x16x32_bf16 v[42:45], v[160:163], v[192:195], v[42:45]
	v_mfma_f32_16x16x32_bf16 v[30:33], v[152:155], v[200:203], v[30:33]
	v_mfma_f32_16x16x32_bf16 v[26:29], v[160:163], v[200:203], v[26:29]
	v_mfma_f32_16x16x32_bf16 v[14:17], v[152:155], v[208:211], v[14:17]
	v_mfma_f32_16x16x32_bf16 v[10:13], v[160:163], v[208:211], v[10:13]
	v_mfma_f32_16x16x32_bf16 v[62:65], v[156:159], v[188:191], v[62:65]
	v_mfma_f32_16x16x32_bf16 v[58:61], v[164:167], v[188:191], v[58:61]
	v_mfma_f32_16x16x32_bf16 v[46:49], v[156:159], v[196:199], v[46:49]
	v_mfma_f32_16x16x32_bf16 v[42:45], v[164:167], v[196:199], v[42:45]
	v_mfma_f32_16x16x32_bf16 v[30:33], v[156:159], v[204:207], v[30:33]
	v_mfma_f32_16x16x32_bf16 v[26:29], v[164:167], v[204:207], v[26:29]
	v_mfma_f32_16x16x32_bf16 v[14:17], v[156:159], v[212:215], v[14:17]
	v_mfma_f32_16x16x32_bf16 v[10:13], v[164:167], v[212:215], v[10:13]
	v_mfma_f32_16x16x32_bf16 v[54:57], v[168:171], v[184:187], v[54:57]
	v_mfma_f32_16x16x32_bf16 v[50:53], v[176:179], v[184:187], v[50:53]
	v_mfma_f32_16x16x32_bf16 v[38:41], v[168:171], v[192:195], v[38:41]
	v_mfma_f32_16x16x32_bf16 v[34:37], v[176:179], v[192:195], v[34:37]
	v_mfma_f32_16x16x32_bf16 v[22:25], v[168:171], v[200:203], v[22:25]
	v_mfma_f32_16x16x32_bf16 v[18:21], v[176:179], v[200:203], v[18:21]
	v_mfma_f32_16x16x32_bf16 v[6:9], v[168:171], v[208:211], v[6:9]
	v_mfma_f32_16x16x32_bf16 v[2:5], v[176:179], v[208:211], v[2:5]
	v_mfma_f32_16x16x32_bf16 v[54:57], v[172:175], v[188:191], v[54:57]
	v_mfma_f32_16x16x32_bf16 v[50:53], v[180:183], v[188:191], v[50:53]
	v_mfma_f32_16x16x32_bf16 v[38:41], v[172:175], v[196:199], v[38:41]
	v_mfma_f32_16x16x32_bf16 v[34:37], v[180:183], v[196:199], v[34:37]
	v_mfma_f32_16x16x32_bf16 v[22:25], v[172:175], v[204:207], v[22:25]
	v_mfma_f32_16x16x32_bf16 v[18:21], v[180:183], v[204:207], v[18:21]
	v_mfma_f32_16x16x32_bf16 v[6:9], v[172:175], v[212:215], v[6:9]
	v_mfma_f32_16x16x32_bf16 v[2:5], v[180:183], v[212:215], v[2:5]
	s_setprio 0
	s_barrier
	s_add_i32 s59, 0, 0x18000
	v_add_u32_e32 v151, s59, v146
	s_add_i32 s60, 0, 0x1c000
	ds_read_b128 v[152:155], v151
	ds_read_b128 v[156:159], v151 offset:1024
	ds_read_b128 v[160:163], v151 offset:2048
	ds_read_b128 v[164:167], v151 offset:3072
	v_add_u32_e32 v151, s60, v146
	ds_read_b128 v[168:171], v151
	ds_read_b128 v[172:175], v151 offset:1024
	ds_read_b128 v[176:179], v151 offset:2048
	ds_read_b128 v[180:183], v151 offset:3072
	s_add_u32 s30, s30, s10
	s_addc_u32 s31, s31, s11
	s_mov_b32 m0, s39
	v_lshl_add_u64 v[228:229], s[30:31], 0, v[130:131]
	ds_read_b128 v[184:187], v150 offset:32768
	ds_read_b128 v[188:191], v150 offset:33792
	ds_read_b128 v[192:195], v150 offset:34816
	ds_read_b128 v[196:199], v150 offset:35840
	ds_read_b128 v[200:203], v150 offset:36864
	ds_read_b128 v[204:207], v150 offset:37888
	ds_read_b128 v[208:211], v150 offset:38912
	ds_read_b128 v[212:215], v150 offset:39936
	global_load_lds_dwordx4 v[228:229], off
	v_lshl_add_u64 v[228:229], s[30:31], 0, v[134:135]
	s_mov_b32 m0, s40
	s_nop 0
	global_load_lds_dwordx4 v[228:229], off
	s_waitcnt vmcnt(8)
	s_waitcnt lgkmcnt(0)
	s_barrier
	s_setprio 1
	v_mfma_f32_16x16x32_bf16 v[122:125], v[152:155], v[184:187], v[122:125]
	v_mfma_f32_16x16x32_bf16 v[126:129], v[160:163], v[184:187], v[126:129]
	v_mfma_f32_16x16x32_bf16 v[110:113], v[152:155], v[192:195], v[110:113]
	v_mfma_f32_16x16x32_bf16 v[106:109], v[160:163], v[192:195], v[106:109]
	v_mfma_f32_16x16x32_bf16 v[94:97], v[152:155], v[200:203], v[94:97]
	v_mfma_f32_16x16x32_bf16 v[90:93], v[160:163], v[200:203], v[90:93]
	v_mfma_f32_16x16x32_bf16 v[78:81], v[152:155], v[208:211], v[78:81]
	v_mfma_f32_16x16x32_bf16 v[74:77], v[160:163], v[208:211], v[74:77]
	v_mfma_f32_16x16x32_bf16 v[122:125], v[156:159], v[188:191], v[122:125]
	v_mfma_f32_16x16x32_bf16 v[126:129], v[164:167], v[188:191], v[126:129]
	v_mfma_f32_16x16x32_bf16 v[110:113], v[156:159], v[196:199], v[110:113]
	v_mfma_f32_16x16x32_bf16 v[106:109], v[164:167], v[196:199], v[106:109]
	v_mfma_f32_16x16x32_bf16 v[94:97], v[156:159], v[204:207], v[94:97]
	v_mfma_f32_16x16x32_bf16 v[90:93], v[164:167], v[204:207], v[90:93]
	v_mfma_f32_16x16x32_bf16 v[78:81], v[156:159], v[212:215], v[78:81]
	v_mfma_f32_16x16x32_bf16 v[74:77], v[164:167], v[212:215], v[74:77]
	v_mfma_f32_16x16x32_bf16 v[118:121], v[168:171], v[184:187], v[118:121]
	v_mfma_f32_16x16x32_bf16 v[114:117], v[176:179], v[184:187], v[114:117]
	v_mfma_f32_16x16x32_bf16 v[102:105], v[168:171], v[192:195], v[102:105]
	v_mfma_f32_16x16x32_bf16 v[98:101], v[176:179], v[192:195], v[98:101]
	v_mfma_f32_16x16x32_bf16 v[86:89], v[168:171], v[200:203], v[86:89]
	v_mfma_f32_16x16x32_bf16 v[82:85], v[176:179], v[200:203], v[82:85]
	v_mfma_f32_16x16x32_bf16 v[70:73], v[168:171], v[208:211], v[70:73]
	v_mfma_f32_16x16x32_bf16 v[66:69], v[176:179], v[208:211], v[66:69]
	v_mfma_f32_16x16x32_bf16 v[118:121], v[172:175], v[188:191], v[118:121]
	v_mfma_f32_16x16x32_bf16 v[114:117], v[180:183], v[188:191], v[114:117]
	v_mfma_f32_16x16x32_bf16 v[102:105], v[172:175], v[196:199], v[102:105]
	v_mfma_f32_16x16x32_bf16 v[98:101], v[180:183], v[196:199], v[98:101]
	v_mfma_f32_16x16x32_bf16 v[86:89], v[172:175], v[204:207], v[86:89]
	v_mfma_f32_16x16x32_bf16 v[82:85], v[180:183], v[204:207], v[82:85]
	v_mfma_f32_16x16x32_bf16 v[70:73], v[172:175], v[212:215], v[70:73]
	v_mfma_f32_16x16x32_bf16 v[66:69], v[180:183], v[212:215], v[66:69]
	s_setprio 0
	s_barrier
; #define PG8_STAGE(bufoff, gbase, voff) do { _Pragma("unroll") for (int _i = 0; _i < 2; ++_i) \
;         __builtin_amdgcn_global_load_lds((const unsigned*)((const char*)(gbase) + (voff)[_i]), (PG8_LAS unsigned*)(lds + (bufoff) + ldsw + _i * 8192), 16, 0, 0); } while (0)
; #define PG8_LDA(dst, b, h) do { _Pragma("unroll") for (int m = 0; m < 4; ++m) _Pragma("unroll") for (int k = 0; k < 2; ++k) dst[m][k] = *(const PG8_LAS bf16x8*)(lds + PG8_SA(b, h) + aoff + m * 2048 + k * 1024); } while (0)
; #define PG8_MMA(ai, bj, At, Bt) do { __builtin_amdgcn_s_setprio(1); _Pragma("unroll") for (int m = 0; m < 4; ++m) _Pragma("unroll") for (int n = 0; n < 2; ++n) _Pragma("unroll") for (int k = 0; k < 2; ++k) \
;         acc[ai][bj][m][n] = __builtin_amdgcn_mfma_f32_16x16x32_bf16(Bt[n][k], At[m][k], acc[ai][bj][m][n], 0, 0, 0); __builtin_amdgcn_s_setprio(0); } while (0)
; #define PG8_WAIT_V(n) asm volatile("s_waitcnt vmcnt(" #n ")" ::: "memory")
; #define PG8_WAIT_L(n) asm volatile("s_waitcnt lgkmcnt(" #n ")" ::: "memory")
; #define PG8_BAR __builtin_amdgcn_s_barrier()
; #define PG8_SCHED __builtin_amdgcn_sched_barrier(0)
; template <class Epi, class Sched, bool ALIGN_EPI = false, bool SP2 = false>
; __device__ __forceinline__ void gemm_phase(PG8_LAS unsigned char* lds, const Gemm g, const Sched& S, const Epi& E) {
;     ...
;             PG8_LDA(At, 1, 1); PG8_STAGE(PG8_SB(1, 0), b3, voffB); PG8_STAGE(PG8_SB(1, 1), b3 + hstep, voffB); PG8_STAGE(PG8_SA(1, 0), a3, voffA);
;             PG8_WAIT_V(8); PG8_WAIT_L(0); PG8_BAR; PG8_MMA(1, 0, At, B0); PG8_MMA(1, 1, At, B1); PG8_BAR; PG8_SCHED;
	s_add_i32 s30, s59, s38
	v_lshl_add_u64 v[216:217], v[216:217], 0, s[18:19]
	s_mov_b32 m0, s30
	ds_read_b128 v[184:187], v150 offset:49152
	ds_read_b128 v[188:191], v150 offset:50176
	ds_read_b128 v[192:195], v150 offset:51200
	ds_read_b128 v[196:199], v150 offset:52224
	ds_read_b128 v[200:203], v150 offset:53248
	ds_read_b128 v[204:207], v150 offset:54272
	ds_read_b128 v[208:211], v150 offset:55296
	ds_read_b128 v[212:215], v150 offset:56320
	global_load_lds_dwordx4 v[216:217], off
	v_lshl_add_u64 v[216:217], v[218:219], 0, s[18:19]
	s_add_i32 m0, s30, 0x2000
	s_add_i32 s30, s60, s38
	global_load_lds_dwordx4 v[216:217], off
	v_lshl_add_u64 v[216:217], v[220:221], 0, s[18:19]
	s_mov_b32 m0, s30
	s_nop 0
	global_load_lds_dwordx4 v[216:217], off
	v_lshl_add_u64 v[216:217], v[222:223], 0, s[18:19]
	s_add_i32 m0, s30, 0x2000
	s_nop 0
	global_load_lds_dwordx4 v[216:217], off
	v_lshl_add_u64 v[216:217], v[224:225], 0, s[18:19]
	s_mov_b32 m0, s42
	s_nop 0
	global_load_lds_dwordx4 v[216:217], off
	v_lshl_add_u64 v[216:217], v[226:227], 0, s[18:19]
	s_mov_b32 m0, s43
	s_nop 0
	global_load_lds_dwordx4 v[216:217], off
	s_waitcnt vmcnt(8)
	s_waitcnt lgkmcnt(0)
	s_barrier
	s_setprio 1
	v_mfma_f32_16x16x32_bf16 v[62:65], v[152:155], v[184:187], v[62:65]
	v_mfma_f32_16x16x32_bf16 v[58:61], v[160:163], v[184:187], v[58:61]
	v_mfma_f32_16x16x32_bf16 v[46:49], v[152:155], v[192:195], v[46:49]
	v_mfma_f32_16x16x32_bf16 v[42:45], v[160:163], v[192:195], v[42:45]
	v_mfma_f32_16x16x32_bf16 v[30:33], v[152:155], v[200:203], v[30:33]
	v_mfma_f32_16x16x32_bf16 v[26:29], v[160:163], v[200:203], v[26:29]
	v_mfma_f32_16x16x32_bf16 v[14:17], v[152:155], v[208:211], v[14:17]
	v_mfma_f32_16x16x32_bf16 v[10:13], v[160:163], v[208:211], v[10:13]
	v_mfma_f32_16x16x32_bf16 v[62:65], v[156:159], v[188:191], v[62:65]
	v_mfma_f32_16x16x32_bf16 v[58:61], v[164:167], v[188:191], v[58:61]
	v_mfma_f32_16x16x32_bf16 v[46:49], v[156:159], v[196:199], v[46:49]
	v_mfma_f32_16x16x32_bf16 v[42:45], v[164:167], v[196:199], v[42:45]
	v_mfma_f32_16x16x32_bf16 v[30:33], v[156:159], v[204:207], v[30:33]
	v_mfma_f32_16x16x32_bf16 v[26:29], v[164:167], v[204:207], v[26:29]
	v_mfma_f32_16x16x32_bf16 v[14:17], v[156:159], v[212:215], v[14:17]
	v_mfma_f32_16x16x32_bf16 v[10:13], v[164:167], v[212:215], v[10:13]
	v_mfma_f32_16x16x32_bf16 v[54:57], v[168:171], v[184:187], v[54:57]
	v_mfma_f32_16x16x32_bf16 v[50:53], v[176:179], v[184:187], v[50:53]
	v_mfma_f32_16x16x32_bf16 v[38:41], v[168:171], v[192:195], v[38:41]
	v_mfma_f32_16x16x32_bf16 v[34:37], v[176:179], v[192:195], v[34:37]
	v_mfma_f32_16x16x32_bf16 v[22:25], v[168:171], v[200:203], v[22:25]
	v_mfma_f32_16x16x32_bf16 v[18:21], v[176:179], v[200:203], v[18:21]
	v_mfma_f32_16x16x32_bf16 v[6:9], v[168:171], v[208:211], v[6:9]
	v_mfma_f32_16x16x32_bf16 v[2:5], v[176:179], v[208:211], v[2:5]
	v_mfma_f32_16x16x32_bf16 v[54:57], v[172:175], v[188:191], v[54:57]
	v_mfma_f32_16x16x32_bf16 v[50:53], v[180:183], v[188:191], v[50:53]
	v_mfma_f32_16x16x32_bf16 v[38:41], v[172:175], v[196:199], v[38:41]
	v_mfma_f32_16x16x32_bf16 v[34:37], v[180:183], v[196:199], v[34:37]
	v_mfma_f32_16x16x32_bf16 v[22:25], v[172:175], v[204:207], v[22:25]
	v_mfma_f32_16x16x32_bf16 v[18:21], v[180:183], v[204:207], v[18:21]
	v_mfma_f32_16x16x32_bf16 v[6:9], v[172:175], v[212:215], v[6:9]
	v_mfma_f32_16x16x32_bf16 v[2:5], v[180:183], v[212:215], v[2:5]
	s_setprio 0
	s_barrier
	s_add_u32 s56, s56, 0x100
	s_addc_u32 s57, s57, 0
	s_add_u32 s28, s28, 0x100
	s_addc_u32 s29, s29, 0
	s_cmp_ge_i32 s58, s44
	s_mov_b32 s30, s58
	s_cbranch_scc0 .LBB0_834

; #define PG8_STAGE(bufoff, gbase, voff) do { _Pragma("unroll") for (int _i = 0; _i < 2; ++_i) \
;         __builtin_amdgcn_global_load_lds((const unsigned*)((const char*)(gbase) + (voff)[_i]), (PG8_LAS unsigned*)(lds + (bufoff) + ldsw + _i * 8192), 16, 0, 0); } while (0)
; #define PG8_LDA(dst, b, h) do { _Pragma("unroll") for (int m = 0; m < 4; ++m) _Pragma("unroll") for (int k = 0; k < 2; ++k) dst[m][k] = *(const PG8_LAS bf16x8*)(lds + PG8_SA(b, h) + aoff + m * 2048 + k * 1024); } while (0)
; #define PG8_LDB(dst, b, h) do { _Pragma("unroll") for (int n = 0; n < 2; ++n) _Pragma("unroll") for (int k = 0; k < 2; ++k) dst[n][k] = *(const PG8_LAS bf16x8*)(lds + PG8_SB(b, h) + boff + n * 2048 + k * 1024); } while (0)
; #define PG8_MMA(ai, bj, At, Bt) do { __builtin_amdgcn_s_setprio(1); _Pragma("unroll") for (int m = 0; m < 4; ++m) _Pragma("unroll") for (int n = 0; n < 2; ++n) _Pragma("unroll") for (int k = 0; k < 2; ++k) \
;         acc[ai][bj][m][n] = __builtin_amdgcn_mfma_f32_16x16x32_bf16(Bt[n][k], At[m][k], acc[ai][bj][m][n], 0, 0, 0); __builtin_amdgcn_s_setprio(0); } while (0)
; #define PG8_WAIT_V(n) asm volatile("s_waitcnt vmcnt(" #n ")" ::: "memory")
; #define PG8_WAIT_L(n) asm volatile("s_waitcnt lgkmcnt(" #n ")" ::: "memory")
; #define PG8_BAR __builtin_amdgcn_s_barrier()
; #define PG8_SCHED __builtin_amdgcn_sched_barrier(0)
; template <class Epi, class Sched, bool ALIGN_EPI = false, bool SP2 = false>
; __device__ __forceinline__ void gemm_phase(PG8_LAS unsigned char* lds, const Gemm g, const Sched& S, const Epi& E) {
;     ...
;             PG8_LDB(B0, 0, 0); PG8_LDB(B1, 0, 1); PG8_SCHED; PG8_LDA(At, 0, 0); PG8_STAGE(PG8_SA(1, 1), a1 + hstep, voffA);
;             PG8_WAIT_V(8); PG8_WAIT_L(0); PG8_BAR; PG8_MMA(0, 0, At, B0); PG8_MMA(0, 1, At, B1); PG8_BAR; PG8_SCHED;
;             PG8_LDA(At, 0, 1); PG8_STAGE(PG8_SB(0, 0), b2, voffB); PG8_STAGE(PG8_SB(0, 1), b2 + hstep, voffB); PG8_STAGE(PG8_SA(0, 0), a2, voffA);
;             PG8_WAIT_V(8); PG8_WAIT_L(0); PG8_BAR; PG8_MMA(1, 0, At, B0); PG8_MMA(1, 1, At, B1); PG8_BAR; PG8_SCHED;
.LBB0_1154:
	ds_read_b128 v[130:133], v160
	ds_read_b128 v[134:137], v160 offset:1024
	ds_read_b128 v[164:167], v160 offset:2048
	ds_read_b128 v[168:171], v160 offset:3072
	ds_read_b128 v[172:175], v161
	ds_read_b128 v[176:179], v161 offset:1024
	ds_read_b128 v[180:183], v161 offset:2048
	ds_read_b128 v[184:187], v161 offset:3072
	s_add_i32 s81, s36, 2
	s_add_u32 s70, s34, 0x80
	s_addc_u32 s37, s35, 0
	s_cmp_eq_u32 s55, s36
	s_cselect_b32 s36, s4, s70
	s_cselect_b32 s37, s5, s37
	s_cselect_b32 s71, s31, s80
	s_cselect_b32 s70, s30, s45
	v_lshl_add_u64 v[158:159], s[34:35], 0, v[152:153]
	s_add_i32 m0, s42, 0xc000
	ds_read_b128 v[188:191], v162
	ds_read_b128 v[192:195], v162 offset:1024
	ds_read_b128 v[196:199], v162 offset:2048
	ds_read_b128 v[200:203], v162 offset:3072
	ds_read_b128 v[204:207], v162 offset:4096
	ds_read_b128 v[208:211], v162 offset:5120
	ds_read_b128 v[212:215], v162 offset:6144
	ds_read_b128 v[216:219], v162 offset:7168
	global_load_lds_dwordx4 v[158:159], off
	v_lshl_add_u64 v[158:159], s[34:35], 0, v[150:151]
	s_add_i32 m0, s42, 0xe000
	s_nop 0
	global_load_lds_dwordx4 v[158:159], off
	s_waitcnt vmcnt(8)
	s_waitcnt lgkmcnt(0)
	s_barrier
	s_setprio 1
	v_mfma_f32_16x16x32_bf16 v[126:129], v[130:133], v[188:191], v[126:129]
	v_mfma_f32_16x16x32_bf16 v[122:125], v[164:167], v[188:191], v[122:125]
	v_mfma_f32_16x16x32_bf16 v[110:113], v[130:133], v[196:199], v[110:113]
	v_mfma_f32_16x16x32_bf16 v[106:109], v[164:167], v[196:199], v[106:109]
	v_mfma_f32_16x16x32_bf16 v[94:97], v[130:133], v[204:207], v[94:97]
	v_mfma_f32_16x16x32_bf16 v[90:93], v[164:167], v[204:207], v[90:93]
	v_mfma_f32_16x16x32_bf16 v[78:81], v[130:133], v[212:215], v[78:81]
	v_mfma_f32_16x16x32_bf16 v[74:77], v[164:167], v[212:215], v[74:77]
	v_mfma_f32_16x16x32_bf16 v[126:129], v[134:137], v[192:195], v[126:129]
	v_mfma_f32_16x16x32_bf16 v[122:125], v[168:171], v[192:195], v[122:125]
	v_mfma_f32_16x16x32_bf16 v[110:113], v[134:137], v[200:203], v[110:113]
	v_mfma_f32_16x16x32_bf16 v[106:109], v[168:171], v[200:203], v[106:109]
	v_mfma_f32_16x16x32_bf16 v[94:97], v[134:137], v[208:211], v[94:97]
	v_mfma_f32_16x16x32_bf16 v[90:93], v[168:171], v[208:211], v[90:93]
	v_mfma_f32_16x16x32_bf16 v[78:81], v[134:137], v[216:219], v[78:81]
	v_mfma_f32_16x16x32_bf16 v[74:77], v[168:171], v[216:219], v[74:77]
	v_mfma_f32_16x16x32_bf16 v[118:121], v[172:175], v[188:191], v[118:121]
	v_mfma_f32_16x16x32_bf16 v[114:117], v[180:183], v[188:191], v[114:117]
	v_mfma_f32_16x16x32_bf16 v[102:105], v[172:175], v[196:199], v[102:105]
	v_mfma_f32_16x16x32_bf16 v[98:101], v[180:183], v[196:199], v[98:101]
	v_mfma_f32_16x16x32_bf16 v[86:89], v[172:175], v[204:207], v[86:89]
	v_mfma_f32_16x16x32_bf16 v[82:85], v[180:183], v[204:207], v[82:85]
	v_mfma_f32_16x16x32_bf16 v[70:73], v[172:175], v[212:215], v[70:73]
	v_mfma_f32_16x16x32_bf16 v[66:69], v[180:183], v[212:215], v[66:69]
	v_mfma_f32_16x16x32_bf16 v[118:121], v[176:179], v[192:195], v[118:121]
	v_mfma_f32_16x16x32_bf16 v[114:117], v[184:187], v[192:195], v[114:117]
	v_mfma_f32_16x16x32_bf16 v[102:105], v[176:179], v[200:203], v[102:105]
	v_mfma_f32_16x16x32_bf16 v[98:101], v[184:187], v[200:203], v[98:101]
	v_mfma_f32_16x16x32_bf16 v[86:89], v[176:179], v[208:211], v[86:89]
	v_mfma_f32_16x16x32_bf16 v[82:85], v[184:187], v[208:211], v[82:85]
	v_mfma_f32_16x16x32_bf16 v[70:73], v[176:179], v[216:219], v[70:73]
	v_mfma_f32_16x16x32_bf16 v[66:69], v[184:187], v[216:219], v[66:69]
	s_setprio 0
	s_barrier
	s_add_i32 s72, s69, s41
	v_lshl_add_u64 v[158:159], s[70:71], 0, v[140:141]
	s_mov_b32 m0, s72
	ds_read_b128 v[188:191], v162 offset:16384
	ds_read_b128 v[192:195], v162 offset:17408
	ds_read_b128 v[196:199], v162 offset:18432
	ds_read_b128 v[200:203], v162 offset:19456
	ds_read_b128 v[204:207], v162 offset:20480
	ds_read_b128 v[208:211], v162 offset:21504
	ds_read_b128 v[212:215], v162 offset:22528
	ds_read_b128 v[216:219], v162 offset:23552
	global_load_lds_dwordx4 v[158:159], off
	s_add_i32 m0, s72, 0x2000
	v_lshl_add_u64 v[220:221], s[70:71], 0, v[144:145]
	s_add_u32 s70, s70, s8
	s_addc_u32 s71, s71, s9
	s_add_i32 s72, s86, s41
	global_load_lds_dwordx4 v[220:221], off
	v_lshl_add_u64 v[222:223], s[70:71], 0, v[140:141]
	s_mov_b32 m0, s72
	v_lshl_add_u64 v[224:225], s[70:71], 0, v[144:145]
	global_load_lds_dwordx4 v[222:223], off
	s_add_i32 m0, s72, 0x2000
	v_lshl_add_u64 v[226:227], s[36:37], 0, v[138:139]
	global_load_lds_dwordx4 v[224:225], off
	s_mov_b32 m0, s42
	v_lshl_add_u64 v[228:229], s[36:37], 0, v[142:143]
	global_load_lds_dwordx4 v[226:227], off
	s_mov_b32 m0, s46
	s_nop 0
	global_load_lds_dwordx4 v[228:229], off
	s_waitcnt vmcnt(8)
	s_waitcnt lgkmcnt(0)
	s_barrier
; #define PG8_STAGE(bufoff, gbase, voff) do { _Pragma("unroll") for (int _i = 0; _i < 2; ++_i) \
;         __builtin_amdgcn_global_load_lds((const unsigned*)((const char*)(gbase) + (voff)[_i]), (PG8_LAS unsigned*)(lds + (bufoff) + ldsw + _i * 8192), 16, 0, 0); } while (0)
; #define PG8_LDA(dst, b, h) do { _Pragma("unroll") for (int m = 0; m < 4; ++m) _Pragma("unroll") for (int k = 0; k < 2; ++k) dst[m][k] = *(const PG8_LAS bf16x8*)(lds + PG8_SA(b, h) + aoff + m * 2048 + k * 1024); } while (0)
; #define PG8_LDB(dst, b, h) do { _Pragma("unroll") for (int n = 0; n < 2; ++n) _Pragma("unroll") for (int k = 0; k < 2; ++k) dst[n][k] = *(const PG8_LAS bf16x8*)(lds + PG8_SB(b, h) + boff + n * 2048 + k * 1024); } while (0)
; #define PG8_MMA(ai, bj, At, Bt) do { __builtin_amdgcn_s_setprio(1); _Pragma("unroll") for (int m = 0; m < 4; ++m) _Pragma("unroll") for (int n = 0; n < 2; ++n) _Pragma("unroll") for (int k = 0; k < 2; ++k) \
;         acc[ai][bj][m][n] = __builtin_amdgcn_mfma_f32_16x16x32_bf16(Bt[n][k], At[m][k], acc[ai][bj][m][n], 0, 0, 0); __builtin_amdgcn_s_setprio(0); } while (0)
; #define PG8_WAIT_V(n) asm volatile("s_waitcnt vmcnt(" #n ")" ::: "memory")
; #define PG8_WAIT_L(n) asm volatile("s_waitcnt lgkmcnt(" #n ")" ::: "memory")
; #define PG8_BAR __builtin_amdgcn_s_barrier()
; #define PG8_SCHED __builtin_amdgcn_sched_barrier(0)
; template <class Epi, class Sched, bool ALIGN_EPI = false, bool SP2 = false>
; __device__ __forceinline__ void gemm_phase(PG8_LAS unsigned char* lds, const Gemm g, const Sched& S, const Epi& E) {
;     ...
;             PG8_WAIT_V(8); PG8_WAIT_L(0); PG8_BAR; PG8_MMA(1, 0, At, B0); PG8_MMA(1, 1, At, B1); PG8_BAR; PG8_SCHED;
;             PG8_LDB(B0, 1, 0); PG8_LDB(B1, 1, 1); PG8_SCHED; PG8_LDA(At, 1, 0); PG8_STAGE(PG8_SA(0, 1), a2 + hstep, voffA);
;             PG8_WAIT_V(8); PG8_WAIT_L(0); PG8_BAR; PG8_MMA(0, 0, At, B0); PG8_MMA(0, 1, At, B1); PG8_BAR; PG8_SCHED;
	s_setprio 1
	v_mfma_f32_16x16x32_bf16 v[62:65], v[130:133], v[188:191], v[62:65]
	v_mfma_f32_16x16x32_bf16 v[58:61], v[164:167], v[188:191], v[58:61]
	v_mfma_f32_16x16x32_bf16 v[46:49], v[130:133], v[196:199], v[46:49]
	v_mfma_f32_16x16x32_bf16 v[42:45], v[164:167], v[196:199], v[42:45]
	v_mfma_f32_16x16x32_bf16 v[30:33], v[130:133], v[204:207], v[30:33]
	v_mfma_f32_16x16x32_bf16 v[26:29], v[164:167], v[204:207], v[26:29]
	v_mfma_f32_16x16x32_bf16 v[14:17], v[130:133], v[212:215], v[14:17]
	v_mfma_f32_16x16x32_bf16 v[10:13], v[164:167], v[212:215], v[10:13]
	v_mfma_f32_16x16x32_bf16 v[62:65], v[134:137], v[192:195], v[62:65]
	v_mfma_f32_16x16x32_bf16 v[58:61], v[168:171], v[192:195], v[58:61]
	v_mfma_f32_16x16x32_bf16 v[46:49], v[134:137], v[200:203], v[46:49]
	v_mfma_f32_16x16x32_bf16 v[42:45], v[168:171], v[200:203], v[42:45]
	v_mfma_f32_16x16x32_bf16 v[30:33], v[134:137], v[208:211], v[30:33]
	v_mfma_f32_16x16x32_bf16 v[26:29], v[168:171], v[208:211], v[26:29]
	v_mfma_f32_16x16x32_bf16 v[14:17], v[134:137], v[216:219], v[14:17]
	v_mfma_f32_16x16x32_bf16 v[10:13], v[168:171], v[216:219], v[10:13]
	v_mfma_f32_16x16x32_bf16 v[54:57], v[172:175], v[188:191], v[54:57]
	v_mfma_f32_16x16x32_bf16 v[50:53], v[180:183], v[188:191], v[50:53]
	v_mfma_f32_16x16x32_bf16 v[38:41], v[172:175], v[196:199], v[38:41]
	v_mfma_f32_16x16x32_bf16 v[34:37], v[180:183], v[196:199], v[34:37]
	v_mfma_f32_16x16x32_bf16 v[22:25], v[172:175], v[204:207], v[22:25]
	v_mfma_f32_16x16x32_bf16 v[18:21], v[180:183], v[204:207], v[18:21]
	v_mfma_f32_16x16x32_bf16 v[6:9], v[172:175], v[212:215], v[6:9]
	v_mfma_f32_16x16x32_bf16 v[2:5], v[180:183], v[212:215], v[2:5]
	v_mfma_f32_16x16x32_bf16 v[54:57], v[176:179], v[192:195], v[54:57]
	v_mfma_f32_16x16x32_bf16 v[50:53], v[184:187], v[192:195], v[50:53]
	v_mfma_f32_16x16x32_bf16 v[38:41], v[176:179], v[200:203], v[38:41]
	v_mfma_f32_16x16x32_bf16 v[34:37], v[184:187], v[200:203], v[34:37]
	v_mfma_f32_16x16x32_bf16 v[22:25], v[176:179], v[208:211], v[22:25]
	v_mfma_f32_16x16x32_bf16 v[18:21], v[184:187], v[208:211], v[18:21]
	v_mfma_f32_16x16x32_bf16 v[6:9], v[176:179], v[216:219], v[6:9]
	v_mfma_f32_16x16x32_bf16 v[2:5], v[184:187], v[216:219], v[2:5]
	s_setprio 0
	s_barrier
	s_add_i32 s70, 0, 0x18000
	v_add_u32_e32 v146, s70, v149
	s_add_i32 s71, 0, 0x1c000
	ds_read_b128 v[130:133], v146
	ds_read_b128 v[134:137], v146 offset:1024
	ds_read_b128 v[164:167], v146 offset:2048
	ds_read_b128 v[168:171], v146 offset:3072
	v_add_u32_e32 v146, s71, v149
	ds_read_b128 v[172:175], v146
	ds_read_b128 v[176:179], v146 offset:1024
	ds_read_b128 v[180:183], v146 offset:2048
	ds_read_b128 v[184:187], v146 offset:3072
	s_add_u32 s36, s36, s8
	s_addc_u32 s37, s37, s9
	s_mov_b32 m0, s47
	v_lshl_add_u64 v[230:231], s[36:37], 0, v[138:139]
	ds_read_b128 v[188:191], v162 offset:32768
	ds_read_b128 v[192:195], v162 offset:33792
	ds_read_b128 v[196:199], v162 offset:34816
	ds_read_b128 v[200:203], v162 offset:35840
	ds_read_b128 v[204:207], v162 offset:36864
	ds_read_b128 v[208:211], v162 offset:37888
	ds_read_b128 v[212:215], v162 offset:38912
	ds_read_b128 v[216:219], v162 offset:39936
	global_load_lds_dwordx4 v[230:231], off
	v_lshl_add_u64 v[230:231], s[36:37], 0, v[142:143]
	s_mov_b32 m0, s48
	s_nop 0
	global_load_lds_dwordx4 v[230:231], off
	s_waitcnt vmcnt(8)
	s_waitcnt lgkmcnt(0)
	s_barrier
	s_setprio 1
	v_mfma_f32_16x16x32_bf16 v[126:129], v[130:133], v[188:191], v[126:129]
	v_mfma_f32_16x16x32_bf16 v[122:125], v[164:167], v[188:191], v[122:125]
	v_mfma_f32_16x16x32_bf16 v[110:113], v[130:133], v[196:199], v[110:113]
	v_mfma_f32_16x16x32_bf16 v[106:109], v[164:167], v[196:199], v[106:109]
	v_mfma_f32_16x16x32_bf16 v[94:97], v[130:133], v[204:207], v[94:97]
	v_mfma_f32_16x16x32_bf16 v[90:93], v[164:167], v[204:207], v[90:93]
	v_mfma_f32_16x16x32_bf16 v[78:81], v[130:133], v[212:215], v[78:81]
	v_mfma_f32_16x16x32_bf16 v[74:77], v[164:167], v[212:215], v[74:77]
	v_mfma_f32_16x16x32_bf16 v[126:129], v[134:137], v[192:195], v[126:129]
	v_mfma_f32_16x16x32_bf16 v[122:125], v[168:171], v[192:195], v[122:125]
	v_mfma_f32_16x16x32_bf16 v[110:113], v[134:137], v[200:203], v[110:113]
	v_mfma_f32_16x16x32_bf16 v[106:109], v[168:171], v[200:203], v[106:109]
	v_mfma_f32_16x16x32_bf16 v[94:97], v[134:137], v[208:211], v[94:97]
	v_mfma_f32_16x16x32_bf16 v[90:93], v[168:171], v[208:211], v[90:93]
	v_mfma_f32_16x16x32_bf16 v[78:81], v[134:137], v[216:219], v[78:81]
	v_mfma_f32_16x16x32_bf16 v[74:77], v[168:171], v[216:219], v[74:77]
	v_mfma_f32_16x16x32_bf16 v[118:121], v[172:175], v[188:191], v[118:121]
	v_mfma_f32_16x16x32_bf16 v[114:117], v[180:183], v[188:191], v[114:117]
	v_mfma_f32_16x16x32_bf16 v[102:105], v[172:175], v[196:199], v[102:105]
	v_mfma_f32_16x16x32_bf16 v[98:101], v[180:183], v[196:199], v[98:101]
	v_mfma_f32_16x16x32_bf16 v[86:89], v[172:175], v[204:207], v[86:89]
	v_mfma_f32_16x16x32_bf16 v[82:85], v[180:183], v[204:207], v[82:85]
	v_mfma_f32_16x16x32_bf16 v[70:73], v[172:175], v[212:215], v[70:73]
	v_mfma_f32_16x16x32_bf16 v[66:69], v[180:183], v[212:215], v[66:69]
	v_mfma_f32_16x16x32_bf16 v[118:121], v[176:179], v[192:195], v[118:121]
	v_mfma_f32_16x16x32_bf16 v[114:117], v[184:187], v[192:195], v[114:117]
	v_mfma_f32_16x16x32_bf16 v[102:105], v[176:179], v[200:203], v[102:105]
	v_mfma_f32_16x16x32_bf16 v[98:101], v[184:187], v[200:203], v[98:101]
	v_mfma_f32_16x16x32_bf16 v[86:89], v[176:179], v[208:211], v[86:89]
	v_mfma_f32_16x16x32_bf16 v[82:85], v[184:187], v[208:211], v[82:85]
	v_mfma_f32_16x16x32_bf16 v[70:73], v[176:179], v[216:219], v[70:73]
	v_mfma_f32_16x16x32_bf16 v[66:69], v[184:187], v[216:219], v[66:69]
	s_setprio 0
	s_barrier
; #define PG8_STAGE(bufoff, gbase, voff) do { _Pragma("unroll") for (int _i = 0; _i < 2; ++_i) \
;         __builtin_amdgcn_global_load_lds((const unsigned*)((const char*)(gbase) + (voff)[_i]), (PG8_LAS unsigned*)(lds + (bufoff) + ldsw + _i * 8192), 16, 0, 0); } while (0)
; #define PG8_LDA(dst, b, h) do { _Pragma("unroll") for (int m = 0; m < 4; ++m) _Pragma("unroll") for (int k = 0; k < 2; ++k) dst[m][k] = *(const PG8_LAS bf16x8*)(lds + PG8_SA(b, h) + aoff + m * 2048 + k * 1024); } while (0)
; #define PG8_MMA(ai, bj, At, Bt) do { __builtin_amdgcn_s_setprio(1); _Pragma("unroll") for (int m = 0; m < 4; ++m) _Pragma("unroll") for (int n = 0; n < 2; ++n) _Pragma("unroll") for (int k = 0; k < 2; ++k) \
;         acc[ai][bj][m][n] = __builtin_amdgcn_mfma_f32_16x16x32_bf16(Bt[n][k], At[m][k], acc[ai][bj][m][n], 0, 0, 0); __builtin_amdgcn_s_setprio(0); } while (0)
; #define PG8_WAIT_V(n) asm volatile("s_waitcnt vmcnt(" #n ")" ::: "memory")
; #define PG8_WAIT_L(n) asm volatile("s_waitcnt lgkmcnt(" #n ")" ::: "memory")
; #define PG8_BAR __builtin_amdgcn_s_barrier()
; #define PG8_SCHED __builtin_amdgcn_sched_barrier(0)
; template <class Epi, class Sched, bool ALIGN_EPI = false, bool SP2 = false>
; __device__ __forceinline__ void gemm_phase(PG8_LAS unsigned char* lds, const Gemm g, const Sched& S, const Epi& E) {
;     ...
;             PG8_LDA(At, 1, 1); PG8_STAGE(PG8_SB(1, 0), b3, voffB); PG8_STAGE(PG8_SB(1, 1), b3 + hstep, voffB); PG8_STAGE(PG8_SA(1, 0), a3, voffA);
;             PG8_WAIT_V(8); PG8_WAIT_L(0); PG8_BAR; PG8_MMA(1, 0, At, B0); PG8_MMA(1, 1, At, B1); PG8_BAR; PG8_SCHED;
	s_add_i32 s36, s70, s41
	v_lshl_add_u64 v[158:159], v[158:159], 0, s[24:25]
	s_mov_b32 m0, s36
	ds_read_b128 v[188:191], v162 offset:49152
	ds_read_b128 v[192:195], v162 offset:50176
	ds_read_b128 v[196:199], v162 offset:51200
	ds_read_b128 v[200:203], v162 offset:52224
	ds_read_b128 v[204:207], v162 offset:53248
	ds_read_b128 v[208:211], v162 offset:54272
	ds_read_b128 v[212:215], v162 offset:55296
	ds_read_b128 v[216:219], v162 offset:56320
	global_load_lds_dwordx4 v[158:159], off
	v_lshl_add_u64 v[158:159], v[220:221], 0, s[24:25]
	s_add_i32 m0, s36, 0x2000
	s_add_i32 s36, s71, s41
	global_load_lds_dwordx4 v[158:159], off
	v_lshl_add_u64 v[158:159], v[222:223], 0, s[24:25]
	s_mov_b32 m0, s36
	s_nop 0
	global_load_lds_dwordx4 v[158:159], off
	v_lshl_add_u64 v[158:159], v[224:225], 0, s[24:25]
	s_add_i32 m0, s36, 0x2000
	s_nop 0
	global_load_lds_dwordx4 v[158:159], off
	v_lshl_add_u64 v[158:159], v[226:227], 0, s[24:25]
	s_mov_b32 m0, s52
	s_nop 0
	global_load_lds_dwordx4 v[158:159], off
	v_lshl_add_u64 v[158:159], v[228:229], 0, s[24:25]
	s_mov_b32 m0, s53
	s_nop 0
	global_load_lds_dwordx4 v[158:159], off
	s_waitcnt vmcnt(8)
	s_waitcnt lgkmcnt(0)
	s_barrier
	s_setprio 1
	v_mfma_f32_16x16x32_bf16 v[62:65], v[130:133], v[188:191], v[62:65]
	v_mfma_f32_16x16x32_bf16 v[58:61], v[164:167], v[188:191], v[58:61]
	v_mfma_f32_16x16x32_bf16 v[46:49], v[130:133], v[196:199], v[46:49]
	v_mfma_f32_16x16x32_bf16 v[42:45], v[164:167], v[196:199], v[42:45]
	v_mfma_f32_16x16x32_bf16 v[30:33], v[130:133], v[204:207], v[30:33]
	v_mfma_f32_16x16x32_bf16 v[26:29], v[164:167], v[204:207], v[26:29]
	v_mfma_f32_16x16x32_bf16 v[14:17], v[130:133], v[212:215], v[14:17]
	v_mfma_f32_16x16x32_bf16 v[10:13], v[164:167], v[212:215], v[10:13]
	v_mfma_f32_16x16x32_bf16 v[62:65], v[134:137], v[192:195], v[62:65]
	v_mfma_f32_16x16x32_bf16 v[58:61], v[168:171], v[192:195], v[58:61]
	v_mfma_f32_16x16x32_bf16 v[46:49], v[134:137], v[200:203], v[46:49]
	v_mfma_f32_16x16x32_bf16 v[42:45], v[168:171], v[200:203], v[42:45]
	v_mfma_f32_16x16x32_bf16 v[30:33], v[134:137], v[208:211], v[30:33]
	v_mfma_f32_16x16x32_bf16 v[26:29], v[168:171], v[208:211], v[26:29]
	v_mfma_f32_16x16x32_bf16 v[14:17], v[134:137], v[216:219], v[14:17]
	v_mfma_f32_16x16x32_bf16 v[10:13], v[168:171], v[216:219], v[10:13]
	v_mfma_f32_16x16x32_bf16 v[54:57], v[172:175], v[188:191], v[54:57]
	v_mfma_f32_16x16x32_bf16 v[50:53], v[180:183], v[188:191], v[50:53]
	v_mfma_f32_16x16x32_bf16 v[38:41], v[172:175], v[196:199], v[38:41]
	v_mfma_f32_16x16x32_bf16 v[34:37], v[180:183], v[196:199], v[34:37]
	v_mfma_f32_16x16x32_bf16 v[22:25], v[172:175], v[204:207], v[22:25]
	v_mfma_f32_16x16x32_bf16 v[18:21], v[180:183], v[204:207], v[18:21]
	v_mfma_f32_16x16x32_bf16 v[6:9], v[172:175], v[212:215], v[6:9]
	v_mfma_f32_16x16x32_bf16 v[2:5], v[180:183], v[212:215], v[2:5]
	v_mfma_f32_16x16x32_bf16 v[54:57], v[176:179], v[192:195], v[54:57]
	v_mfma_f32_16x16x32_bf16 v[50:53], v[184:187], v[192:195], v[50:53]
	v_mfma_f32_16x16x32_bf16 v[38:41], v[176:179], v[200:203], v[38:41]
	v_mfma_f32_16x16x32_bf16 v[34:37], v[184:187], v[200:203], v[34:37]
	v_mfma_f32_16x16x32_bf16 v[22:25], v[176:179], v[208:211], v[22:25]
	v_mfma_f32_16x16x32_bf16 v[18:21], v[184:187], v[208:211], v[18:21]
	v_mfma_f32_16x16x32_bf16 v[6:9], v[176:179], v[216:219], v[6:9]
	v_mfma_f32_16x16x32_bf16 v[2:5], v[184:187], v[216:219], v[2:5]
	s_setprio 0
	s_barrier
	s_add_u32 s45, s45, 0x100
	s_addc_u32 s80, s80, 0
	s_add_u32 s34, s34, 0x100
	s_addc_u32 s35, s35, 0
	s_cmp_ge_i32 s81, s54
	s_mov_b32 s36, s81
	s_cbranch_scc0 .LBB0_1154

; #define PG8_STAGE(bufoff, gbase, voff) do { _Pragma("unroll") for (int _i = 0; _i < 2; ++_i) \
;         __builtin_amdgcn_global_load_lds((const unsigned*)((const char*)(gbase) + (voff)[_i]), (PG8_LAS unsigned*)(lds + (bufoff) + ldsw + _i * 8192), 16, 0, 0); } while (0)
; #define PG8_LDA(dst, b, h) do { _Pragma("unroll") for (int m = 0; m < 4; ++m) _Pragma("unroll") for (int k = 0; k < 2; ++k) dst[m][k] = *(const PG8_LAS bf16x8*)(lds + PG8_SA(b, h) + aoff + m * 2048 + k * 1024); } while (0)
; #define PG8_LDB(dst, b, h) do { _Pragma("unroll") for (int n = 0; n < 2; ++n) _Pragma("unroll") for (int k = 0; k < 2; ++k) dst[n][k] = *(const PG8_LAS bf16x8*)(lds + PG8_SB(b, h) + boff + n * 2048 + k * 1024); } while (0)
; #define PG8_MMA(ai, bj, At, Bt) do { __builtin_amdgcn_s_setprio(1); _Pragma("unroll") for (int m = 0; m < 4; ++m) _Pragma("unroll") for (int n = 0; n < 2; ++n) _Pragma("unroll") for (int k = 0; k < 2; ++k) \
;         acc[ai][bj][m][n] = __builtin_amdgcn_mfma_f32_16x16x32_bf16(Bt[n][k], At[m][k], acc[ai][bj][m][n], 0, 0, 0); __builtin_amdgcn_s_setprio(0); } while (0)
; #define PG8_WAIT_V(n) asm volatile("s_waitcnt vmcnt(" #n ")" ::: "memory")
; #define PG8_WAIT_L(n) asm volatile("s_waitcnt lgkmcnt(" #n ")" ::: "memory")
; #define PG8_BAR __builtin_amdgcn_s_barrier()
; #define PG8_SCHED __builtin_amdgcn_sched_barrier(0)
; template <class Epi, class Sched, bool ALIGN_EPI = false, bool SP2 = false>
; __device__ __forceinline__ void gemm_phase(PG8_LAS unsigned char* lds, const Gemm g, const Sched& S, const Epi& E) {
;     ...
;             PG8_LDB(B0, 0, 0); PG8_LDB(B1, 0, 1); PG8_SCHED; PG8_LDA(At, 0, 0); PG8_STAGE(PG8_SA(1, 1), a1 + hstep, voffA);
;             PG8_WAIT_V(8); PG8_WAIT_L(0); PG8_BAR; PG8_MMA(0, 0, At, B0); PG8_MMA(0, 1, At, B1); PG8_BAR; PG8_SCHED;
;             PG8_LDA(At, 0, 1); PG8_STAGE(PG8_SB(0, 0), b2, voffB); PG8_STAGE(PG8_SB(0, 1), b2 + hstep, voffB); PG8_STAGE(PG8_SA(0, 0), a2, voffA);
;             PG8_WAIT_V(8); PG8_WAIT_L(0); PG8_BAR; PG8_MMA(1, 0, At, B0); PG8_MMA(1, 1, At, B1); PG8_BAR; PG8_SCHED;
.LBB0_1375:
	ds_read_b128 v[166:169], v162
	ds_read_b128 v[170:173], v162 offset:1024
	ds_read_b128 v[174:177], v162 offset:2048
	ds_read_b128 v[178:181], v162 offset:3072
	ds_read_b128 v[182:185], v163
	ds_read_b128 v[186:189], v163 offset:1024
	ds_read_b128 v[190:193], v163 offset:2048
	ds_read_b128 v[194:197], v163 offset:3072
	s_add_i32 s87, s36, 2
	s_add_u32 s70, s34, 0x80
	s_addc_u32 s37, s35, 0
	s_cmp_eq_u32 s52, s36
	s_cselect_b32 s36, s4, s70
	s_cselect_b32 s37, s5, s37
	s_cselect_b32 s71, s31, s86
	s_cselect_b32 s70, s30, s81
	v_lshl_add_u64 v[230:231], s[34:35], 0, v[140:141]
	s_add_i32 m0, s42, 0xc000
	ds_read_b128 v[198:201], v164
	ds_read_b128 v[202:205], v164 offset:1024
	ds_read_b128 v[206:209], v164 offset:2048
	ds_read_b128 v[210:213], v164 offset:3072
	ds_read_b128 v[214:217], v164 offset:4096
	ds_read_b128 v[218:221], v164 offset:5120
	ds_read_b128 v[222:225], v164 offset:6144
	ds_read_b128 v[226:229], v164 offset:7168
	global_load_lds_dwordx4 v[230:231], off
	v_lshl_add_u64 v[230:231], s[34:35], 0, v[138:139]
	s_add_i32 m0, s42, 0xe000
	s_nop 0
	global_load_lds_dwordx4 v[230:231], off
	s_waitcnt vmcnt(8)
	s_waitcnt lgkmcnt(0)
	s_barrier
	s_setprio 1
	v_mfma_f32_16x16x32_bf16 v[122:125], v[166:169], v[198:201], v[122:125]
	v_mfma_f32_16x16x32_bf16 v[126:129], v[174:177], v[198:201], v[126:129]
	v_mfma_f32_16x16x32_bf16 v[110:113], v[166:169], v[206:209], v[110:113]
	v_mfma_f32_16x16x32_bf16 v[106:109], v[174:177], v[206:209], v[106:109]
	v_mfma_f32_16x16x32_bf16 v[94:97], v[166:169], v[214:217], v[94:97]
	v_mfma_f32_16x16x32_bf16 v[90:93], v[174:177], v[214:217], v[90:93]
	v_mfma_f32_16x16x32_bf16 v[78:81], v[166:169], v[222:225], v[78:81]
	v_mfma_f32_16x16x32_bf16 v[74:77], v[174:177], v[222:225], v[74:77]
	v_mfma_f32_16x16x32_bf16 v[122:125], v[170:173], v[202:205], v[122:125]
	v_mfma_f32_16x16x32_bf16 v[126:129], v[178:181], v[202:205], v[126:129]
	v_mfma_f32_16x16x32_bf16 v[110:113], v[170:173], v[210:213], v[110:113]
	v_mfma_f32_16x16x32_bf16 v[106:109], v[178:181], v[210:213], v[106:109]
	v_mfma_f32_16x16x32_bf16 v[94:97], v[170:173], v[218:221], v[94:97]
	v_mfma_f32_16x16x32_bf16 v[90:93], v[178:181], v[218:221], v[90:93]
	v_mfma_f32_16x16x32_bf16 v[78:81], v[170:173], v[226:229], v[78:81]
	v_mfma_f32_16x16x32_bf16 v[74:77], v[178:181], v[226:229], v[74:77]
	v_mfma_f32_16x16x32_bf16 v[118:121], v[182:185], v[198:201], v[118:121]
	v_mfma_f32_16x16x32_bf16 v[114:117], v[190:193], v[198:201], v[114:117]
	v_mfma_f32_16x16x32_bf16 v[102:105], v[182:185], v[206:209], v[102:105]
	v_mfma_f32_16x16x32_bf16 v[98:101], v[190:193], v[206:209], v[98:101]
	v_mfma_f32_16x16x32_bf16 v[86:89], v[182:185], v[214:217], v[86:89]
	v_mfma_f32_16x16x32_bf16 v[82:85], v[190:193], v[214:217], v[82:85]
	v_mfma_f32_16x16x32_bf16 v[70:73], v[182:185], v[222:225], v[70:73]
	v_mfma_f32_16x16x32_bf16 v[66:69], v[190:193], v[222:225], v[66:69]
	v_mfma_f32_16x16x32_bf16 v[118:121], v[186:189], v[202:205], v[118:121]
	v_mfma_f32_16x16x32_bf16 v[114:117], v[194:197], v[202:205], v[114:117]
	v_mfma_f32_16x16x32_bf16 v[102:105], v[186:189], v[210:213], v[102:105]
	v_mfma_f32_16x16x32_bf16 v[98:101], v[194:197], v[210:213], v[98:101]
	v_mfma_f32_16x16x32_bf16 v[86:89], v[186:189], v[218:221], v[86:89]
	v_mfma_f32_16x16x32_bf16 v[82:85], v[194:197], v[218:221], v[82:85]
	v_mfma_f32_16x16x32_bf16 v[70:73], v[186:189], v[226:229], v[70:73]
	v_mfma_f32_16x16x32_bf16 v[66:69], v[194:197], v[226:229], v[66:69]
	s_setprio 0
	s_barrier
	s_add_i32 s72, s55, s41
	v_lshl_add_u64 v[230:231], s[70:71], 0, v[132:133]
	s_mov_b32 m0, s72
	ds_read_b128 v[198:201], v164 offset:16384
	ds_read_b128 v[202:205], v164 offset:17408
	ds_read_b128 v[206:209], v164 offset:18432
	ds_read_b128 v[210:213], v164 offset:19456
	ds_read_b128 v[214:217], v164 offset:20480
	ds_read_b128 v[218:221], v164 offset:21504
	ds_read_b128 v[222:225], v164 offset:22528
	ds_read_b128 v[226:229], v164 offset:23552
	global_load_lds_dwordx4 v[230:231], off
	s_add_i32 m0, s72, 0x2000
	v_lshl_add_u64 v[232:233], s[70:71], 0, v[136:137]
	s_add_u32 s70, s70, s14
	s_addc_u32 s71, s71, s15
	s_add_i32 s72, s56, s41
	global_load_lds_dwordx4 v[232:233], off
	v_lshl_add_u64 v[234:235], s[70:71], 0, v[132:133]
	s_mov_b32 m0, s72
	v_lshl_add_u64 v[236:237], s[70:71], 0, v[136:137]
	global_load_lds_dwordx4 v[234:235], off
	s_add_i32 m0, s72, 0x2000
	v_lshl_add_u64 v[238:239], s[36:37], 0, v[130:131]
	global_load_lds_dwordx4 v[236:237], off
	s_mov_b32 m0, s42
	v_lshl_add_u64 v[240:241], s[36:37], 0, v[134:135]
	global_load_lds_dwordx4 v[238:239], off
	s_mov_b32 m0, s43
	s_nop 0
	global_load_lds_dwordx4 v[240:241], off
	s_waitcnt vmcnt(8)
	s_waitcnt lgkmcnt(0)
	s_barrier
; #define PG8_STAGE(bufoff, gbase, voff) do { _Pragma("unroll") for (int _i = 0; _i < 2; ++_i) \
;         __builtin_amdgcn_global_load_lds((const unsigned*)((const char*)(gbase) + (voff)[_i]), (PG8_LAS unsigned*)(lds + (bufoff) + ldsw + _i * 8192), 16, 0, 0); } while (0)
; #define PG8_LDA(dst, b, h) do { _Pragma("unroll") for (int m = 0; m < 4; ++m) _Pragma("unroll") for (int k = 0; k < 2; ++k) dst[m][k] = *(const PG8_LAS bf16x8*)(lds + PG8_SA(b, h) + aoff + m * 2048 + k * 1024); } while (0)
; #define PG8_LDB(dst, b, h) do { _Pragma("unroll") for (int n = 0; n < 2; ++n) _Pragma("unroll") for (int k = 0; k < 2; ++k) dst[n][k] = *(const PG8_LAS bf16x8*)(lds + PG8_SB(b, h) + boff + n * 2048 + k * 1024); } while (0)
; #define PG8_MMA(ai, bj, At, Bt) do { __builtin_amdgcn_s_setprio(1); _Pragma("unroll") for (int m = 0; m < 4; ++m) _Pragma("unroll") for (int n = 0; n < 2; ++n) _Pragma("unroll") for (int k = 0; k < 2; ++k) \
;         acc[ai][bj][m][n] = __builtin_amdgcn_mfma_f32_16x16x32_bf16(Bt[n][k], At[m][k], acc[ai][bj][m][n], 0, 0, 0); __builtin_amdgcn_s_setprio(0); } while (0)
; #define PG8_WAIT_V(n) asm volatile("s_waitcnt vmcnt(" #n ")" ::: "memory")
; #define PG8_WAIT_L(n) asm volatile("s_waitcnt lgkmcnt(" #n ")" ::: "memory")
; #define PG8_BAR __builtin_amdgcn_s_barrier()
; #define PG8_SCHED __builtin_amdgcn_sched_barrier(0)
; template <class Epi, class Sched, bool ALIGN_EPI = false, bool SP2 = false>
; __device__ __forceinline__ void gemm_phase(PG8_LAS unsigned char* lds, const Gemm g, const Sched& S, const Epi& E) {
;     ...
;             PG8_WAIT_V(8); PG8_WAIT_L(0); PG8_BAR; PG8_MMA(1, 0, At, B0); PG8_MMA(1, 1, At, B1); PG8_BAR; PG8_SCHED;
;             PG8_LDB(B0, 1, 0); PG8_LDB(B1, 1, 1); PG8_SCHED; PG8_LDA(At, 1, 0); PG8_STAGE(PG8_SA(0, 1), a2 + hstep, voffA);
;             PG8_WAIT_V(8); PG8_WAIT_L(0); PG8_BAR; PG8_MMA(0, 0, At, B0); PG8_MMA(0, 1, At, B1); PG8_BAR; PG8_SCHED;
	s_setprio 1
	v_mfma_f32_16x16x32_bf16 v[62:65], v[166:169], v[198:201], v[62:65]
	v_mfma_f32_16x16x32_bf16 v[58:61], v[174:177], v[198:201], v[58:61]
	v_mfma_f32_16x16x32_bf16 v[46:49], v[166:169], v[206:209], v[46:49]
	v_mfma_f32_16x16x32_bf16 v[42:45], v[174:177], v[206:209], v[42:45]
	v_mfma_f32_16x16x32_bf16 v[30:33], v[166:169], v[214:217], v[30:33]
	v_mfma_f32_16x16x32_bf16 v[26:29], v[174:177], v[214:217], v[26:29]
	v_mfma_f32_16x16x32_bf16 v[14:17], v[166:169], v[222:225], v[14:17]
	v_mfma_f32_16x16x32_bf16 v[10:13], v[174:177], v[222:225], v[10:13]
	v_mfma_f32_16x16x32_bf16 v[62:65], v[170:173], v[202:205], v[62:65]
	v_mfma_f32_16x16x32_bf16 v[58:61], v[178:181], v[202:205], v[58:61]
	v_mfma_f32_16x16x32_bf16 v[46:49], v[170:173], v[210:213], v[46:49]
	v_mfma_f32_16x16x32_bf16 v[42:45], v[178:181], v[210:213], v[42:45]
	v_mfma_f32_16x16x32_bf16 v[30:33], v[170:173], v[218:221], v[30:33]
	v_mfma_f32_16x16x32_bf16 v[26:29], v[178:181], v[218:221], v[26:29]
	v_mfma_f32_16x16x32_bf16 v[14:17], v[170:173], v[226:229], v[14:17]
	v_mfma_f32_16x16x32_bf16 v[10:13], v[178:181], v[226:229], v[10:13]
	v_mfma_f32_16x16x32_bf16 v[54:57], v[182:185], v[198:201], v[54:57]
	v_mfma_f32_16x16x32_bf16 v[50:53], v[190:193], v[198:201], v[50:53]
	v_mfma_f32_16x16x32_bf16 v[38:41], v[182:185], v[206:209], v[38:41]
	v_mfma_f32_16x16x32_bf16 v[34:37], v[190:193], v[206:209], v[34:37]
	v_mfma_f32_16x16x32_bf16 v[22:25], v[182:185], v[214:217], v[22:25]
	v_mfma_f32_16x16x32_bf16 v[18:21], v[190:193], v[214:217], v[18:21]
	v_mfma_f32_16x16x32_bf16 v[6:9], v[182:185], v[222:225], v[6:9]
	v_mfma_f32_16x16x32_bf16 v[2:5], v[190:193], v[222:225], v[2:5]
	v_mfma_f32_16x16x32_bf16 v[54:57], v[186:189], v[202:205], v[54:57]
	v_mfma_f32_16x16x32_bf16 v[50:53], v[194:197], v[202:205], v[50:53]
	v_mfma_f32_16x16x32_bf16 v[38:41], v[186:189], v[210:213], v[38:41]
	v_mfma_f32_16x16x32_bf16 v[34:37], v[194:197], v[210:213], v[34:37]
	v_mfma_f32_16x16x32_bf16 v[22:25], v[186:189], v[218:221], v[22:25]
	v_mfma_f32_16x16x32_bf16 v[18:21], v[194:197], v[218:221], v[18:21]
	v_mfma_f32_16x16x32_bf16 v[6:9], v[186:189], v[226:229], v[6:9]
	v_mfma_f32_16x16x32_bf16 v[2:5], v[194:197], v[226:229], v[2:5]
	s_setprio 0
	s_barrier
	s_add_i32 s70, 0, 0x18000
	v_add_u32_e32 v165, s70, v160
	s_add_i32 s71, 0, 0x1c000
	ds_read_b128 v[166:169], v165
	ds_read_b128 v[170:173], v165 offset:1024
	ds_read_b128 v[174:177], v165 offset:2048
	ds_read_b128 v[178:181], v165 offset:3072
	v_add_u32_e32 v165, s71, v160
	ds_read_b128 v[182:185], v165
	ds_read_b128 v[186:189], v165 offset:1024
	ds_read_b128 v[190:193], v165 offset:2048
	ds_read_b128 v[194:197], v165 offset:3072
	s_add_u32 s36, s36, s14
	s_addc_u32 s37, s37, s15
	s_mov_b32 m0, s44
	v_lshl_add_u64 v[242:243], s[36:37], 0, v[130:131]
	ds_read_b128 v[198:201], v164 offset:32768
	ds_read_b128 v[202:205], v164 offset:33792
	ds_read_b128 v[206:209], v164 offset:34816
	ds_read_b128 v[210:213], v164 offset:35840
	ds_read_b128 v[214:217], v164 offset:36864
	ds_read_b128 v[218:221], v164 offset:37888
	ds_read_b128 v[222:225], v164 offset:38912
	ds_read_b128 v[226:229], v164 offset:39936
	global_load_lds_dwordx4 v[242:243], off
	v_lshl_add_u64 v[242:243], s[36:37], 0, v[134:135]
	s_mov_b32 m0, s45
	s_nop 0
	global_load_lds_dwordx4 v[242:243], off
	s_waitcnt vmcnt(8)
	s_waitcnt lgkmcnt(0)
	s_barrier
	s_setprio 1
	v_mfma_f32_16x16x32_bf16 v[122:125], v[166:169], v[198:201], v[122:125]
	v_mfma_f32_16x16x32_bf16 v[126:129], v[174:177], v[198:201], v[126:129]
	v_mfma_f32_16x16x32_bf16 v[110:113], v[166:169], v[206:209], v[110:113]
	v_mfma_f32_16x16x32_bf16 v[106:109], v[174:177], v[206:209], v[106:109]
	v_mfma_f32_16x16x32_bf16 v[94:97], v[166:169], v[214:217], v[94:97]
	v_mfma_f32_16x16x32_bf16 v[90:93], v[174:177], v[214:217], v[90:93]
	v_mfma_f32_16x16x32_bf16 v[78:81], v[166:169], v[222:225], v[78:81]
	v_mfma_f32_16x16x32_bf16 v[74:77], v[174:177], v[222:225], v[74:77]
	v_mfma_f32_16x16x32_bf16 v[122:125], v[170:173], v[202:205], v[122:125]
	v_mfma_f32_16x16x32_bf16 v[126:129], v[178:181], v[202:205], v[126:129]
	v_mfma_f32_16x16x32_bf16 v[110:113], v[170:173], v[210:213], v[110:113]
	v_mfma_f32_16x16x32_bf16 v[106:109], v[178:181], v[210:213], v[106:109]
	v_mfma_f32_16x16x32_bf16 v[94:97], v[170:173], v[218:221], v[94:97]
	v_mfma_f32_16x16x32_bf16 v[90:93], v[178:181], v[218:221], v[90:93]
	v_mfma_f32_16x16x32_bf16 v[78:81], v[170:173], v[226:229], v[78:81]
	v_mfma_f32_16x16x32_bf16 v[74:77], v[178:181], v[226:229], v[74:77]
	v_mfma_f32_16x16x32_bf16 v[118:121], v[182:185], v[198:201], v[118:121]
	v_mfma_f32_16x16x32_bf16 v[114:117], v[190:193], v[198:201], v[114:117]
	v_mfma_f32_16x16x32_bf16 v[102:105], v[182:185], v[206:209], v[102:105]
	v_mfma_f32_16x16x32_bf16 v[98:101], v[190:193], v[206:209], v[98:101]
	v_mfma_f32_16x16x32_bf16 v[86:89], v[182:185], v[214:217], v[86:89]
	v_mfma_f32_16x16x32_bf16 v[82:85], v[190:193], v[214:217], v[82:85]
	v_mfma_f32_16x16x32_bf16 v[70:73], v[182:185], v[222:225], v[70:73]
	v_mfma_f32_16x16x32_bf16 v[66:69], v[190:193], v[222:225], v[66:69]
	v_mfma_f32_16x16x32_bf16 v[118:121], v[186:189], v[202:205], v[118:121]
	v_mfma_f32_16x16x32_bf16 v[114:117], v[194:197], v[202:205], v[114:117]
	v_mfma_f32_16x16x32_bf16 v[102:105], v[186:189], v[210:213], v[102:105]
	v_mfma_f32_16x16x32_bf16 v[98:101], v[194:197], v[210:213], v[98:101]
	v_mfma_f32_16x16x32_bf16 v[86:89], v[186:189], v[218:221], v[86:89]
	v_mfma_f32_16x16x32_bf16 v[82:85], v[194:197], v[218:221], v[82:85]
	v_mfma_f32_16x16x32_bf16 v[70:73], v[186:189], v[226:229], v[70:73]
	v_mfma_f32_16x16x32_bf16 v[66:69], v[194:197], v[226:229], v[66:69]
	s_setprio 0
	s_barrier
; #define PG8_STAGE(bufoff, gbase, voff) do { _Pragma("unroll") for (int _i = 0; _i < 2; ++_i) \
;         __builtin_amdgcn_global_load_lds((const unsigned*)((const char*)(gbase) + (voff)[_i]), (PG8_LAS unsigned*)(lds + (bufoff) + ldsw + _i * 8192), 16, 0, 0); } while (0)
; #define PG8_LDA(dst, b, h) do { _Pragma("unroll") for (int m = 0; m < 4; ++m) _Pragma("unroll") for (int k = 0; k < 2; ++k) dst[m][k] = *(const PG8_LAS bf16x8*)(lds + PG8_SA(b, h) + aoff + m * 2048 + k * 1024); } while (0)
; #define PG8_MMA(ai, bj, At, Bt) do { __builtin_amdgcn_s_setprio(1); _Pragma("unroll") for (int m = 0; m < 4; ++m) _Pragma("unroll") for (int n = 0; n < 2; ++n) _Pragma("unroll") for (int k = 0; k < 2; ++k) \
;         acc[ai][bj][m][n] = __builtin_amdgcn_mfma_f32_16x16x32_bf16(Bt[n][k], At[m][k], acc[ai][bj][m][n], 0, 0, 0); __builtin_amdgcn_s_setprio(0); } while (0)
; #define PG8_WAIT_V(n) asm volatile("s_waitcnt vmcnt(" #n ")" ::: "memory")
; #define PG8_WAIT_L(n) asm volatile("s_waitcnt lgkmcnt(" #n ")" ::: "memory")
; #define PG8_BAR __builtin_amdgcn_s_barrier()
; #define PG8_SCHED __builtin_amdgcn_sched_barrier(0)
; template <class Epi, class Sched, bool ALIGN_EPI = false, bool SP2 = false>
; __device__ __forceinline__ void gemm_phase(PG8_LAS unsigned char* lds, const Gemm g, const Sched& S, const Epi& E) {
;     ...
;             PG8_LDA(At, 1, 1); PG8_STAGE(PG8_SB(1, 0), b3, voffB); PG8_STAGE(PG8_SB(1, 1), b3 + hstep, voffB); PG8_STAGE(PG8_SA(1, 0), a3, voffA);
;             PG8_WAIT_V(8); PG8_WAIT_L(0); PG8_BAR; PG8_MMA(1, 0, At, B0); PG8_MMA(1, 1, At, B1); PG8_BAR; PG8_SCHED;
	s_add_i32 s36, s70, s41
	v_lshl_add_u64 v[230:231], v[230:231], 0, s[24:25]
	s_mov_b32 m0, s36
	ds_read_b128 v[198:201], v164 offset:49152
	ds_read_b128 v[202:205], v164 offset:50176
	ds_read_b128 v[206:209], v164 offset:51200
	ds_read_b128 v[210:213], v164 offset:52224
	ds_read_b128 v[214:217], v164 offset:53248
	ds_read_b128 v[218:221], v164 offset:54272
	ds_read_b128 v[222:225], v164 offset:55296
	ds_read_b128 v[226:229], v164 offset:56320
	global_load_lds_dwordx4 v[230:231], off
	v_lshl_add_u64 v[230:231], v[232:233], 0, s[24:25]
	s_add_i32 m0, s36, 0x2000
	s_add_i32 s36, s71, s41
	global_load_lds_dwordx4 v[230:231], off
	v_lshl_add_u64 v[230:231], v[234:235], 0, s[24:25]
	s_mov_b32 m0, s36
	s_nop 0
	global_load_lds_dwordx4 v[230:231], off
	v_lshl_add_u64 v[230:231], v[236:237], 0, s[24:25]
	s_add_i32 m0, s36, 0x2000
	s_nop 0
	global_load_lds_dwordx4 v[230:231], off
	v_lshl_add_u64 v[230:231], v[238:239], 0, s[24:25]
	s_mov_b32 m0, s47
	s_nop 0
	global_load_lds_dwordx4 v[230:231], off
	v_lshl_add_u64 v[230:231], v[240:241], 0, s[24:25]
	s_mov_b32 m0, s48
	s_nop 0
	global_load_lds_dwordx4 v[230:231], off
	s_waitcnt vmcnt(8)
	s_waitcnt lgkmcnt(0)
	s_barrier
	s_setprio 1
	v_mfma_f32_16x16x32_bf16 v[62:65], v[166:169], v[198:201], v[62:65]
	v_mfma_f32_16x16x32_bf16 v[58:61], v[174:177], v[198:201], v[58:61]
	v_mfma_f32_16x16x32_bf16 v[46:49], v[166:169], v[206:209], v[46:49]
	v_mfma_f32_16x16x32_bf16 v[42:45], v[174:177], v[206:209], v[42:45]
	v_mfma_f32_16x16x32_bf16 v[30:33], v[166:169], v[214:217], v[30:33]
	v_mfma_f32_16x16x32_bf16 v[26:29], v[174:177], v[214:217], v[26:29]
	v_mfma_f32_16x16x32_bf16 v[14:17], v[166:169], v[222:225], v[14:17]
	v_mfma_f32_16x16x32_bf16 v[10:13], v[174:177], v[222:225], v[10:13]
	v_mfma_f32_16x16x32_bf16 v[62:65], v[170:173], v[202:205], v[62:65]
	v_mfma_f32_16x16x32_bf16 v[58:61], v[178:181], v[202:205], v[58:61]
	v_mfma_f32_16x16x32_bf16 v[46:49], v[170:173], v[210:213], v[46:49]
	v_mfma_f32_16x16x32_bf16 v[42:45], v[178:181], v[210:213], v[42:45]
	v_mfma_f32_16x16x32_bf16 v[30:33], v[170:173], v[218:221], v[30:33]
	v_mfma_f32_16x16x32_bf16 v[26:29], v[178:181], v[218:221], v[26:29]
	v_mfma_f32_16x16x32_bf16 v[14:17], v[170:173], v[226:229], v[14:17]
	v_mfma_f32_16x16x32_bf16 v[10:13], v[178:181], v[226:229], v[10:13]
	v_mfma_f32_16x16x32_bf16 v[54:57], v[182:185], v[198:201], v[54:57]
	v_mfma_f32_16x16x32_bf16 v[50:53], v[190:193], v[198:201], v[50:53]
	v_mfma_f32_16x16x32_bf16 v[38:41], v[182:185], v[206:209], v[38:41]
	v_mfma_f32_16x16x32_bf16 v[34:37], v[190:193], v[206:209], v[34:37]
	v_mfma_f32_16x16x32_bf16 v[22:25], v[182:185], v[214:217], v[22:25]
	v_mfma_f32_16x16x32_bf16 v[18:21], v[190:193], v[214:217], v[18:21]
	v_mfma_f32_16x16x32_bf16 v[6:9], v[182:185], v[222:225], v[6:9]
	v_mfma_f32_16x16x32_bf16 v[2:5], v[190:193], v[222:225], v[2:5]
	v_mfma_f32_16x16x32_bf16 v[54:57], v[186:189], v[202:205], v[54:57]
	v_mfma_f32_16x16x32_bf16 v[50:53], v[194:197], v[202:205], v[50:53]
	v_mfma_f32_16x16x32_bf16 v[38:41], v[186:189], v[210:213], v[38:41]
	v_mfma_f32_16x16x32_bf16 v[34:37], v[194:197], v[210:213], v[34:37]
	v_mfma_f32_16x16x32_bf16 v[22:25], v[186:189], v[218:221], v[22:25]
	v_mfma_f32_16x16x32_bf16 v[18:21], v[194:197], v[218:221], v[18:21]
	v_mfma_f32_16x16x32_bf16 v[6:9], v[186:189], v[226:229], v[6:9]
	v_mfma_f32_16x16x32_bf16 v[2:5], v[194:197], v[226:229], v[2:5]
	s_setprio 0
	s_barrier
	s_add_u32 s81, s81, 0x100
	s_addc_u32 s86, s86, 0
	s_add_u32 s34, s34, 0x100
	s_addc_u32 s35, s35, 0
	s_cmp_ge_i32 s87, s49
	s_mov_b32 s36, s87
	s_cbranch_scc0 .LBB0_1375

; #define PG8_STAGE(bufoff, gbase, voff) do { _Pragma("unroll") for (int _i = 0; _i < 2; ++_i) \
;         __builtin_amdgcn_global_load_lds((const unsigned*)((const char*)(gbase) + (voff)[_i]), (PG8_LAS unsigned*)(lds + (bufoff) + ldsw + _i * 8192), 16, 0, 0); } while (0)
; #define PG8_LDA(dst, b, h) do { _Pragma("unroll") for (int m = 0; m < 4; ++m) _Pragma("unroll") for (int k = 0; k < 2; ++k) dst[m][k] = *(const PG8_LAS bf16x8*)(lds + PG8_SA(b, h) + aoff + m * 2048 + k * 1024); } while (0)
; #define PG8_LDB(dst, b, h) do { _Pragma("unroll") for (int n = 0; n < 2; ++n) _Pragma("unroll") for (int k = 0; k < 2; ++k) dst[n][k] = *(const PG8_LAS bf16x8*)(lds + PG8_SB(b, h) + boff + n * 2048 + k * 1024); } while (0)
; #define PG8_MMA(ai, bj, At, Bt) do { __builtin_amdgcn_s_setprio(1); _Pragma("unroll") for (int m = 0; m < 4; ++m) _Pragma("unroll") for (int n = 0; n < 2; ++n) _Pragma("unroll") for (int k = 0; k < 2; ++k) \
;         acc[ai][bj][m][n] = __builtin_amdgcn_mfma_f32_16x16x32_bf16(Bt[n][k], At[m][k], acc[ai][bj][m][n], 0, 0, 0); __builtin_amdgcn_s_setprio(0); } while (0)
; #define PG8_WAIT_V(n) asm volatile("s_waitcnt vmcnt(" #n ")" ::: "memory")
; #define PG8_WAIT_L(n) asm volatile("s_waitcnt lgkmcnt(" #n ")" ::: "memory")
; #define PG8_BAR __builtin_amdgcn_s_barrier()
; #define PG8_SCHED __builtin_amdgcn_sched_barrier(0)
; template <class Epi, class Sched, bool ALIGN_EPI = false, bool SP2 = false>
; __device__ __forceinline__ void gemm_phase(PG8_LAS unsigned char* lds, const Gemm g, const Sched& S, const Epi& E) {
;     ...
;             PG8_LDB(B0, 0, 0); PG8_LDB(B1, 0, 1); PG8_SCHED; PG8_LDA(At, 0, 0); PG8_STAGE(PG8_SA(1, 1), a1 + hstep, voffA);
;             PG8_WAIT_V(8); PG8_WAIT_L(0); PG8_BAR; PG8_MMA(0, 0, At, B0); PG8_MMA(0, 1, At, B1); PG8_BAR; PG8_SCHED;
;             PG8_LDA(At, 0, 1); PG8_STAGE(PG8_SB(0, 0), b2, voffB); PG8_STAGE(PG8_SB(0, 1), b2 + hstep, voffB); PG8_STAGE(PG8_SA(0, 0), a2, voffA);
;             PG8_WAIT_V(8); PG8_WAIT_L(0); PG8_BAR; PG8_MMA(1, 0, At, B0); PG8_MMA(1, 1, At, B1); PG8_BAR; PG8_SCHED;
.LBB0_1404:
	ds_read_b128 v[166:169], v162
	ds_read_b128 v[170:173], v162 offset:1024
	ds_read_b128 v[174:177], v162 offset:2048
	ds_read_b128 v[178:181], v162 offset:3072
	ds_read_b128 v[182:185], v163
	ds_read_b128 v[186:189], v163 offset:1024
	ds_read_b128 v[190:193], v163 offset:2048
	ds_read_b128 v[194:197], v163 offset:3072
	s_add_i32 s86, s34, 2
	s_add_u32 s70, s30, 0x80
	s_addc_u32 s35, s31, 0
	s_cmp_eq_u32 s49, s34
	s_cselect_b32 s34, s6, s70
	s_cselect_b32 s35, s7, s35
	s_cselect_b32 s71, s29, s81
	s_cselect_b32 s70, s28, s80
	v_lshl_add_u64 v[230:231], s[30:31], 0, v[140:141]
	s_add_i32 m0, s41, 0xc000
	ds_read_b128 v[198:201], v164
	ds_read_b128 v[202:205], v164 offset:1024
	ds_read_b128 v[206:209], v164 offset:2048
	ds_read_b128 v[210:213], v164 offset:3072
	ds_read_b128 v[214:217], v164 offset:4096
	ds_read_b128 v[218:221], v164 offset:5120
	ds_read_b128 v[222:225], v164 offset:6144
	ds_read_b128 v[226:229], v164 offset:7168
	global_load_lds_dwordx4 v[230:231], off
	v_lshl_add_u64 v[230:231], s[30:31], 0, v[138:139]
	s_add_i32 m0, s41, 0xe000
	s_nop 0
	global_load_lds_dwordx4 v[230:231], off
	s_waitcnt vmcnt(8)
	s_waitcnt lgkmcnt(0)
	s_barrier
	s_setprio 1
	v_mfma_f32_16x16x32_bf16 v[122:125], v[166:169], v[198:201], v[122:125]
	v_mfma_f32_16x16x32_bf16 v[126:129], v[174:177], v[198:201], v[126:129]
	v_mfma_f32_16x16x32_bf16 v[110:113], v[166:169], v[206:209], v[110:113]
	v_mfma_f32_16x16x32_bf16 v[106:109], v[174:177], v[206:209], v[106:109]
	v_mfma_f32_16x16x32_bf16 v[94:97], v[166:169], v[214:217], v[94:97]
	v_mfma_f32_16x16x32_bf16 v[90:93], v[174:177], v[214:217], v[90:93]
	v_mfma_f32_16x16x32_bf16 v[78:81], v[166:169], v[222:225], v[78:81]
	v_mfma_f32_16x16x32_bf16 v[74:77], v[174:177], v[222:225], v[74:77]
	v_mfma_f32_16x16x32_bf16 v[122:125], v[170:173], v[202:205], v[122:125]
	v_mfma_f32_16x16x32_bf16 v[126:129], v[178:181], v[202:205], v[126:129]
	v_mfma_f32_16x16x32_bf16 v[110:113], v[170:173], v[210:213], v[110:113]
	v_mfma_f32_16x16x32_bf16 v[106:109], v[178:181], v[210:213], v[106:109]
	v_mfma_f32_16x16x32_bf16 v[94:97], v[170:173], v[218:221], v[94:97]
	v_mfma_f32_16x16x32_bf16 v[90:93], v[178:181], v[218:221], v[90:93]
	v_mfma_f32_16x16x32_bf16 v[78:81], v[170:173], v[226:229], v[78:81]
	v_mfma_f32_16x16x32_bf16 v[74:77], v[178:181], v[226:229], v[74:77]
	v_mfma_f32_16x16x32_bf16 v[118:121], v[182:185], v[198:201], v[118:121]
	v_mfma_f32_16x16x32_bf16 v[114:117], v[190:193], v[198:201], v[114:117]
	v_mfma_f32_16x16x32_bf16 v[102:105], v[182:185], v[206:209], v[102:105]
	v_mfma_f32_16x16x32_bf16 v[98:101], v[190:193], v[206:209], v[98:101]
	v_mfma_f32_16x16x32_bf16 v[86:89], v[182:185], v[214:217], v[86:89]
	v_mfma_f32_16x16x32_bf16 v[82:85], v[190:193], v[214:217], v[82:85]
	v_mfma_f32_16x16x32_bf16 v[70:73], v[182:185], v[222:225], v[70:73]
	v_mfma_f32_16x16x32_bf16 v[66:69], v[190:193], v[222:225], v[66:69]
	v_mfma_f32_16x16x32_bf16 v[118:121], v[186:189], v[202:205], v[118:121]
	v_mfma_f32_16x16x32_bf16 v[114:117], v[194:197], v[202:205], v[114:117]
	v_mfma_f32_16x16x32_bf16 v[102:105], v[186:189], v[210:213], v[102:105]
	v_mfma_f32_16x16x32_bf16 v[98:101], v[194:197], v[210:213], v[98:101]
	v_mfma_f32_16x16x32_bf16 v[86:89], v[186:189], v[218:221], v[86:89]
	v_mfma_f32_16x16x32_bf16 v[82:85], v[194:197], v[218:221], v[82:85]
	v_mfma_f32_16x16x32_bf16 v[70:73], v[186:189], v[226:229], v[70:73]
	v_mfma_f32_16x16x32_bf16 v[66:69], v[194:197], v[226:229], v[66:69]
	s_setprio 0
	s_barrier
	s_add_i32 s72, s54, s40
	v_lshl_add_u64 v[230:231], s[70:71], 0, v[132:133]
	s_mov_b32 m0, s72
	ds_read_b128 v[198:201], v164 offset:16384
	ds_read_b128 v[202:205], v164 offset:17408
	ds_read_b128 v[206:209], v164 offset:18432
	ds_read_b128 v[210:213], v164 offset:19456
	ds_read_b128 v[214:217], v164 offset:20480
	ds_read_b128 v[218:221], v164 offset:21504
	ds_read_b128 v[222:225], v164 offset:22528
	ds_read_b128 v[226:229], v164 offset:23552
	global_load_lds_dwordx4 v[230:231], off
	s_add_i32 m0, s72, 0x2000
	v_lshl_add_u64 v[232:233], s[70:71], 0, v[136:137]
	s_add_u32 s70, s70, s12
	s_addc_u32 s71, s71, s13
	s_add_i32 s72, s55, s40
	global_load_lds_dwordx4 v[232:233], off
	v_lshl_add_u64 v[234:235], s[70:71], 0, v[132:133]
	s_mov_b32 m0, s72
	v_lshl_add_u64 v[236:237], s[70:71], 0, v[136:137]
	global_load_lds_dwordx4 v[234:235], off
	s_add_i32 m0, s72, 0x2000
	v_lshl_add_u64 v[238:239], s[34:35], 0, v[130:131]
	global_load_lds_dwordx4 v[236:237], off
	s_mov_b32 m0, s41
	v_lshl_add_u64 v[240:241], s[34:35], 0, v[134:135]
	global_load_lds_dwordx4 v[238:239], off
	s_mov_b32 m0, s42
	s_nop 0
	global_load_lds_dwordx4 v[240:241], off
	s_waitcnt vmcnt(8)
	s_waitcnt lgkmcnt(0)
	s_barrier
; #define PG8_STAGE(bufoff, gbase, voff) do { _Pragma("unroll") for (int _i = 0; _i < 2; ++_i) \
;         __builtin_amdgcn_global_load_lds((const unsigned*)((const char*)(gbase) + (voff)[_i]), (PG8_LAS unsigned*)(lds + (bufoff) + ldsw + _i * 8192), 16, 0, 0); } while (0)
; #define PG8_LDA(dst, b, h) do { _Pragma("unroll") for (int m = 0; m < 4; ++m) _Pragma("unroll") for (int k = 0; k < 2; ++k) dst[m][k] = *(const PG8_LAS bf16x8*)(lds + PG8_SA(b, h) + aoff + m * 2048 + k * 1024); } while (0)
; #define PG8_LDB(dst, b, h) do { _Pragma("unroll") for (int n = 0; n < 2; ++n) _Pragma("unroll") for (int k = 0; k < 2; ++k) dst[n][k] = *(const PG8_LAS bf16x8*)(lds + PG8_SB(b, h) + boff + n * 2048 + k * 1024); } while (0)
; #define PG8_MMA(ai, bj, At, Bt) do { __builtin_amdgcn_s_setprio(1); _Pragma("unroll") for (int m = 0; m < 4; ++m) _Pragma("unroll") for (int n = 0; n < 2; ++n) _Pragma("unroll") for (int k = 0; k < 2; ++k) \
;         acc[ai][bj][m][n] = __builtin_amdgcn_mfma_f32_16x16x32_bf16(Bt[n][k], At[m][k], acc[ai][bj][m][n], 0, 0, 0); __builtin_amdgcn_s_setprio(0); } while (0)
; #define PG8_WAIT_V(n) asm volatile("s_waitcnt vmcnt(" #n ")" ::: "memory")
; #define PG8_WAIT_L(n) asm volatile("s_waitcnt lgkmcnt(" #n ")" ::: "memory")
; #define PG8_BAR __builtin_amdgcn_s_barrier()
; #define PG8_SCHED __builtin_amdgcn_sched_barrier(0)
; template <class Epi, class Sched, bool ALIGN_EPI = false, bool SP2 = false>
; __device__ __forceinline__ void gemm_phase(PG8_LAS unsigned char* lds, const Gemm g, const Sched& S, const Epi& E) {
;     ...
;             PG8_WAIT_V(8); PG8_WAIT_L(0); PG8_BAR; PG8_MMA(1, 0, At, B0); PG8_MMA(1, 1, At, B1); PG8_BAR; PG8_SCHED;
;             PG8_LDB(B0, 1, 0); PG8_LDB(B1, 1, 1); PG8_SCHED; PG8_LDA(At, 1, 0); PG8_STAGE(PG8_SA(0, 1), a2 + hstep, voffA);
;             PG8_WAIT_V(8); PG8_WAIT_L(0); PG8_BAR; PG8_MMA(0, 0, At, B0); PG8_MMA(0, 1, At, B1); PG8_BAR; PG8_SCHED;
	s_setprio 1
	v_mfma_f32_16x16x32_bf16 v[62:65], v[166:169], v[198:201], v[62:65]
	v_mfma_f32_16x16x32_bf16 v[58:61], v[174:177], v[198:201], v[58:61]
	v_mfma_f32_16x16x32_bf16 v[46:49], v[166:169], v[206:209], v[46:49]
	v_mfma_f32_16x16x32_bf16 v[42:45], v[174:177], v[206:209], v[42:45]
	v_mfma_f32_16x16x32_bf16 v[30:33], v[166:169], v[214:217], v[30:33]
	v_mfma_f32_16x16x32_bf16 v[26:29], v[174:177], v[214:217], v[26:29]
	v_mfma_f32_16x16x32_bf16 v[14:17], v[166:169], v[222:225], v[14:17]
	v_mfma_f32_16x16x32_bf16 v[10:13], v[174:177], v[222:225], v[10:13]
	v_mfma_f32_16x16x32_bf16 v[62:65], v[170:173], v[202:205], v[62:65]
	v_mfma_f32_16x16x32_bf16 v[58:61], v[178:181], v[202:205], v[58:61]
	v_mfma_f32_16x16x32_bf16 v[46:49], v[170:173], v[210:213], v[46:49]
	v_mfma_f32_16x16x32_bf16 v[42:45], v[178:181], v[210:213], v[42:45]
	v_mfma_f32_16x16x32_bf16 v[30:33], v[170:173], v[218:221], v[30:33]
	v_mfma_f32_16x16x32_bf16 v[26:29], v[178:181], v[218:221], v[26:29]
	v_mfma_f32_16x16x32_bf16 v[14:17], v[170:173], v[226:229], v[14:17]
	v_mfma_f32_16x16x32_bf16 v[10:13], v[178:181], v[226:229], v[10:13]
	v_mfma_f32_16x16x32_bf16 v[54:57], v[182:185], v[198:201], v[54:57]
	v_mfma_f32_16x16x32_bf16 v[50:53], v[190:193], v[198:201], v[50:53]
	v_mfma_f32_16x16x32_bf16 v[38:41], v[182:185], v[206:209], v[38:41]
	v_mfma_f32_16x16x32_bf16 v[34:37], v[190:193], v[206:209], v[34:37]
	v_mfma_f32_16x16x32_bf16 v[22:25], v[182:185], v[214:217], v[22:25]
	v_mfma_f32_16x16x32_bf16 v[18:21], v[190:193], v[214:217], v[18:21]
	v_mfma_f32_16x16x32_bf16 v[6:9], v[182:185], v[222:225], v[6:9]
	v_mfma_f32_16x16x32_bf16 v[2:5], v[190:193], v[222:225], v[2:5]
	v_mfma_f32_16x16x32_bf16 v[54:57], v[186:189], v[202:205], v[54:57]
	v_mfma_f32_16x16x32_bf16 v[50:53], v[194:197], v[202:205], v[50:53]
	v_mfma_f32_16x16x32_bf16 v[38:41], v[186:189], v[210:213], v[38:41]
	v_mfma_f32_16x16x32_bf16 v[34:37], v[194:197], v[210:213], v[34:37]
	v_mfma_f32_16x16x32_bf16 v[22:25], v[186:189], v[218:221], v[22:25]
	v_mfma_f32_16x16x32_bf16 v[18:21], v[194:197], v[218:221], v[18:21]
	v_mfma_f32_16x16x32_bf16 v[6:9], v[186:189], v[226:229], v[6:9]
	v_mfma_f32_16x16x32_bf16 v[2:5], v[194:197], v[226:229], v[2:5]
	s_setprio 0
	s_barrier
	s_add_i32 s70, 0, 0x18000
	v_add_u32_e32 v165, s70, v160
	s_add_i32 s71, 0, 0x1c000
	ds_read_b128 v[166:169], v165
	ds_read_b128 v[170:173], v165 offset:1024
	ds_read_b128 v[174:177], v165 offset:2048
	ds_read_b128 v[178:181], v165 offset:3072
	v_add_u32_e32 v165, s71, v160
	ds_read_b128 v[182:185], v165
	ds_read_b128 v[186:189], v165 offset:1024
	ds_read_b128 v[190:193], v165 offset:2048
	ds_read_b128 v[194:197], v165 offset:3072
	s_add_u32 s34, s34, s12
	s_addc_u32 s35, s35, s13
	s_mov_b32 m0, s43
	v_lshl_add_u64 v[242:243], s[34:35], 0, v[130:131]
	ds_read_b128 v[198:201], v164 offset:32768
	ds_read_b128 v[202:205], v164 offset:33792
	ds_read_b128 v[206:209], v164 offset:34816
	ds_read_b128 v[210:213], v164 offset:35840
	ds_read_b128 v[214:217], v164 offset:36864
	ds_read_b128 v[218:221], v164 offset:37888
	ds_read_b128 v[222:225], v164 offset:38912
	ds_read_b128 v[226:229], v164 offset:39936
	global_load_lds_dwordx4 v[242:243], off
	v_lshl_add_u64 v[242:243], s[34:35], 0, v[134:135]
	s_mov_b32 m0, s44
	s_nop 0
	global_load_lds_dwordx4 v[242:243], off
	s_waitcnt vmcnt(8)
	s_waitcnt lgkmcnt(0)
	s_barrier
	s_setprio 1
	v_mfma_f32_16x16x32_bf16 v[122:125], v[166:169], v[198:201], v[122:125]
	v_mfma_f32_16x16x32_bf16 v[126:129], v[174:177], v[198:201], v[126:129]
	v_mfma_f32_16x16x32_bf16 v[110:113], v[166:169], v[206:209], v[110:113]
	v_mfma_f32_16x16x32_bf16 v[106:109], v[174:177], v[206:209], v[106:109]
	v_mfma_f32_16x16x32_bf16 v[94:97], v[166:169], v[214:217], v[94:97]
	v_mfma_f32_16x16x32_bf16 v[90:93], v[174:177], v[214:217], v[90:93]
	v_mfma_f32_16x16x32_bf16 v[78:81], v[166:169], v[222:225], v[78:81]
	v_mfma_f32_16x16x32_bf16 v[74:77], v[174:177], v[222:225], v[74:77]
	v_mfma_f32_16x16x32_bf16 v[122:125], v[170:173], v[202:205], v[122:125]
	v_mfma_f32_16x16x32_bf16 v[126:129], v[178:181], v[202:205], v[126:129]
	v_mfma_f32_16x16x32_bf16 v[110:113], v[170:173], v[210:213], v[110:113]
	v_mfma_f32_16x16x32_bf16 v[106:109], v[178:181], v[210:213], v[106:109]
	v_mfma_f32_16x16x32_bf16 v[94:97], v[170:173], v[218:221], v[94:97]
	v_mfma_f32_16x16x32_bf16 v[90:93], v[178:181], v[218:221], v[90:93]
	v_mfma_f32_16x16x32_bf16 v[78:81], v[170:173], v[226:229], v[78:81]
	v_mfma_f32_16x16x32_bf16 v[74:77], v[178:181], v[226:229], v[74:77]
	v_mfma_f32_16x16x32_bf16 v[118:121], v[182:185], v[198:201], v[118:121]
	v_mfma_f32_16x16x32_bf16 v[114:117], v[190:193], v[198:201], v[114:117]
	v_mfma_f32_16x16x32_bf16 v[102:105], v[182:185], v[206:209], v[102:105]
	v_mfma_f32_16x16x32_bf16 v[98:101], v[190:193], v[206:209], v[98:101]
	v_mfma_f32_16x16x32_bf16 v[86:89], v[182:185], v[214:217], v[86:89]
	v_mfma_f32_16x16x32_bf16 v[82:85], v[190:193], v[214:217], v[82:85]
	v_mfma_f32_16x16x32_bf16 v[70:73], v[182:185], v[222:225], v[70:73]
	v_mfma_f32_16x16x32_bf16 v[66:69], v[190:193], v[222:225], v[66:69]
	v_mfma_f32_16x16x32_bf16 v[118:121], v[186:189], v[202:205], v[118:121]
	v_mfma_f32_16x16x32_bf16 v[114:117], v[194:197], v[202:205], v[114:117]
	v_mfma_f32_16x16x32_bf16 v[102:105], v[186:189], v[210:213], v[102:105]
	v_mfma_f32_16x16x32_bf16 v[98:101], v[194:197], v[210:213], v[98:101]
	v_mfma_f32_16x16x32_bf16 v[86:89], v[186:189], v[218:221], v[86:89]
	v_mfma_f32_16x16x32_bf16 v[82:85], v[194:197], v[218:221], v[82:85]
	v_mfma_f32_16x16x32_bf16 v[70:73], v[186:189], v[226:229], v[70:73]
	v_mfma_f32_16x16x32_bf16 v[66:69], v[194:197], v[226:229], v[66:69]
	s_setprio 0
	s_barrier
; #define PG8_STAGE(bufoff, gbase, voff) do { _Pragma("unroll") for (int _i = 0; _i < 2; ++_i) \
;         __builtin_amdgcn_global_load_lds((const unsigned*)((const char*)(gbase) + (voff)[_i]), (PG8_LAS unsigned*)(lds + (bufoff) + ldsw + _i * 8192), 16, 0, 0); } while (0)
; #define PG8_LDA(dst, b, h) do { _Pragma("unroll") for (int m = 0; m < 4; ++m) _Pragma("unroll") for (int k = 0; k < 2; ++k) dst[m][k] = *(const PG8_LAS bf16x8*)(lds + PG8_SA(b, h) + aoff + m * 2048 + k * 1024); } while (0)
; #define PG8_MMA(ai, bj, At, Bt) do { __builtin_amdgcn_s_setprio(1); _Pragma("unroll") for (int m = 0; m < 4; ++m) _Pragma("unroll") for (int n = 0; n < 2; ++n) _Pragma("unroll") for (int k = 0; k < 2; ++k) \
;         acc[ai][bj][m][n] = __builtin_amdgcn_mfma_f32_16x16x32_bf16(Bt[n][k], At[m][k], acc[ai][bj][m][n], 0, 0, 0); __builtin_amdgcn_s_setprio(0); } while (0)
; #define PG8_WAIT_V(n) asm volatile("s_waitcnt vmcnt(" #n ")" ::: "memory")
; #define PG8_WAIT_L(n) asm volatile("s_waitcnt lgkmcnt(" #n ")" ::: "memory")
; #define PG8_BAR __builtin_amdgcn_s_barrier()
; #define PG8_SCHED __builtin_amdgcn_sched_barrier(0)
; template <class Epi, class Sched, bool ALIGN_EPI = false, bool SP2 = false>
; __device__ __forceinline__ void gemm_phase(PG8_LAS unsigned char* lds, const Gemm g, const Sched& S, const Epi& E) {
;     ...
;             PG8_LDA(At, 1, 1); PG8_STAGE(PG8_SB(1, 0), b3, voffB); PG8_STAGE(PG8_SB(1, 1), b3 + hstep, voffB); PG8_STAGE(PG8_SA(1, 0), a3, voffA);
;             PG8_WAIT_V(8); PG8_WAIT_L(0); PG8_BAR; PG8_MMA(1, 0, At, B0); PG8_MMA(1, 1, At, B1); PG8_BAR; PG8_SCHED;
	s_add_i32 s34, s70, s40
	v_lshl_add_u64 v[230:231], v[230:231], 0, s[22:23]
	s_mov_b32 m0, s34
	ds_read_b128 v[198:201], v164 offset:49152
	ds_read_b128 v[202:205], v164 offset:50176
	ds_read_b128 v[206:209], v164 offset:51200
	ds_read_b128 v[210:213], v164 offset:52224
	ds_read_b128 v[214:217], v164 offset:53248
	ds_read_b128 v[218:221], v164 offset:54272
	ds_read_b128 v[222:225], v164 offset:55296
	ds_read_b128 v[226:229], v164 offset:56320
	global_load_lds_dwordx4 v[230:231], off
	v_lshl_add_u64 v[230:231], v[232:233], 0, s[22:23]
	s_add_i32 m0, s34, 0x2000
	s_add_i32 s34, s71, s40
	global_load_lds_dwordx4 v[230:231], off
	v_lshl_add_u64 v[230:231], v[234:235], 0, s[22:23]
	s_mov_b32 m0, s34
	s_nop 0
	global_load_lds_dwordx4 v[230:231], off
	v_lshl_add_u64 v[230:231], v[236:237], 0, s[22:23]
	s_add_i32 m0, s34, 0x2000
	s_nop 0
	global_load_lds_dwordx4 v[230:231], off
	v_lshl_add_u64 v[230:231], v[238:239], 0, s[22:23]
	s_mov_b32 m0, s46
	s_nop 0
	global_load_lds_dwordx4 v[230:231], off
	v_lshl_add_u64 v[230:231], v[240:241], 0, s[22:23]
	s_mov_b32 m0, s47
	s_nop 0
	global_load_lds_dwordx4 v[230:231], off
	s_waitcnt vmcnt(8)
	s_waitcnt lgkmcnt(0)
	s_barrier
	s_setprio 1
	v_mfma_f32_16x16x32_bf16 v[62:65], v[166:169], v[198:201], v[62:65]
	v_mfma_f32_16x16x32_bf16 v[58:61], v[174:177], v[198:201], v[58:61]
	v_mfma_f32_16x16x32_bf16 v[46:49], v[166:169], v[206:209], v[46:49]
	v_mfma_f32_16x16x32_bf16 v[42:45], v[174:177], v[206:209], v[42:45]
	v_mfma_f32_16x16x32_bf16 v[30:33], v[166:169], v[214:217], v[30:33]
	v_mfma_f32_16x16x32_bf16 v[26:29], v[174:177], v[214:217], v[26:29]
	v_mfma_f32_16x16x32_bf16 v[14:17], v[166:169], v[222:225], v[14:17]
	v_mfma_f32_16x16x32_bf16 v[10:13], v[174:177], v[222:225], v[10:13]
	v_mfma_f32_16x16x32_bf16 v[62:65], v[170:173], v[202:205], v[62:65]
	v_mfma_f32_16x16x32_bf16 v[58:61], v[178:181], v[202:205], v[58:61]
	v_mfma_f32_16x16x32_bf16 v[46:49], v[170:173], v[210:213], v[46:49]
	v_mfma_f32_16x16x32_bf16 v[42:45], v[178:181], v[210:213], v[42:45]
	v_mfma_f32_16x16x32_bf16 v[30:33], v[170:173], v[218:221], v[30:33]
	v_mfma_f32_16x16x32_bf16 v[26:29], v[178:181], v[218:221], v[26:29]
	v_mfma_f32_16x16x32_bf16 v[14:17], v[170:173], v[226:229], v[14:17]
	v_mfma_f32_16x16x32_bf16 v[10:13], v[178:181], v[226:229], v[10:13]
	v_mfma_f32_16x16x32_bf16 v[54:57], v[182:185], v[198:201], v[54:57]
	v_mfma_f32_16x16x32_bf16 v[50:53], v[190:193], v[198:201], v[50:53]
	v_mfma_f32_16x16x32_bf16 v[38:41], v[182:185], v[206:209], v[38:41]
	v_mfma_f32_16x16x32_bf16 v[34:37], v[190:193], v[206:209], v[34:37]
	v_mfma_f32_16x16x32_bf16 v[22:25], v[182:185], v[214:217], v[22:25]
	v_mfma_f32_16x16x32_bf16 v[18:21], v[190:193], v[214:217], v[18:21]
	v_mfma_f32_16x16x32_bf16 v[6:9], v[182:185], v[222:225], v[6:9]
	v_mfma_f32_16x16x32_bf16 v[2:5], v[190:193], v[222:225], v[2:5]
	v_mfma_f32_16x16x32_bf16 v[54:57], v[186:189], v[202:205], v[54:57]
	v_mfma_f32_16x16x32_bf16 v[50:53], v[194:197], v[202:205], v[50:53]
	v_mfma_f32_16x16x32_bf16 v[38:41], v[186:189], v[210:213], v[38:41]
	v_mfma_f32_16x16x32_bf16 v[34:37], v[194:197], v[210:213], v[34:37]
	v_mfma_f32_16x16x32_bf16 v[22:25], v[186:189], v[218:221], v[22:25]
	v_mfma_f32_16x16x32_bf16 v[18:21], v[194:197], v[218:221], v[18:21]
	v_mfma_f32_16x16x32_bf16 v[6:9], v[186:189], v[226:229], v[6:9]
	v_mfma_f32_16x16x32_bf16 v[2:5], v[194:197], v[226:229], v[2:5]
	s_setprio 0
	s_barrier
	s_add_u32 s80, s80, 0x100
	s_addc_u32 s81, s81, 0
	s_add_u32 s30, s30, 0x100
	s_addc_u32 s31, s31, 0
	s_cmp_ge_i32 s86, s48
	s_mov_b32 s34, s86
	s_cbranch_scc0 .LBB0_1404

; #define PG8_STAGE(bufoff, gbase, voff) do { _Pragma("unroll") for (int _i = 0; _i < 2; ++_i) \
;         __builtin_amdgcn_global_load_lds((const unsigned*)((const char*)(gbase) + (voff)[_i]), (PG8_LAS unsigned*)(lds + (bufoff) + ldsw + _i * 8192), 16, 0, 0); } while (0)
; #define PG8_LDA(dst, b, h) do { _Pragma("unroll") for (int m = 0; m < 4; ++m) _Pragma("unroll") for (int k = 0; k < 2; ++k) dst[m][k] = *(const PG8_LAS bf16x8*)(lds + PG8_SA(b, h) + aoff + m * 2048 + k * 1024); } while (0)
; #define PG8_LDB(dst, b, h) do { _Pragma("unroll") for (int n = 0; n < 2; ++n) _Pragma("unroll") for (int k = 0; k < 2; ++k) dst[n][k] = *(const PG8_LAS bf16x8*)(lds + PG8_SB(b, h) + boff + n * 2048 + k * 1024); } while (0)
; #define PG8_MMA(ai, bj, At, Bt) do { __builtin_amdgcn_s_setprio(1); _Pragma("unroll") for (int m = 0; m < 4; ++m) _Pragma("unroll") for (int n = 0; n < 2; ++n) _Pragma("unroll") for (int k = 0; k < 2; ++k) \
;         acc[ai][bj][m][n] = __builtin_amdgcn_mfma_f32_16x16x32_bf16(Bt[n][k], At[m][k], acc[ai][bj][m][n], 0, 0, 0); __builtin_amdgcn_s_setprio(0); } while (0)
; #define PG8_WAIT_V(n) asm volatile("s_waitcnt vmcnt(" #n ")" ::: "memory")
; #define PG8_WAIT_L(n) asm volatile("s_waitcnt lgkmcnt(" #n ")" ::: "memory")
; #define PG8_BAR __builtin_amdgcn_s_barrier()
; #define PG8_SCHED __builtin_amdgcn_sched_barrier(0)
; template <class Epi, class Sched, bool ALIGN_EPI = false, bool SP2 = false>
; __device__ __forceinline__ void gemm_phase(PG8_LAS unsigned char* lds, const Gemm g, const Sched& S, const Epi& E) {
;     ...
;             PG8_LDB(B0, 0, 0); PG8_LDB(B1, 0, 1); PG8_SCHED; PG8_LDA(At, 0, 0); PG8_STAGE(PG8_SA(1, 1), a1 + hstep, voffA);
;             PG8_WAIT_V(8); PG8_WAIT_L(0); PG8_BAR; PG8_MMA(0, 0, At, B0); PG8_MMA(0, 1, At, B1); PG8_BAR; PG8_SCHED;
;             PG8_LDA(At, 0, 1); PG8_STAGE(PG8_SB(0, 0), b2, voffB); PG8_STAGE(PG8_SB(0, 1), b2 + hstep, voffB); PG8_STAGE(PG8_SA(0, 0), a2, voffA);
;             PG8_WAIT_V(8); PG8_WAIT_L(0); PG8_BAR; PG8_MMA(1, 0, At, B0); PG8_MMA(1, 1, At, B1); PG8_BAR; PG8_SCHED;
.LBB0_1433:
	ds_read_b128 v[156:159], v1
	ds_read_b128 v[160:163], v1 offset:1024
	ds_read_b128 v[164:167], v1 offset:2048
	ds_read_b128 v[168:171], v1 offset:3072
	ds_read_b128 v[172:175], v146
	ds_read_b128 v[176:179], v146 offset:1024
	ds_read_b128 v[180:183], v146 offset:2048
	ds_read_b128 v[184:187], v146 offset:3072
	s_add_i32 s80, s30, 2
	s_add_u32 s70, s28, 0x80
	s_addc_u32 s31, s29, 0
	s_cmp_eq_u32 s47, s30
	s_cselect_b32 s30, s4, s70
	s_cselect_b32 s31, s5, s31
	s_cselect_b32 s71, s27, s69
	s_cselect_b32 s70, s26, s68
	v_lshl_add_u64 v[152:153], s[28:29], 0, v[140:141]
	s_add_i32 m0, s39, 0xc000
	ds_read_b128 v[188:191], v147
	ds_read_b128 v[192:195], v147 offset:1024
	ds_read_b128 v[196:199], v147 offset:2048
	ds_read_b128 v[200:203], v147 offset:3072
	ds_read_b128 v[204:207], v147 offset:4096
	ds_read_b128 v[208:211], v147 offset:5120
	ds_read_b128 v[212:215], v147 offset:6144
	ds_read_b128 v[216:219], v147 offset:7168
	global_load_lds_dwordx4 v[152:153], off
	v_lshl_add_u64 v[152:153], s[28:29], 0, v[138:139]
	s_add_i32 m0, s39, 0xe000
	s_nop 0
	global_load_lds_dwordx4 v[152:153], off
	s_waitcnt vmcnt(8)
	s_waitcnt lgkmcnt(0)
	s_barrier
	s_setprio 1
	v_mfma_f32_16x16x32_bf16 v[122:125], v[156:159], v[188:191], v[122:125]
	v_mfma_f32_16x16x32_bf16 v[126:129], v[164:167], v[188:191], v[126:129]
	v_mfma_f32_16x16x32_bf16 v[110:113], v[156:159], v[196:199], v[110:113]
	v_mfma_f32_16x16x32_bf16 v[106:109], v[164:167], v[196:199], v[106:109]
	v_mfma_f32_16x16x32_bf16 v[94:97], v[156:159], v[204:207], v[94:97]
	v_mfma_f32_16x16x32_bf16 v[90:93], v[164:167], v[204:207], v[90:93]
	v_mfma_f32_16x16x32_bf16 v[78:81], v[156:159], v[212:215], v[78:81]
	v_mfma_f32_16x16x32_bf16 v[74:77], v[164:167], v[212:215], v[74:77]
	v_mfma_f32_16x16x32_bf16 v[122:125], v[160:163], v[192:195], v[122:125]
	v_mfma_f32_16x16x32_bf16 v[126:129], v[168:171], v[192:195], v[126:129]
	v_mfma_f32_16x16x32_bf16 v[110:113], v[160:163], v[200:203], v[110:113]
	v_mfma_f32_16x16x32_bf16 v[106:109], v[168:171], v[200:203], v[106:109]
	v_mfma_f32_16x16x32_bf16 v[94:97], v[160:163], v[208:211], v[94:97]
	v_mfma_f32_16x16x32_bf16 v[90:93], v[168:171], v[208:211], v[90:93]
	v_mfma_f32_16x16x32_bf16 v[78:81], v[160:163], v[216:219], v[78:81]
	v_mfma_f32_16x16x32_bf16 v[74:77], v[168:171], v[216:219], v[74:77]
	v_mfma_f32_16x16x32_bf16 v[118:121], v[172:175], v[188:191], v[118:121]
	v_mfma_f32_16x16x32_bf16 v[114:117], v[180:183], v[188:191], v[114:117]
	v_mfma_f32_16x16x32_bf16 v[102:105], v[172:175], v[196:199], v[102:105]
	v_mfma_f32_16x16x32_bf16 v[98:101], v[180:183], v[196:199], v[98:101]
	v_mfma_f32_16x16x32_bf16 v[86:89], v[172:175], v[204:207], v[86:89]
	v_mfma_f32_16x16x32_bf16 v[82:85], v[180:183], v[204:207], v[82:85]
	v_mfma_f32_16x16x32_bf16 v[70:73], v[172:175], v[212:215], v[70:73]
	v_mfma_f32_16x16x32_bf16 v[66:69], v[180:183], v[212:215], v[66:69]
	v_mfma_f32_16x16x32_bf16 v[118:121], v[176:179], v[192:195], v[118:121]
	v_mfma_f32_16x16x32_bf16 v[114:117], v[184:187], v[192:195], v[114:117]
	v_mfma_f32_16x16x32_bf16 v[102:105], v[176:179], v[200:203], v[102:105]
	v_mfma_f32_16x16x32_bf16 v[98:101], v[184:187], v[200:203], v[98:101]
	v_mfma_f32_16x16x32_bf16 v[86:89], v[176:179], v[208:211], v[86:89]
	v_mfma_f32_16x16x32_bf16 v[82:85], v[184:187], v[208:211], v[82:85]
	v_mfma_f32_16x16x32_bf16 v[70:73], v[176:179], v[216:219], v[70:73]
	v_mfma_f32_16x16x32_bf16 v[66:69], v[184:187], v[216:219], v[66:69]
	s_setprio 0
	s_barrier
	s_add_i32 s72, s52, s38
	v_lshl_add_u64 v[152:153], s[70:71], 0, v[132:133]
	s_mov_b32 m0, s72
	ds_read_b128 v[188:191], v147 offset:16384
	ds_read_b128 v[192:195], v147 offset:17408
	ds_read_b128 v[196:199], v147 offset:18432
	ds_read_b128 v[200:203], v147 offset:19456
	ds_read_b128 v[204:207], v147 offset:20480
	ds_read_b128 v[208:211], v147 offset:21504
	ds_read_b128 v[212:215], v147 offset:22528
	ds_read_b128 v[216:219], v147 offset:23552
	global_load_lds_dwordx4 v[152:153], off
	s_add_i32 m0, s72, 0x2000
	v_lshl_add_u64 v[220:221], s[70:71], 0, v[136:137]
	s_add_u32 s70, s70, s6
	s_addc_u32 s71, s71, s7
	s_add_i32 s72, s53, s38
	global_load_lds_dwordx4 v[220:221], off
	v_lshl_add_u64 v[222:223], s[70:71], 0, v[132:133]
	s_mov_b32 m0, s72
	v_lshl_add_u64 v[224:225], s[70:71], 0, v[136:137]
	global_load_lds_dwordx4 v[222:223], off
	s_add_i32 m0, s72, 0x2000
	v_lshl_add_u64 v[226:227], s[30:31], 0, v[130:131]
	global_load_lds_dwordx4 v[224:225], off
	s_mov_b32 m0, s39
	v_lshl_add_u64 v[228:229], s[30:31], 0, v[134:135]
	global_load_lds_dwordx4 v[226:227], off
	s_mov_b32 m0, s40
	s_nop 0
	global_load_lds_dwordx4 v[228:229], off
	s_waitcnt vmcnt(8)
	s_waitcnt lgkmcnt(0)
	s_barrier
; #define PG8_STAGE(bufoff, gbase, voff) do { _Pragma("unroll") for (int _i = 0; _i < 2; ++_i) \
;         __builtin_amdgcn_global_load_lds((const unsigned*)((const char*)(gbase) + (voff)[_i]), (PG8_LAS unsigned*)(lds + (bufoff) + ldsw + _i * 8192), 16, 0, 0); } while (0)
; #define PG8_LDA(dst, b, h) do { _Pragma("unroll") for (int m = 0; m < 4; ++m) _Pragma("unroll") for (int k = 0; k < 2; ++k) dst[m][k] = *(const PG8_LAS bf16x8*)(lds + PG8_SA(b, h) + aoff + m * 2048 + k * 1024); } while (0)
; #define PG8_LDB(dst, b, h) do { _Pragma("unroll") for (int n = 0; n < 2; ++n) _Pragma("unroll") for (int k = 0; k < 2; ++k) dst[n][k] = *(const PG8_LAS bf16x8*)(lds + PG8_SB(b, h) + boff + n * 2048 + k * 1024); } while (0)
; #define PG8_MMA(ai, bj, At, Bt) do { __builtin_amdgcn_s_setprio(1); _Pragma("unroll") for (int m = 0; m < 4; ++m) _Pragma("unroll") for (int n = 0; n < 2; ++n) _Pragma("unroll") for (int k = 0; k < 2; ++k) \
;         acc[ai][bj][m][n] = __builtin_amdgcn_mfma_f32_16x16x32_bf16(Bt[n][k], At[m][k], acc[ai][bj][m][n], 0, 0, 0); __builtin_amdgcn_s_setprio(0); } while (0)
; #define PG8_WAIT_V(n) asm volatile("s_waitcnt vmcnt(" #n ")" ::: "memory")
; #define PG8_WAIT_L(n) asm volatile("s_waitcnt lgkmcnt(" #n ")" ::: "memory")
; #define PG8_BAR __builtin_amdgcn_s_barrier()
; #define PG8_SCHED __builtin_amdgcn_sched_barrier(0)
; template <class Epi, class Sched, bool ALIGN_EPI = false, bool SP2 = false>
; __device__ __forceinline__ void gemm_phase(PG8_LAS unsigned char* lds, const Gemm g, const Sched& S, const Epi& E) {
;     ...
;             PG8_WAIT_V(8); PG8_WAIT_L(0); PG8_BAR; PG8_MMA(1, 0, At, B0); PG8_MMA(1, 1, At, B1); PG8_BAR; PG8_SCHED;
;             PG8_LDB(B0, 1, 0); PG8_LDB(B1, 1, 1); PG8_SCHED; PG8_LDA(At, 1, 0); PG8_STAGE(PG8_SA(0, 1), a2 + hstep, voffA);
;             PG8_WAIT_V(8); PG8_WAIT_L(0); PG8_BAR; PG8_MMA(0, 0, At, B0); PG8_MMA(0, 1, At, B1); PG8_BAR; PG8_SCHED;
	s_setprio 1
	v_mfma_f32_16x16x32_bf16 v[62:65], v[156:159], v[188:191], v[62:65]
	v_mfma_f32_16x16x32_bf16 v[58:61], v[164:167], v[188:191], v[58:61]
	v_mfma_f32_16x16x32_bf16 v[46:49], v[156:159], v[196:199], v[46:49]
	v_mfma_f32_16x16x32_bf16 v[42:45], v[164:167], v[196:199], v[42:45]
	v_mfma_f32_16x16x32_bf16 v[30:33], v[156:159], v[204:207], v[30:33]
	v_mfma_f32_16x16x32_bf16 v[26:29], v[164:167], v[204:207], v[26:29]
	v_mfma_f32_16x16x32_bf16 v[14:17], v[156:159], v[212:215], v[14:17]
	v_mfma_f32_16x16x32_bf16 v[10:13], v[164:167], v[212:215], v[10:13]
	v_mfma_f32_16x16x32_bf16 v[62:65], v[160:163], v[192:195], v[62:65]
	v_mfma_f32_16x16x32_bf16 v[58:61], v[168:171], v[192:195], v[58:61]
	v_mfma_f32_16x16x32_bf16 v[46:49], v[160:163], v[200:203], v[46:49]
	v_mfma_f32_16x16x32_bf16 v[42:45], v[168:171], v[200:203], v[42:45]
	v_mfma_f32_16x16x32_bf16 v[30:33], v[160:163], v[208:211], v[30:33]
	v_mfma_f32_16x16x32_bf16 v[26:29], v[168:171], v[208:211], v[26:29]
	v_mfma_f32_16x16x32_bf16 v[14:17], v[160:163], v[216:219], v[14:17]
	v_mfma_f32_16x16x32_bf16 v[10:13], v[168:171], v[216:219], v[10:13]
	v_mfma_f32_16x16x32_bf16 v[54:57], v[172:175], v[188:191], v[54:57]
	v_mfma_f32_16x16x32_bf16 v[50:53], v[180:183], v[188:191], v[50:53]
	v_mfma_f32_16x16x32_bf16 v[38:41], v[172:175], v[196:199], v[38:41]
	v_mfma_f32_16x16x32_bf16 v[34:37], v[180:183], v[196:199], v[34:37]
	v_mfma_f32_16x16x32_bf16 v[22:25], v[172:175], v[204:207], v[22:25]
	v_mfma_f32_16x16x32_bf16 v[18:21], v[180:183], v[204:207], v[18:21]
	v_mfma_f32_16x16x32_bf16 v[6:9], v[172:175], v[212:215], v[6:9]
	v_mfma_f32_16x16x32_bf16 v[2:5], v[180:183], v[212:215], v[2:5]
	v_mfma_f32_16x16x32_bf16 v[54:57], v[176:179], v[192:195], v[54:57]
	v_mfma_f32_16x16x32_bf16 v[50:53], v[184:187], v[192:195], v[50:53]
	v_mfma_f32_16x16x32_bf16 v[38:41], v[176:179], v[200:203], v[38:41]
	v_mfma_f32_16x16x32_bf16 v[34:37], v[184:187], v[200:203], v[34:37]
	v_mfma_f32_16x16x32_bf16 v[22:25], v[176:179], v[208:211], v[22:25]
	v_mfma_f32_16x16x32_bf16 v[18:21], v[184:187], v[208:211], v[18:21]
	v_mfma_f32_16x16x32_bf16 v[6:9], v[176:179], v[216:219], v[6:9]
	v_mfma_f32_16x16x32_bf16 v[2:5], v[184:187], v[216:219], v[2:5]
	s_setprio 0
	s_barrier
	s_add_i32 s70, 0, 0x18000
	v_add_u32_e32 v148, s70, v150
	s_add_i32 s71, 0, 0x1c000
	ds_read_b128 v[156:159], v148
	ds_read_b128 v[160:163], v148 offset:1024
	ds_read_b128 v[164:167], v148 offset:2048
	ds_read_b128 v[168:171], v148 offset:3072
	v_add_u32_e32 v148, s71, v150
	ds_read_b128 v[172:175], v148
	ds_read_b128 v[176:179], v148 offset:1024
	ds_read_b128 v[180:183], v148 offset:2048
	ds_read_b128 v[184:187], v148 offset:3072
	s_add_u32 s30, s30, s6
	s_addc_u32 s31, s31, s7
	s_mov_b32 m0, s41
	v_lshl_add_u64 v[230:231], s[30:31], 0, v[130:131]
	ds_read_b128 v[188:191], v147 offset:32768
	ds_read_b128 v[192:195], v147 offset:33792
	ds_read_b128 v[196:199], v147 offset:34816
	ds_read_b128 v[200:203], v147 offset:35840
	ds_read_b128 v[204:207], v147 offset:36864
	ds_read_b128 v[208:211], v147 offset:37888
	ds_read_b128 v[212:215], v147 offset:38912
	ds_read_b128 v[216:219], v147 offset:39936
	global_load_lds_dwordx4 v[230:231], off
	v_lshl_add_u64 v[230:231], s[30:31], 0, v[134:135]
	s_mov_b32 m0, s42
	s_nop 0
	global_load_lds_dwordx4 v[230:231], off
	s_waitcnt vmcnt(8)
	s_waitcnt lgkmcnt(0)
	s_barrier
	s_setprio 1
	v_mfma_f32_16x16x32_bf16 v[122:125], v[156:159], v[188:191], v[122:125]
	v_mfma_f32_16x16x32_bf16 v[126:129], v[164:167], v[188:191], v[126:129]
	v_mfma_f32_16x16x32_bf16 v[110:113], v[156:159], v[196:199], v[110:113]
	v_mfma_f32_16x16x32_bf16 v[106:109], v[164:167], v[196:199], v[106:109]
	v_mfma_f32_16x16x32_bf16 v[94:97], v[156:159], v[204:207], v[94:97]
	v_mfma_f32_16x16x32_bf16 v[90:93], v[164:167], v[204:207], v[90:93]
	v_mfma_f32_16x16x32_bf16 v[78:81], v[156:159], v[212:215], v[78:81]
	v_mfma_f32_16x16x32_bf16 v[74:77], v[164:167], v[212:215], v[74:77]
	v_mfma_f32_16x16x32_bf16 v[122:125], v[160:163], v[192:195], v[122:125]
	v_mfma_f32_16x16x32_bf16 v[126:129], v[168:171], v[192:195], v[126:129]
	v_mfma_f32_16x16x32_bf16 v[110:113], v[160:163], v[200:203], v[110:113]
	v_mfma_f32_16x16x32_bf16 v[106:109], v[168:171], v[200:203], v[106:109]
	v_mfma_f32_16x16x32_bf16 v[94:97], v[160:163], v[208:211], v[94:97]
	v_mfma_f32_16x16x32_bf16 v[90:93], v[168:171], v[208:211], v[90:93]
	v_mfma_f32_16x16x32_bf16 v[78:81], v[160:163], v[216:219], v[78:81]
	v_mfma_f32_16x16x32_bf16 v[74:77], v[168:171], v[216:219], v[74:77]
	v_mfma_f32_16x16x32_bf16 v[118:121], v[172:175], v[188:191], v[118:121]
	v_mfma_f32_16x16x32_bf16 v[114:117], v[180:183], v[188:191], v[114:117]
	v_mfma_f32_16x16x32_bf16 v[102:105], v[172:175], v[196:199], v[102:105]
	v_mfma_f32_16x16x32_bf16 v[98:101], v[180:183], v[196:199], v[98:101]
	v_mfma_f32_16x16x32_bf16 v[86:89], v[172:175], v[204:207], v[86:89]
	v_mfma_f32_16x16x32_bf16 v[82:85], v[180:183], v[204:207], v[82:85]
	v_mfma_f32_16x16x32_bf16 v[70:73], v[172:175], v[212:215], v[70:73]
	v_mfma_f32_16x16x32_bf16 v[66:69], v[180:183], v[212:215], v[66:69]
	v_mfma_f32_16x16x32_bf16 v[118:121], v[176:179], v[192:195], v[118:121]
	v_mfma_f32_16x16x32_bf16 v[114:117], v[184:187], v[192:195], v[114:117]
	v_mfma_f32_16x16x32_bf16 v[102:105], v[176:179], v[200:203], v[102:105]
	v_mfma_f32_16x16x32_bf16 v[98:101], v[184:187], v[200:203], v[98:101]
	v_mfma_f32_16x16x32_bf16 v[86:89], v[176:179], v[208:211], v[86:89]
	v_mfma_f32_16x16x32_bf16 v[82:85], v[184:187], v[208:211], v[82:85]
	v_mfma_f32_16x16x32_bf16 v[70:73], v[176:179], v[216:219], v[70:73]
	v_mfma_f32_16x16x32_bf16 v[66:69], v[184:187], v[216:219], v[66:69]
	s_setprio 0
	s_barrier
; #define PG8_STAGE(bufoff, gbase, voff) do { _Pragma("unroll") for (int _i = 0; _i < 2; ++_i) \
;         __builtin_amdgcn_global_load_lds((const unsigned*)((const char*)(gbase) + (voff)[_i]), (PG8_LAS unsigned*)(lds + (bufoff) + ldsw + _i * 8192), 16, 0, 0); } while (0)
; #define PG8_LDA(dst, b, h) do { _Pragma("unroll") for (int m = 0; m < 4; ++m) _Pragma("unroll") for (int k = 0; k < 2; ++k) dst[m][k] = *(const PG8_LAS bf16x8*)(lds + PG8_SA(b, h) + aoff + m * 2048 + k * 1024); } while (0)
; #define PG8_MMA(ai, bj, At, Bt) do { __builtin_amdgcn_s_setprio(1); _Pragma("unroll") for (int m = 0; m < 4; ++m) _Pragma("unroll") for (int n = 0; n < 2; ++n) _Pragma("unroll") for (int k = 0; k < 2; ++k) \
;         acc[ai][bj][m][n] = __builtin_amdgcn_mfma_f32_16x16x32_bf16(Bt[n][k], At[m][k], acc[ai][bj][m][n], 0, 0, 0); __builtin_amdgcn_s_setprio(0); } while (0)
; #define PG8_WAIT_V(n) asm volatile("s_waitcnt vmcnt(" #n ")" ::: "memory")
; #define PG8_WAIT_L(n) asm volatile("s_waitcnt lgkmcnt(" #n ")" ::: "memory")
; #define PG8_BAR __builtin_amdgcn_s_barrier()
; #define PG8_SCHED __builtin_amdgcn_sched_barrier(0)
; template <class Epi, class Sched, bool ALIGN_EPI = false, bool SP2 = false>
; __device__ __forceinline__ void gemm_phase(PG8_LAS unsigned char* lds, const Gemm g, const Sched& S, const Epi& E) {
;     ...
;             PG8_LDA(At, 1, 1); PG8_STAGE(PG8_SB(1, 0), b3, voffB); PG8_STAGE(PG8_SB(1, 1), b3 + hstep, voffB); PG8_STAGE(PG8_SA(1, 0), a3, voffA);
;             PG8_WAIT_V(8); PG8_WAIT_L(0); PG8_BAR; PG8_MMA(1, 0, At, B0); PG8_MMA(1, 1, At, B1); PG8_BAR; PG8_SCHED;
	s_add_i32 s30, s70, s38
	v_lshl_add_u64 v[152:153], v[152:153], 0, s[20:21]
	s_mov_b32 m0, s30
	ds_read_b128 v[188:191], v147 offset:49152
	ds_read_b128 v[192:195], v147 offset:50176
	ds_read_b128 v[196:199], v147 offset:51200
	ds_read_b128 v[200:203], v147 offset:52224
	ds_read_b128 v[204:207], v147 offset:53248
	ds_read_b128 v[208:211], v147 offset:54272
	ds_read_b128 v[212:215], v147 offset:55296
	ds_read_b128 v[216:219], v147 offset:56320
	global_load_lds_dwordx4 v[152:153], off
	v_lshl_add_u64 v[152:153], v[220:221], 0, s[20:21]
	s_add_i32 m0, s30, 0x2000
	s_add_i32 s30, s71, s38
	global_load_lds_dwordx4 v[152:153], off
	v_lshl_add_u64 v[152:153], v[222:223], 0, s[20:21]
	s_mov_b32 m0, s30
	s_nop 0
	global_load_lds_dwordx4 v[152:153], off
	v_lshl_add_u64 v[152:153], v[224:225], 0, s[20:21]
	s_add_i32 m0, s30, 0x2000
	s_nop 0
	global_load_lds_dwordx4 v[152:153], off
	v_lshl_add_u64 v[152:153], v[226:227], 0, s[20:21]
	s_mov_b32 m0, s44
	s_nop 0
	global_load_lds_dwordx4 v[152:153], off
	v_lshl_add_u64 v[152:153], v[228:229], 0, s[20:21]
	s_mov_b32 m0, s45
	s_nop 0
	global_load_lds_dwordx4 v[152:153], off
	s_waitcnt vmcnt(8)
	s_waitcnt lgkmcnt(0)
	s_barrier
	s_setprio 1
	v_mfma_f32_16x16x32_bf16 v[62:65], v[156:159], v[188:191], v[62:65]
	v_mfma_f32_16x16x32_bf16 v[58:61], v[164:167], v[188:191], v[58:61]
	v_mfma_f32_16x16x32_bf16 v[46:49], v[156:159], v[196:199], v[46:49]
	v_mfma_f32_16x16x32_bf16 v[42:45], v[164:167], v[196:199], v[42:45]
	v_mfma_f32_16x16x32_bf16 v[30:33], v[156:159], v[204:207], v[30:33]
	v_mfma_f32_16x16x32_bf16 v[26:29], v[164:167], v[204:207], v[26:29]
	v_mfma_f32_16x16x32_bf16 v[14:17], v[156:159], v[212:215], v[14:17]
	v_mfma_f32_16x16x32_bf16 v[10:13], v[164:167], v[212:215], v[10:13]
	v_mfma_f32_16x16x32_bf16 v[62:65], v[160:163], v[192:195], v[62:65]
	v_mfma_f32_16x16x32_bf16 v[58:61], v[168:171], v[192:195], v[58:61]
	v_mfma_f32_16x16x32_bf16 v[46:49], v[160:163], v[200:203], v[46:49]
	v_mfma_f32_16x16x32_bf16 v[42:45], v[168:171], v[200:203], v[42:45]
	v_mfma_f32_16x16x32_bf16 v[30:33], v[160:163], v[208:211], v[30:33]
	v_mfma_f32_16x16x32_bf16 v[26:29], v[168:171], v[208:211], v[26:29]
	v_mfma_f32_16x16x32_bf16 v[14:17], v[160:163], v[216:219], v[14:17]
	v_mfma_f32_16x16x32_bf16 v[10:13], v[168:171], v[216:219], v[10:13]
	v_mfma_f32_16x16x32_bf16 v[54:57], v[172:175], v[188:191], v[54:57]
	v_mfma_f32_16x16x32_bf16 v[50:53], v[180:183], v[188:191], v[50:53]
	v_mfma_f32_16x16x32_bf16 v[38:41], v[172:175], v[196:199], v[38:41]
	v_mfma_f32_16x16x32_bf16 v[34:37], v[180:183], v[196:199], v[34:37]
	v_mfma_f32_16x16x32_bf16 v[22:25], v[172:175], v[204:207], v[22:25]
	v_mfma_f32_16x16x32_bf16 v[18:21], v[180:183], v[204:207], v[18:21]
	v_mfma_f32_16x16x32_bf16 v[6:9], v[172:175], v[212:215], v[6:9]
	v_mfma_f32_16x16x32_bf16 v[2:5], v[180:183], v[212:215], v[2:5]
	v_mfma_f32_16x16x32_bf16 v[54:57], v[176:179], v[192:195], v[54:57]
	v_mfma_f32_16x16x32_bf16 v[50:53], v[184:187], v[192:195], v[50:53]
	v_mfma_f32_16x16x32_bf16 v[38:41], v[176:179], v[200:203], v[38:41]
	v_mfma_f32_16x16x32_bf16 v[34:37], v[184:187], v[200:203], v[34:37]
	v_mfma_f32_16x16x32_bf16 v[22:25], v[176:179], v[208:211], v[22:25]
	v_mfma_f32_16x16x32_bf16 v[18:21], v[184:187], v[208:211], v[18:21]
	v_mfma_f32_16x16x32_bf16 v[6:9], v[176:179], v[216:219], v[6:9]
	v_mfma_f32_16x16x32_bf16 v[2:5], v[184:187], v[216:219], v[2:5]
	s_setprio 0
	s_barrier
	s_add_u32 s68, s68, 0x100
	s_addc_u32 s69, s69, 0
	s_add_u32 s28, s28, 0x100
	s_addc_u32 s29, s29, 0
	s_cmp_ge_i32 s80, s46
	s_mov_b32 s30, s80
	s_cbranch_scc0 .LBB0_1433

; #define PG8_STAGE(bufoff, gbase, voff) do { _Pragma("unroll") for (int _i = 0; _i < 2; ++_i) \
;         __builtin_amdgcn_global_load_lds((const unsigned*)((const char*)(gbase) + (voff)[_i]), (PG8_LAS unsigned*)(lds + (bufoff) + ldsw + _i * 8192), 16, 0, 0); } while (0)
; #define PG8_LDA(dst, b, h) do { _Pragma("unroll") for (int m = 0; m < 4; ++m) _Pragma("unroll") for (int k = 0; k < 2; ++k) dst[m][k] = *(const PG8_LAS bf16x8*)(lds + PG8_SA(b, h) + aoff + m * 2048 + k * 1024); } while (0)
; #define PG8_LDB(dst, b, h) do { _Pragma("unroll") for (int n = 0; n < 2; ++n) _Pragma("unroll") for (int k = 0; k < 2; ++k) dst[n][k] = *(const PG8_LAS bf16x8*)(lds + PG8_SB(b, h) + boff + n * 2048 + k * 1024); } while (0)
; #define PG8_MMA(ai, bj, At, Bt) do { __builtin_amdgcn_s_setprio(1); _Pragma("unroll") for (int m = 0; m < 4; ++m) _Pragma("unroll") for (int n = 0; n < 2; ++n) _Pragma("unroll") for (int k = 0; k < 2; ++k) \
;         acc[ai][bj][m][n] = __builtin_amdgcn_mfma_f32_16x16x32_bf16(Bt[n][k], At[m][k], acc[ai][bj][m][n], 0, 0, 0); __builtin_amdgcn_s_setprio(0); } while (0)
; #define PG8_WAIT_V(n) asm volatile("s_waitcnt vmcnt(" #n ")" ::: "memory")
; #define PG8_WAIT_L(n) asm volatile("s_waitcnt lgkmcnt(" #n ")" ::: "memory")
; #define PG8_BAR __builtin_amdgcn_s_barrier()
; #define PG8_SCHED __builtin_amdgcn_sched_barrier(0)
; template <class Epi, class Sched, bool ALIGN_EPI = false, bool SP2 = false>
; __device__ __forceinline__ void gemm_phase(PG8_LAS unsigned char* lds, const Gemm g, const Sched& S, const Epi& E) {
;     ...
;             PG8_LDB(B0, 0, 0); PG8_LDB(B1, 0, 1); PG8_SCHED; PG8_LDA(At, 0, 0); PG8_STAGE(PG8_SA(1, 1), a1 + hstep, voffA);
;             PG8_WAIT_V(8); PG8_WAIT_L(0); PG8_BAR; PG8_MMA(0, 0, At, B0); PG8_MMA(0, 1, At, B1); PG8_BAR; PG8_SCHED;
;             PG8_LDA(At, 0, 1); PG8_STAGE(PG8_SB(0, 0), b2, voffB); PG8_STAGE(PG8_SB(0, 1), b2 + hstep, voffB); PG8_STAGE(PG8_SA(0, 0), a2, voffA);
;             PG8_WAIT_V(8); PG8_WAIT_L(0); PG8_BAR; PG8_MMA(1, 0, At, B0); PG8_MMA(1, 1, At, B1); PG8_BAR; PG8_SCHED;
.LBB0_1518:
	ds_read_b128 v[146:149], v168
	ds_read_b128 v[172:175], v168 offset:1024
	ds_read_b128 v[176:179], v168 offset:2048
	ds_read_b128 v[180:183], v168 offset:3072
	ds_read_b128 v[184:187], v169
	ds_read_b128 v[188:191], v169 offset:1024
	ds_read_b128 v[192:195], v169 offset:2048
	ds_read_b128 v[196:199], v169 offset:3072
	s_add_i32 s88, s38, 2
	s_add_u32 s70, s36, 0x80
	s_addc_u32 s39, s37, 0
	s_cmp_eq_u32 s53, s38
	s_cselect_b32 s38, s4, s70
	s_cselect_b32 s39, s5, s39
	s_cselect_b32 s71, s35, s87
	s_cselect_b32 s70, s34, s86
	v_lshl_add_u64 v[150:151], s[36:37], 0, v[140:141]
	s_add_i32 m0, s43, 0xc000
	ds_read_b128 v[200:203], v170
	ds_read_b128 v[204:207], v170 offset:1024
	ds_read_b128 v[208:211], v170 offset:2048
	ds_read_b128 v[212:215], v170 offset:3072
	ds_read_b128 v[216:219], v170 offset:4096
	ds_read_b128 v[220:223], v170 offset:5120
	ds_read_b128 v[224:227], v170 offset:6144
	ds_read_b128 v[228:231], v170 offset:7168
	global_load_lds_dwordx4 v[150:151], off
	v_lshl_add_u64 v[150:151], s[36:37], 0, v[138:139]
	s_add_i32 m0, s43, 0xe000
	s_nop 0
	global_load_lds_dwordx4 v[150:151], off
	s_waitcnt vmcnt(8)
	s_waitcnt lgkmcnt(0)
	s_barrier
	s_setprio 1
	v_mfma_f32_16x16x32_bf16 v[122:125], v[146:149], v[200:203], v[122:125]
	v_mfma_f32_16x16x32_bf16 v[126:129], v[176:179], v[200:203], v[126:129]
	v_mfma_f32_16x16x32_bf16 v[110:113], v[146:149], v[208:211], v[110:113]
	v_mfma_f32_16x16x32_bf16 v[106:109], v[176:179], v[208:211], v[106:109]
	v_mfma_f32_16x16x32_bf16 v[94:97], v[146:149], v[216:219], v[94:97]
	v_mfma_f32_16x16x32_bf16 v[90:93], v[176:179], v[216:219], v[90:93]
	v_mfma_f32_16x16x32_bf16 v[78:81], v[146:149], v[224:227], v[78:81]
	v_mfma_f32_16x16x32_bf16 v[74:77], v[176:179], v[224:227], v[74:77]
	v_mfma_f32_16x16x32_bf16 v[122:125], v[172:175], v[204:207], v[122:125]
	v_mfma_f32_16x16x32_bf16 v[126:129], v[180:183], v[204:207], v[126:129]
	v_mfma_f32_16x16x32_bf16 v[110:113], v[172:175], v[212:215], v[110:113]
	v_mfma_f32_16x16x32_bf16 v[106:109], v[180:183], v[212:215], v[106:109]
	v_mfma_f32_16x16x32_bf16 v[94:97], v[172:175], v[220:223], v[94:97]
	v_mfma_f32_16x16x32_bf16 v[90:93], v[180:183], v[220:223], v[90:93]
	v_mfma_f32_16x16x32_bf16 v[78:81], v[172:175], v[228:231], v[78:81]
	v_mfma_f32_16x16x32_bf16 v[74:77], v[180:183], v[228:231], v[74:77]
	v_mfma_f32_16x16x32_bf16 v[118:121], v[184:187], v[200:203], v[118:121]
	v_mfma_f32_16x16x32_bf16 v[114:117], v[192:195], v[200:203], v[114:117]
	v_mfma_f32_16x16x32_bf16 v[102:105], v[184:187], v[208:211], v[102:105]
	v_mfma_f32_16x16x32_bf16 v[98:101], v[192:195], v[208:211], v[98:101]
	v_mfma_f32_16x16x32_bf16 v[86:89], v[184:187], v[216:219], v[86:89]
	v_mfma_f32_16x16x32_bf16 v[82:85], v[192:195], v[216:219], v[82:85]
	v_mfma_f32_16x16x32_bf16 v[70:73], v[184:187], v[224:227], v[70:73]
	v_mfma_f32_16x16x32_bf16 v[66:69], v[192:195], v[224:227], v[66:69]
	v_mfma_f32_16x16x32_bf16 v[118:121], v[188:191], v[204:207], v[118:121]
	v_mfma_f32_16x16x32_bf16 v[114:117], v[196:199], v[204:207], v[114:117]
	v_mfma_f32_16x16x32_bf16 v[102:105], v[188:191], v[212:215], v[102:105]
	v_mfma_f32_16x16x32_bf16 v[98:101], v[196:199], v[212:215], v[98:101]
	v_mfma_f32_16x16x32_bf16 v[86:89], v[188:191], v[220:223], v[86:89]
	v_mfma_f32_16x16x32_bf16 v[82:85], v[196:199], v[220:223], v[82:85]
	v_mfma_f32_16x16x32_bf16 v[70:73], v[188:191], v[228:231], v[70:73]
	v_mfma_f32_16x16x32_bf16 v[66:69], v[196:199], v[228:231], v[66:69]
	s_setprio 0
	s_barrier
	s_add_i32 s72, s56, s42
	v_lshl_add_u64 v[150:151], s[70:71], 0, v[132:133]
	s_mov_b32 m0, s72
	ds_read_b128 v[200:203], v170 offset:16384
	ds_read_b128 v[204:207], v170 offset:17408
	ds_read_b128 v[208:211], v170 offset:18432
	ds_read_b128 v[212:215], v170 offset:19456
	ds_read_b128 v[216:219], v170 offset:20480
	ds_read_b128 v[220:223], v170 offset:21504
	ds_read_b128 v[224:227], v170 offset:22528
	ds_read_b128 v[228:231], v170 offset:23552
	global_load_lds_dwordx4 v[150:151], off
	s_add_i32 m0, s72, 0x2000
	v_lshl_add_u64 v[232:233], s[70:71], 0, v[136:137]
	s_add_u32 s70, s70, s14
	s_addc_u32 s71, s71, s15
	s_add_i32 s72, s57, s42
	global_load_lds_dwordx4 v[232:233], off
	v_lshl_add_u64 v[234:235], s[70:71], 0, v[132:133]
	s_mov_b32 m0, s72
	v_lshl_add_u64 v[236:237], s[70:71], 0, v[136:137]
	global_load_lds_dwordx4 v[234:235], off
	s_add_i32 m0, s72, 0x2000
	v_lshl_add_u64 v[238:239], s[38:39], 0, v[130:131]
	global_load_lds_dwordx4 v[236:237], off
	s_mov_b32 m0, s43
	v_lshl_add_u64 v[240:241], s[38:39], 0, v[134:135]
	global_load_lds_dwordx4 v[238:239], off
	s_mov_b32 m0, s44
	s_nop 0
	global_load_lds_dwordx4 v[240:241], off
	s_waitcnt vmcnt(8)
	s_waitcnt lgkmcnt(0)
	s_barrier
; #define PG8_STAGE(bufoff, gbase, voff) do { _Pragma("unroll") for (int _i = 0; _i < 2; ++_i) \
;         __builtin_amdgcn_global_load_lds((const unsigned*)((const char*)(gbase) + (voff)[_i]), (PG8_LAS unsigned*)(lds + (bufoff) + ldsw + _i * 8192), 16, 0, 0); } while (0)
; #define PG8_LDA(dst, b, h) do { _Pragma("unroll") for (int m = 0; m < 4; ++m) _Pragma("unroll") for (int k = 0; k < 2; ++k) dst[m][k] = *(const PG8_LAS bf16x8*)(lds + PG8_SA(b, h) + aoff + m * 2048 + k * 1024); } while (0)
; #define PG8_LDB(dst, b, h) do { _Pragma("unroll") for (int n = 0; n < 2; ++n) _Pragma("unroll") for (int k = 0; k < 2; ++k) dst[n][k] = *(const PG8_LAS bf16x8*)(lds + PG8_SB(b, h) + boff + n * 2048 + k * 1024); } while (0)
; #define PG8_MMA(ai, bj, At, Bt) do { __builtin_amdgcn_s_setprio(1); _Pragma("unroll") for (int m = 0; m < 4; ++m) _Pragma("unroll") for (int n = 0; n < 2; ++n) _Pragma("unroll") for (int k = 0; k < 2; ++k) \
;         acc[ai][bj][m][n] = __builtin_amdgcn_mfma_f32_16x16x32_bf16(Bt[n][k], At[m][k], acc[ai][bj][m][n], 0, 0, 0); __builtin_amdgcn_s_setprio(0); } while (0)
; #define PG8_WAIT_V(n) asm volatile("s_waitcnt vmcnt(" #n ")" ::: "memory")
; #define PG8_WAIT_L(n) asm volatile("s_waitcnt lgkmcnt(" #n ")" ::: "memory")
; #define PG8_BAR __builtin_amdgcn_s_barrier()
; #define PG8_SCHED __builtin_amdgcn_sched_barrier(0)
; template <class Epi, class Sched, bool ALIGN_EPI = false, bool SP2 = false>
; __device__ __forceinline__ void gemm_phase(PG8_LAS unsigned char* lds, const Gemm g, const Sched& S, const Epi& E) {
;     ...
;             PG8_WAIT_V(8); PG8_WAIT_L(0); PG8_BAR; PG8_MMA(1, 0, At, B0); PG8_MMA(1, 1, At, B1); PG8_BAR; PG8_SCHED;
;             PG8_LDB(B0, 1, 0); PG8_LDB(B1, 1, 1); PG8_SCHED; PG8_LDA(At, 1, 0); PG8_STAGE(PG8_SA(0, 1), a2 + hstep, voffA);
;             PG8_WAIT_V(8); PG8_WAIT_L(0); PG8_BAR; PG8_MMA(0, 0, At, B0); PG8_MMA(0, 1, At, B1); PG8_BAR; PG8_SCHED;
	s_setprio 1
	v_mfma_f32_16x16x32_bf16 v[62:65], v[146:149], v[200:203], v[62:65]
	v_mfma_f32_16x16x32_bf16 v[58:61], v[176:179], v[200:203], v[58:61]
	v_mfma_f32_16x16x32_bf16 v[46:49], v[146:149], v[208:211], v[46:49]
	v_mfma_f32_16x16x32_bf16 v[42:45], v[176:179], v[208:211], v[42:45]
	v_mfma_f32_16x16x32_bf16 v[30:33], v[146:149], v[216:219], v[30:33]
	v_mfma_f32_16x16x32_bf16 v[26:29], v[176:179], v[216:219], v[26:29]
	v_mfma_f32_16x16x32_bf16 v[14:17], v[146:149], v[224:227], v[14:17]
	v_mfma_f32_16x16x32_bf16 v[10:13], v[176:179], v[224:227], v[10:13]
	v_mfma_f32_16x16x32_bf16 v[62:65], v[172:175], v[204:207], v[62:65]
	v_mfma_f32_16x16x32_bf16 v[58:61], v[180:183], v[204:207], v[58:61]
	v_mfma_f32_16x16x32_bf16 v[46:49], v[172:175], v[212:215], v[46:49]
	v_mfma_f32_16x16x32_bf16 v[42:45], v[180:183], v[212:215], v[42:45]
	v_mfma_f32_16x16x32_bf16 v[30:33], v[172:175], v[220:223], v[30:33]
	v_mfma_f32_16x16x32_bf16 v[26:29], v[180:183], v[220:223], v[26:29]
	v_mfma_f32_16x16x32_bf16 v[14:17], v[172:175], v[228:231], v[14:17]
	v_mfma_f32_16x16x32_bf16 v[10:13], v[180:183], v[228:231], v[10:13]
	v_mfma_f32_16x16x32_bf16 v[54:57], v[184:187], v[200:203], v[54:57]
	v_mfma_f32_16x16x32_bf16 v[50:53], v[192:195], v[200:203], v[50:53]
	v_mfma_f32_16x16x32_bf16 v[38:41], v[184:187], v[208:211], v[38:41]
	v_mfma_f32_16x16x32_bf16 v[34:37], v[192:195], v[208:211], v[34:37]
	v_mfma_f32_16x16x32_bf16 v[22:25], v[184:187], v[216:219], v[22:25]
	v_mfma_f32_16x16x32_bf16 v[18:21], v[192:195], v[216:219], v[18:21]
	v_mfma_f32_16x16x32_bf16 v[6:9], v[184:187], v[224:227], v[6:9]
	v_mfma_f32_16x16x32_bf16 v[2:5], v[192:195], v[224:227], v[2:5]
	v_mfma_f32_16x16x32_bf16 v[54:57], v[188:191], v[204:207], v[54:57]
	v_mfma_f32_16x16x32_bf16 v[50:53], v[196:199], v[204:207], v[50:53]
	v_mfma_f32_16x16x32_bf16 v[38:41], v[188:191], v[212:215], v[38:41]
	v_mfma_f32_16x16x32_bf16 v[34:37], v[196:199], v[212:215], v[34:37]
	v_mfma_f32_16x16x32_bf16 v[22:25], v[188:191], v[220:223], v[22:25]
	v_mfma_f32_16x16x32_bf16 v[18:21], v[196:199], v[220:223], v[18:21]
	v_mfma_f32_16x16x32_bf16 v[6:9], v[188:191], v[228:231], v[6:9]
	v_mfma_f32_16x16x32_bf16 v[2:5], v[196:199], v[228:231], v[2:5]
	s_setprio 0
	s_barrier
	s_add_i32 s70, 0, 0x18000
	v_add_u32_e32 v171, s70, v166
	s_add_i32 s71, 0, 0x1c000
	ds_read_b128 v[146:149], v171
	ds_read_b128 v[172:175], v171 offset:1024
	ds_read_b128 v[176:179], v171 offset:2048
	ds_read_b128 v[180:183], v171 offset:3072
	v_add_u32_e32 v171, s71, v166
	ds_read_b128 v[184:187], v171
	ds_read_b128 v[188:191], v171 offset:1024
	ds_read_b128 v[192:195], v171 offset:2048
	ds_read_b128 v[196:199], v171 offset:3072
	s_add_u32 s38, s38, s14
	s_addc_u32 s39, s39, s15
	s_mov_b32 m0, s45
	v_lshl_add_u64 v[242:243], s[38:39], 0, v[130:131]
	ds_read_b128 v[200:203], v170 offset:32768
	ds_read_b128 v[204:207], v170 offset:33792
	ds_read_b128 v[208:211], v170 offset:34816
	ds_read_b128 v[212:215], v170 offset:35840
	ds_read_b128 v[216:219], v170 offset:36864
	ds_read_b128 v[220:223], v170 offset:37888
	ds_read_b128 v[224:227], v170 offset:38912
	ds_read_b128 v[228:231], v170 offset:39936
	global_load_lds_dwordx4 v[242:243], off
	v_lshl_add_u64 v[242:243], s[38:39], 0, v[134:135]
	s_mov_b32 m0, s46
	s_nop 0
	global_load_lds_dwordx4 v[242:243], off
	s_waitcnt vmcnt(8)
	s_waitcnt lgkmcnt(0)
	s_barrier
	s_setprio 1
	v_mfma_f32_16x16x32_bf16 v[122:125], v[146:149], v[200:203], v[122:125]
	v_mfma_f32_16x16x32_bf16 v[126:129], v[176:179], v[200:203], v[126:129]
	v_mfma_f32_16x16x32_bf16 v[110:113], v[146:149], v[208:211], v[110:113]
	v_mfma_f32_16x16x32_bf16 v[106:109], v[176:179], v[208:211], v[106:109]
	v_mfma_f32_16x16x32_bf16 v[94:97], v[146:149], v[216:219], v[94:97]
	v_mfma_f32_16x16x32_bf16 v[90:93], v[176:179], v[216:219], v[90:93]
	v_mfma_f32_16x16x32_bf16 v[78:81], v[146:149], v[224:227], v[78:81]
	v_mfma_f32_16x16x32_bf16 v[74:77], v[176:179], v[224:227], v[74:77]
	v_mfma_f32_16x16x32_bf16 v[122:125], v[172:175], v[204:207], v[122:125]
	v_mfma_f32_16x16x32_bf16 v[126:129], v[180:183], v[204:207], v[126:129]
	v_mfma_f32_16x16x32_bf16 v[110:113], v[172:175], v[212:215], v[110:113]
	v_mfma_f32_16x16x32_bf16 v[106:109], v[180:183], v[212:215], v[106:109]
	v_mfma_f32_16x16x32_bf16 v[94:97], v[172:175], v[220:223], v[94:97]
	v_mfma_f32_16x16x32_bf16 v[90:93], v[180:183], v[220:223], v[90:93]
	v_mfma_f32_16x16x32_bf16 v[78:81], v[172:175], v[228:231], v[78:81]
	v_mfma_f32_16x16x32_bf16 v[74:77], v[180:183], v[228:231], v[74:77]
	v_mfma_f32_16x16x32_bf16 v[118:121], v[184:187], v[200:203], v[118:121]
	v_mfma_f32_16x16x32_bf16 v[114:117], v[192:195], v[200:203], v[114:117]
	v_mfma_f32_16x16x32_bf16 v[102:105], v[184:187], v[208:211], v[102:105]
	v_mfma_f32_16x16x32_bf16 v[98:101], v[192:195], v[208:211], v[98:101]
	v_mfma_f32_16x16x32_bf16 v[86:89], v[184:187], v[216:219], v[86:89]
	v_mfma_f32_16x16x32_bf16 v[82:85], v[192:195], v[216:219], v[82:85]
	v_mfma_f32_16x16x32_bf16 v[70:73], v[184:187], v[224:227], v[70:73]
	v_mfma_f32_16x16x32_bf16 v[66:69], v[192:195], v[224:227], v[66:69]
	v_mfma_f32_16x16x32_bf16 v[118:121], v[188:191], v[204:207], v[118:121]
	v_mfma_f32_16x16x32_bf16 v[114:117], v[196:199], v[204:207], v[114:117]
	v_mfma_f32_16x16x32_bf16 v[102:105], v[188:191], v[212:215], v[102:105]
	v_mfma_f32_16x16x32_bf16 v[98:101], v[196:199], v[212:215], v[98:101]
	v_mfma_f32_16x16x32_bf16 v[86:89], v[188:191], v[220:223], v[86:89]
	v_mfma_f32_16x16x32_bf16 v[82:85], v[196:199], v[220:223], v[82:85]
	v_mfma_f32_16x16x32_bf16 v[70:73], v[188:191], v[228:231], v[70:73]
	v_mfma_f32_16x16x32_bf16 v[66:69], v[196:199], v[228:231], v[66:69]
	s_setprio 0
	s_barrier
; #define PG8_STAGE(bufoff, gbase, voff) do { _Pragma("unroll") for (int _i = 0; _i < 2; ++_i) \
;         __builtin_amdgcn_global_load_lds((const unsigned*)((const char*)(gbase) + (voff)[_i]), (PG8_LAS unsigned*)(lds + (bufoff) + ldsw + _i * 8192), 16, 0, 0); } while (0)
; #define PG8_LDA(dst, b, h) do { _Pragma("unroll") for (int m = 0; m < 4; ++m) _Pragma("unroll") for (int k = 0; k < 2; ++k) dst[m][k] = *(const PG8_LAS bf16x8*)(lds + PG8_SA(b, h) + aoff + m * 2048 + k * 1024); } while (0)
; #define PG8_MMA(ai, bj, At, Bt) do { __builtin_amdgcn_s_setprio(1); _Pragma("unroll") for (int m = 0; m < 4; ++m) _Pragma("unroll") for (int n = 0; n < 2; ++n) _Pragma("unroll") for (int k = 0; k < 2; ++k) \
;         acc[ai][bj][m][n] = __builtin_amdgcn_mfma_f32_16x16x32_bf16(Bt[n][k], At[m][k], acc[ai][bj][m][n], 0, 0, 0); __builtin_amdgcn_s_setprio(0); } while (0)
; #define PG8_WAIT_V(n) asm volatile("s_waitcnt vmcnt(" #n ")" ::: "memory")
; #define PG8_WAIT_L(n) asm volatile("s_waitcnt lgkmcnt(" #n ")" ::: "memory")
; #define PG8_BAR __builtin_amdgcn_s_barrier()
; #define PG8_SCHED __builtin_amdgcn_sched_barrier(0)
; template <class Epi, class Sched, bool ALIGN_EPI = false, bool SP2 = false>
; __device__ __forceinline__ void gemm_phase(PG8_LAS unsigned char* lds, const Gemm g, const Sched& S, const Epi& E) {
;     ...
;             PG8_LDA(At, 1, 1); PG8_STAGE(PG8_SB(1, 0), b3, voffB); PG8_STAGE(PG8_SB(1, 1), b3 + hstep, voffB); PG8_STAGE(PG8_SA(1, 0), a3, voffA);
;             PG8_WAIT_V(8); PG8_WAIT_L(0); PG8_BAR; PG8_MMA(1, 0, At, B0); PG8_MMA(1, 1, At, B1); PG8_BAR; PG8_SCHED;
	s_add_i32 s38, s70, s42
	v_lshl_add_u64 v[150:151], v[150:151], 0, s[24:25]
	s_mov_b32 m0, s38
	ds_read_b128 v[200:203], v170 offset:49152
	ds_read_b128 v[204:207], v170 offset:50176
	ds_read_b128 v[208:211], v170 offset:51200
	ds_read_b128 v[212:215], v170 offset:52224
	ds_read_b128 v[216:219], v170 offset:53248
	ds_read_b128 v[220:223], v170 offset:54272
	ds_read_b128 v[224:227], v170 offset:55296
	ds_read_b128 v[228:231], v170 offset:56320
	global_load_lds_dwordx4 v[150:151], off
	v_lshl_add_u64 v[150:151], v[232:233], 0, s[24:25]
	s_add_i32 m0, s38, 0x2000
	s_add_i32 s38, s71, s42
	global_load_lds_dwordx4 v[150:151], off
	v_lshl_add_u64 v[150:151], v[234:235], 0, s[24:25]
	s_mov_b32 m0, s38
	s_nop 0
	global_load_lds_dwordx4 v[150:151], off
	v_lshl_add_u64 v[150:151], v[236:237], 0, s[24:25]
	s_add_i32 m0, s38, 0x2000
	s_nop 0
	global_load_lds_dwordx4 v[150:151], off
	v_lshl_add_u64 v[150:151], v[238:239], 0, s[24:25]
	s_mov_b32 m0, s48
	s_nop 0
	global_load_lds_dwordx4 v[150:151], off
	v_lshl_add_u64 v[150:151], v[240:241], 0, s[24:25]
	s_mov_b32 m0, s49
	s_nop 0
	global_load_lds_dwordx4 v[150:151], off
	s_waitcnt vmcnt(8)
	s_waitcnt lgkmcnt(0)
	s_barrier
	s_setprio 1
	v_mfma_f32_16x16x32_bf16 v[62:65], v[146:149], v[200:203], v[62:65]
	v_mfma_f32_16x16x32_bf16 v[58:61], v[176:179], v[200:203], v[58:61]
	v_mfma_f32_16x16x32_bf16 v[46:49], v[146:149], v[208:211], v[46:49]
	v_mfma_f32_16x16x32_bf16 v[42:45], v[176:179], v[208:211], v[42:45]
	v_mfma_f32_16x16x32_bf16 v[30:33], v[146:149], v[216:219], v[30:33]
	v_mfma_f32_16x16x32_bf16 v[26:29], v[176:179], v[216:219], v[26:29]
	v_mfma_f32_16x16x32_bf16 v[14:17], v[146:149], v[224:227], v[14:17]
	v_mfma_f32_16x16x32_bf16 v[10:13], v[176:179], v[224:227], v[10:13]
	v_mfma_f32_16x16x32_bf16 v[62:65], v[172:175], v[204:207], v[62:65]
	v_mfma_f32_16x16x32_bf16 v[58:61], v[180:183], v[204:207], v[58:61]
	v_mfma_f32_16x16x32_bf16 v[46:49], v[172:175], v[212:215], v[46:49]
	v_mfma_f32_16x16x32_bf16 v[42:45], v[180:183], v[212:215], v[42:45]
	v_mfma_f32_16x16x32_bf16 v[30:33], v[172:175], v[220:223], v[30:33]
	v_mfma_f32_16x16x32_bf16 v[26:29], v[180:183], v[220:223], v[26:29]
	v_mfma_f32_16x16x32_bf16 v[14:17], v[172:175], v[228:231], v[14:17]
	v_mfma_f32_16x16x32_bf16 v[10:13], v[180:183], v[228:231], v[10:13]
	v_mfma_f32_16x16x32_bf16 v[54:57], v[184:187], v[200:203], v[54:57]
	v_mfma_f32_16x16x32_bf16 v[50:53], v[192:195], v[200:203], v[50:53]
	v_mfma_f32_16x16x32_bf16 v[38:41], v[184:187], v[208:211], v[38:41]
	v_mfma_f32_16x16x32_bf16 v[34:37], v[192:195], v[208:211], v[34:37]
	v_mfma_f32_16x16x32_bf16 v[22:25], v[184:187], v[216:219], v[22:25]
	v_mfma_f32_16x16x32_bf16 v[18:21], v[192:195], v[216:219], v[18:21]
	v_mfma_f32_16x16x32_bf16 v[6:9], v[184:187], v[224:227], v[6:9]
	v_mfma_f32_16x16x32_bf16 v[2:5], v[192:195], v[224:227], v[2:5]
	v_mfma_f32_16x16x32_bf16 v[54:57], v[188:191], v[204:207], v[54:57]
	v_mfma_f32_16x16x32_bf16 v[50:53], v[196:199], v[204:207], v[50:53]
	v_mfma_f32_16x16x32_bf16 v[38:41], v[188:191], v[212:215], v[38:41]
	v_mfma_f32_16x16x32_bf16 v[34:37], v[196:199], v[212:215], v[34:37]
	v_mfma_f32_16x16x32_bf16 v[22:25], v[188:191], v[220:223], v[22:25]
	v_mfma_f32_16x16x32_bf16 v[18:21], v[196:199], v[220:223], v[18:21]
	v_mfma_f32_16x16x32_bf16 v[6:9], v[188:191], v[228:231], v[6:9]
	v_mfma_f32_16x16x32_bf16 v[2:5], v[196:199], v[228:231], v[2:5]
	s_setprio 0
	s_barrier
	s_add_u32 s86, s86, 0x100
	s_addc_u32 s87, s87, 0
	s_add_u32 s36, s36, 0x100
	s_addc_u32 s37, s37, 0
	s_cmp_ge_i32 s88, s52
	s_mov_b32 s38, s88
	s_cbranch_scc0 .LBB0_1518
	v_readlane_b32 s74, v244, 3
	v_readlane_b32 s88, v244, 5
	v_readlane_b32 s75, v244, 4
	v_readlane_b32 s90, v244, 7
	v_readlane_b32 s91, v244, 8
	v_readlane_b32 s92, v244, 9
	v_readlane_b32 s93, v244, 10
	v_readlane_b32 s94, v244, 11
	v_readlane_b32 s95, v244, 12
	v_readlane_b32 s89, v244, 6

; #define PG8_STAGE(bufoff, gbase, voff) do { _Pragma("unroll") for (int _i = 0; _i < 2; ++_i) \
;         __builtin_amdgcn_global_load_lds((const unsigned*)((const char*)(gbase) + (voff)[_i]), (PG8_LAS unsigned*)(lds + (bufoff) + ldsw + _i * 8192), 16, 0, 0); } while (0)
; #define PG8_LDA(dst, b, h) do { _Pragma("unroll") for (int m = 0; m < 4; ++m) _Pragma("unroll") for (int k = 0; k < 2; ++k) dst[m][k] = *(const PG8_LAS bf16x8*)(lds + PG8_SA(b, h) + aoff + m * 2048 + k * 1024); } while (0)
; #define PG8_LDB(dst, b, h) do { _Pragma("unroll") for (int n = 0; n < 2; ++n) _Pragma("unroll") for (int k = 0; k < 2; ++k) dst[n][k] = *(const PG8_LAS bf16x8*)(lds + PG8_SB(b, h) + boff + n * 2048 + k * 1024); } while (0)
; #define PG8_MMA(ai, bj, At, Bt) do { __builtin_amdgcn_s_setprio(1); _Pragma("unroll") for (int m = 0; m < 4; ++m) _Pragma("unroll") for (int n = 0; n < 2; ++n) _Pragma("unroll") for (int k = 0; k < 2; ++k) \
;         acc[ai][bj][m][n] = __builtin_amdgcn_mfma_f32_16x16x32_bf16(Bt[n][k], At[m][k], acc[ai][bj][m][n], 0, 0, 0); __builtin_amdgcn_s_setprio(0); } while (0)
; #define PG8_WAIT_V(n) asm volatile("s_waitcnt vmcnt(" #n ")" ::: "memory")
; #define PG8_WAIT_L(n) asm volatile("s_waitcnt lgkmcnt(" #n ")" ::: "memory")
; #define PG8_BAR __builtin_amdgcn_s_barrier()
; #define PG8_SCHED __builtin_amdgcn_sched_barrier(0)
; template <class Epi, class Sched, bool ALIGN_EPI = false, bool SP2 = false>
; __device__ __forceinline__ void gemm_phase(PG8_LAS unsigned char* lds, const Gemm g, const Sched& S, const Epi& E) {
;     ...
;             PG8_LDB(B0, 0, 0); PG8_LDB(B1, 0, 1); PG8_SCHED; PG8_LDA(At, 0, 0); PG8_STAGE(PG8_SA(1, 1), a1 + hstep, voffA);
;             PG8_WAIT_V(8); PG8_WAIT_L(0); PG8_BAR; PG8_MMA(0, 0, At, B0); PG8_MMA(0, 1, At, B1); PG8_BAR; PG8_SCHED;
;             PG8_LDA(At, 0, 1); PG8_STAGE(PG8_SB(0, 0), b2, voffB); PG8_STAGE(PG8_SB(0, 1), b2 + hstep, voffB); PG8_STAGE(PG8_SA(0, 0), a2, voffA);
;             PG8_WAIT_V(8); PG8_WAIT_L(0); PG8_BAR; PG8_MMA(1, 0, At, B0); PG8_MMA(1, 1, At, B1); PG8_BAR; PG8_SCHED;
.LBB0_1548:
	ds_read_b128 v[146:149], v1
	ds_read_b128 v[162:165], v1 offset:1024
	ds_read_b128 v[166:169], v1 offset:2048
	ds_read_b128 v[170:173], v1 offset:3072
	ds_read_b128 v[174:177], v152
	ds_read_b128 v[178:181], v152 offset:1024
	ds_read_b128 v[182:185], v152 offset:2048
	ds_read_b128 v[186:189], v152 offset:3072
	s_add_i32 s68, s28, 2
	s_add_u32 s69, s26, 0x80
	s_addc_u32 s29, s27, 0
	s_cmp_eq_u32 s45, s28
	s_cselect_b32 s28, s4, s69
	s_cselect_b32 s29, s5, s29
	s_cselect_b32 s71, s9, s57
	s_cselect_b32 s70, s8, s56
	v_lshl_add_u64 v[150:151], s[26:27], 0, v[140:141]
	s_add_i32 m0, s37, 0xc000
	ds_read_b128 v[190:193], v153
	ds_read_b128 v[194:197], v153 offset:1024
	ds_read_b128 v[198:201], v153 offset:2048
	ds_read_b128 v[202:205], v153 offset:3072
	ds_read_b128 v[206:209], v153 offset:4096
	ds_read_b128 v[210:213], v153 offset:5120
	ds_read_b128 v[214:217], v153 offset:6144
	ds_read_b128 v[218:221], v153 offset:7168
	global_load_lds_dwordx4 v[150:151], off
	v_lshl_add_u64 v[150:151], s[26:27], 0, v[138:139]
	s_add_i32 m0, s37, 0xe000
	s_nop 0
	global_load_lds_dwordx4 v[150:151], off
	s_waitcnt vmcnt(8)
	s_waitcnt lgkmcnt(0)
	s_barrier
	s_setprio 1
	v_mfma_f32_16x16x32_bf16 v[122:125], v[146:149], v[190:193], v[122:125]
	v_mfma_f32_16x16x32_bf16 v[126:129], v[166:169], v[190:193], v[126:129]
	v_mfma_f32_16x16x32_bf16 v[110:113], v[146:149], v[198:201], v[110:113]
	v_mfma_f32_16x16x32_bf16 v[106:109], v[166:169], v[198:201], v[106:109]
	v_mfma_f32_16x16x32_bf16 v[94:97], v[146:149], v[206:209], v[94:97]
	v_mfma_f32_16x16x32_bf16 v[90:93], v[166:169], v[206:209], v[90:93]
	v_mfma_f32_16x16x32_bf16 v[78:81], v[146:149], v[214:217], v[78:81]
	v_mfma_f32_16x16x32_bf16 v[74:77], v[166:169], v[214:217], v[74:77]
	v_mfma_f32_16x16x32_bf16 v[122:125], v[162:165], v[194:197], v[122:125]
	v_mfma_f32_16x16x32_bf16 v[126:129], v[170:173], v[194:197], v[126:129]
	v_mfma_f32_16x16x32_bf16 v[110:113], v[162:165], v[202:205], v[110:113]
	v_mfma_f32_16x16x32_bf16 v[106:109], v[170:173], v[202:205], v[106:109]
	v_mfma_f32_16x16x32_bf16 v[94:97], v[162:165], v[210:213], v[94:97]
	v_mfma_f32_16x16x32_bf16 v[90:93], v[170:173], v[210:213], v[90:93]
	v_mfma_f32_16x16x32_bf16 v[78:81], v[162:165], v[218:221], v[78:81]
	v_mfma_f32_16x16x32_bf16 v[74:77], v[170:173], v[218:221], v[74:77]
	v_mfma_f32_16x16x32_bf16 v[118:121], v[174:177], v[190:193], v[118:121]
	v_mfma_f32_16x16x32_bf16 v[114:117], v[182:185], v[190:193], v[114:117]
	v_mfma_f32_16x16x32_bf16 v[102:105], v[174:177], v[198:201], v[102:105]
	v_mfma_f32_16x16x32_bf16 v[98:101], v[182:185], v[198:201], v[98:101]
	v_mfma_f32_16x16x32_bf16 v[86:89], v[174:177], v[206:209], v[86:89]
	v_mfma_f32_16x16x32_bf16 v[82:85], v[182:185], v[206:209], v[82:85]
	v_mfma_f32_16x16x32_bf16 v[70:73], v[174:177], v[214:217], v[70:73]
	v_mfma_f32_16x16x32_bf16 v[66:69], v[182:185], v[214:217], v[66:69]
	v_mfma_f32_16x16x32_bf16 v[118:121], v[178:181], v[194:197], v[118:121]
	v_mfma_f32_16x16x32_bf16 v[114:117], v[186:189], v[194:197], v[114:117]
	v_mfma_f32_16x16x32_bf16 v[102:105], v[178:181], v[202:205], v[102:105]
	v_mfma_f32_16x16x32_bf16 v[98:101], v[186:189], v[202:205], v[98:101]
	v_mfma_f32_16x16x32_bf16 v[86:89], v[178:181], v[210:213], v[86:89]
	v_mfma_f32_16x16x32_bf16 v[82:85], v[186:189], v[210:213], v[82:85]
	v_mfma_f32_16x16x32_bf16 v[70:73], v[178:181], v[218:221], v[70:73]
	v_mfma_f32_16x16x32_bf16 v[66:69], v[186:189], v[218:221], v[66:69]
	s_setprio 0
	s_barrier
	s_add_i32 s69, s48, s36
	v_lshl_add_u64 v[150:151], s[70:71], 0, v[132:133]
	s_mov_b32 m0, s69
	ds_read_b128 v[190:193], v153 offset:16384
	ds_read_b128 v[194:197], v153 offset:17408
	ds_read_b128 v[198:201], v153 offset:18432
	ds_read_b128 v[202:205], v153 offset:19456
	ds_read_b128 v[206:209], v153 offset:20480
	ds_read_b128 v[210:213], v153 offset:21504
	ds_read_b128 v[214:217], v153 offset:22528
	ds_read_b128 v[218:221], v153 offset:23552
	global_load_lds_dwordx4 v[150:151], off
	s_add_i32 m0, s69, 0x2000
	v_lshl_add_u64 v[158:159], s[70:71], 0, v[136:137]
	s_add_u32 s70, s70, s10
	s_addc_u32 s71, s71, s11
	s_add_i32 s69, s49, s36
	global_load_lds_dwordx4 v[158:159], off
	v_lshl_add_u64 v[222:223], s[70:71], 0, v[132:133]
	s_mov_b32 m0, s69
	v_lshl_add_u64 v[224:225], s[70:71], 0, v[136:137]
	global_load_lds_dwordx4 v[222:223], off
	s_add_i32 m0, s69, 0x2000
	v_lshl_add_u64 v[226:227], s[28:29], 0, v[130:131]
	global_load_lds_dwordx4 v[224:225], off
	s_mov_b32 m0, s37
	v_lshl_add_u64 v[228:229], s[28:29], 0, v[134:135]
	global_load_lds_dwordx4 v[226:227], off
	s_mov_b32 m0, s38
	s_nop 0
	global_load_lds_dwordx4 v[228:229], off
	s_waitcnt vmcnt(8)
	s_waitcnt lgkmcnt(0)
	s_barrier
; #define PG8_STAGE(bufoff, gbase, voff) do { _Pragma("unroll") for (int _i = 0; _i < 2; ++_i) \
;         __builtin_amdgcn_global_load_lds((const unsigned*)((const char*)(gbase) + (voff)[_i]), (PG8_LAS unsigned*)(lds + (bufoff) + ldsw + _i * 8192), 16, 0, 0); } while (0)
; #define PG8_LDA(dst, b, h) do { _Pragma("unroll") for (int m = 0; m < 4; ++m) _Pragma("unroll") for (int k = 0; k < 2; ++k) dst[m][k] = *(const PG8_LAS bf16x8*)(lds + PG8_SA(b, h) + aoff + m * 2048 + k * 1024); } while (0)
; #define PG8_LDB(dst, b, h) do { _Pragma("unroll") for (int n = 0; n < 2; ++n) _Pragma("unroll") for (int k = 0; k < 2; ++k) dst[n][k] = *(const PG8_LAS bf16x8*)(lds + PG8_SB(b, h) + boff + n * 2048 + k * 1024); } while (0)
; #define PG8_MMA(ai, bj, At, Bt) do { __builtin_amdgcn_s_setprio(1); _Pragma("unroll") for (int m = 0; m < 4; ++m) _Pragma("unroll") for (int n = 0; n < 2; ++n) _Pragma("unroll") for (int k = 0; k < 2; ++k) \
;         acc[ai][bj][m][n] = __builtin_amdgcn_mfma_f32_16x16x32_bf16(Bt[n][k], At[m][k], acc[ai][bj][m][n], 0, 0, 0); __builtin_amdgcn_s_setprio(0); } while (0)
; #define PG8_WAIT_V(n) asm volatile("s_waitcnt vmcnt(" #n ")" ::: "memory")
; #define PG8_WAIT_L(n) asm volatile("s_waitcnt lgkmcnt(" #n ")" ::: "memory")
; #define PG8_BAR __builtin_amdgcn_s_barrier()
; #define PG8_SCHED __builtin_amdgcn_sched_barrier(0)
; template <class Epi, class Sched, bool ALIGN_EPI = false, bool SP2 = false>
; __device__ __forceinline__ void gemm_phase(PG8_LAS unsigned char* lds, const Gemm g, const Sched& S, const Epi& E) {
;     ...
;             PG8_WAIT_V(8); PG8_WAIT_L(0); PG8_BAR; PG8_MMA(1, 0, At, B0); PG8_MMA(1, 1, At, B1); PG8_BAR; PG8_SCHED;
;             PG8_LDB(B0, 1, 0); PG8_LDB(B1, 1, 1); PG8_SCHED; PG8_LDA(At, 1, 0); PG8_STAGE(PG8_SA(0, 1), a2 + hstep, voffA);
;             PG8_WAIT_V(8); PG8_WAIT_L(0); PG8_BAR; PG8_MMA(0, 0, At, B0); PG8_MMA(0, 1, At, B1); PG8_BAR; PG8_SCHED;
	s_setprio 1
	v_mfma_f32_16x16x32_bf16 v[62:65], v[146:149], v[190:193], v[62:65]
	v_mfma_f32_16x16x32_bf16 v[58:61], v[166:169], v[190:193], v[58:61]
	v_mfma_f32_16x16x32_bf16 v[46:49], v[146:149], v[198:201], v[46:49]
	v_mfma_f32_16x16x32_bf16 v[42:45], v[166:169], v[198:201], v[42:45]
	v_mfma_f32_16x16x32_bf16 v[30:33], v[146:149], v[206:209], v[30:33]
	v_mfma_f32_16x16x32_bf16 v[26:29], v[166:169], v[206:209], v[26:29]
	v_mfma_f32_16x16x32_bf16 v[14:17], v[146:149], v[214:217], v[14:17]
	v_mfma_f32_16x16x32_bf16 v[10:13], v[166:169], v[214:217], v[10:13]
	v_mfma_f32_16x16x32_bf16 v[62:65], v[162:165], v[194:197], v[62:65]
	v_mfma_f32_16x16x32_bf16 v[58:61], v[170:173], v[194:197], v[58:61]
	v_mfma_f32_16x16x32_bf16 v[46:49], v[162:165], v[202:205], v[46:49]
	v_mfma_f32_16x16x32_bf16 v[42:45], v[170:173], v[202:205], v[42:45]
	v_mfma_f32_16x16x32_bf16 v[30:33], v[162:165], v[210:213], v[30:33]
	v_mfma_f32_16x16x32_bf16 v[26:29], v[170:173], v[210:213], v[26:29]
	v_mfma_f32_16x16x32_bf16 v[14:17], v[162:165], v[218:221], v[14:17]
	v_mfma_f32_16x16x32_bf16 v[10:13], v[170:173], v[218:221], v[10:13]
	v_mfma_f32_16x16x32_bf16 v[54:57], v[174:177], v[190:193], v[54:57]
	v_mfma_f32_16x16x32_bf16 v[50:53], v[182:185], v[190:193], v[50:53]
	v_mfma_f32_16x16x32_bf16 v[38:41], v[174:177], v[198:201], v[38:41]
	v_mfma_f32_16x16x32_bf16 v[34:37], v[182:185], v[198:201], v[34:37]
	v_mfma_f32_16x16x32_bf16 v[22:25], v[174:177], v[206:209], v[22:25]
	v_mfma_f32_16x16x32_bf16 v[18:21], v[182:185], v[206:209], v[18:21]
	v_mfma_f32_16x16x32_bf16 v[6:9], v[174:177], v[214:217], v[6:9]
	v_mfma_f32_16x16x32_bf16 v[2:5], v[182:185], v[214:217], v[2:5]
	v_mfma_f32_16x16x32_bf16 v[54:57], v[178:181], v[194:197], v[54:57]
	v_mfma_f32_16x16x32_bf16 v[50:53], v[186:189], v[194:197], v[50:53]
	v_mfma_f32_16x16x32_bf16 v[38:41], v[178:181], v[202:205], v[38:41]
	v_mfma_f32_16x16x32_bf16 v[34:37], v[186:189], v[202:205], v[34:37]
	v_mfma_f32_16x16x32_bf16 v[22:25], v[178:181], v[210:213], v[22:25]
	v_mfma_f32_16x16x32_bf16 v[18:21], v[186:189], v[210:213], v[18:21]
	v_mfma_f32_16x16x32_bf16 v[6:9], v[178:181], v[218:221], v[6:9]
	v_mfma_f32_16x16x32_bf16 v[2:5], v[186:189], v[218:221], v[2:5]
	s_setprio 0
	s_barrier
	s_add_i32 s69, 0, 0x18000
	v_add_u32_e32 v154, s69, v156
	s_add_i32 s70, 0, 0x1c000
	ds_read_b128 v[146:149], v154
	ds_read_b128 v[162:165], v154 offset:1024
	ds_read_b128 v[166:169], v154 offset:2048
	ds_read_b128 v[170:173], v154 offset:3072
	v_add_u32_e32 v154, s70, v156
	ds_read_b128 v[174:177], v154
	ds_read_b128 v[178:181], v154 offset:1024
	ds_read_b128 v[182:185], v154 offset:2048
	ds_read_b128 v[186:189], v154 offset:3072
	s_add_u32 s28, s28, s10
	s_addc_u32 s29, s29, s11
	s_mov_b32 m0, s39
	v_lshl_add_u64 v[230:231], s[28:29], 0, v[130:131]
	ds_read_b128 v[190:193], v153 offset:32768
	ds_read_b128 v[194:197], v153 offset:33792
	ds_read_b128 v[198:201], v153 offset:34816
	ds_read_b128 v[202:205], v153 offset:35840
	ds_read_b128 v[206:209], v153 offset:36864
	ds_read_b128 v[210:213], v153 offset:37888
	ds_read_b128 v[214:217], v153 offset:38912
	ds_read_b128 v[218:221], v153 offset:39936
	global_load_lds_dwordx4 v[230:231], off
	v_lshl_add_u64 v[230:231], s[28:29], 0, v[134:135]
	s_mov_b32 m0, s40
	s_nop 0
	global_load_lds_dwordx4 v[230:231], off
	s_waitcnt vmcnt(8)
	s_waitcnt lgkmcnt(0)
	s_barrier
	s_setprio 1
	v_mfma_f32_16x16x32_bf16 v[122:125], v[146:149], v[190:193], v[122:125]
	v_mfma_f32_16x16x32_bf16 v[126:129], v[166:169], v[190:193], v[126:129]
	v_mfma_f32_16x16x32_bf16 v[110:113], v[146:149], v[198:201], v[110:113]
	v_mfma_f32_16x16x32_bf16 v[106:109], v[166:169], v[198:201], v[106:109]
	v_mfma_f32_16x16x32_bf16 v[94:97], v[146:149], v[206:209], v[94:97]
	v_mfma_f32_16x16x32_bf16 v[90:93], v[166:169], v[206:209], v[90:93]
	v_mfma_f32_16x16x32_bf16 v[78:81], v[146:149], v[214:217], v[78:81]
	v_mfma_f32_16x16x32_bf16 v[74:77], v[166:169], v[214:217], v[74:77]
	v_mfma_f32_16x16x32_bf16 v[122:125], v[162:165], v[194:197], v[122:125]
	v_mfma_f32_16x16x32_bf16 v[126:129], v[170:173], v[194:197], v[126:129]
	v_mfma_f32_16x16x32_bf16 v[110:113], v[162:165], v[202:205], v[110:113]
	v_mfma_f32_16x16x32_bf16 v[106:109], v[170:173], v[202:205], v[106:109]
	v_mfma_f32_16x16x32_bf16 v[94:97], v[162:165], v[210:213], v[94:97]
	v_mfma_f32_16x16x32_bf16 v[90:93], v[170:173], v[210:213], v[90:93]
	v_mfma_f32_16x16x32_bf16 v[78:81], v[162:165], v[218:221], v[78:81]
	v_mfma_f32_16x16x32_bf16 v[74:77], v[170:173], v[218:221], v[74:77]
	v_mfma_f32_16x16x32_bf16 v[118:121], v[174:177], v[190:193], v[118:121]
	v_mfma_f32_16x16x32_bf16 v[114:117], v[182:185], v[190:193], v[114:117]
	v_mfma_f32_16x16x32_bf16 v[102:105], v[174:177], v[198:201], v[102:105]
	v_mfma_f32_16x16x32_bf16 v[98:101], v[182:185], v[198:201], v[98:101]
	v_mfma_f32_16x16x32_bf16 v[86:89], v[174:177], v[206:209], v[86:89]
	v_mfma_f32_16x16x32_bf16 v[82:85], v[182:185], v[206:209], v[82:85]
	v_mfma_f32_16x16x32_bf16 v[70:73], v[174:177], v[214:217], v[70:73]
	v_mfma_f32_16x16x32_bf16 v[66:69], v[182:185], v[214:217], v[66:69]
	v_mfma_f32_16x16x32_bf16 v[118:121], v[178:181], v[194:197], v[118:121]
	v_mfma_f32_16x16x32_bf16 v[114:117], v[186:189], v[194:197], v[114:117]
	v_mfma_f32_16x16x32_bf16 v[102:105], v[178:181], v[202:205], v[102:105]
	v_mfma_f32_16x16x32_bf16 v[98:101], v[186:189], v[202:205], v[98:101]
	v_mfma_f32_16x16x32_bf16 v[86:89], v[178:181], v[210:213], v[86:89]
	v_mfma_f32_16x16x32_bf16 v[82:85], v[186:189], v[210:213], v[82:85]
	v_mfma_f32_16x16x32_bf16 v[70:73], v[178:181], v[218:221], v[70:73]
	v_mfma_f32_16x16x32_bf16 v[66:69], v[186:189], v[218:221], v[66:69]
	s_setprio 0
	s_barrier
; #define PG8_STAGE(bufoff, gbase, voff) do { _Pragma("unroll") for (int _i = 0; _i < 2; ++_i) \
;         __builtin_amdgcn_global_load_lds((const unsigned*)((const char*)(gbase) + (voff)[_i]), (PG8_LAS unsigned*)(lds + (bufoff) + ldsw + _i * 8192), 16, 0, 0); } while (0)
; #define PG8_LDA(dst, b, h) do { _Pragma("unroll") for (int m = 0; m < 4; ++m) _Pragma("unroll") for (int k = 0; k < 2; ++k) dst[m][k] = *(const PG8_LAS bf16x8*)(lds + PG8_SA(b, h) + aoff + m * 2048 + k * 1024); } while (0)
; #define PG8_MMA(ai, bj, At, Bt) do { __builtin_amdgcn_s_setprio(1); _Pragma("unroll") for (int m = 0; m < 4; ++m) _Pragma("unroll") for (int n = 0; n < 2; ++n) _Pragma("unroll") for (int k = 0; k < 2; ++k) \
;         acc[ai][bj][m][n] = __builtin_amdgcn_mfma_f32_16x16x32_bf16(Bt[n][k], At[m][k], acc[ai][bj][m][n], 0, 0, 0); __builtin_amdgcn_s_setprio(0); } while (0)
; #define PG8_WAIT_V(n) asm volatile("s_waitcnt vmcnt(" #n ")" ::: "memory")
; #define PG8_WAIT_L(n) asm volatile("s_waitcnt lgkmcnt(" #n ")" ::: "memory")
; #define PG8_BAR __builtin_amdgcn_s_barrier()
; #define PG8_SCHED __builtin_amdgcn_sched_barrier(0)
; template <class Epi, class Sched, bool ALIGN_EPI = false, bool SP2 = false>
; __device__ __forceinline__ void gemm_phase(PG8_LAS unsigned char* lds, const Gemm g, const Sched& S, const Epi& E) {
;     ...
;             PG8_LDA(At, 1, 1); PG8_STAGE(PG8_SB(1, 0), b3, voffB); PG8_STAGE(PG8_SB(1, 1), b3 + hstep, voffB); PG8_STAGE(PG8_SA(1, 0), a3, voffA);
;             PG8_WAIT_V(8); PG8_WAIT_L(0); PG8_BAR; PG8_MMA(1, 0, At, B0); PG8_MMA(1, 1, At, B1); PG8_BAR; PG8_SCHED;
	s_add_i32 s28, s69, s36
	v_lshl_add_u64 v[150:151], v[150:151], 0, s[20:21]
	s_mov_b32 m0, s28
	ds_read_b128 v[190:193], v153 offset:49152
	ds_read_b128 v[194:197], v153 offset:50176
	ds_read_b128 v[198:201], v153 offset:51200
	ds_read_b128 v[202:205], v153 offset:52224
	ds_read_b128 v[206:209], v153 offset:53248
	ds_read_b128 v[210:213], v153 offset:54272
	ds_read_b128 v[214:217], v153 offset:55296
	ds_read_b128 v[218:221], v153 offset:56320
	global_load_lds_dwordx4 v[150:151], off
	v_lshl_add_u64 v[150:151], v[158:159], 0, s[20:21]
	s_add_i32 m0, s28, 0x2000
	s_add_i32 s28, s70, s36
	global_load_lds_dwordx4 v[150:151], off
	v_lshl_add_u64 v[150:151], v[222:223], 0, s[20:21]
	s_mov_b32 m0, s28
	s_nop 0
	global_load_lds_dwordx4 v[150:151], off
	v_lshl_add_u64 v[150:151], v[224:225], 0, s[20:21]
	s_add_i32 m0, s28, 0x2000
	s_nop 0
	global_load_lds_dwordx4 v[150:151], off
	v_lshl_add_u64 v[150:151], v[226:227], 0, s[20:21]
	s_mov_b32 m0, s42
	s_nop 0
	global_load_lds_dwordx4 v[150:151], off
	v_lshl_add_u64 v[150:151], v[228:229], 0, s[20:21]
	s_mov_b32 m0, s43
	s_nop 0
	global_load_lds_dwordx4 v[150:151], off
	s_waitcnt vmcnt(8)
	s_waitcnt lgkmcnt(0)
	s_barrier
	s_setprio 1
	v_mfma_f32_16x16x32_bf16 v[62:65], v[146:149], v[190:193], v[62:65]
	v_mfma_f32_16x16x32_bf16 v[58:61], v[166:169], v[190:193], v[58:61]
	v_mfma_f32_16x16x32_bf16 v[46:49], v[146:149], v[198:201], v[46:49]
	v_mfma_f32_16x16x32_bf16 v[42:45], v[166:169], v[198:201], v[42:45]
	v_mfma_f32_16x16x32_bf16 v[30:33], v[146:149], v[206:209], v[30:33]
	v_mfma_f32_16x16x32_bf16 v[26:29], v[166:169], v[206:209], v[26:29]
	v_mfma_f32_16x16x32_bf16 v[14:17], v[146:149], v[214:217], v[14:17]
	v_mfma_f32_16x16x32_bf16 v[10:13], v[166:169], v[214:217], v[10:13]
	v_mfma_f32_16x16x32_bf16 v[62:65], v[162:165], v[194:197], v[62:65]
	v_mfma_f32_16x16x32_bf16 v[58:61], v[170:173], v[194:197], v[58:61]
	v_mfma_f32_16x16x32_bf16 v[46:49], v[162:165], v[202:205], v[46:49]
	v_mfma_f32_16x16x32_bf16 v[42:45], v[170:173], v[202:205], v[42:45]
	v_mfma_f32_16x16x32_bf16 v[30:33], v[162:165], v[210:213], v[30:33]
	v_mfma_f32_16x16x32_bf16 v[26:29], v[170:173], v[210:213], v[26:29]
	v_mfma_f32_16x16x32_bf16 v[14:17], v[162:165], v[218:221], v[14:17]
	v_mfma_f32_16x16x32_bf16 v[10:13], v[170:173], v[218:221], v[10:13]
	v_mfma_f32_16x16x32_bf16 v[54:57], v[174:177], v[190:193], v[54:57]
	v_mfma_f32_16x16x32_bf16 v[50:53], v[182:185], v[190:193], v[50:53]
	v_mfma_f32_16x16x32_bf16 v[38:41], v[174:177], v[198:201], v[38:41]
	v_mfma_f32_16x16x32_bf16 v[34:37], v[182:185], v[198:201], v[34:37]
	v_mfma_f32_16x16x32_bf16 v[22:25], v[174:177], v[206:209], v[22:25]
	v_mfma_f32_16x16x32_bf16 v[18:21], v[182:185], v[206:209], v[18:21]
	v_mfma_f32_16x16x32_bf16 v[6:9], v[174:177], v[214:217], v[6:9]
	v_mfma_f32_16x16x32_bf16 v[2:5], v[182:185], v[214:217], v[2:5]
	v_mfma_f32_16x16x32_bf16 v[54:57], v[178:181], v[194:197], v[54:57]
	v_mfma_f32_16x16x32_bf16 v[50:53], v[186:189], v[194:197], v[50:53]
	v_mfma_f32_16x16x32_bf16 v[38:41], v[178:181], v[202:205], v[38:41]
	v_mfma_f32_16x16x32_bf16 v[34:37], v[186:189], v[202:205], v[34:37]
	v_mfma_f32_16x16x32_bf16 v[22:25], v[178:181], v[210:213], v[22:25]
	v_mfma_f32_16x16x32_bf16 v[18:21], v[186:189], v[210:213], v[18:21]
	v_mfma_f32_16x16x32_bf16 v[6:9], v[178:181], v[218:221], v[6:9]
	v_mfma_f32_16x16x32_bf16 v[2:5], v[186:189], v[218:221], v[2:5]
	s_setprio 0
	s_barrier
	s_add_u32 s56, s56, 0x100
	s_addc_u32 s57, s57, 0
	s_add_u32 s26, s26, 0x100
	s_addc_u32 s27, s27, 0
	s_cmp_ge_i32 s68, s44
	s_mov_b32 s28, s68
	s_cbranch_scc0 .LBB0_1548

; #define PG8_STAGE(bufoff, gbase, voff) do { _Pragma("unroll") for (int _i = 0; _i < 2; ++_i) \
;         __builtin_amdgcn_global_load_lds((const unsigned*)((const char*)(gbase) + (voff)[_i]), (PG8_LAS unsigned*)(lds + (bufoff) + ldsw + _i * 8192), 16, 0, 0); } while (0)
; #define PG8_LDA(dst, b, h) do { _Pragma("unroll") for (int m = 0; m < 4; ++m) _Pragma("unroll") for (int k = 0; k < 2; ++k) dst[m][k] = *(const PG8_LAS bf16x8*)(lds + PG8_SA(b, h) + aoff + m * 2048 + k * 1024); } while (0)
; #define PG8_LDB(dst, b, h) do { _Pragma("unroll") for (int n = 0; n < 2; ++n) _Pragma("unroll") for (int k = 0; k < 2; ++k) dst[n][k] = *(const PG8_LAS bf16x8*)(lds + PG8_SB(b, h) + boff + n * 2048 + k * 1024); } while (0)
; #define PG8_MMA(ai, bj, At, Bt) do { __builtin_amdgcn_s_setprio(1); _Pragma("unroll") for (int m = 0; m < 4; ++m) _Pragma("unroll") for (int n = 0; n < 2; ++n) _Pragma("unroll") for (int k = 0; k < 2; ++k) \
;         acc[ai][bj][m][n] = __builtin_amdgcn_mfma_f32_16x16x32_bf16(Bt[n][k], At[m][k], acc[ai][bj][m][n], 0, 0, 0); __builtin_amdgcn_s_setprio(0); } while (0)
; #define PG8_WAIT_V(n) asm volatile("s_waitcnt vmcnt(" #n ")" ::: "memory")
; #define PG8_WAIT_L(n) asm volatile("s_waitcnt lgkmcnt(" #n ")" ::: "memory")
; #define PG8_BAR __builtin_amdgcn_s_barrier()
; #define PG8_SCHED __builtin_amdgcn_sched_barrier(0)
; template <class Epi, class Sched, bool ALIGN_EPI = false, bool SP2 = false>
; __device__ __forceinline__ void gemm_phase(PG8_LAS unsigned char* lds, const Gemm g, const Sched& S, const Epi& E) {
;     ...
;             PG8_LDB(B0, 0, 0); PG8_LDB(B1, 0, 1); PG8_SCHED; PG8_LDA(At, 0, 0); PG8_STAGE(PG8_SA(1, 1), a1 + hstep, voffA);
;             PG8_WAIT_V(8); PG8_WAIT_L(0); PG8_BAR; PG8_MMA(0, 0, At, B0); PG8_MMA(0, 1, At, B1); PG8_BAR; PG8_SCHED;
;             PG8_LDA(At, 0, 1); PG8_STAGE(PG8_SB(0, 0), b2, voffB); PG8_STAGE(PG8_SB(0, 1), b2 + hstep, voffB); PG8_STAGE(PG8_SA(0, 0), a2, voffA);
;             PG8_WAIT_V(8); PG8_WAIT_L(0); PG8_BAR; PG8_MMA(1, 0, At, B0); PG8_MMA(1, 1, At, B1); PG8_BAR; PG8_SCHED;
.LBB0_1724:
	ds_read_b128 v[148:151], v157
	ds_read_b128 v[152:155], v157 offset:1024
	ds_read_b128 v[160:163], v157 offset:2048
	ds_read_b128 v[164:167], v157 offset:3072
	ds_read_b128 v[168:171], v158
	ds_read_b128 v[172:175], v158 offset:1024
	ds_read_b128 v[176:179], v158 offset:2048
	ds_read_b128 v[180:183], v158 offset:3072
	s_add_i32 s80, s38, 2
	s_add_u32 s70, s36, 0x80
	s_addc_u32 s39, s37, 0
	s_cmp_eq_u32 s59, s38
	s_cselect_b32 s38, s4, s70
	s_cselect_b32 s39, s5, s39
	s_cselect_b32 s71, s35, s45
	s_cselect_b32 s70, s34, s44
	v_lshl_add_u64 v[216:217], s[36:37], 0, v[142:143]
	s_add_i32 m0, s48, 0xc000
	ds_read_b128 v[184:187], v159
	ds_read_b128 v[188:191], v159 offset:1024
	ds_read_b128 v[192:195], v159 offset:2048
	ds_read_b128 v[196:199], v159 offset:3072
	ds_read_b128 v[200:203], v159 offset:4096
	ds_read_b128 v[204:207], v159 offset:5120
	ds_read_b128 v[208:211], v159 offset:6144
	ds_read_b128 v[212:215], v159 offset:7168
	global_load_lds_dwordx4 v[216:217], off
	v_lshl_add_u64 v[216:217], s[36:37], 0, v[140:141]
	s_add_i32 m0, s48, 0xe000
	s_nop 0
	global_load_lds_dwordx4 v[216:217], off
	s_waitcnt vmcnt(8)
	s_waitcnt lgkmcnt(0)
	s_barrier
	s_setprio 1
	v_mfma_f32_16x16x32_bf16 v[122:125], v[148:151], v[184:187], v[122:125]
	v_mfma_f32_16x16x32_bf16 v[126:129], v[160:163], v[184:187], v[126:129]
	v_mfma_f32_16x16x32_bf16 v[110:113], v[148:151], v[192:195], v[110:113]
	v_mfma_f32_16x16x32_bf16 v[106:109], v[160:163], v[192:195], v[106:109]
	v_mfma_f32_16x16x32_bf16 v[94:97], v[148:151], v[200:203], v[94:97]
	v_mfma_f32_16x16x32_bf16 v[90:93], v[160:163], v[200:203], v[90:93]
	v_mfma_f32_16x16x32_bf16 v[78:81], v[148:151], v[208:211], v[78:81]
	v_mfma_f32_16x16x32_bf16 v[74:77], v[160:163], v[208:211], v[74:77]
	v_mfma_f32_16x16x32_bf16 v[122:125], v[152:155], v[188:191], v[122:125]
	v_mfma_f32_16x16x32_bf16 v[126:129], v[164:167], v[188:191], v[126:129]
	v_mfma_f32_16x16x32_bf16 v[110:113], v[152:155], v[196:199], v[110:113]
	v_mfma_f32_16x16x32_bf16 v[106:109], v[164:167], v[196:199], v[106:109]
	v_mfma_f32_16x16x32_bf16 v[94:97], v[152:155], v[204:207], v[94:97]
	v_mfma_f32_16x16x32_bf16 v[90:93], v[164:167], v[204:207], v[90:93]
	v_mfma_f32_16x16x32_bf16 v[78:81], v[152:155], v[212:215], v[78:81]
	v_mfma_f32_16x16x32_bf16 v[74:77], v[164:167], v[212:215], v[74:77]
	v_mfma_f32_16x16x32_bf16 v[118:121], v[168:171], v[184:187], v[118:121]
	v_mfma_f32_16x16x32_bf16 v[114:117], v[176:179], v[184:187], v[114:117]
	v_mfma_f32_16x16x32_bf16 v[102:105], v[168:171], v[192:195], v[102:105]
	v_mfma_f32_16x16x32_bf16 v[98:101], v[176:179], v[192:195], v[98:101]
	v_mfma_f32_16x16x32_bf16 v[86:89], v[168:171], v[200:203], v[86:89]
	v_mfma_f32_16x16x32_bf16 v[82:85], v[176:179], v[200:203], v[82:85]
	v_mfma_f32_16x16x32_bf16 v[70:73], v[168:171], v[208:211], v[70:73]
	v_mfma_f32_16x16x32_bf16 v[66:69], v[176:179], v[208:211], v[66:69]
	v_mfma_f32_16x16x32_bf16 v[118:121], v[172:175], v[188:191], v[118:121]
	v_mfma_f32_16x16x32_bf16 v[114:117], v[180:183], v[188:191], v[114:117]
	v_mfma_f32_16x16x32_bf16 v[102:105], v[172:175], v[196:199], v[102:105]
	v_mfma_f32_16x16x32_bf16 v[98:101], v[180:183], v[196:199], v[98:101]
	v_mfma_f32_16x16x32_bf16 v[86:89], v[172:175], v[204:207], v[86:89]
	v_mfma_f32_16x16x32_bf16 v[82:85], v[180:183], v[204:207], v[82:85]
	v_mfma_f32_16x16x32_bf16 v[70:73], v[172:175], v[212:215], v[70:73]
	v_mfma_f32_16x16x32_bf16 v[66:69], v[180:183], v[212:215], v[66:69]
	s_setprio 0
	s_barrier
	s_add_i32 s72, s62, s47
	v_lshl_add_u64 v[216:217], s[70:71], 0, v[134:135]
	s_mov_b32 m0, s72
	ds_read_b128 v[184:187], v159 offset:16384
	ds_read_b128 v[188:191], v159 offset:17408
	ds_read_b128 v[192:195], v159 offset:18432
	ds_read_b128 v[196:199], v159 offset:19456
	ds_read_b128 v[200:203], v159 offset:20480
	ds_read_b128 v[204:207], v159 offset:21504
	ds_read_b128 v[208:211], v159 offset:22528
	ds_read_b128 v[212:215], v159 offset:23552
	global_load_lds_dwordx4 v[216:217], off
	s_add_i32 m0, s72, 0x2000
	v_lshl_add_u64 v[218:219], s[70:71], 0, v[138:139]
	s_add_u32 s70, s70, s8
	s_addc_u32 s71, s71, s9
	s_add_i32 s72, s63, s47
	global_load_lds_dwordx4 v[218:219], off
	v_lshl_add_u64 v[220:221], s[70:71], 0, v[134:135]
	s_mov_b32 m0, s72
	v_lshl_add_u64 v[222:223], s[70:71], 0, v[138:139]
	global_load_lds_dwordx4 v[220:221], off
	s_add_i32 m0, s72, 0x2000
	v_lshl_add_u64 v[224:225], s[38:39], 0, v[132:133]
	global_load_lds_dwordx4 v[222:223], off
	s_mov_b32 m0, s48
	v_lshl_add_u64 v[226:227], s[38:39], 0, v[136:137]
	global_load_lds_dwordx4 v[224:225], off
	s_mov_b32 m0, s49
	s_nop 0
	global_load_lds_dwordx4 v[226:227], off
	s_waitcnt vmcnt(8)
	s_waitcnt lgkmcnt(0)
	s_barrier
; #define PG8_STAGE(bufoff, gbase, voff) do { _Pragma("unroll") for (int _i = 0; _i < 2; ++_i) \
;         __builtin_amdgcn_global_load_lds((const unsigned*)((const char*)(gbase) + (voff)[_i]), (PG8_LAS unsigned*)(lds + (bufoff) + ldsw + _i * 8192), 16, 0, 0); } while (0)
; #define PG8_LDA(dst, b, h) do { _Pragma("unroll") for (int m = 0; m < 4; ++m) _Pragma("unroll") for (int k = 0; k < 2; ++k) dst[m][k] = *(const PG8_LAS bf16x8*)(lds + PG8_SA(b, h) + aoff + m * 2048 + k * 1024); } while (0)
; #define PG8_LDB(dst, b, h) do { _Pragma("unroll") for (int n = 0; n < 2; ++n) _Pragma("unroll") for (int k = 0; k < 2; ++k) dst[n][k] = *(const PG8_LAS bf16x8*)(lds + PG8_SB(b, h) + boff + n * 2048 + k * 1024); } while (0)
; #define PG8_MMA(ai, bj, At, Bt) do { __builtin_amdgcn_s_setprio(1); _Pragma("unroll") for (int m = 0; m < 4; ++m) _Pragma("unroll") for (int n = 0; n < 2; ++n) _Pragma("unroll") for (int k = 0; k < 2; ++k) \
;         acc[ai][bj][m][n] = __builtin_amdgcn_mfma_f32_16x16x32_bf16(Bt[n][k], At[m][k], acc[ai][bj][m][n], 0, 0, 0); __builtin_amdgcn_s_setprio(0); } while (0)
; #define PG8_WAIT_V(n) asm volatile("s_waitcnt vmcnt(" #n ")" ::: "memory")
; #define PG8_WAIT_L(n) asm volatile("s_waitcnt lgkmcnt(" #n ")" ::: "memory")
; #define PG8_BAR __builtin_amdgcn_s_barrier()
; #define PG8_SCHED __builtin_amdgcn_sched_barrier(0)
; template <class Epi, class Sched, bool ALIGN_EPI = false, bool SP2 = false>
; __device__ __forceinline__ void gemm_phase(PG8_LAS unsigned char* lds, const Gemm g, const Sched& S, const Epi& E) {
;     ...
;             PG8_WAIT_V(8); PG8_WAIT_L(0); PG8_BAR; PG8_MMA(1, 0, At, B0); PG8_MMA(1, 1, At, B1); PG8_BAR; PG8_SCHED;
;             PG8_LDB(B0, 1, 0); PG8_LDB(B1, 1, 1); PG8_SCHED; PG8_LDA(At, 1, 0); PG8_STAGE(PG8_SA(0, 1), a2 + hstep, voffA);
;             PG8_WAIT_V(8); PG8_WAIT_L(0); PG8_BAR; PG8_MMA(0, 0, At, B0); PG8_MMA(0, 1, At, B1); PG8_BAR; PG8_SCHED;
	s_setprio 1
	v_mfma_f32_16x16x32_bf16 v[62:65], v[148:151], v[184:187], v[62:65]
	v_mfma_f32_16x16x32_bf16 v[58:61], v[160:163], v[184:187], v[58:61]
	v_mfma_f32_16x16x32_bf16 v[46:49], v[148:151], v[192:195], v[46:49]
	v_mfma_f32_16x16x32_bf16 v[42:45], v[160:163], v[192:195], v[42:45]
	v_mfma_f32_16x16x32_bf16 v[30:33], v[148:151], v[200:203], v[30:33]
	v_mfma_f32_16x16x32_bf16 v[26:29], v[160:163], v[200:203], v[26:29]
	v_mfma_f32_16x16x32_bf16 v[14:17], v[148:151], v[208:211], v[14:17]
	v_mfma_f32_16x16x32_bf16 v[10:13], v[160:163], v[208:211], v[10:13]
	v_mfma_f32_16x16x32_bf16 v[62:65], v[152:155], v[188:191], v[62:65]
	v_mfma_f32_16x16x32_bf16 v[58:61], v[164:167], v[188:191], v[58:61]
	v_mfma_f32_16x16x32_bf16 v[46:49], v[152:155], v[196:199], v[46:49]
	v_mfma_f32_16x16x32_bf16 v[42:45], v[164:167], v[196:199], v[42:45]
	v_mfma_f32_16x16x32_bf16 v[30:33], v[152:155], v[204:207], v[30:33]
	v_mfma_f32_16x16x32_bf16 v[26:29], v[164:167], v[204:207], v[26:29]
	v_mfma_f32_16x16x32_bf16 v[14:17], v[152:155], v[212:215], v[14:17]
	v_mfma_f32_16x16x32_bf16 v[10:13], v[164:167], v[212:215], v[10:13]
	v_mfma_f32_16x16x32_bf16 v[54:57], v[168:171], v[184:187], v[54:57]
	v_mfma_f32_16x16x32_bf16 v[50:53], v[176:179], v[184:187], v[50:53]
	v_mfma_f32_16x16x32_bf16 v[38:41], v[168:171], v[192:195], v[38:41]
	v_mfma_f32_16x16x32_bf16 v[34:37], v[176:179], v[192:195], v[34:37]
	v_mfma_f32_16x16x32_bf16 v[22:25], v[168:171], v[200:203], v[22:25]
	v_mfma_f32_16x16x32_bf16 v[18:21], v[176:179], v[200:203], v[18:21]
	v_mfma_f32_16x16x32_bf16 v[6:9], v[168:171], v[208:211], v[6:9]
	v_mfma_f32_16x16x32_bf16 v[2:5], v[176:179], v[208:211], v[2:5]
	v_mfma_f32_16x16x32_bf16 v[54:57], v[172:175], v[188:191], v[54:57]
	v_mfma_f32_16x16x32_bf16 v[50:53], v[180:183], v[188:191], v[50:53]
	v_mfma_f32_16x16x32_bf16 v[38:41], v[172:175], v[196:199], v[38:41]
	v_mfma_f32_16x16x32_bf16 v[34:37], v[180:183], v[196:199], v[34:37]
	v_mfma_f32_16x16x32_bf16 v[22:25], v[172:175], v[204:207], v[22:25]
	v_mfma_f32_16x16x32_bf16 v[18:21], v[180:183], v[204:207], v[18:21]
	v_mfma_f32_16x16x32_bf16 v[6:9], v[172:175], v[212:215], v[6:9]
	v_mfma_f32_16x16x32_bf16 v[2:5], v[180:183], v[212:215], v[2:5]
	s_setprio 0
	s_barrier
	s_add_i32 s70, 0, 0x18000
	s_add_i32 s71, 0, 0x1c000
	v_add_u32_e32 v164, s70, v156
	v_add_u32_e32 v180, s71, v156
	ds_read_b128 v[148:151], v164
	ds_read_b128 v[152:155], v164 offset:1024
	ds_read_b128 v[160:163], v164 offset:2048
	ds_read_b128 v[164:167], v164 offset:3072
	ds_read_b128 v[168:171], v180
	ds_read_b128 v[172:175], v180 offset:1024
	ds_read_b128 v[176:179], v180 offset:2048
	ds_read_b128 v[180:183], v180 offset:3072
	s_add_u32 s38, s38, s8
	s_addc_u32 s39, s39, s9
	s_mov_b32 m0, s52
	v_lshl_add_u64 v[228:229], s[38:39], 0, v[132:133]
	ds_read_b128 v[184:187], v159 offset:32768
	ds_read_b128 v[188:191], v159 offset:33792
	ds_read_b128 v[192:195], v159 offset:34816
	ds_read_b128 v[196:199], v159 offset:35840
	ds_read_b128 v[200:203], v159 offset:36864
	ds_read_b128 v[204:207], v159 offset:37888
	ds_read_b128 v[208:211], v159 offset:38912
	ds_read_b128 v[212:215], v159 offset:39936
	global_load_lds_dwordx4 v[228:229], off
	v_lshl_add_u64 v[228:229], s[38:39], 0, v[136:137]
	s_mov_b32 m0, s53
	s_nop 0
	global_load_lds_dwordx4 v[228:229], off
	s_waitcnt vmcnt(8)
	s_waitcnt lgkmcnt(0)
	s_barrier
	s_setprio 1
	v_mfma_f32_16x16x32_bf16 v[122:125], v[148:151], v[184:187], v[122:125]
	v_mfma_f32_16x16x32_bf16 v[126:129], v[160:163], v[184:187], v[126:129]
	v_mfma_f32_16x16x32_bf16 v[110:113], v[148:151], v[192:195], v[110:113]
	v_mfma_f32_16x16x32_bf16 v[106:109], v[160:163], v[192:195], v[106:109]
	v_mfma_f32_16x16x32_bf16 v[94:97], v[148:151], v[200:203], v[94:97]
	v_mfma_f32_16x16x32_bf16 v[90:93], v[160:163], v[200:203], v[90:93]
	v_mfma_f32_16x16x32_bf16 v[78:81], v[148:151], v[208:211], v[78:81]
	v_mfma_f32_16x16x32_bf16 v[74:77], v[160:163], v[208:211], v[74:77]
	v_mfma_f32_16x16x32_bf16 v[122:125], v[152:155], v[188:191], v[122:125]
	v_mfma_f32_16x16x32_bf16 v[126:129], v[164:167], v[188:191], v[126:129]
	v_mfma_f32_16x16x32_bf16 v[110:113], v[152:155], v[196:199], v[110:113]
	v_mfma_f32_16x16x32_bf16 v[106:109], v[164:167], v[196:199], v[106:109]
	v_mfma_f32_16x16x32_bf16 v[94:97], v[152:155], v[204:207], v[94:97]
	v_mfma_f32_16x16x32_bf16 v[90:93], v[164:167], v[204:207], v[90:93]
	v_mfma_f32_16x16x32_bf16 v[78:81], v[152:155], v[212:215], v[78:81]
	v_mfma_f32_16x16x32_bf16 v[74:77], v[164:167], v[212:215], v[74:77]
	v_mfma_f32_16x16x32_bf16 v[118:121], v[168:171], v[184:187], v[118:121]
	v_mfma_f32_16x16x32_bf16 v[114:117], v[176:179], v[184:187], v[114:117]
	v_mfma_f32_16x16x32_bf16 v[102:105], v[168:171], v[192:195], v[102:105]
	v_mfma_f32_16x16x32_bf16 v[98:101], v[176:179], v[192:195], v[98:101]
	v_mfma_f32_16x16x32_bf16 v[86:89], v[168:171], v[200:203], v[86:89]
	v_mfma_f32_16x16x32_bf16 v[82:85], v[176:179], v[200:203], v[82:85]
	v_mfma_f32_16x16x32_bf16 v[70:73], v[168:171], v[208:211], v[70:73]
	v_mfma_f32_16x16x32_bf16 v[66:69], v[176:179], v[208:211], v[66:69]
	v_mfma_f32_16x16x32_bf16 v[118:121], v[172:175], v[188:191], v[118:121]
	v_mfma_f32_16x16x32_bf16 v[114:117], v[180:183], v[188:191], v[114:117]
	v_mfma_f32_16x16x32_bf16 v[102:105], v[172:175], v[196:199], v[102:105]
	v_mfma_f32_16x16x32_bf16 v[98:101], v[180:183], v[196:199], v[98:101]
	v_mfma_f32_16x16x32_bf16 v[86:89], v[172:175], v[204:207], v[86:89]
	v_mfma_f32_16x16x32_bf16 v[82:85], v[180:183], v[204:207], v[82:85]
	v_mfma_f32_16x16x32_bf16 v[70:73], v[172:175], v[212:215], v[70:73]
	v_mfma_f32_16x16x32_bf16 v[66:69], v[180:183], v[212:215], v[66:69]
	s_setprio 0
	s_barrier
; #define PG8_STAGE(bufoff, gbase, voff) do { _Pragma("unroll") for (int _i = 0; _i < 2; ++_i) \
;         __builtin_amdgcn_global_load_lds((const unsigned*)((const char*)(gbase) + (voff)[_i]), (PG8_LAS unsigned*)(lds + (bufoff) + ldsw + _i * 8192), 16, 0, 0); } while (0)
; #define PG8_LDA(dst, b, h) do { _Pragma("unroll") for (int m = 0; m < 4; ++m) _Pragma("unroll") for (int k = 0; k < 2; ++k) dst[m][k] = *(const PG8_LAS bf16x8*)(lds + PG8_SA(b, h) + aoff + m * 2048 + k * 1024); } while (0)
; #define PG8_MMA(ai, bj, At, Bt) do { __builtin_amdgcn_s_setprio(1); _Pragma("unroll") for (int m = 0; m < 4; ++m) _Pragma("unroll") for (int n = 0; n < 2; ++n) _Pragma("unroll") for (int k = 0; k < 2; ++k) \
;         acc[ai][bj][m][n] = __builtin_amdgcn_mfma_f32_16x16x32_bf16(Bt[n][k], At[m][k], acc[ai][bj][m][n], 0, 0, 0); __builtin_amdgcn_s_setprio(0); } while (0)
; #define PG8_WAIT_V(n) asm volatile("s_waitcnt vmcnt(" #n ")" ::: "memory")
; #define PG8_WAIT_L(n) asm volatile("s_waitcnt lgkmcnt(" #n ")" ::: "memory")
; #define PG8_BAR __builtin_amdgcn_s_barrier()
; #define PG8_SCHED __builtin_amdgcn_sched_barrier(0)
; template <class Epi, class Sched, bool ALIGN_EPI = false, bool SP2 = false>
; __device__ __forceinline__ void gemm_phase(PG8_LAS unsigned char* lds, const Gemm g, const Sched& S, const Epi& E) {
;     ...
;             PG8_LDA(At, 1, 1); PG8_STAGE(PG8_SB(1, 0), b3, voffB); PG8_STAGE(PG8_SB(1, 1), b3 + hstep, voffB); PG8_STAGE(PG8_SA(1, 0), a3, voffA);
;             PG8_WAIT_V(8); PG8_WAIT_L(0); PG8_BAR; PG8_MMA(1, 0, At, B0); PG8_MMA(1, 1, At, B1); PG8_BAR; PG8_SCHED;
	s_add_i32 s38, s70, s47
	v_lshl_add_u64 v[216:217], v[216:217], 0, s[24:25]
	s_mov_b32 m0, s38
	ds_read_b128 v[184:187], v159 offset:49152
	ds_read_b128 v[188:191], v159 offset:50176
	ds_read_b128 v[192:195], v159 offset:51200
	ds_read_b128 v[196:199], v159 offset:52224
	ds_read_b128 v[200:203], v159 offset:53248
	ds_read_b128 v[204:207], v159 offset:54272
	ds_read_b128 v[208:211], v159 offset:55296
	ds_read_b128 v[212:215], v159 offset:56320
	global_load_lds_dwordx4 v[216:217], off
	v_lshl_add_u64 v[216:217], v[218:219], 0, s[24:25]
	s_add_i32 m0, s38, 0x2000
	s_add_i32 s38, s71, s47
	global_load_lds_dwordx4 v[216:217], off
	v_lshl_add_u64 v[216:217], v[220:221], 0, s[24:25]
	s_mov_b32 m0, s38
	s_nop 0
	global_load_lds_dwordx4 v[216:217], off
	v_lshl_add_u64 v[216:217], v[222:223], 0, s[24:25]
	s_add_i32 m0, s38, 0x2000
	s_nop 0
	global_load_lds_dwordx4 v[216:217], off
	v_lshl_add_u64 v[216:217], v[224:225], 0, s[24:25]
	s_mov_b32 m0, s55
	s_nop 0
	global_load_lds_dwordx4 v[216:217], off
	v_lshl_add_u64 v[216:217], v[226:227], 0, s[24:25]
	s_mov_b32 m0, s56
	s_nop 0
	global_load_lds_dwordx4 v[216:217], off
	s_waitcnt vmcnt(8)
	s_waitcnt lgkmcnt(0)
	s_barrier
	s_setprio 1
	v_mfma_f32_16x16x32_bf16 v[62:65], v[148:151], v[184:187], v[62:65]
	v_mfma_f32_16x16x32_bf16 v[58:61], v[160:163], v[184:187], v[58:61]
	v_mfma_f32_16x16x32_bf16 v[46:49], v[148:151], v[192:195], v[46:49]
	v_mfma_f32_16x16x32_bf16 v[42:45], v[160:163], v[192:195], v[42:45]
	v_mfma_f32_16x16x32_bf16 v[30:33], v[148:151], v[200:203], v[30:33]
	v_mfma_f32_16x16x32_bf16 v[26:29], v[160:163], v[200:203], v[26:29]
	v_mfma_f32_16x16x32_bf16 v[14:17], v[148:151], v[208:211], v[14:17]
	v_mfma_f32_16x16x32_bf16 v[10:13], v[160:163], v[208:211], v[10:13]
	v_mfma_f32_16x16x32_bf16 v[62:65], v[152:155], v[188:191], v[62:65]
	v_mfma_f32_16x16x32_bf16 v[58:61], v[164:167], v[188:191], v[58:61]
	v_mfma_f32_16x16x32_bf16 v[46:49], v[152:155], v[196:199], v[46:49]
	v_mfma_f32_16x16x32_bf16 v[42:45], v[164:167], v[196:199], v[42:45]
	v_mfma_f32_16x16x32_bf16 v[30:33], v[152:155], v[204:207], v[30:33]
	v_mfma_f32_16x16x32_bf16 v[26:29], v[164:167], v[204:207], v[26:29]
	v_mfma_f32_16x16x32_bf16 v[14:17], v[152:155], v[212:215], v[14:17]
	v_mfma_f32_16x16x32_bf16 v[10:13], v[164:167], v[212:215], v[10:13]
	v_mfma_f32_16x16x32_bf16 v[54:57], v[168:171], v[184:187], v[54:57]
	v_mfma_f32_16x16x32_bf16 v[50:53], v[176:179], v[184:187], v[50:53]
	v_mfma_f32_16x16x32_bf16 v[38:41], v[168:171], v[192:195], v[38:41]
	v_mfma_f32_16x16x32_bf16 v[34:37], v[176:179], v[192:195], v[34:37]
	v_mfma_f32_16x16x32_bf16 v[22:25], v[168:171], v[200:203], v[22:25]
	v_mfma_f32_16x16x32_bf16 v[18:21], v[176:179], v[200:203], v[18:21]
	v_mfma_f32_16x16x32_bf16 v[6:9], v[168:171], v[208:211], v[6:9]
	v_mfma_f32_16x16x32_bf16 v[2:5], v[176:179], v[208:211], v[2:5]
	v_mfma_f32_16x16x32_bf16 v[54:57], v[172:175], v[188:191], v[54:57]
	v_mfma_f32_16x16x32_bf16 v[50:53], v[180:183], v[188:191], v[50:53]
	v_mfma_f32_16x16x32_bf16 v[38:41], v[172:175], v[196:199], v[38:41]
	v_mfma_f32_16x16x32_bf16 v[34:37], v[180:183], v[196:199], v[34:37]
	v_mfma_f32_16x16x32_bf16 v[22:25], v[172:175], v[204:207], v[22:25]
	v_mfma_f32_16x16x32_bf16 v[18:21], v[180:183], v[204:207], v[18:21]
	v_mfma_f32_16x16x32_bf16 v[6:9], v[172:175], v[212:215], v[6:9]
	v_mfma_f32_16x16x32_bf16 v[2:5], v[180:183], v[212:215], v[2:5]
	s_setprio 0
	s_barrier
	s_add_u32 s44, s44, 0x100
	s_addc_u32 s45, s45, 0
	s_add_u32 s36, s36, 0x100
	s_addc_u32 s37, s37, 0
	s_cmp_ge_i32 s80, s57
	s_mov_b32 s38, s80
	s_cbranch_scc0 .LBB0_1724

; #define PG8_STAGE(bufoff, gbase, voff) do { _Pragma("unroll") for (int _i = 0; _i < 2; ++_i) \
;         __builtin_amdgcn_global_load_lds((const unsigned*)((const char*)(gbase) + (voff)[_i]), (PG8_LAS unsigned*)(lds + (bufoff) + ldsw + _i * 8192), 16, 0, 0); } while (0)
; #define PG8_LDA(dst, b, h) do { _Pragma("unroll") for (int m = 0; m < 4; ++m) _Pragma("unroll") for (int k = 0; k < 2; ++k) dst[m][k] = *(const PG8_LAS bf16x8*)(lds + PG8_SA(b, h) + aoff + m * 2048 + k * 1024); } while (0)
; #define PG8_LDB(dst, b, h) do { _Pragma("unroll") for (int n = 0; n < 2; ++n) _Pragma("unroll") for (int k = 0; k < 2; ++k) dst[n][k] = *(const PG8_LAS bf16x8*)(lds + PG8_SB(b, h) + boff + n * 2048 + k * 1024); } while (0)
; #define PG8_MMA(ai, bj, At, Bt) do { __builtin_amdgcn_s_setprio(1); _Pragma("unroll") for (int m = 0; m < 4; ++m) _Pragma("unroll") for (int n = 0; n < 2; ++n) _Pragma("unroll") for (int k = 0; k < 2; ++k) \
;         acc[ai][bj][m][n] = __builtin_amdgcn_mfma_f32_16x16x32_bf16(Bt[n][k], At[m][k], acc[ai][bj][m][n], 0, 0, 0); __builtin_amdgcn_s_setprio(0); } while (0)
; #define PG8_WAIT_V(n) asm volatile("s_waitcnt vmcnt(" #n ")" ::: "memory")
; #define PG8_WAIT_L(n) asm volatile("s_waitcnt lgkmcnt(" #n ")" ::: "memory")
; #define PG8_BAR __builtin_amdgcn_s_barrier()
; #define PG8_SCHED __builtin_amdgcn_sched_barrier(0)
; template <class Epi, class Sched, bool ALIGN_EPI = false, bool SP2 = false>
; __device__ __forceinline__ void gemm_phase(PG8_LAS unsigned char* lds, const Gemm g, const Sched& S, const Epi& E) {
;     ...
;             PG8_LDB(B0, 0, 0); PG8_LDB(B1, 0, 1); PG8_SCHED; PG8_LDA(At, 0, 0); PG8_STAGE(PG8_SA(1, 1), a1 + hstep, voffA);
;             PG8_WAIT_V(8); PG8_WAIT_L(0); PG8_BAR; PG8_MMA(0, 0, At, B0); PG8_MMA(0, 1, At, B1); PG8_BAR; PG8_SCHED;
;             PG8_LDA(At, 0, 1); PG8_STAGE(PG8_SB(0, 0), b2, voffB); PG8_STAGE(PG8_SB(0, 1), b2 + hstep, voffB); PG8_STAGE(PG8_SA(0, 0), a2, voffA);
;             PG8_WAIT_V(8); PG8_WAIT_L(0); PG8_BAR; PG8_MMA(1, 0, At, B0); PG8_MMA(1, 1, At, B1); PG8_BAR; PG8_SCHED;
.LBB0_1809:
	ds_read_b128 v[152:155], v148
	ds_read_b128 v[156:159], v148 offset:1024
	ds_read_b128 v[160:163], v148 offset:2048
	ds_read_b128 v[164:167], v148 offset:3072
	ds_read_b128 v[168:171], v149
	ds_read_b128 v[172:175], v149 offset:1024
	ds_read_b128 v[176:179], v149 offset:2048
	ds_read_b128 v[180:183], v149 offset:3072
	s_add_i32 s56, s26, 2
	s_add_u32 s57, s24, 0x80
	s_addc_u32 s27, s25, 0
	s_cmp_eq_u32 s43, s26
	s_cselect_b32 s26, s4, s57
	s_cselect_b32 s27, s5, s27
	s_cselect_b32 s59, s23, s55
	s_cselect_b32 s58, s22, s54
	v_lshl_add_u64 v[216:217], s[24:25], 0, v[140:141]
	s_add_i32 m0, s35, 0xc000
	ds_read_b128 v[184:187], v150
	ds_read_b128 v[188:191], v150 offset:1024
	ds_read_b128 v[192:195], v150 offset:2048
	ds_read_b128 v[196:199], v150 offset:3072
	ds_read_b128 v[200:203], v150 offset:4096
	ds_read_b128 v[204:207], v150 offset:5120
	ds_read_b128 v[208:211], v150 offset:6144
	ds_read_b128 v[212:215], v150 offset:7168
	global_load_lds_dwordx4 v[216:217], off
	v_lshl_add_u64 v[216:217], s[24:25], 0, v[138:139]
	s_add_i32 m0, s35, 0xe000
	s_nop 0
	global_load_lds_dwordx4 v[216:217], off
	s_waitcnt vmcnt(8)
	s_waitcnt lgkmcnt(0)
	s_barrier
	s_setprio 1
	v_mfma_f32_16x16x32_bf16 v[122:125], v[152:155], v[184:187], v[122:125]
	v_mfma_f32_16x16x32_bf16 v[126:129], v[160:163], v[184:187], v[126:129]
	v_mfma_f32_16x16x32_bf16 v[110:113], v[152:155], v[192:195], v[110:113]
	v_mfma_f32_16x16x32_bf16 v[106:109], v[160:163], v[192:195], v[106:109]
	v_mfma_f32_16x16x32_bf16 v[94:97], v[152:155], v[200:203], v[94:97]
	v_mfma_f32_16x16x32_bf16 v[90:93], v[160:163], v[200:203], v[90:93]
	v_mfma_f32_16x16x32_bf16 v[78:81], v[152:155], v[208:211], v[78:81]
	v_mfma_f32_16x16x32_bf16 v[74:77], v[160:163], v[208:211], v[74:77]
	v_mfma_f32_16x16x32_bf16 v[122:125], v[156:159], v[188:191], v[122:125]
	v_mfma_f32_16x16x32_bf16 v[126:129], v[164:167], v[188:191], v[126:129]
	v_mfma_f32_16x16x32_bf16 v[110:113], v[156:159], v[196:199], v[110:113]
	v_mfma_f32_16x16x32_bf16 v[106:109], v[164:167], v[196:199], v[106:109]
	v_mfma_f32_16x16x32_bf16 v[94:97], v[156:159], v[204:207], v[94:97]
	v_mfma_f32_16x16x32_bf16 v[90:93], v[164:167], v[204:207], v[90:93]
	v_mfma_f32_16x16x32_bf16 v[78:81], v[156:159], v[212:215], v[78:81]
	v_mfma_f32_16x16x32_bf16 v[74:77], v[164:167], v[212:215], v[74:77]
	v_mfma_f32_16x16x32_bf16 v[118:121], v[168:171], v[184:187], v[118:121]
	v_mfma_f32_16x16x32_bf16 v[114:117], v[176:179], v[184:187], v[114:117]
	v_mfma_f32_16x16x32_bf16 v[102:105], v[168:171], v[192:195], v[102:105]
	v_mfma_f32_16x16x32_bf16 v[98:101], v[176:179], v[192:195], v[98:101]
	v_mfma_f32_16x16x32_bf16 v[86:89], v[168:171], v[200:203], v[86:89]
	v_mfma_f32_16x16x32_bf16 v[82:85], v[176:179], v[200:203], v[82:85]
	v_mfma_f32_16x16x32_bf16 v[70:73], v[168:171], v[208:211], v[70:73]
	v_mfma_f32_16x16x32_bf16 v[66:69], v[176:179], v[208:211], v[66:69]
	v_mfma_f32_16x16x32_bf16 v[118:121], v[172:175], v[188:191], v[118:121]
	v_mfma_f32_16x16x32_bf16 v[114:117], v[180:183], v[188:191], v[114:117]
	v_mfma_f32_16x16x32_bf16 v[102:105], v[172:175], v[196:199], v[102:105]
	v_mfma_f32_16x16x32_bf16 v[98:101], v[180:183], v[196:199], v[98:101]
	v_mfma_f32_16x16x32_bf16 v[86:89], v[172:175], v[204:207], v[86:89]
	v_mfma_f32_16x16x32_bf16 v[82:85], v[180:183], v[204:207], v[82:85]
	v_mfma_f32_16x16x32_bf16 v[70:73], v[172:175], v[212:215], v[70:73]
	v_mfma_f32_16x16x32_bf16 v[66:69], v[180:183], v[212:215], v[66:69]
	s_setprio 0
	s_barrier
	s_add_i32 s57, s46, s34
	v_lshl_add_u64 v[216:217], s[58:59], 0, v[132:133]
	s_mov_b32 m0, s57
	ds_read_b128 v[184:187], v150 offset:16384
	ds_read_b128 v[188:191], v150 offset:17408
	ds_read_b128 v[192:195], v150 offset:18432
	ds_read_b128 v[196:199], v150 offset:19456
	ds_read_b128 v[200:203], v150 offset:20480
	ds_read_b128 v[204:207], v150 offset:21504
	ds_read_b128 v[208:211], v150 offset:22528
	ds_read_b128 v[212:215], v150 offset:23552
	global_load_lds_dwordx4 v[216:217], off
	s_add_i32 m0, s57, 0x2000
	v_lshl_add_u64 v[218:219], s[58:59], 0, v[136:137]
	s_add_u32 s58, s58, s8
	s_addc_u32 s59, s59, s9
	s_add_i32 s57, s47, s34
	global_load_lds_dwordx4 v[218:219], off
	v_lshl_add_u64 v[220:221], s[58:59], 0, v[132:133]
	s_mov_b32 m0, s57
	v_lshl_add_u64 v[222:223], s[58:59], 0, v[136:137]
	global_load_lds_dwordx4 v[220:221], off
	s_add_i32 m0, s57, 0x2000
	v_lshl_add_u64 v[224:225], s[26:27], 0, v[130:131]
	global_load_lds_dwordx4 v[222:223], off
	s_mov_b32 m0, s35
	v_lshl_add_u64 v[226:227], s[26:27], 0, v[134:135]
	global_load_lds_dwordx4 v[224:225], off
	s_mov_b32 m0, s36
	s_nop 0
	global_load_lds_dwordx4 v[226:227], off
	s_waitcnt vmcnt(8)
	s_waitcnt lgkmcnt(0)
	s_barrier
; #define PG8_STAGE(bufoff, gbase, voff) do { _Pragma("unroll") for (int _i = 0; _i < 2; ++_i) \
;         __builtin_amdgcn_global_load_lds((const unsigned*)((const char*)(gbase) + (voff)[_i]), (PG8_LAS unsigned*)(lds + (bufoff) + ldsw + _i * 8192), 16, 0, 0); } while (0)
; #define PG8_LDA(dst, b, h) do { _Pragma("unroll") for (int m = 0; m < 4; ++m) _Pragma("unroll") for (int k = 0; k < 2; ++k) dst[m][k] = *(const PG8_LAS bf16x8*)(lds + PG8_SA(b, h) + aoff + m * 2048 + k * 1024); } while (0)
; #define PG8_LDB(dst, b, h) do { _Pragma("unroll") for (int n = 0; n < 2; ++n) _Pragma("unroll") for (int k = 0; k < 2; ++k) dst[n][k] = *(const PG8_LAS bf16x8*)(lds + PG8_SB(b, h) + boff + n * 2048 + k * 1024); } while (0)
; #define PG8_MMA(ai, bj, At, Bt) do { __builtin_amdgcn_s_setprio(1); _Pragma("unroll") for (int m = 0; m < 4; ++m) _Pragma("unroll") for (int n = 0; n < 2; ++n) _Pragma("unroll") for (int k = 0; k < 2; ++k) \
;         acc[ai][bj][m][n] = __builtin_amdgcn_mfma_f32_16x16x32_bf16(Bt[n][k], At[m][k], acc[ai][bj][m][n], 0, 0, 0); __builtin_amdgcn_s_setprio(0); } while (0)
; #define PG8_WAIT_V(n) asm volatile("s_waitcnt vmcnt(" #n ")" ::: "memory")
; #define PG8_WAIT_L(n) asm volatile("s_waitcnt lgkmcnt(" #n ")" ::: "memory")
; #define PG8_BAR __builtin_amdgcn_s_barrier()
; #define PG8_SCHED __builtin_amdgcn_sched_barrier(0)
; template <class Epi, class Sched, bool ALIGN_EPI = false, bool SP2 = false>
; __device__ __forceinline__ void gemm_phase(PG8_LAS unsigned char* lds, const Gemm g, const Sched& S, const Epi& E) {
;     ...
;             PG8_WAIT_V(8); PG8_WAIT_L(0); PG8_BAR; PG8_MMA(1, 0, At, B0); PG8_MMA(1, 1, At, B1); PG8_BAR; PG8_SCHED;
;             PG8_LDB(B0, 1, 0); PG8_LDB(B1, 1, 1); PG8_SCHED; PG8_LDA(At, 1, 0); PG8_STAGE(PG8_SA(0, 1), a2 + hstep, voffA);
;             PG8_WAIT_V(8); PG8_WAIT_L(0); PG8_BAR; PG8_MMA(0, 0, At, B0); PG8_MMA(0, 1, At, B1); PG8_BAR; PG8_SCHED;
	s_setprio 1
	v_mfma_f32_16x16x32_bf16 v[62:65], v[152:155], v[184:187], v[62:65]
	v_mfma_f32_16x16x32_bf16 v[58:61], v[160:163], v[184:187], v[58:61]
	v_mfma_f32_16x16x32_bf16 v[46:49], v[152:155], v[192:195], v[46:49]
	v_mfma_f32_16x16x32_bf16 v[42:45], v[160:163], v[192:195], v[42:45]
	v_mfma_f32_16x16x32_bf16 v[30:33], v[152:155], v[200:203], v[30:33]
	v_mfma_f32_16x16x32_bf16 v[26:29], v[160:163], v[200:203], v[26:29]
	v_mfma_f32_16x16x32_bf16 v[14:17], v[152:155], v[208:211], v[14:17]
	v_mfma_f32_16x16x32_bf16 v[10:13], v[160:163], v[208:211], v[10:13]
	v_mfma_f32_16x16x32_bf16 v[62:65], v[156:159], v[188:191], v[62:65]
	v_mfma_f32_16x16x32_bf16 v[58:61], v[164:167], v[188:191], v[58:61]
	v_mfma_f32_16x16x32_bf16 v[46:49], v[156:159], v[196:199], v[46:49]
	v_mfma_f32_16x16x32_bf16 v[42:45], v[164:167], v[196:199], v[42:45]
	v_mfma_f32_16x16x32_bf16 v[30:33], v[156:159], v[204:207], v[30:33]
	v_mfma_f32_16x16x32_bf16 v[26:29], v[164:167], v[204:207], v[26:29]
	v_mfma_f32_16x16x32_bf16 v[14:17], v[156:159], v[212:215], v[14:17]
	v_mfma_f32_16x16x32_bf16 v[10:13], v[164:167], v[212:215], v[10:13]
	v_mfma_f32_16x16x32_bf16 v[54:57], v[168:171], v[184:187], v[54:57]
	v_mfma_f32_16x16x32_bf16 v[50:53], v[176:179], v[184:187], v[50:53]
	v_mfma_f32_16x16x32_bf16 v[38:41], v[168:171], v[192:195], v[38:41]
	v_mfma_f32_16x16x32_bf16 v[34:37], v[176:179], v[192:195], v[34:37]
	v_mfma_f32_16x16x32_bf16 v[22:25], v[168:171], v[200:203], v[22:25]
	v_mfma_f32_16x16x32_bf16 v[18:21], v[176:179], v[200:203], v[18:21]
	v_mfma_f32_16x16x32_bf16 v[6:9], v[168:171], v[208:211], v[6:9]
	v_mfma_f32_16x16x32_bf16 v[2:5], v[176:179], v[208:211], v[2:5]
	v_mfma_f32_16x16x32_bf16 v[54:57], v[172:175], v[188:191], v[54:57]
	v_mfma_f32_16x16x32_bf16 v[50:53], v[180:183], v[188:191], v[50:53]
	v_mfma_f32_16x16x32_bf16 v[38:41], v[172:175], v[196:199], v[38:41]
	v_mfma_f32_16x16x32_bf16 v[34:37], v[180:183], v[196:199], v[34:37]
	v_mfma_f32_16x16x32_bf16 v[22:25], v[172:175], v[204:207], v[22:25]
	v_mfma_f32_16x16x32_bf16 v[18:21], v[180:183], v[204:207], v[18:21]
	v_mfma_f32_16x16x32_bf16 v[6:9], v[172:175], v[212:215], v[6:9]
	v_mfma_f32_16x16x32_bf16 v[2:5], v[180:183], v[212:215], v[2:5]
	s_setprio 0
	s_barrier
	s_add_i32 s57, 0, 0x18000
	v_add_u32_e32 v151, s57, v146
	s_add_i32 s58, 0, 0x1c000
	ds_read_b128 v[152:155], v151
	ds_read_b128 v[156:159], v151 offset:1024
	ds_read_b128 v[160:163], v151 offset:2048
	ds_read_b128 v[164:167], v151 offset:3072
	v_add_u32_e32 v151, s58, v146
	ds_read_b128 v[168:171], v151
	ds_read_b128 v[172:175], v151 offset:1024
	ds_read_b128 v[176:179], v151 offset:2048
	ds_read_b128 v[180:183], v151 offset:3072
	s_add_u32 s26, s26, s8
	s_addc_u32 s27, s27, s9
	s_mov_b32 m0, s37
	v_lshl_add_u64 v[228:229], s[26:27], 0, v[130:131]
	ds_read_b128 v[184:187], v150 offset:32768
	ds_read_b128 v[188:191], v150 offset:33792
	ds_read_b128 v[192:195], v150 offset:34816
	ds_read_b128 v[196:199], v150 offset:35840
	ds_read_b128 v[200:203], v150 offset:36864
	ds_read_b128 v[204:207], v150 offset:37888
	ds_read_b128 v[208:211], v150 offset:38912
	ds_read_b128 v[212:215], v150 offset:39936
	global_load_lds_dwordx4 v[228:229], off
	v_lshl_add_u64 v[228:229], s[26:27], 0, v[134:135]
	s_mov_b32 m0, s38
	s_nop 0
	global_load_lds_dwordx4 v[228:229], off
	s_waitcnt vmcnt(8)
	s_waitcnt lgkmcnt(0)
	s_barrier
	s_setprio 1
	v_mfma_f32_16x16x32_bf16 v[122:125], v[152:155], v[184:187], v[122:125]
	v_mfma_f32_16x16x32_bf16 v[126:129], v[160:163], v[184:187], v[126:129]
	v_mfma_f32_16x16x32_bf16 v[110:113], v[152:155], v[192:195], v[110:113]
	v_mfma_f32_16x16x32_bf16 v[106:109], v[160:163], v[192:195], v[106:109]
	v_mfma_f32_16x16x32_bf16 v[94:97], v[152:155], v[200:203], v[94:97]
	v_mfma_f32_16x16x32_bf16 v[90:93], v[160:163], v[200:203], v[90:93]
	v_mfma_f32_16x16x32_bf16 v[78:81], v[152:155], v[208:211], v[78:81]
	v_mfma_f32_16x16x32_bf16 v[74:77], v[160:163], v[208:211], v[74:77]
	v_mfma_f32_16x16x32_bf16 v[122:125], v[156:159], v[188:191], v[122:125]
	v_mfma_f32_16x16x32_bf16 v[126:129], v[164:167], v[188:191], v[126:129]
	v_mfma_f32_16x16x32_bf16 v[110:113], v[156:159], v[196:199], v[110:113]
	v_mfma_f32_16x16x32_bf16 v[106:109], v[164:167], v[196:199], v[106:109]
	v_mfma_f32_16x16x32_bf16 v[94:97], v[156:159], v[204:207], v[94:97]
	v_mfma_f32_16x16x32_bf16 v[90:93], v[164:167], v[204:207], v[90:93]
	v_mfma_f32_16x16x32_bf16 v[78:81], v[156:159], v[212:215], v[78:81]
	v_mfma_f32_16x16x32_bf16 v[74:77], v[164:167], v[212:215], v[74:77]
	v_mfma_f32_16x16x32_bf16 v[118:121], v[168:171], v[184:187], v[118:121]
	v_mfma_f32_16x16x32_bf16 v[114:117], v[176:179], v[184:187], v[114:117]
	v_mfma_f32_16x16x32_bf16 v[102:105], v[168:171], v[192:195], v[102:105]
	v_mfma_f32_16x16x32_bf16 v[98:101], v[176:179], v[192:195], v[98:101]
	v_mfma_f32_16x16x32_bf16 v[86:89], v[168:171], v[200:203], v[86:89]
	v_mfma_f32_16x16x32_bf16 v[82:85], v[176:179], v[200:203], v[82:85]
	v_mfma_f32_16x16x32_bf16 v[70:73], v[168:171], v[208:211], v[70:73]
	v_mfma_f32_16x16x32_bf16 v[66:69], v[176:179], v[208:211], v[66:69]
	v_mfma_f32_16x16x32_bf16 v[118:121], v[172:175], v[188:191], v[118:121]
	v_mfma_f32_16x16x32_bf16 v[114:117], v[180:183], v[188:191], v[114:117]
	v_mfma_f32_16x16x32_bf16 v[102:105], v[172:175], v[196:199], v[102:105]
	v_mfma_f32_16x16x32_bf16 v[98:101], v[180:183], v[196:199], v[98:101]
	v_mfma_f32_16x16x32_bf16 v[86:89], v[172:175], v[204:207], v[86:89]
	v_mfma_f32_16x16x32_bf16 v[82:85], v[180:183], v[204:207], v[82:85]
	v_mfma_f32_16x16x32_bf16 v[70:73], v[172:175], v[212:215], v[70:73]
	v_mfma_f32_16x16x32_bf16 v[66:69], v[180:183], v[212:215], v[66:69]
	s_setprio 0
	s_barrier
; #define PG8_STAGE(bufoff, gbase, voff) do { _Pragma("unroll") for (int _i = 0; _i < 2; ++_i) \
;         __builtin_amdgcn_global_load_lds((const unsigned*)((const char*)(gbase) + (voff)[_i]), (PG8_LAS unsigned*)(lds + (bufoff) + ldsw + _i * 8192), 16, 0, 0); } while (0)
; #define PG8_LDA(dst, b, h) do { _Pragma("unroll") for (int m = 0; m < 4; ++m) _Pragma("unroll") for (int k = 0; k < 2; ++k) dst[m][k] = *(const PG8_LAS bf16x8*)(lds + PG8_SA(b, h) + aoff + m * 2048 + k * 1024); } while (0)
; #define PG8_MMA(ai, bj, At, Bt) do { __builtin_amdgcn_s_setprio(1); _Pragma("unroll") for (int m = 0; m < 4; ++m) _Pragma("unroll") for (int n = 0; n < 2; ++n) _Pragma("unroll") for (int k = 0; k < 2; ++k) \
;         acc[ai][bj][m][n] = __builtin_amdgcn_mfma_f32_16x16x32_bf16(Bt[n][k], At[m][k], acc[ai][bj][m][n], 0, 0, 0); __builtin_amdgcn_s_setprio(0); } while (0)
; #define PG8_WAIT_V(n) asm volatile("s_waitcnt vmcnt(" #n ")" ::: "memory")
; #define PG8_WAIT_L(n) asm volatile("s_waitcnt lgkmcnt(" #n ")" ::: "memory")
; #define PG8_BAR __builtin_amdgcn_s_barrier()
; #define PG8_SCHED __builtin_amdgcn_sched_barrier(0)
; template <class Epi, class Sched, bool ALIGN_EPI = false, bool SP2 = false>
; __device__ __forceinline__ void gemm_phase(PG8_LAS unsigned char* lds, const Gemm g, const Sched& S, const Epi& E) {
;     ...
;             PG8_LDA(At, 1, 1); PG8_STAGE(PG8_SB(1, 0), b3, voffB); PG8_STAGE(PG8_SB(1, 1), b3 + hstep, voffB); PG8_STAGE(PG8_SA(1, 0), a3, voffA);
;             PG8_WAIT_V(8); PG8_WAIT_L(0); PG8_BAR; PG8_MMA(1, 0, At, B0); PG8_MMA(1, 1, At, B1); PG8_BAR; PG8_SCHED;
	s_add_i32 s26, s57, s34
	v_lshl_add_u64 v[216:217], v[216:217], 0, s[16:17]
	s_mov_b32 m0, s26
	ds_read_b128 v[184:187], v150 offset:49152
	ds_read_b128 v[188:191], v150 offset:50176
	ds_read_b128 v[192:195], v150 offset:51200
	ds_read_b128 v[196:199], v150 offset:52224
	ds_read_b128 v[200:203], v150 offset:53248
	ds_read_b128 v[204:207], v150 offset:54272
	ds_read_b128 v[208:211], v150 offset:55296
	ds_read_b128 v[212:215], v150 offset:56320
	global_load_lds_dwordx4 v[216:217], off
	v_lshl_add_u64 v[216:217], v[218:219], 0, s[16:17]
	s_add_i32 m0, s26, 0x2000
	s_add_i32 s26, s58, s34
	global_load_lds_dwordx4 v[216:217], off
	v_lshl_add_u64 v[216:217], v[220:221], 0, s[16:17]
	s_mov_b32 m0, s26
	s_nop 0
	global_load_lds_dwordx4 v[216:217], off
	v_lshl_add_u64 v[216:217], v[222:223], 0, s[16:17]
	s_add_i32 m0, s26, 0x2000
	s_nop 0
	global_load_lds_dwordx4 v[216:217], off
	v_lshl_add_u64 v[216:217], v[224:225], 0, s[16:17]
	s_mov_b32 m0, s40
	s_nop 0
	global_load_lds_dwordx4 v[216:217], off
	v_lshl_add_u64 v[216:217], v[226:227], 0, s[16:17]
	s_mov_b32 m0, s41
	s_nop 0
	global_load_lds_dwordx4 v[216:217], off
	s_waitcnt vmcnt(8)
	s_waitcnt lgkmcnt(0)
	s_barrier
	s_setprio 1
	v_mfma_f32_16x16x32_bf16 v[62:65], v[152:155], v[184:187], v[62:65]
	v_mfma_f32_16x16x32_bf16 v[58:61], v[160:163], v[184:187], v[58:61]
	v_mfma_f32_16x16x32_bf16 v[46:49], v[152:155], v[192:195], v[46:49]
	v_mfma_f32_16x16x32_bf16 v[42:45], v[160:163], v[192:195], v[42:45]
	v_mfma_f32_16x16x32_bf16 v[30:33], v[152:155], v[200:203], v[30:33]
	v_mfma_f32_16x16x32_bf16 v[26:29], v[160:163], v[200:203], v[26:29]
	v_mfma_f32_16x16x32_bf16 v[14:17], v[152:155], v[208:211], v[14:17]
	v_mfma_f32_16x16x32_bf16 v[10:13], v[160:163], v[208:211], v[10:13]
	v_mfma_f32_16x16x32_bf16 v[62:65], v[156:159], v[188:191], v[62:65]
	v_mfma_f32_16x16x32_bf16 v[58:61], v[164:167], v[188:191], v[58:61]
	v_mfma_f32_16x16x32_bf16 v[46:49], v[156:159], v[196:199], v[46:49]
	v_mfma_f32_16x16x32_bf16 v[42:45], v[164:167], v[196:199], v[42:45]
	v_mfma_f32_16x16x32_bf16 v[30:33], v[156:159], v[204:207], v[30:33]
	v_mfma_f32_16x16x32_bf16 v[26:29], v[164:167], v[204:207], v[26:29]
	v_mfma_f32_16x16x32_bf16 v[14:17], v[156:159], v[212:215], v[14:17]
	v_mfma_f32_16x16x32_bf16 v[10:13], v[164:167], v[212:215], v[10:13]
	v_mfma_f32_16x16x32_bf16 v[54:57], v[168:171], v[184:187], v[54:57]
	v_mfma_f32_16x16x32_bf16 v[50:53], v[176:179], v[184:187], v[50:53]
	v_mfma_f32_16x16x32_bf16 v[38:41], v[168:171], v[192:195], v[38:41]
	v_mfma_f32_16x16x32_bf16 v[34:37], v[176:179], v[192:195], v[34:37]
	v_mfma_f32_16x16x32_bf16 v[22:25], v[168:171], v[200:203], v[22:25]
	v_mfma_f32_16x16x32_bf16 v[18:21], v[176:179], v[200:203], v[18:21]
	v_mfma_f32_16x16x32_bf16 v[6:9], v[168:171], v[208:211], v[6:9]
	v_mfma_f32_16x16x32_bf16 v[2:5], v[176:179], v[208:211], v[2:5]
	v_mfma_f32_16x16x32_bf16 v[54:57], v[172:175], v[188:191], v[54:57]
	v_mfma_f32_16x16x32_bf16 v[50:53], v[180:183], v[188:191], v[50:53]
	v_mfma_f32_16x16x32_bf16 v[38:41], v[172:175], v[196:199], v[38:41]
	v_mfma_f32_16x16x32_bf16 v[34:37], v[180:183], v[196:199], v[34:37]
	v_mfma_f32_16x16x32_bf16 v[22:25], v[172:175], v[204:207], v[22:25]
	v_mfma_f32_16x16x32_bf16 v[18:21], v[180:183], v[204:207], v[18:21]
	v_mfma_f32_16x16x32_bf16 v[6:9], v[172:175], v[212:215], v[6:9]
	v_mfma_f32_16x16x32_bf16 v[2:5], v[180:183], v[212:215], v[2:5]
	s_setprio 0
	s_barrier
	s_add_u32 s54, s54, 0x100
	s_addc_u32 s55, s55, 0
	s_add_u32 s24, s24, 0x100
	s_addc_u32 s25, s25, 0
	s_cmp_ge_i32 s56, s42
	s_mov_b32 s26, s56
	s_cbranch_scc0 .LBB0_1809

; #define PG8_STAGE(bufoff, gbase, voff) do { _Pragma("unroll") for (int _i = 0; _i < 2; ++_i) \
;         __builtin_amdgcn_global_load_lds((const unsigned*)((const char*)(gbase) + (voff)[_i]), (PG8_LAS unsigned*)(lds + (bufoff) + ldsw + _i * 8192), 16, 0, 0); } while (0)
; #define PG8_LDA(dst, b, h) do { _Pragma("unroll") for (int m = 0; m < 4; ++m) _Pragma("unroll") for (int k = 0; k < 2; ++k) dst[m][k] = *(const PG8_LAS bf16x8*)(lds + PG8_SA(b, h) + aoff + m * 2048 + k * 1024); } while (0)
; #define PG8_LDB(dst, b, h) do { _Pragma("unroll") for (int n = 0; n < 2; ++n) _Pragma("unroll") for (int k = 0; k < 2; ++k) dst[n][k] = *(const PG8_LAS bf16x8*)(lds + PG8_SB(b, h) + boff + n * 2048 + k * 1024); } while (0)
; #define PG8_MMA(ai, bj, At, Bt) do { __builtin_amdgcn_s_setprio(1); _Pragma("unroll") for (int m = 0; m < 4; ++m) _Pragma("unroll") for (int n = 0; n < 2; ++n) _Pragma("unroll") for (int k = 0; k < 2; ++k) \
;         acc[ai][bj][m][n] = __builtin_amdgcn_mfma_f32_16x16x32_bf16(Bt[n][k], At[m][k], acc[ai][bj][m][n], 0, 0, 0); __builtin_amdgcn_s_setprio(0); } while (0)
; #define PG8_WAIT_V(n) asm volatile("s_waitcnt vmcnt(" #n ")" ::: "memory")
; #define PG8_WAIT_L(n) asm volatile("s_waitcnt lgkmcnt(" #n ")" ::: "memory")
; #define PG8_BAR __builtin_amdgcn_s_barrier()
; #define PG8_SCHED __builtin_amdgcn_sched_barrier(0)
; template <class Epi, class Sched, bool ALIGN_EPI = false, bool SP2 = false>
; __device__ __forceinline__ void gemm_phase(PG8_LAS unsigned char* lds, const Gemm g, const Sched& S, const Epi& E) {
;     ...
;             PG8_LDB(B0, 0, 0); PG8_LDB(B1, 0, 1); PG8_SCHED; PG8_LDA(At, 0, 0); PG8_STAGE(PG8_SA(1, 1), a1 + hstep, voffA);
;             PG8_WAIT_V(8); PG8_WAIT_L(0); PG8_BAR; PG8_MMA(0, 0, At, B0); PG8_MMA(0, 1, At, B1); PG8_BAR; PG8_SCHED;
;             PG8_LDA(At, 0, 1); PG8_STAGE(PG8_SB(0, 0), b2, voffB); PG8_STAGE(PG8_SB(0, 1), b2 + hstep, voffB); PG8_STAGE(PG8_SA(0, 0), a2, voffA);
;             PG8_WAIT_V(8); PG8_WAIT_L(0); PG8_BAR; PG8_MMA(1, 0, At, B0); PG8_MMA(1, 1, At, B1); PG8_BAR; PG8_SCHED;
.LBB0_1976:
	ds_read_b128 v[152:155], v148
	ds_read_b128 v[156:159], v148 offset:1024
	ds_read_b128 v[160:163], v148 offset:2048
	ds_read_b128 v[164:167], v148 offset:3072
	ds_read_b128 v[168:171], v149
	ds_read_b128 v[172:175], v149 offset:1024
	ds_read_b128 v[176:179], v149 offset:2048
	ds_read_b128 v[180:183], v149 offset:3072
	s_add_i32 s58, s26, 2
	s_add_u32 s59, s24, 0x80
	s_addc_u32 s27, s25, 0
	s_cmp_eq_u32 s44, s26
	s_cselect_b32 s26, s4, s59
	s_cselect_b32 s27, s5, s27
	s_cselect_b32 s61, s23, s57
	s_cselect_b32 s60, s22, s56
	v_lshl_add_u64 v[216:217], s[24:25], 0, v[140:141]
	s_add_i32 m0, s36, 0xc000
	ds_read_b128 v[184:187], v150
	ds_read_b128 v[188:191], v150 offset:1024
	ds_read_b128 v[192:195], v150 offset:2048
	ds_read_b128 v[196:199], v150 offset:3072
	ds_read_b128 v[200:203], v150 offset:4096
	ds_read_b128 v[204:207], v150 offset:5120
	ds_read_b128 v[208:211], v150 offset:6144
	ds_read_b128 v[212:215], v150 offset:7168
	global_load_lds_dwordx4 v[216:217], off
	v_lshl_add_u64 v[216:217], s[24:25], 0, v[138:139]
	s_add_i32 m0, s36, 0xe000
	s_nop 0
	global_load_lds_dwordx4 v[216:217], off
	s_waitcnt vmcnt(8)
	s_waitcnt lgkmcnt(0)
	s_barrier
	s_setprio 1
	v_mfma_f32_16x16x32_bf16 v[122:125], v[152:155], v[184:187], v[122:125]
	v_mfma_f32_16x16x32_bf16 v[118:121], v[160:163], v[184:187], v[118:121]
	v_mfma_f32_16x16x32_bf16 v[110:113], v[152:155], v[192:195], v[110:113]
	v_mfma_f32_16x16x32_bf16 v[102:105], v[160:163], v[192:195], v[102:105]
	v_mfma_f32_16x16x32_bf16 v[94:97], v[152:155], v[200:203], v[94:97]
	v_mfma_f32_16x16x32_bf16 v[86:89], v[160:163], v[200:203], v[86:89]
	v_mfma_f32_16x16x32_bf16 v[78:81], v[152:155], v[208:211], v[78:81]
	v_mfma_f32_16x16x32_bf16 v[70:73], v[160:163], v[208:211], v[70:73]
	v_mfma_f32_16x16x32_bf16 v[122:125], v[156:159], v[188:191], v[122:125]
	v_mfma_f32_16x16x32_bf16 v[118:121], v[164:167], v[188:191], v[118:121]
	v_mfma_f32_16x16x32_bf16 v[110:113], v[156:159], v[196:199], v[110:113]
	v_mfma_f32_16x16x32_bf16 v[102:105], v[164:167], v[196:199], v[102:105]
	v_mfma_f32_16x16x32_bf16 v[94:97], v[156:159], v[204:207], v[94:97]
	v_mfma_f32_16x16x32_bf16 v[86:89], v[164:167], v[204:207], v[86:89]
	v_mfma_f32_16x16x32_bf16 v[78:81], v[156:159], v[212:215], v[78:81]
	v_mfma_f32_16x16x32_bf16 v[70:73], v[164:167], v[212:215], v[70:73]
	v_mfma_f32_16x16x32_bf16 v[126:129], v[168:171], v[184:187], v[126:129]
	v_mfma_f32_16x16x32_bf16 v[114:117], v[176:179], v[184:187], v[114:117]
	v_mfma_f32_16x16x32_bf16 v[106:109], v[168:171], v[192:195], v[106:109]
	v_mfma_f32_16x16x32_bf16 v[98:101], v[176:179], v[192:195], v[98:101]
	v_mfma_f32_16x16x32_bf16 v[90:93], v[168:171], v[200:203], v[90:93]
	v_mfma_f32_16x16x32_bf16 v[82:85], v[176:179], v[200:203], v[82:85]
	v_mfma_f32_16x16x32_bf16 v[74:77], v[168:171], v[208:211], v[74:77]
	v_mfma_f32_16x16x32_bf16 v[66:69], v[176:179], v[208:211], v[66:69]
	v_mfma_f32_16x16x32_bf16 v[126:129], v[172:175], v[188:191], v[126:129]
	v_mfma_f32_16x16x32_bf16 v[114:117], v[180:183], v[188:191], v[114:117]
	v_mfma_f32_16x16x32_bf16 v[106:109], v[172:175], v[196:199], v[106:109]
	v_mfma_f32_16x16x32_bf16 v[98:101], v[180:183], v[196:199], v[98:101]
	v_mfma_f32_16x16x32_bf16 v[90:93], v[172:175], v[204:207], v[90:93]
	v_mfma_f32_16x16x32_bf16 v[82:85], v[180:183], v[204:207], v[82:85]
	v_mfma_f32_16x16x32_bf16 v[74:77], v[172:175], v[212:215], v[74:77]
	v_mfma_f32_16x16x32_bf16 v[66:69], v[180:183], v[212:215], v[66:69]
	s_setprio 0
	s_barrier
	s_add_i32 s59, s47, s31
	v_lshl_add_u64 v[216:217], s[60:61], 0, v[134:135]
	s_mov_b32 m0, s59
	ds_read_b128 v[184:187], v150 offset:16384
	ds_read_b128 v[188:191], v150 offset:17408
	ds_read_b128 v[192:195], v150 offset:18432
	ds_read_b128 v[196:199], v150 offset:19456
	ds_read_b128 v[200:203], v150 offset:20480
	ds_read_b128 v[204:207], v150 offset:21504
	ds_read_b128 v[208:211], v150 offset:22528
	ds_read_b128 v[212:215], v150 offset:23552
	global_load_lds_dwordx4 v[216:217], off
	s_add_i32 m0, s59, 0x2000
	v_lshl_add_u64 v[218:219], s[60:61], 0, v[130:131]
	s_add_u32 s60, s60, s8
	s_addc_u32 s61, s61, s9
	s_add_i32 s59, s48, s31
	global_load_lds_dwordx4 v[218:219], off
	v_lshl_add_u64 v[220:221], s[60:61], 0, v[134:135]
	s_mov_b32 m0, s59
	v_lshl_add_u64 v[222:223], s[60:61], 0, v[130:131]
	global_load_lds_dwordx4 v[220:221], off
	s_add_i32 m0, s59, 0x2000
	v_lshl_add_u64 v[224:225], s[26:27], 0, v[136:137]
	global_load_lds_dwordx4 v[222:223], off
	s_mov_b32 m0, s36
	v_lshl_add_u64 v[226:227], s[26:27], 0, v[132:133]
	global_load_lds_dwordx4 v[224:225], off
	s_mov_b32 m0, s37
	s_nop 0
	global_load_lds_dwordx4 v[226:227], off
	s_waitcnt vmcnt(8)
	s_waitcnt lgkmcnt(0)
	s_barrier
; #define PG8_STAGE(bufoff, gbase, voff) do { _Pragma("unroll") for (int _i = 0; _i < 2; ++_i) \
;         __builtin_amdgcn_global_load_lds((const unsigned*)((const char*)(gbase) + (voff)[_i]), (PG8_LAS unsigned*)(lds + (bufoff) + ldsw + _i * 8192), 16, 0, 0); } while (0)
; #define PG8_LDA(dst, b, h) do { _Pragma("unroll") for (int m = 0; m < 4; ++m) _Pragma("unroll") for (int k = 0; k < 2; ++k) dst[m][k] = *(const PG8_LAS bf16x8*)(lds + PG8_SA(b, h) + aoff + m * 2048 + k * 1024); } while (0)
; #define PG8_LDB(dst, b, h) do { _Pragma("unroll") for (int n = 0; n < 2; ++n) _Pragma("unroll") for (int k = 0; k < 2; ++k) dst[n][k] = *(const PG8_LAS bf16x8*)(lds + PG8_SB(b, h) + boff + n * 2048 + k * 1024); } while (0)
; #define PG8_MMA(ai, bj, At, Bt) do { __builtin_amdgcn_s_setprio(1); _Pragma("unroll") for (int m = 0; m < 4; ++m) _Pragma("unroll") for (int n = 0; n < 2; ++n) _Pragma("unroll") for (int k = 0; k < 2; ++k) \
;         acc[ai][bj][m][n] = __builtin_amdgcn_mfma_f32_16x16x32_bf16(Bt[n][k], At[m][k], acc[ai][bj][m][n], 0, 0, 0); __builtin_amdgcn_s_setprio(0); } while (0)
; #define PG8_WAIT_V(n) asm volatile("s_waitcnt vmcnt(" #n ")" ::: "memory")
; #define PG8_WAIT_L(n) asm volatile("s_waitcnt lgkmcnt(" #n ")" ::: "memory")
; #define PG8_BAR __builtin_amdgcn_s_barrier()
; #define PG8_SCHED __builtin_amdgcn_sched_barrier(0)
; template <class Epi, class Sched, bool ALIGN_EPI = false, bool SP2 = false>
; __device__ __forceinline__ void gemm_phase(PG8_LAS unsigned char* lds, const Gemm g, const Sched& S, const Epi& E) {
;     ...
;             PG8_WAIT_V(8); PG8_WAIT_L(0); PG8_BAR; PG8_MMA(1, 0, At, B0); PG8_MMA(1, 1, At, B1); PG8_BAR; PG8_SCHED;
;             PG8_LDB(B0, 1, 0); PG8_LDB(B1, 1, 1); PG8_SCHED; PG8_LDA(At, 1, 0); PG8_STAGE(PG8_SA(0, 1), a2 + hstep, voffA);
;             PG8_WAIT_V(8); PG8_WAIT_L(0); PG8_BAR; PG8_MMA(0, 0, At, B0); PG8_MMA(0, 1, At, B1); PG8_BAR; PG8_SCHED;
	s_setprio 1
	v_mfma_f32_16x16x32_bf16 v[62:65], v[152:155], v[184:187], v[62:65]
	v_mfma_f32_16x16x32_bf16 v[54:57], v[160:163], v[184:187], v[54:57]
	v_mfma_f32_16x16x32_bf16 v[46:49], v[152:155], v[192:195], v[46:49]
	v_mfma_f32_16x16x32_bf16 v[38:41], v[160:163], v[192:195], v[38:41]
	v_mfma_f32_16x16x32_bf16 v[30:33], v[152:155], v[200:203], v[30:33]
	v_mfma_f32_16x16x32_bf16 v[22:25], v[160:163], v[200:203], v[22:25]
	v_mfma_f32_16x16x32_bf16 v[14:17], v[152:155], v[208:211], v[14:17]
	v_mfma_f32_16x16x32_bf16 v[6:9], v[160:163], v[208:211], v[6:9]
	v_mfma_f32_16x16x32_bf16 v[62:65], v[156:159], v[188:191], v[62:65]
	v_mfma_f32_16x16x32_bf16 v[54:57], v[164:167], v[188:191], v[54:57]
	v_mfma_f32_16x16x32_bf16 v[46:49], v[156:159], v[196:199], v[46:49]
	v_mfma_f32_16x16x32_bf16 v[38:41], v[164:167], v[196:199], v[38:41]
	v_mfma_f32_16x16x32_bf16 v[30:33], v[156:159], v[204:207], v[30:33]
	v_mfma_f32_16x16x32_bf16 v[22:25], v[164:167], v[204:207], v[22:25]
	v_mfma_f32_16x16x32_bf16 v[14:17], v[156:159], v[212:215], v[14:17]
	v_mfma_f32_16x16x32_bf16 v[6:9], v[164:167], v[212:215], v[6:9]
	v_mfma_f32_16x16x32_bf16 v[58:61], v[168:171], v[184:187], v[58:61]
	v_mfma_f32_16x16x32_bf16 v[50:53], v[176:179], v[184:187], v[50:53]
	v_mfma_f32_16x16x32_bf16 v[42:45], v[168:171], v[192:195], v[42:45]
	v_mfma_f32_16x16x32_bf16 v[34:37], v[176:179], v[192:195], v[34:37]
	v_mfma_f32_16x16x32_bf16 v[26:29], v[168:171], v[200:203], v[26:29]
	v_mfma_f32_16x16x32_bf16 v[18:21], v[176:179], v[200:203], v[18:21]
	v_mfma_f32_16x16x32_bf16 v[10:13], v[168:171], v[208:211], v[10:13]
	v_mfma_f32_16x16x32_bf16 v[2:5], v[176:179], v[208:211], v[2:5]
	v_mfma_f32_16x16x32_bf16 v[58:61], v[172:175], v[188:191], v[58:61]
	v_mfma_f32_16x16x32_bf16 v[50:53], v[180:183], v[188:191], v[50:53]
	v_mfma_f32_16x16x32_bf16 v[42:45], v[172:175], v[196:199], v[42:45]
	v_mfma_f32_16x16x32_bf16 v[34:37], v[180:183], v[196:199], v[34:37]
	v_mfma_f32_16x16x32_bf16 v[26:29], v[172:175], v[204:207], v[26:29]
	v_mfma_f32_16x16x32_bf16 v[18:21], v[180:183], v[204:207], v[18:21]
	v_mfma_f32_16x16x32_bf16 v[10:13], v[172:175], v[212:215], v[10:13]
	v_mfma_f32_16x16x32_bf16 v[2:5], v[180:183], v[212:215], v[2:5]
	s_setprio 0
	s_barrier
	s_add_i32 s59, 0, 0x18000
	v_add_u32_e32 v151, s59, v146
	s_add_i32 s60, 0, 0x1c000
	ds_read_b128 v[152:155], v151
	ds_read_b128 v[156:159], v151 offset:1024
	ds_read_b128 v[160:163], v151 offset:2048
	ds_read_b128 v[164:167], v151 offset:3072
	v_add_u32_e32 v151, s60, v146
	ds_read_b128 v[168:171], v151
	ds_read_b128 v[172:175], v151 offset:1024
	ds_read_b128 v[176:179], v151 offset:2048
	ds_read_b128 v[180:183], v151 offset:3072
	s_add_u32 s26, s26, s8
	s_addc_u32 s27, s27, s9
	s_mov_b32 m0, s38
	v_lshl_add_u64 v[228:229], s[26:27], 0, v[136:137]
	ds_read_b128 v[184:187], v150 offset:32768
	ds_read_b128 v[188:191], v150 offset:33792
	ds_read_b128 v[192:195], v150 offset:34816
	ds_read_b128 v[196:199], v150 offset:35840
	ds_read_b128 v[200:203], v150 offset:36864
	ds_read_b128 v[204:207], v150 offset:37888
	ds_read_b128 v[208:211], v150 offset:38912
	ds_read_b128 v[212:215], v150 offset:39936
	global_load_lds_dwordx4 v[228:229], off
	v_lshl_add_u64 v[228:229], s[26:27], 0, v[132:133]
	s_mov_b32 m0, s39
	s_nop 0
	global_load_lds_dwordx4 v[228:229], off
	s_waitcnt vmcnt(8)
	s_waitcnt lgkmcnt(0)
	s_barrier
	s_setprio 1
	v_mfma_f32_16x16x32_bf16 v[122:125], v[152:155], v[184:187], v[122:125]
	v_mfma_f32_16x16x32_bf16 v[118:121], v[160:163], v[184:187], v[118:121]
	v_mfma_f32_16x16x32_bf16 v[110:113], v[152:155], v[192:195], v[110:113]
	v_mfma_f32_16x16x32_bf16 v[102:105], v[160:163], v[192:195], v[102:105]
	v_mfma_f32_16x16x32_bf16 v[94:97], v[152:155], v[200:203], v[94:97]
	v_mfma_f32_16x16x32_bf16 v[86:89], v[160:163], v[200:203], v[86:89]
	v_mfma_f32_16x16x32_bf16 v[78:81], v[152:155], v[208:211], v[78:81]
	v_mfma_f32_16x16x32_bf16 v[70:73], v[160:163], v[208:211], v[70:73]
	v_mfma_f32_16x16x32_bf16 v[122:125], v[156:159], v[188:191], v[122:125]
	v_mfma_f32_16x16x32_bf16 v[118:121], v[164:167], v[188:191], v[118:121]
	v_mfma_f32_16x16x32_bf16 v[110:113], v[156:159], v[196:199], v[110:113]
	v_mfma_f32_16x16x32_bf16 v[102:105], v[164:167], v[196:199], v[102:105]
	v_mfma_f32_16x16x32_bf16 v[94:97], v[156:159], v[204:207], v[94:97]
	v_mfma_f32_16x16x32_bf16 v[86:89], v[164:167], v[204:207], v[86:89]
	v_mfma_f32_16x16x32_bf16 v[78:81], v[156:159], v[212:215], v[78:81]
	v_mfma_f32_16x16x32_bf16 v[70:73], v[164:167], v[212:215], v[70:73]
	v_mfma_f32_16x16x32_bf16 v[126:129], v[168:171], v[184:187], v[126:129]
	v_mfma_f32_16x16x32_bf16 v[114:117], v[176:179], v[184:187], v[114:117]
	v_mfma_f32_16x16x32_bf16 v[106:109], v[168:171], v[192:195], v[106:109]
	v_mfma_f32_16x16x32_bf16 v[98:101], v[176:179], v[192:195], v[98:101]
	v_mfma_f32_16x16x32_bf16 v[90:93], v[168:171], v[200:203], v[90:93]
	v_mfma_f32_16x16x32_bf16 v[82:85], v[176:179], v[200:203], v[82:85]
	v_mfma_f32_16x16x32_bf16 v[74:77], v[168:171], v[208:211], v[74:77]
	v_mfma_f32_16x16x32_bf16 v[66:69], v[176:179], v[208:211], v[66:69]
	v_mfma_f32_16x16x32_bf16 v[126:129], v[172:175], v[188:191], v[126:129]
	v_mfma_f32_16x16x32_bf16 v[114:117], v[180:183], v[188:191], v[114:117]
	v_mfma_f32_16x16x32_bf16 v[106:109], v[172:175], v[196:199], v[106:109]
	v_mfma_f32_16x16x32_bf16 v[98:101], v[180:183], v[196:199], v[98:101]
	v_mfma_f32_16x16x32_bf16 v[90:93], v[172:175], v[204:207], v[90:93]
	v_mfma_f32_16x16x32_bf16 v[82:85], v[180:183], v[204:207], v[82:85]
	v_mfma_f32_16x16x32_bf16 v[74:77], v[172:175], v[212:215], v[74:77]
	v_mfma_f32_16x16x32_bf16 v[66:69], v[180:183], v[212:215], v[66:69]
	s_setprio 0
	s_barrier
; #define PG8_STAGE(bufoff, gbase, voff) do { _Pragma("unroll") for (int _i = 0; _i < 2; ++_i) \
;         __builtin_amdgcn_global_load_lds((const unsigned*)((const char*)(gbase) + (voff)[_i]), (PG8_LAS unsigned*)(lds + (bufoff) + ldsw + _i * 8192), 16, 0, 0); } while (0)
; #define PG8_LDA(dst, b, h) do { _Pragma("unroll") for (int m = 0; m < 4; ++m) _Pragma("unroll") for (int k = 0; k < 2; ++k) dst[m][k] = *(const PG8_LAS bf16x8*)(lds + PG8_SA(b, h) + aoff + m * 2048 + k * 1024); } while (0)
; #define PG8_MMA(ai, bj, At, Bt) do { __builtin_amdgcn_s_setprio(1); _Pragma("unroll") for (int m = 0; m < 4; ++m) _Pragma("unroll") for (int n = 0; n < 2; ++n) _Pragma("unroll") for (int k = 0; k < 2; ++k) \
;         acc[ai][bj][m][n] = __builtin_amdgcn_mfma_f32_16x16x32_bf16(Bt[n][k], At[m][k], acc[ai][bj][m][n], 0, 0, 0); __builtin_amdgcn_s_setprio(0); } while (0)
; #define PG8_WAIT_V(n) asm volatile("s_waitcnt vmcnt(" #n ")" ::: "memory")
; #define PG8_WAIT_L(n) asm volatile("s_waitcnt lgkmcnt(" #n ")" ::: "memory")
; #define PG8_BAR __builtin_amdgcn_s_barrier()
; #define PG8_SCHED __builtin_amdgcn_sched_barrier(0)
; template <class Epi, class Sched, bool ALIGN_EPI = false, bool SP2 = false>
; __device__ __forceinline__ void gemm_phase(PG8_LAS unsigned char* lds, const Gemm g, const Sched& S, const Epi& E) {
;     ...
;         for (int t = 0; t < nt; t += 2) {
;             const bool last = (t == nt - 2);
;             const char* a1 = cA + (size_t)(t + 1) * kstep;
;             const char* a2 = last ? nA : cA + (size_t)(t + 2) * kstep; const char* b2 = last ? nB : cB + (size_t)(t + 2) * kstep;
;             const char* a3 = a2 + kstep; const char* b3 = b2 + kstep;
;     ...
;             PG8_LDA(At, 1, 1); PG8_STAGE(PG8_SB(1, 0), b3, voffB); PG8_STAGE(PG8_SB(1, 1), b3 + hstep, voffB); PG8_STAGE(PG8_SA(1, 0), a3, voffA);
;             PG8_WAIT_V(8); PG8_WAIT_L(0); PG8_BAR; PG8_MMA(1, 0, At, B0); PG8_MMA(1, 1, At, B1); PG8_BAR; PG8_SCHED;
	s_add_i32 s26, s59, s31
	v_lshl_add_u64 v[216:217], v[216:217], 0, s[16:17]
	s_mov_b32 m0, s26
	ds_read_b128 v[184:187], v150 offset:49152
	ds_read_b128 v[188:191], v150 offset:50176
	ds_read_b128 v[192:195], v150 offset:51200
	ds_read_b128 v[196:199], v150 offset:52224
	ds_read_b128 v[200:203], v150 offset:53248
	ds_read_b128 v[204:207], v150 offset:54272
	ds_read_b128 v[208:211], v150 offset:55296
	ds_read_b128 v[212:215], v150 offset:56320
	global_load_lds_dwordx4 v[216:217], off
	v_lshl_add_u64 v[216:217], v[218:219], 0, s[16:17]
	s_add_i32 m0, s26, 0x2000
	s_add_i32 s26, s60, s31
	global_load_lds_dwordx4 v[216:217], off
	v_lshl_add_u64 v[216:217], v[220:221], 0, s[16:17]
	s_mov_b32 m0, s26
	s_nop 0
	global_load_lds_dwordx4 v[216:217], off
	v_lshl_add_u64 v[216:217], v[222:223], 0, s[16:17]
	s_add_i32 m0, s26, 0x2000
	s_nop 0
	global_load_lds_dwordx4 v[216:217], off
	v_lshl_add_u64 v[216:217], v[224:225], 0, s[16:17]
	s_mov_b32 m0, s41
	s_nop 0
	global_load_lds_dwordx4 v[216:217], off
	v_lshl_add_u64 v[216:217], v[226:227], 0, s[16:17]
	s_mov_b32 m0, s42
	s_nop 0
	global_load_lds_dwordx4 v[216:217], off
	s_waitcnt vmcnt(8)
	s_waitcnt lgkmcnt(0)
	s_barrier
	s_setprio 1
	v_mfma_f32_16x16x32_bf16 v[62:65], v[152:155], v[184:187], v[62:65]
	v_mfma_f32_16x16x32_bf16 v[54:57], v[160:163], v[184:187], v[54:57]
	v_mfma_f32_16x16x32_bf16 v[46:49], v[152:155], v[192:195], v[46:49]
	v_mfma_f32_16x16x32_bf16 v[38:41], v[160:163], v[192:195], v[38:41]
	v_mfma_f32_16x16x32_bf16 v[30:33], v[152:155], v[200:203], v[30:33]
	v_mfma_f32_16x16x32_bf16 v[22:25], v[160:163], v[200:203], v[22:25]
	v_mfma_f32_16x16x32_bf16 v[14:17], v[152:155], v[208:211], v[14:17]
	v_mfma_f32_16x16x32_bf16 v[6:9], v[160:163], v[208:211], v[6:9]
	v_mfma_f32_16x16x32_bf16 v[62:65], v[156:159], v[188:191], v[62:65]
	v_mfma_f32_16x16x32_bf16 v[54:57], v[164:167], v[188:191], v[54:57]
	v_mfma_f32_16x16x32_bf16 v[46:49], v[156:159], v[196:199], v[46:49]
	v_mfma_f32_16x16x32_bf16 v[38:41], v[164:167], v[196:199], v[38:41]
	v_mfma_f32_16x16x32_bf16 v[30:33], v[156:159], v[204:207], v[30:33]
	v_mfma_f32_16x16x32_bf16 v[22:25], v[164:167], v[204:207], v[22:25]
	v_mfma_f32_16x16x32_bf16 v[14:17], v[156:159], v[212:215], v[14:17]
	v_mfma_f32_16x16x32_bf16 v[6:9], v[164:167], v[212:215], v[6:9]
	v_mfma_f32_16x16x32_bf16 v[58:61], v[168:171], v[184:187], v[58:61]
	v_mfma_f32_16x16x32_bf16 v[50:53], v[176:179], v[184:187], v[50:53]
	v_mfma_f32_16x16x32_bf16 v[42:45], v[168:171], v[192:195], v[42:45]
	v_mfma_f32_16x16x32_bf16 v[34:37], v[176:179], v[192:195], v[34:37]
	v_mfma_f32_16x16x32_bf16 v[26:29], v[168:171], v[200:203], v[26:29]
	v_mfma_f32_16x16x32_bf16 v[18:21], v[176:179], v[200:203], v[18:21]
	v_mfma_f32_16x16x32_bf16 v[10:13], v[168:171], v[208:211], v[10:13]
	v_mfma_f32_16x16x32_bf16 v[2:5], v[176:179], v[208:211], v[2:5]
	v_mfma_f32_16x16x32_bf16 v[58:61], v[172:175], v[188:191], v[58:61]
	v_mfma_f32_16x16x32_bf16 v[50:53], v[180:183], v[188:191], v[50:53]
	v_mfma_f32_16x16x32_bf16 v[42:45], v[172:175], v[196:199], v[42:45]
	v_mfma_f32_16x16x32_bf16 v[34:37], v[180:183], v[196:199], v[34:37]
	v_mfma_f32_16x16x32_bf16 v[26:29], v[172:175], v[204:207], v[26:29]
	v_mfma_f32_16x16x32_bf16 v[18:21], v[180:183], v[204:207], v[18:21]
	v_mfma_f32_16x16x32_bf16 v[10:13], v[172:175], v[212:215], v[10:13]
	v_mfma_f32_16x16x32_bf16 v[2:5], v[180:183], v[212:215], v[2:5]
	s_setprio 0
	s_barrier
	s_add_u32 s56, s56, 0x100
	s_addc_u32 s57, s57, 0
	s_add_u32 s24, s24, 0x100
	s_addc_u32 s25, s25, 0
	s_cmp_ge_i32 s58, s43
	s_mov_b32 s26, s58
	s_cbranch_scc0 .LBB0_1976
